# v20 + GEMM M-phase tail: hand-off barrier signalled before s_setprio 0 (one fewer instruction between the last MFMA and the barrier)
# baseline (speedup 1.0000x reference)
; #define PG8_STAGE(bufoff, gbase, voff) do { _Pragma("unroll") for (int _i = 0; _i < 2; ++_i) \
;         dma16((const char*)(gbase), (voff)[_i], ldsb + (bufoff) + ldsw + _i * 8192); } while (0)
; #define PG8_LDA(dst, b, h) do { const int a1_ = opqv(aoff0) ^ 64; _Pragma("unroll") for (int m = 0; m < 4; ++m) { dst[m][0] = *(const LAS bf16x8*)(lds + PG8_SA(b, h) + aoff0 + m * 2048); dst[m][1] = *(const LAS bf16x8*)(lds + PG8_SA(b, h) + a1_ + m * 2048); } } while (0)
; #define PG8_LDB(dst, b, h) do { const int b1_ = opqv(boff0) ^ 64; _Pragma("unroll") for (int n = 0; n < 2; ++n) { dst[n][0] = *(const LAS bf16x8*)(lds + PG8_SB(b, h) + boff0 + n * 2048); dst[n][1] = *(const LAS bf16x8*)(lds + PG8_SB(b, h) + b1_ + n * 2048); } } while (0)
; #define PG8_MMA(ai, bj, At, Bt) do { __builtin_amdgcn_s_setprio(1); _Pragma("unroll") for (int m = 0; m < 4; ++m) _Pragma("unroll") for (int n = 0; n < 2; ++n) _Pragma("unroll") for (int k = 0; k < 2; ++k) \
;         acc[ai][bj][m][n] = __builtin_amdgcn_mfma_f32_16x16x32_bf16(Bt[n][k], At[m][k], acc[ai][bj][m][n], 0, 0, 0); __builtin_amdgcn_s_setprio(0); } while (0)
; template <class Epi>
; __device__ __forceinline__ void gemm_phase(LAS unsigned char* lds, const Gemm g, const StaticOrder& S, const Epi& E, int wave_) {
;     ...
;         const bool has_next = S.next(ui + 1, nxt);
;         const char* nA = has_next ? (const char*)g.A + (size_t)nxt.pm * tstepA : cA; const char* nB = has_next ? (const char*)g.Bt + (size_t)nxt.pn * tstepB : cB;
; #pragma unroll 1
;         for (int t = 0; t < nt; t += 2) {
;             const bool last = (t == nt - 2);
;             const char* a1 = cA + (size_t)(t + 1) * kstep;
;             const char* a2 = last ? nA : cA + (size_t)(t + 2) * kstep; const char* b2 = last ? nB : cB + (size_t)(t + 2) * kstep;
;             const char* a3 = a2 + kstep; const char* b3 = b2 + kstep;
;             PG8_STAGE(PG8_SA(1, 1), a1 + hstepA, voffA); PG8_LDB(B0, 0, 0); PG8_LDB(B1, 0, 1); PG8_SCHED; PG8_LDA(At, 0, 0);
;             PG8_WAIT_V(8); PG8_WAIT_L(0); PG8_BAR; PG8_MMA(0, 0, At, B0); PG8_MMA(0, 1, At, B1); PG8_BAR; PG8_SCHED;
;             PG8_STAGE(PG8_SB(0, 0), b2, voffB); PG8_STAGE(PG8_SB(0, 1), b2 + hstepB, voffB); PG8_STAGE(PG8_SA(0, 0), a2, voffA); PG8_LDA(At, 0, 1);
;             PG8_WAIT_V(8); PG8_WAIT_L(0); PG8_BAR; PG8_MMA(1, 0, At, B0); PG8_MMA(1, 1, At, B1); PG8_BAR; PG8_SCHED;
.LBB0_190:
	s_ashr_i32 s7, s6, 31
	s_lshl_b64 s[8:9], s[6:7], 20
	s_add_u32 s8, s16, s8
	s_addc_u32 s9, s17, s9
	s_and_b64 s[10:11], s[40:41], exec
	s_cselect_b32 s7, s9, s19
	s_cselect_b32 s45, s8, s18
	s_ashr_i32 s5, s4, 31
	s_lshl_b64 s[10:11], s[4:5], 20
	s_add_u32 s10, s21, s10
	s_addc_u32 s11, s30, s11
	s_and_b64 s[24:25], s[40:41], exec
	s_cselect_b32 s5, s11, s13
	s_cselect_b32 s46, s10, s12
	s_add_u32 s47, s12, 0x100
	s_addc_u32 s48, s13, 0
	s_add_u32 s12, s18, 0x80080
	s_addc_u32 s13, s19, 0
	s_mov_b32 s49, -2
	s_add_u32 s18, s12, 0xfff80080
	s_addc_u32 s19, s13, -1
	s_cmp_eq_u32 s49, 28
	s_cselect_b32 s26, s45, s18
	v_mov_b32_e32 v128, v139
	s_cselect_b32 s27, s7, s19
	s_cselect_b32 s24, s46, s47
	s_cselect_b32 s25, s5, s48
	s_add_u32 s18, s26, 0x80
	v_xad_u32 v128, v128, 64, s23
	v_add_u32_e32 v141, s23, v139
	s_addc_u32 s19, s27, 0
	ds_read_b128 v[130:133], v141
	ds_read_b128 v[142:145], v141 offset:2048
	ds_read_b128 v[146:149], v128
	ds_read_b128 v[150:153], v128 offset:2048
	v_mov_b32_e32 v128, v139
	s_add_i32 s52, 0, 0x14000
	v_add_u32_e32 v141, s52, v139
	v_xad_u32 v128, v128, 64, s52
	ds_read_b128 v[154:157], v141
	ds_read_b128 v[158:161], v141 offset:2048
	ds_read_b128 v[162:165], v128
	ds_read_b128 v[166:169], v128 offset:2048
	v_mov_b32_e32 v128, v138
	v_add_u32_e32 v141, 0, v138
	v_xad_u32 v128, v128, 64, 0
	ds_read_b128 v[170:173], v141
	ds_read_b128 v[174:177], v141 offset:2048
	ds_read_b128 v[178:181], v128
	ds_read_b128 v[192:195], v128 offset:2048
	ds_read_b128 v[196:199], v141 offset:4096
	ds_read_b128 v[200:203], v141 offset:6144
	ds_read_b128 v[204:207], v128 offset:4096
	ds_read_b128 v[208:211], v128 offset:6144
	s_mov_b32 m0, s14
	s_nop 0
	global_load_lds_dwordx4 v129, s[12:13]
	s_mov_b32 m0, s15
	s_nop 0
	global_load_lds_dwordx4 v135, s[12:13]
	s_waitcnt vmcnt(8)
	s_waitcnt lgkmcnt(0)
	s_setprio 1
	s_barrier
	v_mfma_f32_16x16x32_bf16 v[124:127], v[130:133], v[170:173], 0
	v_mfma_f32_16x16x32_bf16 v[120:123], v[142:145], v[170:173], 0
	v_mfma_f32_16x16x32_bf16 v[112:115], v[130:133], v[174:177], 0
	v_mfma_f32_16x16x32_bf16 v[104:107], v[142:145], v[174:177], 0
	v_mfma_f32_16x16x32_bf16 v[96:99], v[130:133], v[196:199], 0
	v_mfma_f32_16x16x32_bf16 v[88:91], v[142:145], v[196:199], 0
	v_mfma_f32_16x16x32_bf16 v[80:83], v[130:133], v[200:203], 0
	v_mfma_f32_16x16x32_bf16 v[72:75], v[142:145], v[200:203], 0
	v_mfma_f32_16x16x32_bf16 v[124:127], v[146:149], v[178:181], v[124:127]
	v_mfma_f32_16x16x32_bf16 v[120:123], v[150:153], v[178:181], v[120:123]
	v_mfma_f32_16x16x32_bf16 v[112:115], v[146:149], v[192:195], v[112:115]
	v_mfma_f32_16x16x32_bf16 v[104:107], v[150:153], v[192:195], v[104:107]
	v_mfma_f32_16x16x32_bf16 v[96:99], v[146:149], v[204:207], v[96:99]
	v_mfma_f32_16x16x32_bf16 v[88:91], v[150:153], v[204:207], v[88:91]
	v_mfma_f32_16x16x32_bf16 v[80:83], v[146:149], v[208:211], v[80:83]
	v_mfma_f32_16x16x32_bf16 v[72:75], v[150:153], v[208:211], v[72:75]
	s_setprio 0
	s_setprio 1
	v_mfma_f32_16x16x32_bf16 v[116:119], v[154:157], v[170:173], 0
	v_mfma_f32_16x16x32_bf16 v[108:111], v[158:161], v[170:173], 0
	v_mfma_f32_16x16x32_bf16 v[100:103], v[154:157], v[174:177], 0
	v_mfma_f32_16x16x32_bf16 v[92:95], v[158:161], v[174:177], 0
	v_mfma_f32_16x16x32_bf16 v[84:87], v[154:157], v[196:199], 0
	v_mfma_f32_16x16x32_bf16 v[76:79], v[158:161], v[196:199], 0
	v_mfma_f32_16x16x32_bf16 v[68:71], v[154:157], v[200:203], 0
	v_mfma_f32_16x16x32_bf16 v[64:67], v[158:161], v[200:203], 0
	v_mfma_f32_16x16x32_bf16 v[116:119], v[162:165], v[178:181], v[116:119]
	v_mfma_f32_16x16x32_bf16 v[108:111], v[166:169], v[178:181], v[108:111]
	v_mfma_f32_16x16x32_bf16 v[100:103], v[162:165], v[192:195], v[100:103]
	v_mfma_f32_16x16x32_bf16 v[92:95], v[166:169], v[192:195], v[92:95]
	v_mfma_f32_16x16x32_bf16 v[84:87], v[162:165], v[204:207], v[84:87]
	v_mfma_f32_16x16x32_bf16 v[76:79], v[166:169], v[204:207], v[76:79]
	v_mfma_f32_16x16x32_bf16 v[68:71], v[162:165], v[208:211], v[68:71]
	v_mfma_f32_16x16x32_bf16 v[64:67], v[166:169], v[208:211], v[64:67]
	s_barrier
	s_setprio 0
	s_add_u32 s54, s24, 0x80000
	s_addc_u32 s55, s25, 0
	v_mov_b32_e32 v128, v138
	s_nop 0
	s_nop 0
	s_nop 0
	v_xad_u32 v128, v128, 64, 0
	ds_read_b128 v[170:173], v141 offset:16384
	ds_read_b128 v[174:177], v141 offset:18432
	ds_read_b128 v[178:181], v128 offset:16384
	ds_read_b128 v[192:195], v128 offset:18432
	ds_read_b128 v[196:199], v141 offset:20480
	ds_read_b128 v[200:203], v141 offset:22528
	ds_read_b128 v[204:207], v128 offset:20480
	ds_read_b128 v[208:211], v128 offset:22528
	s_mov_b32 m0, s80
	s_nop 0
	global_load_lds_dwordx4 v134, s[24:25]
	s_mov_b32 m0, s81
	s_nop 0
	global_load_lds_dwordx4 v136, s[24:25]
	s_mov_b32 m0, s29
	s_nop 0
	global_load_lds_dwordx4 v134, s[54:55]
	s_mov_b32 m0, s88
	s_nop 0
	global_load_lds_dwordx4 v136, s[54:55]
	s_mov_b32 m0, s76
	s_nop 0
	global_load_lds_dwordx4 v129, s[26:27]
	s_mov_b32 m0, s89
	s_nop 0
	global_load_lds_dwordx4 v135, s[26:27]
	s_waitcnt vmcnt(8)
	s_waitcnt lgkmcnt(0)
	s_setprio 1
	s_barrier
; #define PG8_STAGE(bufoff, gbase, voff) do { _Pragma("unroll") for (int _i = 0; _i < 2; ++_i) \
;         dma16((const char*)(gbase), (voff)[_i], ldsb + (bufoff) + ldsw + _i * 8192); } while (0)
; #define PG8_LDA(dst, b, h) do { const int a1_ = opqv(aoff0) ^ 64; _Pragma("unroll") for (int m = 0; m < 4; ++m) { dst[m][0] = *(const LAS bf16x8*)(lds + PG8_SA(b, h) + aoff0 + m * 2048); dst[m][1] = *(const LAS bf16x8*)(lds + PG8_SA(b, h) + a1_ + m * 2048); } } while (0)
; #define PG8_LDB(dst, b, h) do { const int b1_ = opqv(boff0) ^ 64; _Pragma("unroll") for (int n = 0; n < 2; ++n) { dst[n][0] = *(const LAS bf16x8*)(lds + PG8_SB(b, h) + boff0 + n * 2048); dst[n][1] = *(const LAS bf16x8*)(lds + PG8_SB(b, h) + b1_ + n * 2048); } } while (0)
; #define PG8_MMA(ai, bj, At, Bt) do { __builtin_amdgcn_s_setprio(1); _Pragma("unroll") for (int m = 0; m < 4; ++m) _Pragma("unroll") for (int n = 0; n < 2; ++n) _Pragma("unroll") for (int k = 0; k < 2; ++k) \
;         acc[ai][bj][m][n] = __builtin_amdgcn_mfma_f32_16x16x32_bf16(Bt[n][k], At[m][k], acc[ai][bj][m][n], 0, 0, 0); __builtin_amdgcn_s_setprio(0); } while (0)
; #define PG8_WAIT_V(n) asm volatile("s_waitcnt vmcnt(" #n ")" ::: "memory")
; #define PG8_WAIT_L(n) asm volatile("s_waitcnt lgkmcnt(" #n ")" ::: "memory")
; #define PG8_BAR __builtin_amdgcn_s_barrier()
; #define PG8_SCHED __builtin_amdgcn_sched_barrier(0)
; template <class Epi>
; __device__ __forceinline__ void gemm_phase(LAS unsigned char* lds, const Gemm g, const StaticOrder& S, const Epi& E, int wave_) {
;     ...
;             PG8_WAIT_V(8); PG8_WAIT_L(0); PG8_BAR; PG8_MMA(1, 0, At, B0); PG8_MMA(1, 1, At, B1); PG8_BAR; PG8_SCHED;
;             PG8_STAGE(PG8_SA(0, 1), a2 + hstepA, voffA); PG8_LDB(B0, 1, 0); PG8_LDB(B1, 1, 1); PG8_SCHED; PG8_LDA(At, 1, 0);
;             PG8_WAIT_V(8); PG8_WAIT_L(0); PG8_BAR; PG8_MMA(0, 0, At, B0); PG8_MMA(0, 1, At, B1); PG8_BAR; PG8_SCHED;
	v_mfma_f32_16x16x32_bf16 v[60:63], v[130:133], v[170:173], 0
	v_mfma_f32_16x16x32_bf16 v[56:59], v[142:145], v[170:173], 0
	v_mfma_f32_16x16x32_bf16 v[48:51], v[130:133], v[174:177], 0
	v_mfma_f32_16x16x32_bf16 v[40:43], v[142:145], v[174:177], 0
	v_mfma_f32_16x16x32_bf16 v[32:35], v[130:133], v[196:199], 0
	v_mfma_f32_16x16x32_bf16 v[24:27], v[142:145], v[196:199], 0
	v_mfma_f32_16x16x32_bf16 v[16:19], v[130:133], v[200:203], 0
	v_mfma_f32_16x16x32_bf16 v[8:11], v[142:145], v[200:203], 0
	v_mfma_f32_16x16x32_bf16 v[60:63], v[146:149], v[178:181], v[60:63]
	v_mfma_f32_16x16x32_bf16 v[56:59], v[150:153], v[178:181], v[56:59]
	v_mfma_f32_16x16x32_bf16 v[48:51], v[146:149], v[192:195], v[48:51]
	v_mfma_f32_16x16x32_bf16 v[40:43], v[150:153], v[192:195], v[40:43]
	v_mfma_f32_16x16x32_bf16 v[32:35], v[146:149], v[204:207], v[32:35]
	v_mfma_f32_16x16x32_bf16 v[24:27], v[150:153], v[204:207], v[24:27]
	v_mfma_f32_16x16x32_bf16 v[16:19], v[146:149], v[208:211], v[16:19]
	v_mfma_f32_16x16x32_bf16 v[8:11], v[150:153], v[208:211], v[8:11]
	s_setprio 0
	s_setprio 1
	v_mfma_f32_16x16x32_bf16 v[52:55], v[154:157], v[170:173], 0
	v_mfma_f32_16x16x32_bf16 v[44:47], v[158:161], v[170:173], 0
	v_mfma_f32_16x16x32_bf16 v[36:39], v[154:157], v[174:177], 0
	v_mfma_f32_16x16x32_bf16 v[28:31], v[158:161], v[174:177], 0
	v_mfma_f32_16x16x32_bf16 v[20:23], v[154:157], v[196:199], 0
	v_mfma_f32_16x16x32_bf16 v[12:15], v[158:161], v[196:199], 0
	v_mfma_f32_16x16x32_bf16 v[4:7], v[154:157], v[200:203], 0
	v_mfma_f32_16x16x32_bf16 v[0:3], v[158:161], v[200:203], 0
	v_mfma_f32_16x16x32_bf16 v[52:55], v[162:165], v[178:181], v[52:55]
	v_mfma_f32_16x16x32_bf16 v[44:47], v[166:169], v[178:181], v[44:47]
	v_mfma_f32_16x16x32_bf16 v[36:39], v[162:165], v[192:195], v[36:39]
	v_mfma_f32_16x16x32_bf16 v[28:31], v[166:169], v[192:195], v[28:31]
	v_mfma_f32_16x16x32_bf16 v[20:23], v[162:165], v[204:207], v[20:23]
	v_mfma_f32_16x16x32_bf16 v[12:15], v[166:169], v[204:207], v[12:15]
	v_mfma_f32_16x16x32_bf16 v[4:7], v[162:165], v[208:211], v[4:7]
	v_mfma_f32_16x16x32_bf16 v[0:3], v[166:169], v[208:211], v[0:3]
	s_barrier
	s_setprio 0
	s_add_u32 s26, s26, 0x80000
	s_addc_u32 s27, s27, 0
	s_mov_b32 m0, s1
	s_nop 0
	global_load_lds_dwordx4 v129, s[26:27]
	v_mov_b32_e32 v128, v139
	s_mov_b32 m0, s69
	s_nop 0
	global_load_lds_dwordx4 v135, s[26:27]
	v_add_u32_e32 v142, s34, v139
	v_xad_u32 v128, v128, 64, s34
	ds_read_b128 v[130:133], v142
	ds_read_b128 v[142:145], v142 offset:2048
	ds_read_b128 v[146:149], v128
	ds_read_b128 v[150:153], v128 offset:2048
	v_mov_b32_e32 v128, v139
	s_add_i32 s26, 0, 0x1c000
	v_add_u32_e32 v158, s26, v139
	v_xad_u32 v128, v128, 64, s26
	ds_read_b128 v[154:157], v158
	ds_read_b128 v[158:161], v158 offset:2048
	ds_read_b128 v[162:165], v128
	ds_read_b128 v[166:169], v128 offset:2048
	v_mov_b32_e32 v128, v138
	s_nop 0
	v_xad_u32 v128, v128, 64, 0
	ds_read_b128 v[170:173], v141 offset:32768
	ds_read_b128 v[174:177], v141 offset:34816
	ds_read_b128 v[178:181], v128 offset:32768
	ds_read_b128 v[192:195], v128 offset:34816
	ds_read_b128 v[196:199], v141 offset:36864
	ds_read_b128 v[200:203], v141 offset:38912
	ds_read_b128 v[204:207], v128 offset:36864
	ds_read_b128 v[208:211], v128 offset:38912
	s_waitcnt vmcnt(8)
	s_waitcnt lgkmcnt(0)
	s_setprio 1
	s_barrier
	v_mfma_f32_16x16x32_bf16 v[124:127], v[130:133], v[170:173], v[124:127]
	v_mfma_f32_16x16x32_bf16 v[120:123], v[142:145], v[170:173], v[120:123]
	v_mfma_f32_16x16x32_bf16 v[112:115], v[130:133], v[174:177], v[112:115]
	v_mfma_f32_16x16x32_bf16 v[104:107], v[142:145], v[174:177], v[104:107]
	v_mfma_f32_16x16x32_bf16 v[96:99], v[130:133], v[196:199], v[96:99]
	v_mfma_f32_16x16x32_bf16 v[88:91], v[142:145], v[196:199], v[88:91]
	v_mfma_f32_16x16x32_bf16 v[80:83], v[130:133], v[200:203], v[80:83]
	v_mfma_f32_16x16x32_bf16 v[72:75], v[142:145], v[200:203], v[72:75]
	v_mfma_f32_16x16x32_bf16 v[124:127], v[146:149], v[178:181], v[124:127]
	v_mfma_f32_16x16x32_bf16 v[120:123], v[150:153], v[178:181], v[120:123]
	v_mfma_f32_16x16x32_bf16 v[112:115], v[146:149], v[192:195], v[112:115]
	v_mfma_f32_16x16x32_bf16 v[104:107], v[150:153], v[192:195], v[104:107]
	v_mfma_f32_16x16x32_bf16 v[96:99], v[146:149], v[204:207], v[96:99]
	v_mfma_f32_16x16x32_bf16 v[88:91], v[150:153], v[204:207], v[88:91]
	v_mfma_f32_16x16x32_bf16 v[80:83], v[146:149], v[208:211], v[80:83]
	v_mfma_f32_16x16x32_bf16 v[72:75], v[150:153], v[208:211], v[72:75]
	s_setprio 0
	s_setprio 1
	v_mfma_f32_16x16x32_bf16 v[116:119], v[154:157], v[170:173], v[116:119]
	s_add_u32 s26, s24, 0x80
	s_addc_u32 s27, s25, 0
	v_mfma_f32_16x16x32_bf16 v[108:111], v[158:161], v[170:173], v[108:111]
	v_mfma_f32_16x16x32_bf16 v[100:103], v[154:157], v[174:177], v[100:103]
	v_mfma_f32_16x16x32_bf16 v[92:95], v[158:161], v[174:177], v[92:95]
	v_mfma_f32_16x16x32_bf16 v[84:87], v[154:157], v[196:199], v[84:87]
	v_mfma_f32_16x16x32_bf16 v[76:79], v[158:161], v[196:199], v[76:79]
	v_mfma_f32_16x16x32_bf16 v[68:71], v[154:157], v[200:203], v[68:71]
	v_mfma_f32_16x16x32_bf16 v[64:67], v[158:161], v[200:203], v[64:67]
	v_mfma_f32_16x16x32_bf16 v[116:119], v[162:165], v[178:181], v[116:119]
	v_mfma_f32_16x16x32_bf16 v[108:111], v[166:169], v[178:181], v[108:111]
	v_mfma_f32_16x16x32_bf16 v[100:103], v[162:165], v[192:195], v[100:103]
	v_mfma_f32_16x16x32_bf16 v[92:95], v[166:169], v[192:195], v[92:95]
	v_mfma_f32_16x16x32_bf16 v[84:87], v[162:165], v[204:207], v[84:87]
	v_mfma_f32_16x16x32_bf16 v[76:79], v[166:169], v[204:207], v[76:79]
	v_mfma_f32_16x16x32_bf16 v[68:71], v[162:165], v[208:211], v[68:71]
	v_mfma_f32_16x16x32_bf16 v[64:67], v[166:169], v[208:211], v[64:67]
	s_barrier
; #define PG8_STAGE(bufoff, gbase, voff) do { _Pragma("unroll") for (int _i = 0; _i < 2; ++_i) \
;         dma16((const char*)(gbase), (voff)[_i], ldsb + (bufoff) + ldsw + _i * 8192); } while (0)
; #define PG8_LDA(dst, b, h) do { const int a1_ = opqv(aoff0) ^ 64; _Pragma("unroll") for (int m = 0; m < 4; ++m) { dst[m][0] = *(const LAS bf16x8*)(lds + PG8_SA(b, h) + aoff0 + m * 2048); dst[m][1] = *(const LAS bf16x8*)(lds + PG8_SA(b, h) + a1_ + m * 2048); } } while (0)
; #define PG8_LDB(dst, b, h) do { const int b1_ = opqv(boff0) ^ 64; _Pragma("unroll") for (int n = 0; n < 2; ++n) { dst[n][0] = *(const LAS bf16x8*)(lds + PG8_SB(b, h) + boff0 + n * 2048); dst[n][1] = *(const LAS bf16x8*)(lds + PG8_SB(b, h) + b1_ + n * 2048); } } while (0)
; #define PG8_WAIT_V(n) asm volatile("s_waitcnt vmcnt(" #n ")" ::: "memory")
; #define PG8_WAIT_L(n) asm volatile("s_waitcnt lgkmcnt(" #n ")" ::: "memory")
; #define PG8_BAR __builtin_amdgcn_s_barrier()
; #define PG8_SCHED __builtin_amdgcn_sched_barrier(0)
; template <class Epi>
; __device__ __forceinline__ void gemm_phase(LAS unsigned char* lds, const Gemm g, const StaticOrder& S, const Epi& E, int wave_) {
;     ...
;             const char* a2 = last ? nA : cA + (size_t)(t + 2) * kstep; const char* b2 = last ? nB : cB + (size_t)(t + 2) * kstep;
;             const char* a3 = a2 + kstep; const char* b3 = b2 + kstep;
;             PG8_STAGE(PG8_SA(1, 1), a1 + hstepA, voffA); PG8_LDB(B0, 0, 0); PG8_LDB(B1, 0, 1); PG8_SCHED; PG8_LDA(At, 0, 0);
;             PG8_WAIT_V(8); PG8_WAIT_L(0); PG8_BAR; PG8_MMA(0, 0, At, B0); PG8_MMA(0, 1, At, B1); PG8_BAR; PG8_SCHED;
;             PG8_STAGE(PG8_SB(0, 0), b2, voffB); PG8_STAGE(PG8_SB(0, 1), b2 + hstepB, voffB); PG8_STAGE(PG8_SA(0, 0), a2, voffA); PG8_LDA(At, 0, 1);
;             PG8_WAIT_V(8); PG8_WAIT_L(0); PG8_BAR; PG8_MMA(1, 0, At, B0); PG8_MMA(1, 1, At, B1); PG8_BAR; PG8_SCHED;
;             PG8_STAGE(PG8_SA(0, 1), a2 + hstepA, voffA); PG8_LDB(B0, 1, 0); PG8_LDB(B1, 1, 1); PG8_SCHED; PG8_LDA(At, 1, 0);
;             PG8_WAIT_V(8); PG8_WAIT_L(0); PG8_BAR; PG8_MMA(0, 0, At, B0); PG8_MMA(0, 1, At, B1); PG8_BAR; PG8_SCHED;
;             PG8_STAGE(PG8_SB(1, 0), b3, voffB); PG8_STAGE(PG8_SB(1, 1), b3 + hstepB, voffB); PG8_STAGE(PG8_SA(1, 0), a3, voffA); PG8_LDA(At, 1, 1);
;             PG8_WAIT_V(8); PG8_WAIT_L(0); PG8_BAR; PG8_MMA(1, 0, At, B0); PG8_MMA(1, 1, At, B1); PG8_BAR; PG8_SCHED;
	s_setprio 0
	s_add_u32 s24, s24, 0x80080
	s_addc_u32 s25, s25, 0
	v_mov_b32_e32 v128, v138
	s_nop 0
	s_nop 0
	v_xad_u32 v128, v128, 64, 0
	ds_read_b128 v[170:173], v141 offset:49152
	ds_read_b128 v[174:177], v141 offset:51200
	ds_read_b128 v[178:181], v128 offset:49152
	ds_read_b128 v[192:195], v128 offset:51200
	ds_read_b128 v[196:199], v141 offset:53248
	ds_read_b128 v[200:203], v141 offset:55296
	ds_read_b128 v[204:207], v128 offset:53248
	ds_read_b128 v[208:211], v128 offset:55296
	s_mov_b32 m0, s35
	s_nop 0
	global_load_lds_dwordx4 v134, s[26:27]
	s_mov_b32 m0, s33
	s_nop 0
	global_load_lds_dwordx4 v136, s[26:27]
	s_mov_b32 m0, s77
	s_nop 0
	global_load_lds_dwordx4 v134, s[24:25]
	s_mov_b32 m0, s3
	s_nop 0
	global_load_lds_dwordx4 v136, s[24:25]
	s_mov_b32 m0, s22
	s_nop 0
	global_load_lds_dwordx4 v129, s[18:19]
	s_mov_b32 m0, s2
	s_nop 0
	global_load_lds_dwordx4 v135, s[18:19]
	s_waitcnt vmcnt(8)
	s_waitcnt lgkmcnt(0)
	s_setprio 1
	s_barrier
	v_mfma_f32_16x16x32_bf16 v[60:63], v[130:133], v[170:173], v[60:63]
	v_mfma_f32_16x16x32_bf16 v[56:59], v[142:145], v[170:173], v[56:59]
	v_mfma_f32_16x16x32_bf16 v[48:51], v[130:133], v[174:177], v[48:51]
	v_mfma_f32_16x16x32_bf16 v[40:43], v[142:145], v[174:177], v[40:43]
	v_mfma_f32_16x16x32_bf16 v[32:35], v[130:133], v[196:199], v[32:35]
	v_mfma_f32_16x16x32_bf16 v[24:27], v[142:145], v[196:199], v[24:27]
	v_mfma_f32_16x16x32_bf16 v[16:19], v[130:133], v[200:203], v[16:19]
	v_mfma_f32_16x16x32_bf16 v[8:11], v[142:145], v[200:203], v[8:11]
	v_mfma_f32_16x16x32_bf16 v[60:63], v[146:149], v[178:181], v[60:63]
	v_mfma_f32_16x16x32_bf16 v[56:59], v[150:153], v[178:181], v[56:59]
	v_mfma_f32_16x16x32_bf16 v[48:51], v[146:149], v[192:195], v[48:51]
	v_mfma_f32_16x16x32_bf16 v[40:43], v[150:153], v[192:195], v[40:43]
	v_mfma_f32_16x16x32_bf16 v[32:35], v[146:149], v[204:207], v[32:35]
	v_mfma_f32_16x16x32_bf16 v[24:27], v[150:153], v[204:207], v[24:27]
	v_mfma_f32_16x16x32_bf16 v[16:19], v[146:149], v[208:211], v[16:19]
	v_mfma_f32_16x16x32_bf16 v[8:11], v[150:153], v[208:211], v[8:11]
	s_setprio 0
	s_setprio 1
	v_mfma_f32_16x16x32_bf16 v[52:55], v[154:157], v[170:173], v[52:55]
	v_mfma_f32_16x16x32_bf16 v[44:47], v[158:161], v[170:173], v[44:47]
	v_mfma_f32_16x16x32_bf16 v[36:39], v[154:157], v[174:177], v[36:39]
	v_mfma_f32_16x16x32_bf16 v[28:31], v[158:161], v[174:177], v[28:31]
	v_mfma_f32_16x16x32_bf16 v[20:23], v[154:157], v[196:199], v[20:23]
	v_mfma_f32_16x16x32_bf16 v[12:15], v[158:161], v[196:199], v[12:15]
	v_mfma_f32_16x16x32_bf16 v[4:7], v[154:157], v[200:203], v[4:7]
	v_mfma_f32_16x16x32_bf16 v[0:3], v[158:161], v[200:203], v[0:3]
	v_mfma_f32_16x16x32_bf16 v[52:55], v[162:165], v[178:181], v[52:55]
	v_mfma_f32_16x16x32_bf16 v[44:47], v[166:169], v[178:181], v[44:47]
	v_mfma_f32_16x16x32_bf16 v[36:39], v[162:165], v[192:195], v[36:39]
	v_mfma_f32_16x16x32_bf16 v[28:31], v[166:169], v[192:195], v[28:31]
	v_mfma_f32_16x16x32_bf16 v[20:23], v[162:165], v[204:207], v[20:23]
	v_mfma_f32_16x16x32_bf16 v[12:15], v[166:169], v[204:207], v[12:15]
	v_mfma_f32_16x16x32_bf16 v[4:7], v[162:165], v[208:211], v[4:7]
	v_mfma_f32_16x16x32_bf16 v[0:3], v[166:169], v[208:211], v[0:3]
	s_barrier
	s_setprio 0
	s_add_i32 s49, s49, 2
	s_add_u32 s47, s47, 0x100
	s_addc_u32 s48, s48, 0
	s_add_u32 s12, s12, 0x100
	s_addc_u32 s13, s13, 0
	s_cmp_gt_u32 s49, 29
	s_cbranch_scc0 .LBB0_191
	s_branch .Lpeel_exit_8
.LBB0_191:
	s_add_u32 s18, s12, 0xfff80080
	s_addc_u32 s19, s13, -1
	s_cmp_eq_u32 s49, 28
	s_cselect_b32 s26, s45, s18
	v_mov_b32_e32 v128, v139
	s_cselect_b32 s27, s7, s19
	s_cselect_b32 s24, s46, s47
	s_cselect_b32 s25, s5, s48
	s_add_u32 s18, s26, 0x80
	v_xad_u32 v128, v128, 64, s23
	v_add_u32_e32 v141, s23, v139
	s_addc_u32 s19, s27, 0
	ds_read_b128 v[130:133], v141
	ds_read_b128 v[142:145], v141 offset:2048
	ds_read_b128 v[146:149], v128
	ds_read_b128 v[150:153], v128 offset:2048
	v_mov_b32_e32 v128, v139
	s_add_i32 s52, 0, 0x14000
	v_add_u32_e32 v141, s52, v139
	v_xad_u32 v128, v128, 64, s52
	ds_read_b128 v[154:157], v141
	ds_read_b128 v[158:161], v141 offset:2048
	ds_read_b128 v[162:165], v128
	ds_read_b128 v[166:169], v128 offset:2048
	v_mov_b32_e32 v128, v138
	v_add_u32_e32 v141, 0, v138
	v_xad_u32 v128, v128, 64, 0
	ds_read_b128 v[170:173], v141
	ds_read_b128 v[174:177], v141 offset:2048
	ds_read_b128 v[178:181], v128
	ds_read_b128 v[192:195], v128 offset:2048
	ds_read_b128 v[196:199], v141 offset:4096
	ds_read_b128 v[200:203], v141 offset:6144
	ds_read_b128 v[204:207], v128 offset:4096
	ds_read_b128 v[208:211], v128 offset:6144
	s_mov_b32 m0, s14
	s_nop 0
	global_load_lds_dwordx4 v129, s[12:13]
	s_mov_b32 m0, s15
	s_nop 0
	global_load_lds_dwordx4 v135, s[12:13]
	s_waitcnt vmcnt(8)
	s_waitcnt lgkmcnt(0)
	s_setprio 1
	s_barrier
; #define PG8_STAGE(bufoff, gbase, voff) do { _Pragma("unroll") for (int _i = 0; _i < 2; ++_i) \
;         dma16((const char*)(gbase), (voff)[_i], ldsb + (bufoff) + ldsw + _i * 8192); } while (0)
; #define PG8_LDA(dst, b, h) do { const int a1_ = opqv(aoff0) ^ 64; _Pragma("unroll") for (int m = 0; m < 4; ++m) { dst[m][0] = *(const LAS bf16x8*)(lds + PG8_SA(b, h) + aoff0 + m * 2048); dst[m][1] = *(const LAS bf16x8*)(lds + PG8_SA(b, h) + a1_ + m * 2048); } } while (0)
; #define PG8_LDB(dst, b, h) do { const int b1_ = opqv(boff0) ^ 64; _Pragma("unroll") for (int n = 0; n < 2; ++n) { dst[n][0] = *(const LAS bf16x8*)(lds + PG8_SB(b, h) + boff0 + n * 2048); dst[n][1] = *(const LAS bf16x8*)(lds + PG8_SB(b, h) + b1_ + n * 2048); } } while (0)
; #define PG8_MMA(ai, bj, At, Bt) do { __builtin_amdgcn_s_setprio(1); _Pragma("unroll") for (int m = 0; m < 4; ++m) _Pragma("unroll") for (int n = 0; n < 2; ++n) _Pragma("unroll") for (int k = 0; k < 2; ++k) \
;         acc[ai][bj][m][n] = __builtin_amdgcn_mfma_f32_16x16x32_bf16(Bt[n][k], At[m][k], acc[ai][bj][m][n], 0, 0, 0); __builtin_amdgcn_s_setprio(0); } while (0)
; #define PG8_WAIT_V(n) asm volatile("s_waitcnt vmcnt(" #n ")" ::: "memory")
; #define PG8_WAIT_L(n) asm volatile("s_waitcnt lgkmcnt(" #n ")" ::: "memory")
; #define PG8_BAR __builtin_amdgcn_s_barrier()
; #define PG8_SCHED __builtin_amdgcn_sched_barrier(0)
; template <class Epi>
; __device__ __forceinline__ void gemm_phase(LAS unsigned char* lds, const Gemm g, const StaticOrder& S, const Epi& E, int wave_) {
;     ...
;             PG8_WAIT_V(8); PG8_WAIT_L(0); PG8_BAR; PG8_MMA(0, 0, At, B0); PG8_MMA(0, 1, At, B1); PG8_BAR; PG8_SCHED;
;             PG8_STAGE(PG8_SB(0, 0), b2, voffB); PG8_STAGE(PG8_SB(0, 1), b2 + hstepB, voffB); PG8_STAGE(PG8_SA(0, 0), a2, voffA); PG8_LDA(At, 0, 1);
;             PG8_WAIT_V(8); PG8_WAIT_L(0); PG8_BAR; PG8_MMA(1, 0, At, B0); PG8_MMA(1, 1, At, B1); PG8_BAR; PG8_SCHED;
;             PG8_STAGE(PG8_SA(0, 1), a2 + hstepA, voffA); PG8_LDB(B0, 1, 0); PG8_LDB(B1, 1, 1); PG8_SCHED; PG8_LDA(At, 1, 0);
;             PG8_WAIT_V(8); PG8_WAIT_L(0); PG8_BAR; PG8_MMA(0, 0, At, B0); PG8_MMA(0, 1, At, B1); PG8_BAR; PG8_SCHED;
	v_mfma_f32_16x16x32_bf16 v[124:127], v[130:133], v[170:173], v[124:127]
	v_mfma_f32_16x16x32_bf16 v[120:123], v[142:145], v[170:173], v[120:123]
	v_mfma_f32_16x16x32_bf16 v[112:115], v[130:133], v[174:177], v[112:115]
	v_mfma_f32_16x16x32_bf16 v[104:107], v[142:145], v[174:177], v[104:107]
	v_mfma_f32_16x16x32_bf16 v[96:99], v[130:133], v[196:199], v[96:99]
	v_mfma_f32_16x16x32_bf16 v[88:91], v[142:145], v[196:199], v[88:91]
	v_mfma_f32_16x16x32_bf16 v[80:83], v[130:133], v[200:203], v[80:83]
	v_mfma_f32_16x16x32_bf16 v[72:75], v[142:145], v[200:203], v[72:75]
	v_mfma_f32_16x16x32_bf16 v[124:127], v[146:149], v[178:181], v[124:127]
	v_mfma_f32_16x16x32_bf16 v[120:123], v[150:153], v[178:181], v[120:123]
	v_mfma_f32_16x16x32_bf16 v[112:115], v[146:149], v[192:195], v[112:115]
	v_mfma_f32_16x16x32_bf16 v[104:107], v[150:153], v[192:195], v[104:107]
	v_mfma_f32_16x16x32_bf16 v[96:99], v[146:149], v[204:207], v[96:99]
	v_mfma_f32_16x16x32_bf16 v[88:91], v[150:153], v[204:207], v[88:91]
	v_mfma_f32_16x16x32_bf16 v[80:83], v[146:149], v[208:211], v[80:83]
	v_mfma_f32_16x16x32_bf16 v[72:75], v[150:153], v[208:211], v[72:75]
	s_setprio 0
	s_setprio 1
	v_mfma_f32_16x16x32_bf16 v[116:119], v[154:157], v[170:173], v[116:119]
	v_mfma_f32_16x16x32_bf16 v[108:111], v[158:161], v[170:173], v[108:111]
	v_mfma_f32_16x16x32_bf16 v[100:103], v[154:157], v[174:177], v[100:103]
	v_mfma_f32_16x16x32_bf16 v[92:95], v[158:161], v[174:177], v[92:95]
	v_mfma_f32_16x16x32_bf16 v[84:87], v[154:157], v[196:199], v[84:87]
	v_mfma_f32_16x16x32_bf16 v[76:79], v[158:161], v[196:199], v[76:79]
	v_mfma_f32_16x16x32_bf16 v[68:71], v[154:157], v[200:203], v[68:71]
	v_mfma_f32_16x16x32_bf16 v[64:67], v[158:161], v[200:203], v[64:67]
	v_mfma_f32_16x16x32_bf16 v[116:119], v[162:165], v[178:181], v[116:119]
	v_mfma_f32_16x16x32_bf16 v[108:111], v[166:169], v[178:181], v[108:111]
	v_mfma_f32_16x16x32_bf16 v[100:103], v[162:165], v[192:195], v[100:103]
	v_mfma_f32_16x16x32_bf16 v[92:95], v[166:169], v[192:195], v[92:95]
	v_mfma_f32_16x16x32_bf16 v[84:87], v[162:165], v[204:207], v[84:87]
	v_mfma_f32_16x16x32_bf16 v[76:79], v[166:169], v[204:207], v[76:79]
	v_mfma_f32_16x16x32_bf16 v[68:71], v[162:165], v[208:211], v[68:71]
	v_mfma_f32_16x16x32_bf16 v[64:67], v[166:169], v[208:211], v[64:67]
	s_barrier
	s_setprio 0
	s_add_u32 s54, s24, 0x80000
	s_addc_u32 s55, s25, 0
	v_mov_b32_e32 v128, v138
	s_nop 0
	s_nop 0
	s_nop 0
	v_xad_u32 v128, v128, 64, 0
	ds_read_b128 v[170:173], v141 offset:16384
	ds_read_b128 v[174:177], v141 offset:18432
	ds_read_b128 v[178:181], v128 offset:16384
	ds_read_b128 v[192:195], v128 offset:18432
	ds_read_b128 v[196:199], v141 offset:20480
	ds_read_b128 v[200:203], v141 offset:22528
	ds_read_b128 v[204:207], v128 offset:20480
	ds_read_b128 v[208:211], v128 offset:22528
	s_mov_b32 m0, s80
	s_nop 0
	global_load_lds_dwordx4 v134, s[24:25]
	s_mov_b32 m0, s81
	s_nop 0
	global_load_lds_dwordx4 v136, s[24:25]
	s_mov_b32 m0, s29
	s_nop 0
	global_load_lds_dwordx4 v134, s[54:55]
	s_mov_b32 m0, s88
	s_nop 0
	global_load_lds_dwordx4 v136, s[54:55]
	s_mov_b32 m0, s76
	s_nop 0
	global_load_lds_dwordx4 v129, s[26:27]
	s_mov_b32 m0, s89
	s_nop 0
	global_load_lds_dwordx4 v135, s[26:27]
	s_waitcnt vmcnt(8)
	s_waitcnt lgkmcnt(0)
	s_setprio 1
	s_barrier
	v_mfma_f32_16x16x32_bf16 v[60:63], v[130:133], v[170:173], v[60:63]
	v_mfma_f32_16x16x32_bf16 v[56:59], v[142:145], v[170:173], v[56:59]
	v_mfma_f32_16x16x32_bf16 v[48:51], v[130:133], v[174:177], v[48:51]
	v_mfma_f32_16x16x32_bf16 v[40:43], v[142:145], v[174:177], v[40:43]
	v_mfma_f32_16x16x32_bf16 v[32:35], v[130:133], v[196:199], v[32:35]
	v_mfma_f32_16x16x32_bf16 v[24:27], v[142:145], v[196:199], v[24:27]
	v_mfma_f32_16x16x32_bf16 v[16:19], v[130:133], v[200:203], v[16:19]
	v_mfma_f32_16x16x32_bf16 v[8:11], v[142:145], v[200:203], v[8:11]
	v_mfma_f32_16x16x32_bf16 v[60:63], v[146:149], v[178:181], v[60:63]
	v_mfma_f32_16x16x32_bf16 v[56:59], v[150:153], v[178:181], v[56:59]
	v_mfma_f32_16x16x32_bf16 v[48:51], v[146:149], v[192:195], v[48:51]
	v_mfma_f32_16x16x32_bf16 v[40:43], v[150:153], v[192:195], v[40:43]
	v_mfma_f32_16x16x32_bf16 v[32:35], v[146:149], v[204:207], v[32:35]
	v_mfma_f32_16x16x32_bf16 v[24:27], v[150:153], v[204:207], v[24:27]
	v_mfma_f32_16x16x32_bf16 v[16:19], v[146:149], v[208:211], v[16:19]
	v_mfma_f32_16x16x32_bf16 v[8:11], v[150:153], v[208:211], v[8:11]
	s_setprio 0
	s_setprio 1
	v_mfma_f32_16x16x32_bf16 v[52:55], v[154:157], v[170:173], v[52:55]
	v_mfma_f32_16x16x32_bf16 v[44:47], v[158:161], v[170:173], v[44:47]
	v_mfma_f32_16x16x32_bf16 v[36:39], v[154:157], v[174:177], v[36:39]
	v_mfma_f32_16x16x32_bf16 v[28:31], v[158:161], v[174:177], v[28:31]
	v_mfma_f32_16x16x32_bf16 v[20:23], v[154:157], v[196:199], v[20:23]
	v_mfma_f32_16x16x32_bf16 v[12:15], v[158:161], v[196:199], v[12:15]
	v_mfma_f32_16x16x32_bf16 v[4:7], v[154:157], v[200:203], v[4:7]
	v_mfma_f32_16x16x32_bf16 v[0:3], v[158:161], v[200:203], v[0:3]
	v_mfma_f32_16x16x32_bf16 v[52:55], v[162:165], v[178:181], v[52:55]
	v_mfma_f32_16x16x32_bf16 v[44:47], v[166:169], v[178:181], v[44:47]
	v_mfma_f32_16x16x32_bf16 v[36:39], v[162:165], v[192:195], v[36:39]
	v_mfma_f32_16x16x32_bf16 v[28:31], v[166:169], v[192:195], v[28:31]
	v_mfma_f32_16x16x32_bf16 v[20:23], v[162:165], v[204:207], v[20:23]
	v_mfma_f32_16x16x32_bf16 v[12:15], v[166:169], v[204:207], v[12:15]
	v_mfma_f32_16x16x32_bf16 v[4:7], v[162:165], v[208:211], v[4:7]
	v_mfma_f32_16x16x32_bf16 v[0:3], v[166:169], v[208:211], v[0:3]
	s_barrier
; #define PG8_STAGE(bufoff, gbase, voff) do { _Pragma("unroll") for (int _i = 0; _i < 2; ++_i) \
;         dma16((const char*)(gbase), (voff)[_i], ldsb + (bufoff) + ldsw + _i * 8192); } while (0)
; #define PG8_LDA(dst, b, h) do { const int a1_ = opqv(aoff0) ^ 64; _Pragma("unroll") for (int m = 0; m < 4; ++m) { dst[m][0] = *(const LAS bf16x8*)(lds + PG8_SA(b, h) + aoff0 + m * 2048); dst[m][1] = *(const LAS bf16x8*)(lds + PG8_SA(b, h) + a1_ + m * 2048); } } while (0)
; #define PG8_LDB(dst, b, h) do { const int b1_ = opqv(boff0) ^ 64; _Pragma("unroll") for (int n = 0; n < 2; ++n) { dst[n][0] = *(const LAS bf16x8*)(lds + PG8_SB(b, h) + boff0 + n * 2048); dst[n][1] = *(const LAS bf16x8*)(lds + PG8_SB(b, h) + b1_ + n * 2048); } } while (0)
; #define PG8_MMA(ai, bj, At, Bt) do { __builtin_amdgcn_s_setprio(1); _Pragma("unroll") for (int m = 0; m < 4; ++m) _Pragma("unroll") for (int n = 0; n < 2; ++n) _Pragma("unroll") for (int k = 0; k < 2; ++k) \
;         acc[ai][bj][m][n] = __builtin_amdgcn_mfma_f32_16x16x32_bf16(Bt[n][k], At[m][k], acc[ai][bj][m][n], 0, 0, 0); __builtin_amdgcn_s_setprio(0); } while (0)
; #define PG8_WAIT_V(n) asm volatile("s_waitcnt vmcnt(" #n ")" ::: "memory")
; #define PG8_WAIT_L(n) asm volatile("s_waitcnt lgkmcnt(" #n ")" ::: "memory")
; #define PG8_BAR __builtin_amdgcn_s_barrier()
; #define PG8_SCHED __builtin_amdgcn_sched_barrier(0)
; template <class Epi>
; __device__ __forceinline__ void gemm_phase(LAS unsigned char* lds, const Gemm g, const StaticOrder& S, const Epi& E, int wave_) {
;     ...
;             PG8_STAGE(PG8_SA(0, 1), a2 + hstepA, voffA); PG8_LDB(B0, 1, 0); PG8_LDB(B1, 1, 1); PG8_SCHED; PG8_LDA(At, 1, 0);
;             PG8_WAIT_V(8); PG8_WAIT_L(0); PG8_BAR; PG8_MMA(0, 0, At, B0); PG8_MMA(0, 1, At, B1); PG8_BAR; PG8_SCHED;
;             PG8_STAGE(PG8_SB(1, 0), b3, voffB); PG8_STAGE(PG8_SB(1, 1), b3 + hstepB, voffB); PG8_STAGE(PG8_SA(1, 0), a3, voffA); PG8_LDA(At, 1, 1);
;             PG8_WAIT_V(8); PG8_WAIT_L(0); PG8_BAR; PG8_MMA(1, 0, At, B0); PG8_MMA(1, 1, At, B1); PG8_BAR; PG8_SCHED;
;         }
	s_setprio 0
	s_add_u32 s26, s26, 0x80000
	s_addc_u32 s27, s27, 0
	s_mov_b32 m0, s1
	s_nop 0
	global_load_lds_dwordx4 v129, s[26:27]
	v_mov_b32_e32 v128, v139
	s_mov_b32 m0, s69
	s_nop 0
	global_load_lds_dwordx4 v135, s[26:27]
	v_add_u32_e32 v142, s34, v139
	v_xad_u32 v128, v128, 64, s34
	ds_read_b128 v[130:133], v142
	ds_read_b128 v[142:145], v142 offset:2048
	ds_read_b128 v[146:149], v128
	ds_read_b128 v[150:153], v128 offset:2048
	v_mov_b32_e32 v128, v139
	s_add_i32 s26, 0, 0x1c000
	v_add_u32_e32 v158, s26, v139
	v_xad_u32 v128, v128, 64, s26
	ds_read_b128 v[154:157], v158
	ds_read_b128 v[158:161], v158 offset:2048
	ds_read_b128 v[162:165], v128
	ds_read_b128 v[166:169], v128 offset:2048
	v_mov_b32_e32 v128, v138
	s_nop 0
	v_xad_u32 v128, v128, 64, 0
	ds_read_b128 v[170:173], v141 offset:32768
	ds_read_b128 v[174:177], v141 offset:34816
	ds_read_b128 v[178:181], v128 offset:32768
	ds_read_b128 v[192:195], v128 offset:34816
	ds_read_b128 v[196:199], v141 offset:36864
	ds_read_b128 v[200:203], v141 offset:38912
	ds_read_b128 v[204:207], v128 offset:36864
	ds_read_b128 v[208:211], v128 offset:38912
	s_waitcnt vmcnt(8)
	s_waitcnt lgkmcnt(0)
	s_setprio 1
	s_barrier
	v_mfma_f32_16x16x32_bf16 v[124:127], v[130:133], v[170:173], v[124:127]
	v_mfma_f32_16x16x32_bf16 v[120:123], v[142:145], v[170:173], v[120:123]
	v_mfma_f32_16x16x32_bf16 v[112:115], v[130:133], v[174:177], v[112:115]
	v_mfma_f32_16x16x32_bf16 v[104:107], v[142:145], v[174:177], v[104:107]
	v_mfma_f32_16x16x32_bf16 v[96:99], v[130:133], v[196:199], v[96:99]
	v_mfma_f32_16x16x32_bf16 v[88:91], v[142:145], v[196:199], v[88:91]
	v_mfma_f32_16x16x32_bf16 v[80:83], v[130:133], v[200:203], v[80:83]
	v_mfma_f32_16x16x32_bf16 v[72:75], v[142:145], v[200:203], v[72:75]
	v_mfma_f32_16x16x32_bf16 v[124:127], v[146:149], v[178:181], v[124:127]
	v_mfma_f32_16x16x32_bf16 v[120:123], v[150:153], v[178:181], v[120:123]
	v_mfma_f32_16x16x32_bf16 v[112:115], v[146:149], v[192:195], v[112:115]
	v_mfma_f32_16x16x32_bf16 v[104:107], v[150:153], v[192:195], v[104:107]
	v_mfma_f32_16x16x32_bf16 v[96:99], v[146:149], v[204:207], v[96:99]
	v_mfma_f32_16x16x32_bf16 v[88:91], v[150:153], v[204:207], v[88:91]
	v_mfma_f32_16x16x32_bf16 v[80:83], v[146:149], v[208:211], v[80:83]
	v_mfma_f32_16x16x32_bf16 v[72:75], v[150:153], v[208:211], v[72:75]
	s_setprio 0
	s_setprio 1
	v_mfma_f32_16x16x32_bf16 v[116:119], v[154:157], v[170:173], v[116:119]
	s_add_u32 s26, s24, 0x80
	s_addc_u32 s27, s25, 0
	v_mfma_f32_16x16x32_bf16 v[108:111], v[158:161], v[170:173], v[108:111]
	v_mfma_f32_16x16x32_bf16 v[100:103], v[154:157], v[174:177], v[100:103]
	v_mfma_f32_16x16x32_bf16 v[92:95], v[158:161], v[174:177], v[92:95]
	v_mfma_f32_16x16x32_bf16 v[84:87], v[154:157], v[196:199], v[84:87]
	v_mfma_f32_16x16x32_bf16 v[76:79], v[158:161], v[196:199], v[76:79]
	v_mfma_f32_16x16x32_bf16 v[68:71], v[154:157], v[200:203], v[68:71]
	v_mfma_f32_16x16x32_bf16 v[64:67], v[158:161], v[200:203], v[64:67]
	v_mfma_f32_16x16x32_bf16 v[116:119], v[162:165], v[178:181], v[116:119]
	v_mfma_f32_16x16x32_bf16 v[108:111], v[166:169], v[178:181], v[108:111]
	v_mfma_f32_16x16x32_bf16 v[100:103], v[162:165], v[192:195], v[100:103]
	v_mfma_f32_16x16x32_bf16 v[92:95], v[166:169], v[192:195], v[92:95]
	v_mfma_f32_16x16x32_bf16 v[84:87], v[162:165], v[204:207], v[84:87]
	v_mfma_f32_16x16x32_bf16 v[76:79], v[166:169], v[204:207], v[76:79]
	v_mfma_f32_16x16x32_bf16 v[68:71], v[162:165], v[208:211], v[68:71]
	v_mfma_f32_16x16x32_bf16 v[64:67], v[166:169], v[208:211], v[64:67]
	s_barrier
	s_setprio 0
	s_add_u32 s24, s24, 0x80080
	s_addc_u32 s25, s25, 0
	v_mov_b32_e32 v128, v138
	s_nop 0
	s_nop 0
	v_xad_u32 v128, v128, 64, 0
	ds_read_b128 v[170:173], v141 offset:49152
	ds_read_b128 v[174:177], v141 offset:51200
	ds_read_b128 v[178:181], v128 offset:49152
	ds_read_b128 v[192:195], v128 offset:51200
	ds_read_b128 v[196:199], v141 offset:53248
	ds_read_b128 v[200:203], v141 offset:55296
	ds_read_b128 v[204:207], v128 offset:53248
	ds_read_b128 v[208:211], v128 offset:55296
	s_mov_b32 m0, s35
	s_nop 0
	global_load_lds_dwordx4 v134, s[26:27]
	s_mov_b32 m0, s33
	s_nop 0
	global_load_lds_dwordx4 v136, s[26:27]
	s_mov_b32 m0, s77
	s_nop 0
	global_load_lds_dwordx4 v134, s[24:25]
	s_mov_b32 m0, s3
	s_nop 0
	global_load_lds_dwordx4 v136, s[24:25]
	s_mov_b32 m0, s22
	s_nop 0
	global_load_lds_dwordx4 v129, s[18:19]
	s_mov_b32 m0, s2
	s_nop 0
	global_load_lds_dwordx4 v135, s[18:19]
	s_waitcnt vmcnt(8)
	s_waitcnt lgkmcnt(0)
	s_setprio 1
	s_barrier
	v_mfma_f32_16x16x32_bf16 v[60:63], v[130:133], v[170:173], v[60:63]
	v_mfma_f32_16x16x32_bf16 v[56:59], v[142:145], v[170:173], v[56:59]
	v_mfma_f32_16x16x32_bf16 v[48:51], v[130:133], v[174:177], v[48:51]
	v_mfma_f32_16x16x32_bf16 v[40:43], v[142:145], v[174:177], v[40:43]
	v_mfma_f32_16x16x32_bf16 v[32:35], v[130:133], v[196:199], v[32:35]
	v_mfma_f32_16x16x32_bf16 v[24:27], v[142:145], v[196:199], v[24:27]
	v_mfma_f32_16x16x32_bf16 v[16:19], v[130:133], v[200:203], v[16:19]
	v_mfma_f32_16x16x32_bf16 v[8:11], v[142:145], v[200:203], v[8:11]
	v_mfma_f32_16x16x32_bf16 v[60:63], v[146:149], v[178:181], v[60:63]
	v_mfma_f32_16x16x32_bf16 v[56:59], v[150:153], v[178:181], v[56:59]
	v_mfma_f32_16x16x32_bf16 v[48:51], v[146:149], v[192:195], v[48:51]
	v_mfma_f32_16x16x32_bf16 v[40:43], v[150:153], v[192:195], v[40:43]
	v_mfma_f32_16x16x32_bf16 v[32:35], v[146:149], v[204:207], v[32:35]
	v_mfma_f32_16x16x32_bf16 v[24:27], v[150:153], v[204:207], v[24:27]
	v_mfma_f32_16x16x32_bf16 v[16:19], v[146:149], v[208:211], v[16:19]
	v_mfma_f32_16x16x32_bf16 v[8:11], v[150:153], v[208:211], v[8:11]
	s_setprio 0
	s_setprio 1
	v_mfma_f32_16x16x32_bf16 v[52:55], v[154:157], v[170:173], v[52:55]
	v_mfma_f32_16x16x32_bf16 v[44:47], v[158:161], v[170:173], v[44:47]
	v_mfma_f32_16x16x32_bf16 v[36:39], v[154:157], v[174:177], v[36:39]
	v_mfma_f32_16x16x32_bf16 v[28:31], v[158:161], v[174:177], v[28:31]
	v_mfma_f32_16x16x32_bf16 v[20:23], v[154:157], v[196:199], v[20:23]
	v_mfma_f32_16x16x32_bf16 v[12:15], v[158:161], v[196:199], v[12:15]
	v_mfma_f32_16x16x32_bf16 v[4:7], v[154:157], v[200:203], v[4:7]
	v_mfma_f32_16x16x32_bf16 v[0:3], v[158:161], v[200:203], v[0:3]
	v_mfma_f32_16x16x32_bf16 v[52:55], v[162:165], v[178:181], v[52:55]
	v_mfma_f32_16x16x32_bf16 v[44:47], v[166:169], v[178:181], v[44:47]
	v_mfma_f32_16x16x32_bf16 v[36:39], v[162:165], v[192:195], v[36:39]
	v_mfma_f32_16x16x32_bf16 v[28:31], v[166:169], v[192:195], v[28:31]
	v_mfma_f32_16x16x32_bf16 v[20:23], v[162:165], v[204:207], v[20:23]
	v_mfma_f32_16x16x32_bf16 v[12:15], v[166:169], v[204:207], v[12:15]
	v_mfma_f32_16x16x32_bf16 v[4:7], v[162:165], v[208:211], v[4:7]
	v_mfma_f32_16x16x32_bf16 v[0:3], v[166:169], v[208:211], v[0:3]
	s_barrier
	s_setprio 0
	s_add_i32 s49, s49, 2
	s_add_u32 s47, s47, 0x100
	s_addc_u32 s48, s48, 0
	s_add_u32 s12, s12, 0x100
	s_addc_u32 s13, s13, 0
	s_cmp_gt_u32 s49, 29
	s_cbranch_scc0 .LBB0_191

; #define PG8_STAGE(bufoff, gbase, voff) do { _Pragma("unroll") for (int _i = 0; _i < 2; ++_i) \
;         dma16((const char*)(gbase), (voff)[_i], ldsb + (bufoff) + ldsw + _i * 8192); } while (0)
; #define PG8_LDA(dst, b, h) do { const int a1_ = opqv(aoff0) ^ 64; _Pragma("unroll") for (int m = 0; m < 4; ++m) { dst[m][0] = *(const LAS bf16x8*)(lds + PG8_SA(b, h) + aoff0 + m * 2048); dst[m][1] = *(const LAS bf16x8*)(lds + PG8_SA(b, h) + a1_ + m * 2048); } } while (0)
; #define PG8_LDB(dst, b, h) do { const int b1_ = opqv(boff0) ^ 64; _Pragma("unroll") for (int n = 0; n < 2; ++n) { dst[n][0] = *(const LAS bf16x8*)(lds + PG8_SB(b, h) + boff0 + n * 2048); dst[n][1] = *(const LAS bf16x8*)(lds + PG8_SB(b, h) + b1_ + n * 2048); } } while (0)
; #define PG8_MMA(ai, bj, At, Bt) do { __builtin_amdgcn_s_setprio(1); _Pragma("unroll") for (int m = 0; m < 4; ++m) _Pragma("unroll") for (int n = 0; n < 2; ++n) _Pragma("unroll") for (int k = 0; k < 2; ++k) \
;         acc[ai][bj][m][n] = __builtin_amdgcn_mfma_f32_16x16x32_bf16(Bt[n][k], At[m][k], acc[ai][bj][m][n], 0, 0, 0); __builtin_amdgcn_s_setprio(0); } while (0)
; template <class Epi>
; __device__ __forceinline__ void gemm_phase(LAS unsigned char* lds, const Gemm g, const StaticOrder& S, const Epi& E, int wave_) {
;     ...
;         const bool has_next = S.next(ui + 1, nxt);
;         const char* nA = has_next ? (const char*)g.A + (size_t)nxt.pm * tstepA : cA; const char* nB = has_next ? (const char*)g.Bt + (size_t)nxt.pn * tstepB : cB;
; #pragma unroll 1
;         for (int t = 0; t < nt; t += 2) {
;             const bool last = (t == nt - 2);
;             const char* a1 = cA + (size_t)(t + 1) * kstep;
;             const char* a2 = last ? nA : cA + (size_t)(t + 2) * kstep; const char* b2 = last ? nB : cB + (size_t)(t + 2) * kstep;
;             const char* a3 = a2 + kstep; const char* b3 = b2 + kstep;
;             PG8_STAGE(PG8_SA(1, 1), a1 + hstepA, voffA); PG8_LDB(B0, 0, 0); PG8_LDB(B1, 0, 1); PG8_SCHED; PG8_LDA(At, 0, 0);
;             PG8_WAIT_V(8); PG8_WAIT_L(0); PG8_BAR; PG8_MMA(0, 0, At, B0); PG8_MMA(0, 1, At, B1); PG8_BAR; PG8_SCHED;
;             PG8_STAGE(PG8_SB(0, 0), b2, voffB); PG8_STAGE(PG8_SB(0, 1), b2 + hstepB, voffB); PG8_STAGE(PG8_SA(0, 0), a2, voffA); PG8_LDA(At, 0, 1);
;             PG8_WAIT_V(8); PG8_WAIT_L(0); PG8_BAR; PG8_MMA(1, 0, At, B0); PG8_MMA(1, 1, At, B1); PG8_BAR; PG8_SCHED;
.LBB0_573:
	s_ashr_i32 s11, s10, 31
	s_lshl_b64 s[16:17], s[10:11], 20
	s_add_u32 s18, s21, s16
	s_addc_u32 s19, s44, s17
	s_and_b64 s[16:17], s[42:43], exec
	s_cselect_b32 s11, s19, s27
	s_cselect_b32 s16, s18, s26
	s_ashr_i32 s9, s8, 31
	s_lshl_b64 s[24:25], s[8:9], 20
	s_add_u32 s24, s45, s24
	s_addc_u32 s25, s46, s25
	s_and_b64 s[30:31], s[42:43], exec
	s_cselect_b32 s9, s25, s13
	s_cselect_b32 s17, s24, s12
	s_add_u32 s52, s12, 0x100
	s_addc_u32 s56, s13, 0
	s_add_u32 s12, s26, 0x80080
	s_addc_u32 s13, s27, 0
	s_mov_b32 s57, -2
	s_add_u32 s26, s12, 0xfff80080
	s_addc_u32 s27, s13, -1
	s_cmp_eq_u32 s57, 28
	s_cselect_b32 s36, s16, s26
	v_mov_b32_e32 v128, v144
	s_cselect_b32 s37, s11, s27
	s_cselect_b32 s30, s17, s52
	s_cselect_b32 s31, s9, s56
	s_add_u32 s26, s36, 0x80
	v_add_u32_e32 v137, s23, v144
	v_xad_u32 v136, v128, 64, s23
	s_addc_u32 s27, s37, 0
	ds_read_b128 v[128:131], v137
	ds_read_b128 v[146:149], v137 offset:2048
	ds_read_b128 v[150:153], v136
	ds_read_b128 v[154:157], v136 offset:2048
	v_mov_b32_e32 v136, v144
	s_add_i32 s58, 0, 0x14000
	v_add_u32_e32 v137, s58, v144
	v_xad_u32 v136, v136, 64, s58
	ds_read_b128 v[158:161], v137
	ds_read_b128 v[162:165], v137 offset:2048
	ds_read_b128 v[166:169], v136
	ds_read_b128 v[170:173], v136 offset:2048
	v_mov_b32_e32 v136, v143
	v_add_u32_e32 v137, 0, v143
	v_xad_u32 v136, v136, 64, 0
	ds_read_b128 v[174:177], v137
	ds_read_b128 v[178:181], v137 offset:2048
	ds_read_b128 v[192:195], v136
	ds_read_b128 v[196:199], v136 offset:2048
	ds_read_b128 v[200:203], v137 offset:4096
	ds_read_b128 v[204:207], v137 offset:6144
	ds_read_b128 v[208:211], v136 offset:4096
	ds_read_b128 v[212:215], v136 offset:6144
	s_mov_b32 m0, s14
	s_nop 0
	global_load_lds_dwordx4 v138, s[12:13]
	s_mov_b32 m0, s15
	s_nop 0
	global_load_lds_dwordx4 v140, s[12:13]
	s_waitcnt vmcnt(8)
	s_waitcnt lgkmcnt(0)
	s_setprio 1
	s_barrier
	v_mfma_f32_16x16x32_bf16 v[124:127], v[128:131], v[174:177], 0
	v_mfma_f32_16x16x32_bf16 v[120:123], v[146:149], v[174:177], 0
	v_mfma_f32_16x16x32_bf16 v[108:111], v[128:131], v[178:181], 0
	v_mfma_f32_16x16x32_bf16 v[104:107], v[146:149], v[178:181], 0
	v_mfma_f32_16x16x32_bf16 v[92:95], v[128:131], v[200:203], 0
	v_mfma_f32_16x16x32_bf16 v[88:91], v[146:149], v[200:203], 0
	v_mfma_f32_16x16x32_bf16 v[76:79], v[128:131], v[204:207], 0
	v_mfma_f32_16x16x32_bf16 v[72:75], v[146:149], v[204:207], 0
	v_mfma_f32_16x16x32_bf16 v[124:127], v[150:153], v[192:195], v[124:127]
	v_mfma_f32_16x16x32_bf16 v[120:123], v[154:157], v[192:195], v[120:123]
	v_mfma_f32_16x16x32_bf16 v[108:111], v[150:153], v[196:199], v[108:111]
	v_mfma_f32_16x16x32_bf16 v[104:107], v[154:157], v[196:199], v[104:107]
	v_mfma_f32_16x16x32_bf16 v[92:95], v[150:153], v[208:211], v[92:95]
	v_mfma_f32_16x16x32_bf16 v[88:91], v[154:157], v[208:211], v[88:91]
	v_mfma_f32_16x16x32_bf16 v[76:79], v[150:153], v[212:215], v[76:79]
	v_mfma_f32_16x16x32_bf16 v[72:75], v[154:157], v[212:215], v[72:75]
	s_setprio 0
	s_setprio 1
	v_mfma_f32_16x16x32_bf16 v[116:119], v[158:161], v[174:177], 0
	v_mfma_f32_16x16x32_bf16 v[112:115], v[162:165], v[174:177], 0
	v_mfma_f32_16x16x32_bf16 v[100:103], v[158:161], v[178:181], 0
	v_mfma_f32_16x16x32_bf16 v[96:99], v[162:165], v[178:181], 0
	v_mfma_f32_16x16x32_bf16 v[84:87], v[158:161], v[200:203], 0
	v_mfma_f32_16x16x32_bf16 v[80:83], v[162:165], v[200:203], 0
	v_mfma_f32_16x16x32_bf16 v[68:71], v[158:161], v[204:207], 0
	v_mfma_f32_16x16x32_bf16 v[64:67], v[162:165], v[204:207], 0
	v_mfma_f32_16x16x32_bf16 v[116:119], v[166:169], v[192:195], v[116:119]
	v_mfma_f32_16x16x32_bf16 v[112:115], v[170:173], v[192:195], v[112:115]
	v_mfma_f32_16x16x32_bf16 v[100:103], v[166:169], v[196:199], v[100:103]
	v_mfma_f32_16x16x32_bf16 v[96:99], v[170:173], v[196:199], v[96:99]
	v_mfma_f32_16x16x32_bf16 v[84:87], v[166:169], v[208:211], v[84:87]
	v_mfma_f32_16x16x32_bf16 v[80:83], v[170:173], v[208:211], v[80:83]
	v_mfma_f32_16x16x32_bf16 v[68:71], v[166:169], v[212:215], v[68:71]
	v_mfma_f32_16x16x32_bf16 v[64:67], v[170:173], v[212:215], v[64:67]
	s_barrier
	s_setprio 0
	v_mov_b32_e32 v136, v143
	s_add_u32 s58, s30, 0x80000
	s_addc_u32 s59, s31, 0
	s_nop 0
	s_nop 0
	s_nop 0
	v_xad_u32 v136, v136, 64, 0
	ds_read_b128 v[174:177], v137 offset:16384
	ds_read_b128 v[178:181], v137 offset:18432
	ds_read_b128 v[192:195], v136 offset:16384
	ds_read_b128 v[196:199], v136 offset:18432
	ds_read_b128 v[200:203], v137 offset:20480
	ds_read_b128 v[204:207], v137 offset:22528
	ds_read_b128 v[208:211], v136 offset:20480
	ds_read_b128 v[212:215], v136 offset:22528
	s_mov_b32 m0, s80
	s_nop 0
	global_load_lds_dwordx4 v139, s[30:31]
	s_mov_b32 m0, s81
	s_nop 0
	global_load_lds_dwordx4 v141, s[30:31]
	s_mov_b32 m0, s29
	s_nop 0
	global_load_lds_dwordx4 v139, s[58:59]
	s_mov_b32 m0, s88
	s_nop 0
	global_load_lds_dwordx4 v141, s[58:59]
	s_mov_b32 m0, s76
	s_nop 0
	global_load_lds_dwordx4 v138, s[36:37]
	s_mov_b32 m0, s89
	s_nop 0
	global_load_lds_dwordx4 v140, s[36:37]
	s_waitcnt vmcnt(8)
	s_waitcnt lgkmcnt(0)
	s_setprio 1
	s_barrier
; #define PG8_STAGE(bufoff, gbase, voff) do { _Pragma("unroll") for (int _i = 0; _i < 2; ++_i) \
;         dma16((const char*)(gbase), (voff)[_i], ldsb + (bufoff) + ldsw + _i * 8192); } while (0)
; #define PG8_LDA(dst, b, h) do { const int a1_ = opqv(aoff0) ^ 64; _Pragma("unroll") for (int m = 0; m < 4; ++m) { dst[m][0] = *(const LAS bf16x8*)(lds + PG8_SA(b, h) + aoff0 + m * 2048); dst[m][1] = *(const LAS bf16x8*)(lds + PG8_SA(b, h) + a1_ + m * 2048); } } while (0)
; #define PG8_LDB(dst, b, h) do { const int b1_ = opqv(boff0) ^ 64; _Pragma("unroll") for (int n = 0; n < 2; ++n) { dst[n][0] = *(const LAS bf16x8*)(lds + PG8_SB(b, h) + boff0 + n * 2048); dst[n][1] = *(const LAS bf16x8*)(lds + PG8_SB(b, h) + b1_ + n * 2048); } } while (0)
; #define PG8_MMA(ai, bj, At, Bt) do { __builtin_amdgcn_s_setprio(1); _Pragma("unroll") for (int m = 0; m < 4; ++m) _Pragma("unroll") for (int n = 0; n < 2; ++n) _Pragma("unroll") for (int k = 0; k < 2; ++k) \
;         acc[ai][bj][m][n] = __builtin_amdgcn_mfma_f32_16x16x32_bf16(Bt[n][k], At[m][k], acc[ai][bj][m][n], 0, 0, 0); __builtin_amdgcn_s_setprio(0); } while (0)
; #define PG8_WAIT_V(n) asm volatile("s_waitcnt vmcnt(" #n ")" ::: "memory")
; #define PG8_WAIT_L(n) asm volatile("s_waitcnt lgkmcnt(" #n ")" ::: "memory")
; #define PG8_BAR __builtin_amdgcn_s_barrier()
; template <class Epi>
; __device__ __forceinline__ void gemm_phase(LAS unsigned char* lds, const Gemm g, const StaticOrder& S, const Epi& E, int wave_) {
;     ...
;             PG8_WAIT_V(8); PG8_WAIT_L(0); PG8_BAR; PG8_MMA(0, 0, At, B0); PG8_MMA(0, 1, At, B1); PG8_BAR; PG8_SCHED;
;             PG8_STAGE(PG8_SB(0, 0), b2, voffB); PG8_STAGE(PG8_SB(0, 1), b2 + hstepB, voffB); PG8_STAGE(PG8_SA(0, 0), a2, voffA); PG8_LDA(At, 0, 1);
;             PG8_WAIT_V(8); PG8_WAIT_L(0); PG8_BAR; PG8_MMA(1, 0, At, B0); PG8_MMA(1, 1, At, B1); PG8_BAR; PG8_SCHED;
;             PG8_STAGE(PG8_SA(0, 1), a2 + hstepA, voffA); PG8_LDB(B0, 1, 0); PG8_LDB(B1, 1, 1); PG8_SCHED; PG8_LDA(At, 1, 0);
;             PG8_WAIT_V(8); PG8_WAIT_L(0); PG8_BAR; PG8_MMA(0, 0, At, B0); PG8_MMA(0, 1, At, B1); PG8_BAR; PG8_SCHED;
;             PG8_STAGE(PG8_SB(1, 0), b3, voffB); PG8_STAGE(PG8_SB(1, 1), b3 + hstepB, voffB); PG8_STAGE(PG8_SA(1, 0), a3, voffA); PG8_LDA(At, 1, 1);
;             PG8_WAIT_V(8); PG8_WAIT_L(0); PG8_BAR; PG8_MMA(1, 0, At, B0); PG8_MMA(1, 1, At, B1); PG8_BAR; PG8_SCHED;
	v_mfma_f32_16x16x32_bf16 v[60:63], v[128:131], v[174:177], 0
	v_mfma_f32_16x16x32_bf16 v[56:59], v[146:149], v[174:177], 0
	v_mfma_f32_16x16x32_bf16 v[44:47], v[128:131], v[178:181], 0
	v_mfma_f32_16x16x32_bf16 v[40:43], v[146:149], v[178:181], 0
	v_mfma_f32_16x16x32_bf16 v[28:31], v[128:131], v[200:203], 0
	v_mfma_f32_16x16x32_bf16 v[24:27], v[146:149], v[200:203], 0
	v_mfma_f32_16x16x32_bf16 v[12:15], v[128:131], v[204:207], 0
	v_mfma_f32_16x16x32_bf16 v[8:11], v[146:149], v[204:207], 0
	v_mfma_f32_16x16x32_bf16 v[60:63], v[150:153], v[192:195], v[60:63]
	v_mfma_f32_16x16x32_bf16 v[56:59], v[154:157], v[192:195], v[56:59]
	v_mfma_f32_16x16x32_bf16 v[44:47], v[150:153], v[196:199], v[44:47]
	v_mfma_f32_16x16x32_bf16 v[40:43], v[154:157], v[196:199], v[40:43]
	v_mfma_f32_16x16x32_bf16 v[28:31], v[150:153], v[208:211], v[28:31]
	v_mfma_f32_16x16x32_bf16 v[24:27], v[154:157], v[208:211], v[24:27]
	v_mfma_f32_16x16x32_bf16 v[12:15], v[150:153], v[212:215], v[12:15]
	v_mfma_f32_16x16x32_bf16 v[8:11], v[154:157], v[212:215], v[8:11]
	s_setprio 0
	s_setprio 1
	v_mfma_f32_16x16x32_bf16 v[52:55], v[158:161], v[174:177], 0
	v_mfma_f32_16x16x32_bf16 v[48:51], v[162:165], v[174:177], 0
	v_mfma_f32_16x16x32_bf16 v[36:39], v[158:161], v[178:181], 0
	v_mfma_f32_16x16x32_bf16 v[32:35], v[162:165], v[178:181], 0
	v_mfma_f32_16x16x32_bf16 v[20:23], v[158:161], v[200:203], 0
	v_mfma_f32_16x16x32_bf16 v[16:19], v[162:165], v[200:203], 0
	v_mfma_f32_16x16x32_bf16 v[4:7], v[158:161], v[204:207], 0
	v_mfma_f32_16x16x32_bf16 v[0:3], v[162:165], v[204:207], 0
	v_mfma_f32_16x16x32_bf16 v[52:55], v[166:169], v[192:195], v[52:55]
	v_mfma_f32_16x16x32_bf16 v[48:51], v[170:173], v[192:195], v[48:51]
	v_mfma_f32_16x16x32_bf16 v[36:39], v[166:169], v[196:199], v[36:39]
	v_mfma_f32_16x16x32_bf16 v[32:35], v[170:173], v[196:199], v[32:35]
	v_mfma_f32_16x16x32_bf16 v[20:23], v[166:169], v[208:211], v[20:23]
	v_mfma_f32_16x16x32_bf16 v[16:19], v[170:173], v[208:211], v[16:19]
	v_mfma_f32_16x16x32_bf16 v[4:7], v[166:169], v[212:215], v[4:7]
	v_mfma_f32_16x16x32_bf16 v[0:3], v[170:173], v[212:215], v[0:3]
	s_barrier
	s_setprio 0
	s_add_u32 s36, s36, 0x80000
	s_addc_u32 s37, s37, 0
	s_mov_b32 m0, s1
	s_nop 0
	global_load_lds_dwordx4 v138, s[36:37]
	v_mov_b32_e32 v128, v144
	s_mov_b32 m0, s69
	s_nop 0
	global_load_lds_dwordx4 v140, s[36:37]
	v_add_u32_e32 v146, s34, v144
	v_xad_u32 v136, v128, 64, s34
	ds_read_b128 v[128:131], v146
	ds_read_b128 v[146:149], v146 offset:2048
	ds_read_b128 v[150:153], v136
	ds_read_b128 v[154:157], v136 offset:2048
	v_mov_b32_e32 v136, v144
	s_add_i32 s36, 0, 0x1c000
	v_add_u32_e32 v162, s36, v144
	v_xad_u32 v136, v136, 64, s36
	ds_read_b128 v[158:161], v162
	ds_read_b128 v[162:165], v162 offset:2048
	ds_read_b128 v[166:169], v136
	ds_read_b128 v[170:173], v136 offset:2048
	v_mov_b32_e32 v136, v143
	s_nop 0
	v_xad_u32 v136, v136, 64, 0
	ds_read_b128 v[174:177], v137 offset:32768
	ds_read_b128 v[178:181], v137 offset:34816
	ds_read_b128 v[192:195], v136 offset:32768
	ds_read_b128 v[196:199], v136 offset:34816
	ds_read_b128 v[200:203], v137 offset:36864
	ds_read_b128 v[204:207], v137 offset:38912
	ds_read_b128 v[208:211], v136 offset:36864
	ds_read_b128 v[212:215], v136 offset:38912
	s_waitcnt vmcnt(8)
	s_waitcnt lgkmcnt(0)
	s_setprio 1
	s_barrier
	v_mfma_f32_16x16x32_bf16 v[124:127], v[128:131], v[174:177], v[124:127]
	v_mfma_f32_16x16x32_bf16 v[120:123], v[146:149], v[174:177], v[120:123]
	v_mfma_f32_16x16x32_bf16 v[108:111], v[128:131], v[178:181], v[108:111]
	v_mfma_f32_16x16x32_bf16 v[104:107], v[146:149], v[178:181], v[104:107]
	v_mfma_f32_16x16x32_bf16 v[92:95], v[128:131], v[200:203], v[92:95]
	v_mfma_f32_16x16x32_bf16 v[88:91], v[146:149], v[200:203], v[88:91]
	v_mfma_f32_16x16x32_bf16 v[76:79], v[128:131], v[204:207], v[76:79]
	v_mfma_f32_16x16x32_bf16 v[72:75], v[146:149], v[204:207], v[72:75]
	v_mfma_f32_16x16x32_bf16 v[124:127], v[150:153], v[192:195], v[124:127]
	v_mfma_f32_16x16x32_bf16 v[120:123], v[154:157], v[192:195], v[120:123]
	v_mfma_f32_16x16x32_bf16 v[108:111], v[150:153], v[196:199], v[108:111]
	v_mfma_f32_16x16x32_bf16 v[104:107], v[154:157], v[196:199], v[104:107]
	v_mfma_f32_16x16x32_bf16 v[92:95], v[150:153], v[208:211], v[92:95]
	v_mfma_f32_16x16x32_bf16 v[88:91], v[154:157], v[208:211], v[88:91]
	v_mfma_f32_16x16x32_bf16 v[76:79], v[150:153], v[212:215], v[76:79]
	v_mfma_f32_16x16x32_bf16 v[72:75], v[154:157], v[212:215], v[72:75]
	s_setprio 0
	s_setprio 1
	v_mfma_f32_16x16x32_bf16 v[116:119], v[158:161], v[174:177], v[116:119]
	s_add_u32 s36, s30, 0x80
	s_addc_u32 s37, s31, 0
	v_mfma_f32_16x16x32_bf16 v[112:115], v[162:165], v[174:177], v[112:115]
	v_mfma_f32_16x16x32_bf16 v[100:103], v[158:161], v[178:181], v[100:103]
	v_mfma_f32_16x16x32_bf16 v[96:99], v[162:165], v[178:181], v[96:99]
	v_mfma_f32_16x16x32_bf16 v[84:87], v[158:161], v[200:203], v[84:87]
	v_mfma_f32_16x16x32_bf16 v[80:83], v[162:165], v[200:203], v[80:83]
	v_mfma_f32_16x16x32_bf16 v[68:71], v[158:161], v[204:207], v[68:71]
	v_mfma_f32_16x16x32_bf16 v[64:67], v[162:165], v[204:207], v[64:67]
	v_mfma_f32_16x16x32_bf16 v[116:119], v[166:169], v[192:195], v[116:119]
	v_mfma_f32_16x16x32_bf16 v[112:115], v[170:173], v[192:195], v[112:115]
	v_mfma_f32_16x16x32_bf16 v[100:103], v[166:169], v[196:199], v[100:103]
	v_mfma_f32_16x16x32_bf16 v[96:99], v[170:173], v[196:199], v[96:99]
	v_mfma_f32_16x16x32_bf16 v[84:87], v[166:169], v[208:211], v[84:87]
	v_mfma_f32_16x16x32_bf16 v[80:83], v[170:173], v[208:211], v[80:83]
	v_mfma_f32_16x16x32_bf16 v[68:71], v[166:169], v[212:215], v[68:71]
	v_mfma_f32_16x16x32_bf16 v[64:67], v[170:173], v[212:215], v[64:67]
	s_barrier
; #define PG8_STAGE(bufoff, gbase, voff) do { _Pragma("unroll") for (int _i = 0; _i < 2; ++_i) \
;         dma16((const char*)(gbase), (voff)[_i], ldsb + (bufoff) + ldsw + _i * 8192); } while (0)
; #define PG8_LDA(dst, b, h) do { const int a1_ = opqv(aoff0) ^ 64; _Pragma("unroll") for (int m = 0; m < 4; ++m) { dst[m][0] = *(const LAS bf16x8*)(lds + PG8_SA(b, h) + aoff0 + m * 2048); dst[m][1] = *(const LAS bf16x8*)(lds + PG8_SA(b, h) + a1_ + m * 2048); } } while (0)
; #define PG8_LDB(dst, b, h) do { const int b1_ = opqv(boff0) ^ 64; _Pragma("unroll") for (int n = 0; n < 2; ++n) { dst[n][0] = *(const LAS bf16x8*)(lds + PG8_SB(b, h) + boff0 + n * 2048); dst[n][1] = *(const LAS bf16x8*)(lds + PG8_SB(b, h) + b1_ + n * 2048); } } while (0)
; #define PG8_WAIT_V(n) asm volatile("s_waitcnt vmcnt(" #n ")" ::: "memory")
; template <class Epi>
; __device__ __forceinline__ void gemm_phase(LAS unsigned char* lds, const Gemm g, const StaticOrder& S, const Epi& E, int wave_) {
;     ...
;         for (int t = 0; t < nt; t += 2) {
;             const bool last = (t == nt - 2);
;             const char* a1 = cA + (size_t)(t + 1) * kstep;
;             const char* a2 = last ? nA : cA + (size_t)(t + 2) * kstep; const char* b2 = last ? nB : cB + (size_t)(t + 2) * kstep;
;             const char* a3 = a2 + kstep; const char* b3 = b2 + kstep;
;             PG8_STAGE(PG8_SA(1, 1), a1 + hstepA, voffA); PG8_LDB(B0, 0, 0); PG8_LDB(B1, 0, 1); PG8_SCHED; PG8_LDA(At, 0, 0);
;             PG8_WAIT_V(8); PG8_WAIT_L(0); PG8_BAR; PG8_MMA(0, 0, At, B0); PG8_MMA(0, 1, At, B1); PG8_BAR; PG8_SCHED;
;             PG8_STAGE(PG8_SB(0, 0), b2, voffB); PG8_STAGE(PG8_SB(0, 1), b2 + hstepB, voffB); PG8_STAGE(PG8_SA(0, 0), a2, voffA); PG8_LDA(At, 0, 1);
;             PG8_WAIT_V(8); PG8_WAIT_L(0); PG8_BAR; PG8_MMA(1, 0, At, B0); PG8_MMA(1, 1, At, B1); PG8_BAR; PG8_SCHED;
;             PG8_STAGE(PG8_SA(0, 1), a2 + hstepA, voffA); PG8_LDB(B0, 1, 0); PG8_LDB(B1, 1, 1); PG8_SCHED; PG8_LDA(At, 1, 0);
;             PG8_WAIT_V(8); PG8_WAIT_L(0); PG8_BAR; PG8_MMA(0, 0, At, B0); PG8_MMA(0, 1, At, B1); PG8_BAR; PG8_SCHED;
;             PG8_STAGE(PG8_SB(1, 0), b3, voffB); PG8_STAGE(PG8_SB(1, 1), b3 + hstepB, voffB); PG8_STAGE(PG8_SA(1, 0), a3, voffA); PG8_LDA(At, 1, 1);
;             PG8_WAIT_V(8); PG8_WAIT_L(0); PG8_BAR; PG8_MMA(1, 0, At, B0); PG8_MMA(1, 1, At, B1); PG8_BAR; PG8_SCHED;
	s_setprio 0
	s_add_u32 s30, s30, 0x80080
	s_addc_u32 s31, s31, 0
	v_mov_b32_e32 v136, v143
	s_nop 0
	s_nop 0
	v_xad_u32 v136, v136, 64, 0
	ds_read_b128 v[174:177], v137 offset:49152
	ds_read_b128 v[178:181], v137 offset:51200
	ds_read_b128 v[192:195], v136 offset:49152
	ds_read_b128 v[196:199], v136 offset:51200
	ds_read_b128 v[200:203], v137 offset:53248
	ds_read_b128 v[204:207], v137 offset:55296
	ds_read_b128 v[208:211], v136 offset:53248
	ds_read_b128 v[212:215], v136 offset:55296
	s_mov_b32 m0, s35
	s_nop 0
	global_load_lds_dwordx4 v139, s[36:37]
	s_mov_b32 m0, s33
	s_nop 0
	global_load_lds_dwordx4 v141, s[36:37]
	s_mov_b32 m0, s77
	s_nop 0
	global_load_lds_dwordx4 v139, s[30:31]
	s_mov_b32 m0, s3
	s_nop 0
	global_load_lds_dwordx4 v141, s[30:31]
	s_mov_b32 m0, s22
	s_nop 0
	global_load_lds_dwordx4 v138, s[26:27]
	s_mov_b32 m0, s2
	s_nop 0
	global_load_lds_dwordx4 v140, s[26:27]
	s_waitcnt vmcnt(8)
	s_waitcnt lgkmcnt(0)
	s_setprio 1
	s_barrier
	v_mfma_f32_16x16x32_bf16 v[60:63], v[128:131], v[174:177], v[60:63]
	v_mfma_f32_16x16x32_bf16 v[56:59], v[146:149], v[174:177], v[56:59]
	v_mfma_f32_16x16x32_bf16 v[44:47], v[128:131], v[178:181], v[44:47]
	v_mfma_f32_16x16x32_bf16 v[40:43], v[146:149], v[178:181], v[40:43]
	v_mfma_f32_16x16x32_bf16 v[28:31], v[128:131], v[200:203], v[28:31]
	v_mfma_f32_16x16x32_bf16 v[24:27], v[146:149], v[200:203], v[24:27]
	v_mfma_f32_16x16x32_bf16 v[12:15], v[128:131], v[204:207], v[12:15]
	v_mfma_f32_16x16x32_bf16 v[8:11], v[146:149], v[204:207], v[8:11]
	v_mfma_f32_16x16x32_bf16 v[60:63], v[150:153], v[192:195], v[60:63]
	v_mfma_f32_16x16x32_bf16 v[56:59], v[154:157], v[192:195], v[56:59]
	v_mfma_f32_16x16x32_bf16 v[44:47], v[150:153], v[196:199], v[44:47]
	v_mfma_f32_16x16x32_bf16 v[40:43], v[154:157], v[196:199], v[40:43]
	v_mfma_f32_16x16x32_bf16 v[28:31], v[150:153], v[208:211], v[28:31]
	v_mfma_f32_16x16x32_bf16 v[24:27], v[154:157], v[208:211], v[24:27]
	v_mfma_f32_16x16x32_bf16 v[12:15], v[150:153], v[212:215], v[12:15]
	v_mfma_f32_16x16x32_bf16 v[8:11], v[154:157], v[212:215], v[8:11]
	s_setprio 0
	s_setprio 1
	v_mfma_f32_16x16x32_bf16 v[52:55], v[158:161], v[174:177], v[52:55]
	v_mfma_f32_16x16x32_bf16 v[48:51], v[162:165], v[174:177], v[48:51]
	v_mfma_f32_16x16x32_bf16 v[36:39], v[158:161], v[178:181], v[36:39]
	v_mfma_f32_16x16x32_bf16 v[32:35], v[162:165], v[178:181], v[32:35]
	v_mfma_f32_16x16x32_bf16 v[20:23], v[158:161], v[200:203], v[20:23]
	v_mfma_f32_16x16x32_bf16 v[16:19], v[162:165], v[200:203], v[16:19]
	v_mfma_f32_16x16x32_bf16 v[4:7], v[158:161], v[204:207], v[4:7]
	v_mfma_f32_16x16x32_bf16 v[0:3], v[162:165], v[204:207], v[0:3]
	v_mfma_f32_16x16x32_bf16 v[52:55], v[166:169], v[192:195], v[52:55]
	v_mfma_f32_16x16x32_bf16 v[48:51], v[170:173], v[192:195], v[48:51]
	v_mfma_f32_16x16x32_bf16 v[36:39], v[166:169], v[196:199], v[36:39]
	v_mfma_f32_16x16x32_bf16 v[32:35], v[170:173], v[196:199], v[32:35]
	v_mfma_f32_16x16x32_bf16 v[20:23], v[166:169], v[208:211], v[20:23]
	v_mfma_f32_16x16x32_bf16 v[16:19], v[170:173], v[208:211], v[16:19]
	v_mfma_f32_16x16x32_bf16 v[4:7], v[166:169], v[212:215], v[4:7]
	v_mfma_f32_16x16x32_bf16 v[0:3], v[170:173], v[212:215], v[0:3]
	s_barrier
	s_setprio 0
	s_add_i32 s57, s57, 2
	s_add_u32 s52, s52, 0x100
	s_addc_u32 s56, s56, 0
	s_add_u32 s12, s12, 0x100
	s_addc_u32 s13, s13, 0
	s_cmp_gt_u32 s57, 29
	s_cbranch_scc0 .LBB0_574
	s_branch .Lpeel_exit_7
.LBB0_574:
	s_add_u32 s26, s12, 0xfff80080
	s_addc_u32 s27, s13, -1
	s_cmp_eq_u32 s57, 28
	s_cselect_b32 s36, s16, s26
	v_mov_b32_e32 v128, v144
	s_cselect_b32 s37, s11, s27
	s_cselect_b32 s30, s17, s52
	s_cselect_b32 s31, s9, s56
	s_add_u32 s26, s36, 0x80
	v_add_u32_e32 v137, s23, v144
	v_xad_u32 v136, v128, 64, s23
	s_addc_u32 s27, s37, 0
	ds_read_b128 v[128:131], v137
	ds_read_b128 v[146:149], v137 offset:2048
	ds_read_b128 v[150:153], v136
	ds_read_b128 v[154:157], v136 offset:2048
	v_mov_b32_e32 v136, v144
	s_add_i32 s58, 0, 0x14000
	v_add_u32_e32 v137, s58, v144
	v_xad_u32 v136, v136, 64, s58
	ds_read_b128 v[158:161], v137
	ds_read_b128 v[162:165], v137 offset:2048
	ds_read_b128 v[166:169], v136
	ds_read_b128 v[170:173], v136 offset:2048
	v_mov_b32_e32 v136, v143
	v_add_u32_e32 v137, 0, v143
	v_xad_u32 v136, v136, 64, 0
	ds_read_b128 v[174:177], v137
	ds_read_b128 v[178:181], v137 offset:2048
	ds_read_b128 v[192:195], v136
	ds_read_b128 v[196:199], v136 offset:2048
	ds_read_b128 v[200:203], v137 offset:4096
	ds_read_b128 v[204:207], v137 offset:6144
	ds_read_b128 v[208:211], v136 offset:4096
	ds_read_b128 v[212:215], v136 offset:6144
	s_mov_b32 m0, s14
	s_nop 0
	global_load_lds_dwordx4 v138, s[12:13]
	s_mov_b32 m0, s15
	s_nop 0
	global_load_lds_dwordx4 v140, s[12:13]
	s_waitcnt vmcnt(8)
	s_waitcnt lgkmcnt(0)
	s_setprio 1
	s_barrier
; #define PG8_STAGE(bufoff, gbase, voff) do { _Pragma("unroll") for (int _i = 0; _i < 2; ++_i) \
;         dma16((const char*)(gbase), (voff)[_i], ldsb + (bufoff) + ldsw + _i * 8192); } while (0)
; #define PG8_LDA(dst, b, h) do { const int a1_ = opqv(aoff0) ^ 64; _Pragma("unroll") for (int m = 0; m < 4; ++m) { dst[m][0] = *(const LAS bf16x8*)(lds + PG8_SA(b, h) + aoff0 + m * 2048); dst[m][1] = *(const LAS bf16x8*)(lds + PG8_SA(b, h) + a1_ + m * 2048); } } while (0)
; #define PG8_LDB(dst, b, h) do { const int b1_ = opqv(boff0) ^ 64; _Pragma("unroll") for (int n = 0; n < 2; ++n) { dst[n][0] = *(const LAS bf16x8*)(lds + PG8_SB(b, h) + boff0 + n * 2048); dst[n][1] = *(const LAS bf16x8*)(lds + PG8_SB(b, h) + b1_ + n * 2048); } } while (0)
; #define PG8_MMA(ai, bj, At, Bt) do { __builtin_amdgcn_s_setprio(1); _Pragma("unroll") for (int m = 0; m < 4; ++m) _Pragma("unroll") for (int n = 0; n < 2; ++n) _Pragma("unroll") for (int k = 0; k < 2; ++k) \
;         acc[ai][bj][m][n] = __builtin_amdgcn_mfma_f32_16x16x32_bf16(Bt[n][k], At[m][k], acc[ai][bj][m][n], 0, 0, 0); __builtin_amdgcn_s_setprio(0); } while (0)
; #define PG8_WAIT_V(n) asm volatile("s_waitcnt vmcnt(" #n ")" ::: "memory")
; #define PG8_WAIT_L(n) asm volatile("s_waitcnt lgkmcnt(" #n ")" ::: "memory")
; #define PG8_BAR __builtin_amdgcn_s_barrier()
; #define PG8_SCHED __builtin_amdgcn_sched_barrier(0)
; template <class Epi>
; __device__ __forceinline__ void gemm_phase(LAS unsigned char* lds, const Gemm g, const StaticOrder& S, const Epi& E, int wave_) {
;     ...
;             PG8_STAGE(PG8_SA(1, 1), a1 + hstepA, voffA); PG8_LDB(B0, 0, 0); PG8_LDB(B1, 0, 1); PG8_SCHED; PG8_LDA(At, 0, 0);
;             PG8_WAIT_V(8); PG8_WAIT_L(0); PG8_BAR; PG8_MMA(0, 0, At, B0); PG8_MMA(0, 1, At, B1); PG8_BAR; PG8_SCHED;
;             PG8_STAGE(PG8_SB(0, 0), b2, voffB); PG8_STAGE(PG8_SB(0, 1), b2 + hstepB, voffB); PG8_STAGE(PG8_SA(0, 0), a2, voffA); PG8_LDA(At, 0, 1);
;             PG8_WAIT_V(8); PG8_WAIT_L(0); PG8_BAR; PG8_MMA(1, 0, At, B0); PG8_MMA(1, 1, At, B1); PG8_BAR; PG8_SCHED;
;             PG8_STAGE(PG8_SA(0, 1), a2 + hstepA, voffA); PG8_LDB(B0, 1, 0); PG8_LDB(B1, 1, 1); PG8_SCHED; PG8_LDA(At, 1, 0);
;             PG8_WAIT_V(8); PG8_WAIT_L(0); PG8_BAR; PG8_MMA(0, 0, At, B0); PG8_MMA(0, 1, At, B1); PG8_BAR; PG8_SCHED;
	v_mfma_f32_16x16x32_bf16 v[124:127], v[128:131], v[174:177], v[124:127]
	v_mfma_f32_16x16x32_bf16 v[120:123], v[146:149], v[174:177], v[120:123]
	v_mfma_f32_16x16x32_bf16 v[108:111], v[128:131], v[178:181], v[108:111]
	v_mfma_f32_16x16x32_bf16 v[104:107], v[146:149], v[178:181], v[104:107]
	v_mfma_f32_16x16x32_bf16 v[92:95], v[128:131], v[200:203], v[92:95]
	v_mfma_f32_16x16x32_bf16 v[88:91], v[146:149], v[200:203], v[88:91]
	v_mfma_f32_16x16x32_bf16 v[76:79], v[128:131], v[204:207], v[76:79]
	v_mfma_f32_16x16x32_bf16 v[72:75], v[146:149], v[204:207], v[72:75]
	v_mfma_f32_16x16x32_bf16 v[124:127], v[150:153], v[192:195], v[124:127]
	v_mfma_f32_16x16x32_bf16 v[120:123], v[154:157], v[192:195], v[120:123]
	v_mfma_f32_16x16x32_bf16 v[108:111], v[150:153], v[196:199], v[108:111]
	v_mfma_f32_16x16x32_bf16 v[104:107], v[154:157], v[196:199], v[104:107]
	v_mfma_f32_16x16x32_bf16 v[92:95], v[150:153], v[208:211], v[92:95]
	v_mfma_f32_16x16x32_bf16 v[88:91], v[154:157], v[208:211], v[88:91]
	v_mfma_f32_16x16x32_bf16 v[76:79], v[150:153], v[212:215], v[76:79]
	v_mfma_f32_16x16x32_bf16 v[72:75], v[154:157], v[212:215], v[72:75]
	s_setprio 0
	s_setprio 1
	v_mfma_f32_16x16x32_bf16 v[116:119], v[158:161], v[174:177], v[116:119]
	v_mfma_f32_16x16x32_bf16 v[112:115], v[162:165], v[174:177], v[112:115]
	v_mfma_f32_16x16x32_bf16 v[100:103], v[158:161], v[178:181], v[100:103]
	v_mfma_f32_16x16x32_bf16 v[96:99], v[162:165], v[178:181], v[96:99]
	v_mfma_f32_16x16x32_bf16 v[84:87], v[158:161], v[200:203], v[84:87]
	v_mfma_f32_16x16x32_bf16 v[80:83], v[162:165], v[200:203], v[80:83]
	v_mfma_f32_16x16x32_bf16 v[68:71], v[158:161], v[204:207], v[68:71]
	v_mfma_f32_16x16x32_bf16 v[64:67], v[162:165], v[204:207], v[64:67]
	v_mfma_f32_16x16x32_bf16 v[116:119], v[166:169], v[192:195], v[116:119]
	v_mfma_f32_16x16x32_bf16 v[112:115], v[170:173], v[192:195], v[112:115]
	v_mfma_f32_16x16x32_bf16 v[100:103], v[166:169], v[196:199], v[100:103]
	v_mfma_f32_16x16x32_bf16 v[96:99], v[170:173], v[196:199], v[96:99]
	v_mfma_f32_16x16x32_bf16 v[84:87], v[166:169], v[208:211], v[84:87]
	v_mfma_f32_16x16x32_bf16 v[80:83], v[170:173], v[208:211], v[80:83]
	v_mfma_f32_16x16x32_bf16 v[68:71], v[166:169], v[212:215], v[68:71]
	v_mfma_f32_16x16x32_bf16 v[64:67], v[170:173], v[212:215], v[64:67]
	s_barrier
	s_setprio 0
	v_mov_b32_e32 v136, v143
	s_add_u32 s58, s30, 0x80000
	s_addc_u32 s59, s31, 0
	s_nop 0
	s_nop 0
	s_nop 0
	v_xad_u32 v136, v136, 64, 0
	ds_read_b128 v[174:177], v137 offset:16384
	ds_read_b128 v[178:181], v137 offset:18432
	ds_read_b128 v[192:195], v136 offset:16384
	ds_read_b128 v[196:199], v136 offset:18432
	ds_read_b128 v[200:203], v137 offset:20480
	ds_read_b128 v[204:207], v137 offset:22528
	ds_read_b128 v[208:211], v136 offset:20480
	ds_read_b128 v[212:215], v136 offset:22528
	s_mov_b32 m0, s80
	s_nop 0
	global_load_lds_dwordx4 v139, s[30:31]
	s_mov_b32 m0, s81
	s_nop 0
	global_load_lds_dwordx4 v141, s[30:31]
	s_mov_b32 m0, s29
	s_nop 0
	global_load_lds_dwordx4 v139, s[58:59]
	s_mov_b32 m0, s88
	s_nop 0
	global_load_lds_dwordx4 v141, s[58:59]
	s_mov_b32 m0, s76
	s_nop 0
	global_load_lds_dwordx4 v138, s[36:37]
	s_mov_b32 m0, s89
	s_nop 0
	global_load_lds_dwordx4 v140, s[36:37]
	s_waitcnt vmcnt(8)
	s_waitcnt lgkmcnt(0)
	s_setprio 1
	s_barrier
	v_mfma_f32_16x16x32_bf16 v[60:63], v[128:131], v[174:177], v[60:63]
	v_mfma_f32_16x16x32_bf16 v[56:59], v[146:149], v[174:177], v[56:59]
	v_mfma_f32_16x16x32_bf16 v[44:47], v[128:131], v[178:181], v[44:47]
	v_mfma_f32_16x16x32_bf16 v[40:43], v[146:149], v[178:181], v[40:43]
	v_mfma_f32_16x16x32_bf16 v[28:31], v[128:131], v[200:203], v[28:31]
	v_mfma_f32_16x16x32_bf16 v[24:27], v[146:149], v[200:203], v[24:27]
	v_mfma_f32_16x16x32_bf16 v[12:15], v[128:131], v[204:207], v[12:15]
	v_mfma_f32_16x16x32_bf16 v[8:11], v[146:149], v[204:207], v[8:11]
	v_mfma_f32_16x16x32_bf16 v[60:63], v[150:153], v[192:195], v[60:63]
	v_mfma_f32_16x16x32_bf16 v[56:59], v[154:157], v[192:195], v[56:59]
	v_mfma_f32_16x16x32_bf16 v[44:47], v[150:153], v[196:199], v[44:47]
	v_mfma_f32_16x16x32_bf16 v[40:43], v[154:157], v[196:199], v[40:43]
	v_mfma_f32_16x16x32_bf16 v[28:31], v[150:153], v[208:211], v[28:31]
	v_mfma_f32_16x16x32_bf16 v[24:27], v[154:157], v[208:211], v[24:27]
	v_mfma_f32_16x16x32_bf16 v[12:15], v[150:153], v[212:215], v[12:15]
	v_mfma_f32_16x16x32_bf16 v[8:11], v[154:157], v[212:215], v[8:11]
	s_setprio 0
	s_setprio 1
	v_mfma_f32_16x16x32_bf16 v[52:55], v[158:161], v[174:177], v[52:55]
	v_mfma_f32_16x16x32_bf16 v[48:51], v[162:165], v[174:177], v[48:51]
	v_mfma_f32_16x16x32_bf16 v[36:39], v[158:161], v[178:181], v[36:39]
	v_mfma_f32_16x16x32_bf16 v[32:35], v[162:165], v[178:181], v[32:35]
	v_mfma_f32_16x16x32_bf16 v[20:23], v[158:161], v[200:203], v[20:23]
	v_mfma_f32_16x16x32_bf16 v[16:19], v[162:165], v[200:203], v[16:19]
	v_mfma_f32_16x16x32_bf16 v[4:7], v[158:161], v[204:207], v[4:7]
	v_mfma_f32_16x16x32_bf16 v[0:3], v[162:165], v[204:207], v[0:3]
	v_mfma_f32_16x16x32_bf16 v[52:55], v[166:169], v[192:195], v[52:55]
	v_mfma_f32_16x16x32_bf16 v[48:51], v[170:173], v[192:195], v[48:51]
	v_mfma_f32_16x16x32_bf16 v[36:39], v[166:169], v[196:199], v[36:39]
	v_mfma_f32_16x16x32_bf16 v[32:35], v[170:173], v[196:199], v[32:35]
	v_mfma_f32_16x16x32_bf16 v[20:23], v[166:169], v[208:211], v[20:23]
	v_mfma_f32_16x16x32_bf16 v[16:19], v[170:173], v[208:211], v[16:19]
	v_mfma_f32_16x16x32_bf16 v[4:7], v[166:169], v[212:215], v[4:7]
	v_mfma_f32_16x16x32_bf16 v[0:3], v[170:173], v[212:215], v[0:3]
	s_barrier
; #define PG8_STAGE(bufoff, gbase, voff) do { _Pragma("unroll") for (int _i = 0; _i < 2; ++_i) \
;         dma16((const char*)(gbase), (voff)[_i], ldsb + (bufoff) + ldsw + _i * 8192); } while (0)
; #define PG8_LDA(dst, b, h) do { const int a1_ = opqv(aoff0) ^ 64; _Pragma("unroll") for (int m = 0; m < 4; ++m) { dst[m][0] = *(const LAS bf16x8*)(lds + PG8_SA(b, h) + aoff0 + m * 2048); dst[m][1] = *(const LAS bf16x8*)(lds + PG8_SA(b, h) + a1_ + m * 2048); } } while (0)
; #define PG8_LDB(dst, b, h) do { const int b1_ = opqv(boff0) ^ 64; _Pragma("unroll") for (int n = 0; n < 2; ++n) { dst[n][0] = *(const LAS bf16x8*)(lds + PG8_SB(b, h) + boff0 + n * 2048); dst[n][1] = *(const LAS bf16x8*)(lds + PG8_SB(b, h) + b1_ + n * 2048); } } while (0)
; #define PG8_MMA(ai, bj, At, Bt) do { __builtin_amdgcn_s_setprio(1); _Pragma("unroll") for (int m = 0; m < 4; ++m) _Pragma("unroll") for (int n = 0; n < 2; ++n) _Pragma("unroll") for (int k = 0; k < 2; ++k) \
;         acc[ai][bj][m][n] = __builtin_amdgcn_mfma_f32_16x16x32_bf16(Bt[n][k], At[m][k], acc[ai][bj][m][n], 0, 0, 0); __builtin_amdgcn_s_setprio(0); } while (0)
; #define PG8_WAIT_V(n) asm volatile("s_waitcnt vmcnt(" #n ")" ::: "memory")
; #define PG8_WAIT_L(n) asm volatile("s_waitcnt lgkmcnt(" #n ")" ::: "memory")
; #define PG8_BAR __builtin_amdgcn_s_barrier()
; #define PG8_SCHED __builtin_amdgcn_sched_barrier(0)
; template <class Epi>
; __device__ __forceinline__ void gemm_phase(LAS unsigned char* lds, const Gemm g, const StaticOrder& S, const Epi& E, int wave_) {
;     ...
;             PG8_STAGE(PG8_SA(0, 1), a2 + hstepA, voffA); PG8_LDB(B0, 1, 0); PG8_LDB(B1, 1, 1); PG8_SCHED; PG8_LDA(At, 1, 0);
;             PG8_WAIT_V(8); PG8_WAIT_L(0); PG8_BAR; PG8_MMA(0, 0, At, B0); PG8_MMA(0, 1, At, B1); PG8_BAR; PG8_SCHED;
;             PG8_STAGE(PG8_SB(1, 0), b3, voffB); PG8_STAGE(PG8_SB(1, 1), b3 + hstepB, voffB); PG8_STAGE(PG8_SA(1, 0), a3, voffA); PG8_LDA(At, 1, 1);
;             PG8_WAIT_V(8); PG8_WAIT_L(0); PG8_BAR; PG8_MMA(1, 0, At, B0); PG8_MMA(1, 1, At, B1); PG8_BAR; PG8_SCHED;
;         }
	s_setprio 0
	s_add_u32 s36, s36, 0x80000
	s_addc_u32 s37, s37, 0
	s_mov_b32 m0, s1
	s_nop 0
	global_load_lds_dwordx4 v138, s[36:37]
	v_mov_b32_e32 v128, v144
	s_mov_b32 m0, s69
	s_nop 0
	global_load_lds_dwordx4 v140, s[36:37]
	v_add_u32_e32 v146, s34, v144
	v_xad_u32 v136, v128, 64, s34
	ds_read_b128 v[128:131], v146
	ds_read_b128 v[146:149], v146 offset:2048
	ds_read_b128 v[150:153], v136
	ds_read_b128 v[154:157], v136 offset:2048
	v_mov_b32_e32 v136, v144
	s_add_i32 s36, 0, 0x1c000
	v_add_u32_e32 v162, s36, v144
	v_xad_u32 v136, v136, 64, s36
	ds_read_b128 v[158:161], v162
	ds_read_b128 v[162:165], v162 offset:2048
	ds_read_b128 v[166:169], v136
	ds_read_b128 v[170:173], v136 offset:2048
	v_mov_b32_e32 v136, v143
	s_nop 0
	v_xad_u32 v136, v136, 64, 0
	ds_read_b128 v[174:177], v137 offset:32768
	ds_read_b128 v[178:181], v137 offset:34816
	ds_read_b128 v[192:195], v136 offset:32768
	ds_read_b128 v[196:199], v136 offset:34816
	ds_read_b128 v[200:203], v137 offset:36864
	ds_read_b128 v[204:207], v137 offset:38912
	ds_read_b128 v[208:211], v136 offset:36864
	ds_read_b128 v[212:215], v136 offset:38912
	s_waitcnt vmcnt(8)
	s_waitcnt lgkmcnt(0)
	s_setprio 1
	s_barrier
	v_mfma_f32_16x16x32_bf16 v[124:127], v[128:131], v[174:177], v[124:127]
	v_mfma_f32_16x16x32_bf16 v[120:123], v[146:149], v[174:177], v[120:123]
	v_mfma_f32_16x16x32_bf16 v[108:111], v[128:131], v[178:181], v[108:111]
	v_mfma_f32_16x16x32_bf16 v[104:107], v[146:149], v[178:181], v[104:107]
	v_mfma_f32_16x16x32_bf16 v[92:95], v[128:131], v[200:203], v[92:95]
	v_mfma_f32_16x16x32_bf16 v[88:91], v[146:149], v[200:203], v[88:91]
	v_mfma_f32_16x16x32_bf16 v[76:79], v[128:131], v[204:207], v[76:79]
	v_mfma_f32_16x16x32_bf16 v[72:75], v[146:149], v[204:207], v[72:75]
	v_mfma_f32_16x16x32_bf16 v[124:127], v[150:153], v[192:195], v[124:127]
	v_mfma_f32_16x16x32_bf16 v[120:123], v[154:157], v[192:195], v[120:123]
	v_mfma_f32_16x16x32_bf16 v[108:111], v[150:153], v[196:199], v[108:111]
	v_mfma_f32_16x16x32_bf16 v[104:107], v[154:157], v[196:199], v[104:107]
	v_mfma_f32_16x16x32_bf16 v[92:95], v[150:153], v[208:211], v[92:95]
	v_mfma_f32_16x16x32_bf16 v[88:91], v[154:157], v[208:211], v[88:91]
	v_mfma_f32_16x16x32_bf16 v[76:79], v[150:153], v[212:215], v[76:79]
	v_mfma_f32_16x16x32_bf16 v[72:75], v[154:157], v[212:215], v[72:75]
	s_setprio 0
	s_setprio 1
	v_mfma_f32_16x16x32_bf16 v[116:119], v[158:161], v[174:177], v[116:119]
	s_add_u32 s36, s30, 0x80
	s_addc_u32 s37, s31, 0
	v_mfma_f32_16x16x32_bf16 v[112:115], v[162:165], v[174:177], v[112:115]
	v_mfma_f32_16x16x32_bf16 v[100:103], v[158:161], v[178:181], v[100:103]
	v_mfma_f32_16x16x32_bf16 v[96:99], v[162:165], v[178:181], v[96:99]
	v_mfma_f32_16x16x32_bf16 v[84:87], v[158:161], v[200:203], v[84:87]
	v_mfma_f32_16x16x32_bf16 v[80:83], v[162:165], v[200:203], v[80:83]
	v_mfma_f32_16x16x32_bf16 v[68:71], v[158:161], v[204:207], v[68:71]
	v_mfma_f32_16x16x32_bf16 v[64:67], v[162:165], v[204:207], v[64:67]
	v_mfma_f32_16x16x32_bf16 v[116:119], v[166:169], v[192:195], v[116:119]
	v_mfma_f32_16x16x32_bf16 v[112:115], v[170:173], v[192:195], v[112:115]
	v_mfma_f32_16x16x32_bf16 v[100:103], v[166:169], v[196:199], v[100:103]
	v_mfma_f32_16x16x32_bf16 v[96:99], v[170:173], v[196:199], v[96:99]
	v_mfma_f32_16x16x32_bf16 v[84:87], v[166:169], v[208:211], v[84:87]
	v_mfma_f32_16x16x32_bf16 v[80:83], v[170:173], v[208:211], v[80:83]
	v_mfma_f32_16x16x32_bf16 v[68:71], v[166:169], v[212:215], v[68:71]
	v_mfma_f32_16x16x32_bf16 v[64:67], v[170:173], v[212:215], v[64:67]
	s_barrier
	s_setprio 0
	s_add_u32 s30, s30, 0x80080
	s_addc_u32 s31, s31, 0
	v_mov_b32_e32 v136, v143
	s_nop 0
	s_nop 0
	v_xad_u32 v136, v136, 64, 0
	ds_read_b128 v[174:177], v137 offset:49152
	ds_read_b128 v[178:181], v137 offset:51200
	ds_read_b128 v[192:195], v136 offset:49152
	ds_read_b128 v[196:199], v136 offset:51200
	ds_read_b128 v[200:203], v137 offset:53248
	ds_read_b128 v[204:207], v137 offset:55296
	ds_read_b128 v[208:211], v136 offset:53248
	ds_read_b128 v[212:215], v136 offset:55296
	s_mov_b32 m0, s35
	s_nop 0
	global_load_lds_dwordx4 v139, s[36:37]
	s_mov_b32 m0, s33
	s_nop 0
	global_load_lds_dwordx4 v141, s[36:37]
	s_mov_b32 m0, s77
	s_nop 0
	global_load_lds_dwordx4 v139, s[30:31]
	s_mov_b32 m0, s3
	s_nop 0
	global_load_lds_dwordx4 v141, s[30:31]
	s_mov_b32 m0, s22
	s_nop 0
	global_load_lds_dwordx4 v138, s[26:27]
	s_mov_b32 m0, s2
	s_nop 0
	global_load_lds_dwordx4 v140, s[26:27]
	s_waitcnt vmcnt(8)
	s_waitcnt lgkmcnt(0)
	s_setprio 1
	s_barrier
	v_mfma_f32_16x16x32_bf16 v[60:63], v[128:131], v[174:177], v[60:63]
	v_mfma_f32_16x16x32_bf16 v[56:59], v[146:149], v[174:177], v[56:59]
	v_mfma_f32_16x16x32_bf16 v[44:47], v[128:131], v[178:181], v[44:47]
	v_mfma_f32_16x16x32_bf16 v[40:43], v[146:149], v[178:181], v[40:43]
	v_mfma_f32_16x16x32_bf16 v[28:31], v[128:131], v[200:203], v[28:31]
	v_mfma_f32_16x16x32_bf16 v[24:27], v[146:149], v[200:203], v[24:27]
	v_mfma_f32_16x16x32_bf16 v[12:15], v[128:131], v[204:207], v[12:15]
	v_mfma_f32_16x16x32_bf16 v[8:11], v[146:149], v[204:207], v[8:11]
	v_mfma_f32_16x16x32_bf16 v[60:63], v[150:153], v[192:195], v[60:63]
	v_mfma_f32_16x16x32_bf16 v[56:59], v[154:157], v[192:195], v[56:59]
	v_mfma_f32_16x16x32_bf16 v[44:47], v[150:153], v[196:199], v[44:47]
	v_mfma_f32_16x16x32_bf16 v[40:43], v[154:157], v[196:199], v[40:43]
	v_mfma_f32_16x16x32_bf16 v[28:31], v[150:153], v[208:211], v[28:31]
	v_mfma_f32_16x16x32_bf16 v[24:27], v[154:157], v[208:211], v[24:27]
	v_mfma_f32_16x16x32_bf16 v[12:15], v[150:153], v[212:215], v[12:15]
	v_mfma_f32_16x16x32_bf16 v[8:11], v[154:157], v[212:215], v[8:11]
	s_setprio 0
	s_setprio 1
	v_mfma_f32_16x16x32_bf16 v[52:55], v[158:161], v[174:177], v[52:55]
	v_mfma_f32_16x16x32_bf16 v[48:51], v[162:165], v[174:177], v[48:51]
	v_mfma_f32_16x16x32_bf16 v[36:39], v[158:161], v[178:181], v[36:39]
	v_mfma_f32_16x16x32_bf16 v[32:35], v[162:165], v[178:181], v[32:35]
	v_mfma_f32_16x16x32_bf16 v[20:23], v[158:161], v[200:203], v[20:23]
	v_mfma_f32_16x16x32_bf16 v[16:19], v[162:165], v[200:203], v[16:19]
	v_mfma_f32_16x16x32_bf16 v[4:7], v[158:161], v[204:207], v[4:7]
	v_mfma_f32_16x16x32_bf16 v[0:3], v[162:165], v[204:207], v[0:3]
	v_mfma_f32_16x16x32_bf16 v[52:55], v[166:169], v[192:195], v[52:55]
	v_mfma_f32_16x16x32_bf16 v[48:51], v[170:173], v[192:195], v[48:51]
	v_mfma_f32_16x16x32_bf16 v[36:39], v[166:169], v[196:199], v[36:39]
	v_mfma_f32_16x16x32_bf16 v[32:35], v[170:173], v[196:199], v[32:35]
	v_mfma_f32_16x16x32_bf16 v[20:23], v[166:169], v[208:211], v[20:23]
	v_mfma_f32_16x16x32_bf16 v[16:19], v[170:173], v[208:211], v[16:19]
	v_mfma_f32_16x16x32_bf16 v[4:7], v[166:169], v[212:215], v[4:7]
	v_mfma_f32_16x16x32_bf16 v[0:3], v[170:173], v[212:215], v[0:3]
	s_barrier
	s_setprio 0
	s_add_i32 s57, s57, 2
	s_add_u32 s52, s52, 0x100
	s_addc_u32 s56, s56, 0
	s_add_u32 s12, s12, 0x100
	s_addc_u32 s13, s13, 0
	s_cmp_gt_u32 s57, 29
	s_cbranch_scc0 .LBB0_574

; #define PG8_STAGE(bufoff, gbase, voff) do { _Pragma("unroll") for (int _i = 0; _i < 2; ++_i) \
;         dma16((const char*)(gbase), (voff)[_i], ldsb + (bufoff) + ldsw + _i * 8192); } while (0)
; #define PG8_LDA(dst, b, h) do { const int a1_ = opqv(aoff0) ^ 64; _Pragma("unroll") for (int m = 0; m < 4; ++m) { dst[m][0] = *(const LAS bf16x8*)(lds + PG8_SA(b, h) + aoff0 + m * 2048); dst[m][1] = *(const LAS bf16x8*)(lds + PG8_SA(b, h) + a1_ + m * 2048); } } while (0)
; #define PG8_LDB(dst, b, h) do { const int b1_ = opqv(boff0) ^ 64; _Pragma("unroll") for (int n = 0; n < 2; ++n) { dst[n][0] = *(const LAS bf16x8*)(lds + PG8_SB(b, h) + boff0 + n * 2048); dst[n][1] = *(const LAS bf16x8*)(lds + PG8_SB(b, h) + b1_ + n * 2048); } } while (0)
; #define PG8_MMA(ai, bj, At, Bt) do { __builtin_amdgcn_s_setprio(1); _Pragma("unroll") for (int m = 0; m < 4; ++m) _Pragma("unroll") for (int n = 0; n < 2; ++n) _Pragma("unroll") for (int k = 0; k < 2; ++k) \
;         acc[ai][bj][m][n] = __builtin_amdgcn_mfma_f32_16x16x32_bf16(Bt[n][k], At[m][k], acc[ai][bj][m][n], 0, 0, 0); __builtin_amdgcn_s_setprio(0); } while (0)
; template <class Epi>
; __device__ __forceinline__ void gemm_phase(LAS unsigned char* lds, const Gemm g, const StaticOrder& S, const Epi& E, int wave_) {
;     ...
;         const bool has_next = S.next(ui + 1, nxt);
;         const char* nA = has_next ? (const char*)g.A + (size_t)nxt.pm * tstepA : cA; const char* nB = has_next ? (const char*)g.Bt + (size_t)nxt.pn * tstepB : cB;
; #pragma unroll 1
;         for (int t = 0; t < nt; t += 2) {
;             const bool last = (t == nt - 2);
;             const char* a1 = cA + (size_t)(t + 1) * kstep;
;             const char* a2 = last ? nA : cA + (size_t)(t + 2) * kstep; const char* b2 = last ? nB : cB + (size_t)(t + 2) * kstep;
;             const char* a3 = a2 + kstep; const char* b3 = b2 + kstep;
;             PG8_STAGE(PG8_SA(1, 1), a1 + hstepA, voffA); PG8_LDB(B0, 0, 0); PG8_LDB(B1, 0, 1); PG8_SCHED; PG8_LDA(At, 0, 0);
;             PG8_WAIT_V(8); PG8_WAIT_L(0); PG8_BAR; PG8_MMA(0, 0, At, B0); PG8_MMA(0, 1, At, B1); PG8_BAR; PG8_SCHED;
;             PG8_STAGE(PG8_SB(0, 0), b2, voffB); PG8_STAGE(PG8_SB(0, 1), b2 + hstepB, voffB); PG8_STAGE(PG8_SA(0, 0), a2, voffA); PG8_LDA(At, 0, 1);
;             PG8_WAIT_V(8); PG8_WAIT_L(0); PG8_BAR; PG8_MMA(1, 0, At, B0); PG8_MMA(1, 1, At, B1); PG8_BAR; PG8_SCHED;
.LBB0_743:
	s_ashr_i32 s19, s18, 31
	s_lshl_b64 s[16:17], s[18:19], 19
	s_add_u32 s24, s21, s16
	s_addc_u32 s25, s46, s17
	s_and_b64 s[16:17], s[40:41], exec
	s_cselect_b32 s16, s25, s31
	s_cselect_b32 s17, s24, s30
	s_ashr_i32 s11, s10, 31
	s_lshl_b64 s[26:27], s[10:11], 18
	s_add_u32 s26, s47, s26
	s_addc_u32 s27, s48, s27
	s_and_b64 s[36:37], s[40:41], exec
	s_cselect_b32 s11, s27, s13
	s_cselect_b32 s19, s26, s12
	s_add_u32 s52, s12, 0x100
	s_addc_u32 s56, s13, 0
	s_add_u32 s12, s30, 0x40080
	s_addc_u32 s13, s31, 0
	s_mov_b32 s57, -2
	s_add_u32 s30, s12, 0xfffc0080
	s_addc_u32 s31, s13, -1
	s_cmp_eq_u32 s57, 4
	s_cselect_b32 s42, s17, s30
	s_cselect_b32 s43, s16, s31
	s_cselect_b32 s36, s19, s52
	s_cselect_b32 s37, s11, s56
	s_add_u32 s30, s42, 0x80
	v_mov_b32_e32 v128, v180
	s_addc_u32 s31, s43, 0
	v_add_u32_e32 v132, s23, v180
	v_xad_u32 v144, v128, 64, s23
	v_mov_b32_e32 v148, v180
	s_add_i32 s58, 0, 0x14000
	ds_read_b128 v[128:131], v132
	ds_read_b128 v[132:135], v132 offset:2048
	ds_read_b128 v[140:143], v144
	ds_read_b128 v[144:147], v144 offset:2048
	v_add_u32_e32 v152, s58, v180
	v_xad_u32 v160, v148, 64, s58
	ds_read_b128 v[148:151], v152
	ds_read_b128 v[152:155], v152 offset:2048
	ds_read_b128 v[156:159], v160
	ds_read_b128 v[160:163], v160 offset:2048
	v_mov_b32_e32 v164, v179
	v_add_u32_e32 v182, 0, v179
	v_xad_u32 v172, v164, 64, 0
	ds_read_b128 v[164:167], v182
	ds_read_b128 v[168:171], v182 offset:2048
	ds_read_b128 v[192:195], v172
	ds_read_b128 v[196:199], v172 offset:2048
	ds_read_b128 v[200:203], v182 offset:4096
	ds_read_b128 v[204:207], v182 offset:6144
	ds_read_b128 v[208:211], v172 offset:4096
	ds_read_b128 v[212:215], v172 offset:6144
	s_mov_b32 m0, s14
	s_nop 0
	global_load_lds_dwordx4 v137, s[12:13]
	s_mov_b32 m0, s15
	s_nop 0
	global_load_lds_dwordx4 v176, s[12:13]
	s_waitcnt vmcnt(8)
	s_waitcnt lgkmcnt(0)
	s_setprio 1
	s_barrier
	v_mfma_f32_16x16x32_bf16 v[124:127], v[128:131], v[164:167], 0
	v_mfma_f32_16x16x32_bf16 v[120:123], v[132:135], v[164:167], 0
	v_mfma_f32_16x16x32_bf16 v[108:111], v[128:131], v[168:171], 0
	v_mfma_f32_16x16x32_bf16 v[104:107], v[132:135], v[168:171], 0
	v_mfma_f32_16x16x32_bf16 v[92:95], v[128:131], v[200:203], 0
	v_mfma_f32_16x16x32_bf16 v[88:91], v[132:135], v[200:203], 0
	v_mfma_f32_16x16x32_bf16 v[76:79], v[128:131], v[204:207], 0
	v_mfma_f32_16x16x32_bf16 v[72:75], v[132:135], v[204:207], 0
	v_mfma_f32_16x16x32_bf16 v[124:127], v[140:143], v[192:195], v[124:127]
	v_mfma_f32_16x16x32_bf16 v[120:123], v[144:147], v[192:195], v[120:123]
	v_mfma_f32_16x16x32_bf16 v[108:111], v[140:143], v[196:199], v[108:111]
	v_mfma_f32_16x16x32_bf16 v[104:107], v[144:147], v[196:199], v[104:107]
	v_mfma_f32_16x16x32_bf16 v[92:95], v[140:143], v[208:211], v[92:95]
	v_mfma_f32_16x16x32_bf16 v[88:91], v[144:147], v[208:211], v[88:91]
	v_mfma_f32_16x16x32_bf16 v[76:79], v[140:143], v[212:215], v[76:79]
	v_mfma_f32_16x16x32_bf16 v[72:75], v[144:147], v[212:215], v[72:75]
	s_setprio 0
	s_setprio 1
	v_mfma_f32_16x16x32_bf16 v[116:119], v[148:151], v[164:167], 0
	v_mfma_f32_16x16x32_bf16 v[112:115], v[152:155], v[164:167], 0
	v_mfma_f32_16x16x32_bf16 v[100:103], v[148:151], v[168:171], 0
	v_mfma_f32_16x16x32_bf16 v[96:99], v[152:155], v[168:171], 0
	v_mfma_f32_16x16x32_bf16 v[84:87], v[148:151], v[200:203], 0
	v_mfma_f32_16x16x32_bf16 v[80:83], v[152:155], v[200:203], 0
	v_mfma_f32_16x16x32_bf16 v[68:71], v[148:151], v[204:207], 0
	v_mfma_f32_16x16x32_bf16 v[64:67], v[152:155], v[204:207], 0
	v_mfma_f32_16x16x32_bf16 v[116:119], v[156:159], v[192:195], v[116:119]
	v_mfma_f32_16x16x32_bf16 v[112:115], v[160:163], v[192:195], v[112:115]
	v_mfma_f32_16x16x32_bf16 v[100:103], v[156:159], v[196:199], v[100:103]
	v_mfma_f32_16x16x32_bf16 v[96:99], v[160:163], v[196:199], v[96:99]
	v_mfma_f32_16x16x32_bf16 v[84:87], v[156:159], v[208:211], v[84:87]
	v_mfma_f32_16x16x32_bf16 v[80:83], v[160:163], v[208:211], v[80:83]
	v_mfma_f32_16x16x32_bf16 v[68:71], v[156:159], v[212:215], v[68:71]
	v_mfma_f32_16x16x32_bf16 v[64:67], v[160:163], v[212:215], v[64:67]
	s_barrier
	s_setprio 0
	v_mov_b32_e32 v164, v179
	s_add_u32 s58, s36, 0x20000
	s_addc_u32 s59, s37, 0
	s_nop 0
	s_nop 0
	s_nop 0
	v_xad_u32 v172, v164, 64, 0
	ds_read_b128 v[164:167], v182 offset:16384
	ds_read_b128 v[168:171], v182 offset:18432
	ds_read_b128 v[192:195], v172 offset:16384
	ds_read_b128 v[196:199], v172 offset:18432
	ds_read_b128 v[200:203], v182 offset:20480
	ds_read_b128 v[204:207], v182 offset:22528
	ds_read_b128 v[208:211], v172 offset:20480
	ds_read_b128 v[212:215], v172 offset:22528
	s_mov_b32 m0, s80
	s_nop 0
	global_load_lds_dwordx4 v175, s[36:37]
	s_mov_b32 m0, s81
	s_nop 0
	global_load_lds_dwordx4 v177, s[36:37]
	s_mov_b32 m0, s29
	s_nop 0
	global_load_lds_dwordx4 v175, s[58:59]
	s_mov_b32 m0, s88
	s_nop 0
	global_load_lds_dwordx4 v177, s[58:59]
	s_mov_b32 m0, s76
	s_nop 0
	global_load_lds_dwordx4 v137, s[42:43]
	s_mov_b32 m0, s89
	s_nop 0
	global_load_lds_dwordx4 v176, s[42:43]
	s_waitcnt vmcnt(8)
	s_waitcnt lgkmcnt(0)
	s_setprio 1
	s_barrier
; #define PG8_STAGE(bufoff, gbase, voff) do { _Pragma("unroll") for (int _i = 0; _i < 2; ++_i) \
;         dma16((const char*)(gbase), (voff)[_i], ldsb + (bufoff) + ldsw + _i * 8192); } while (0)
; #define PG8_LDA(dst, b, h) do { const int a1_ = opqv(aoff0) ^ 64; _Pragma("unroll") for (int m = 0; m < 4; ++m) { dst[m][0] = *(const LAS bf16x8*)(lds + PG8_SA(b, h) + aoff0 + m * 2048); dst[m][1] = *(const LAS bf16x8*)(lds + PG8_SA(b, h) + a1_ + m * 2048); } } while (0)
; #define PG8_LDB(dst, b, h) do { const int b1_ = opqv(boff0) ^ 64; _Pragma("unroll") for (int n = 0; n < 2; ++n) { dst[n][0] = *(const LAS bf16x8*)(lds + PG8_SB(b, h) + boff0 + n * 2048); dst[n][1] = *(const LAS bf16x8*)(lds + PG8_SB(b, h) + b1_ + n * 2048); } } while (0)
; #define PG8_MMA(ai, bj, At, Bt) do { __builtin_amdgcn_s_setprio(1); _Pragma("unroll") for (int m = 0; m < 4; ++m) _Pragma("unroll") for (int n = 0; n < 2; ++n) _Pragma("unroll") for (int k = 0; k < 2; ++k) \
;         acc[ai][bj][m][n] = __builtin_amdgcn_mfma_f32_16x16x32_bf16(Bt[n][k], At[m][k], acc[ai][bj][m][n], 0, 0, 0); __builtin_amdgcn_s_setprio(0); } while (0)
; #define PG8_WAIT_V(n) asm volatile("s_waitcnt vmcnt(" #n ")" ::: "memory")
; #define PG8_WAIT_L(n) asm volatile("s_waitcnt lgkmcnt(" #n ")" ::: "memory")
; #define PG8_BAR __builtin_amdgcn_s_barrier()
; #define PG8_SCHED __builtin_amdgcn_sched_barrier(0)
; template <class Epi>
; __device__ __forceinline__ void gemm_phase(LAS unsigned char* lds, const Gemm g, const StaticOrder& S, const Epi& E, int wave_) {
;     ...
;             PG8_WAIT_V(8); PG8_WAIT_L(0); PG8_BAR; PG8_MMA(1, 0, At, B0); PG8_MMA(1, 1, At, B1); PG8_BAR; PG8_SCHED;
;             PG8_STAGE(PG8_SA(0, 1), a2 + hstepA, voffA); PG8_LDB(B0, 1, 0); PG8_LDB(B1, 1, 1); PG8_SCHED; PG8_LDA(At, 1, 0);
;             PG8_WAIT_V(8); PG8_WAIT_L(0); PG8_BAR; PG8_MMA(0, 0, At, B0); PG8_MMA(0, 1, At, B1); PG8_BAR; PG8_SCHED;
	v_mfma_f32_16x16x32_bf16 v[60:63], v[128:131], v[164:167], 0
	v_mfma_f32_16x16x32_bf16 v[56:59], v[132:135], v[164:167], 0
	v_mfma_f32_16x16x32_bf16 v[44:47], v[128:131], v[168:171], 0
	v_mfma_f32_16x16x32_bf16 v[40:43], v[132:135], v[168:171], 0
	v_mfma_f32_16x16x32_bf16 v[28:31], v[128:131], v[200:203], 0
	v_mfma_f32_16x16x32_bf16 v[24:27], v[132:135], v[200:203], 0
	v_mfma_f32_16x16x32_bf16 v[12:15], v[128:131], v[204:207], 0
	v_mfma_f32_16x16x32_bf16 v[8:11], v[132:135], v[204:207], 0
	v_mfma_f32_16x16x32_bf16 v[60:63], v[140:143], v[192:195], v[60:63]
	v_mfma_f32_16x16x32_bf16 v[56:59], v[144:147], v[192:195], v[56:59]
	v_mfma_f32_16x16x32_bf16 v[44:47], v[140:143], v[196:199], v[44:47]
	v_mfma_f32_16x16x32_bf16 v[40:43], v[144:147], v[196:199], v[40:43]
	v_mfma_f32_16x16x32_bf16 v[28:31], v[140:143], v[208:211], v[28:31]
	v_mfma_f32_16x16x32_bf16 v[24:27], v[144:147], v[208:211], v[24:27]
	v_mfma_f32_16x16x32_bf16 v[12:15], v[140:143], v[212:215], v[12:15]
	v_mfma_f32_16x16x32_bf16 v[8:11], v[144:147], v[212:215], v[8:11]
	s_setprio 0
	s_setprio 1
	v_mfma_f32_16x16x32_bf16 v[52:55], v[148:151], v[164:167], 0
	v_mfma_f32_16x16x32_bf16 v[48:51], v[152:155], v[164:167], 0
	v_mfma_f32_16x16x32_bf16 v[36:39], v[148:151], v[168:171], 0
	v_mfma_f32_16x16x32_bf16 v[32:35], v[152:155], v[168:171], 0
	v_mfma_f32_16x16x32_bf16 v[20:23], v[148:151], v[200:203], 0
	v_mfma_f32_16x16x32_bf16 v[16:19], v[152:155], v[200:203], 0
	v_mfma_f32_16x16x32_bf16 v[4:7], v[148:151], v[204:207], 0
	v_mfma_f32_16x16x32_bf16 v[0:3], v[152:155], v[204:207], 0
	v_mfma_f32_16x16x32_bf16 v[52:55], v[156:159], v[192:195], v[52:55]
	v_mfma_f32_16x16x32_bf16 v[48:51], v[160:163], v[192:195], v[48:51]
	v_mfma_f32_16x16x32_bf16 v[36:39], v[156:159], v[196:199], v[36:39]
	v_mfma_f32_16x16x32_bf16 v[32:35], v[160:163], v[196:199], v[32:35]
	v_mfma_f32_16x16x32_bf16 v[20:23], v[156:159], v[208:211], v[20:23]
	v_mfma_f32_16x16x32_bf16 v[16:19], v[160:163], v[208:211], v[16:19]
	v_mfma_f32_16x16x32_bf16 v[4:7], v[156:159], v[212:215], v[4:7]
	v_mfma_f32_16x16x32_bf16 v[0:3], v[160:163], v[212:215], v[0:3]
	s_barrier
	s_setprio 0
	s_add_u32 s42, s42, 0x40000
	s_addc_u32 s43, s43, 0
	s_mov_b32 m0, s1
	s_nop 0
	global_load_lds_dwordx4 v137, s[42:43]
	v_mov_b32_e32 v128, v180
	s_mov_b32 m0, s69
	s_nop 0
	global_load_lds_dwordx4 v176, s[42:43]
	v_add_u32_e32 v132, s34, v180
	v_xad_u32 v144, v128, 64, s34
	v_mov_b32_e32 v148, v180
	s_add_i32 s42, 0, 0x1c000
	ds_read_b128 v[128:131], v132
	ds_read_b128 v[132:135], v132 offset:2048
	ds_read_b128 v[140:143], v144
	ds_read_b128 v[144:147], v144 offset:2048
	v_add_u32_e32 v152, s42, v180
	v_xad_u32 v160, v148, 64, s42
	ds_read_b128 v[148:151], v152
	ds_read_b128 v[152:155], v152 offset:2048
	ds_read_b128 v[156:159], v160
	ds_read_b128 v[160:163], v160 offset:2048
	v_mov_b32_e32 v164, v179
	s_nop 0
	v_xad_u32 v172, v164, 64, 0
	ds_read_b128 v[164:167], v182 offset:32768
	ds_read_b128 v[168:171], v182 offset:34816
	ds_read_b128 v[192:195], v172 offset:32768
	ds_read_b128 v[196:199], v172 offset:34816
	ds_read_b128 v[200:203], v182 offset:36864
	ds_read_b128 v[204:207], v182 offset:38912
	ds_read_b128 v[208:211], v172 offset:36864
	ds_read_b128 v[212:215], v172 offset:38912
	s_waitcnt vmcnt(8)
	s_waitcnt lgkmcnt(0)
	s_setprio 1
	s_barrier
	v_mfma_f32_16x16x32_bf16 v[124:127], v[128:131], v[164:167], v[124:127]
	v_mfma_f32_16x16x32_bf16 v[120:123], v[132:135], v[164:167], v[120:123]
	v_mfma_f32_16x16x32_bf16 v[108:111], v[128:131], v[168:171], v[108:111]
	v_mfma_f32_16x16x32_bf16 v[104:107], v[132:135], v[168:171], v[104:107]
	v_mfma_f32_16x16x32_bf16 v[92:95], v[128:131], v[200:203], v[92:95]
	v_mfma_f32_16x16x32_bf16 v[88:91], v[132:135], v[200:203], v[88:91]
	v_mfma_f32_16x16x32_bf16 v[76:79], v[128:131], v[204:207], v[76:79]
	v_mfma_f32_16x16x32_bf16 v[72:75], v[132:135], v[204:207], v[72:75]
	v_mfma_f32_16x16x32_bf16 v[124:127], v[140:143], v[192:195], v[124:127]
	v_mfma_f32_16x16x32_bf16 v[120:123], v[144:147], v[192:195], v[120:123]
	v_mfma_f32_16x16x32_bf16 v[108:111], v[140:143], v[196:199], v[108:111]
	v_mfma_f32_16x16x32_bf16 v[104:107], v[144:147], v[196:199], v[104:107]
	v_mfma_f32_16x16x32_bf16 v[92:95], v[140:143], v[208:211], v[92:95]
	v_mfma_f32_16x16x32_bf16 v[88:91], v[144:147], v[208:211], v[88:91]
	v_mfma_f32_16x16x32_bf16 v[76:79], v[140:143], v[212:215], v[76:79]
	v_mfma_f32_16x16x32_bf16 v[72:75], v[144:147], v[212:215], v[72:75]
	s_setprio 0
	s_setprio 1
	v_mfma_f32_16x16x32_bf16 v[116:119], v[148:151], v[164:167], v[116:119]
	s_add_u32 s42, s36, 0x80
	s_addc_u32 s43, s37, 0
	v_mfma_f32_16x16x32_bf16 v[112:115], v[152:155], v[164:167], v[112:115]
	v_mfma_f32_16x16x32_bf16 v[100:103], v[148:151], v[168:171], v[100:103]
	v_mfma_f32_16x16x32_bf16 v[96:99], v[152:155], v[168:171], v[96:99]
	v_mfma_f32_16x16x32_bf16 v[84:87], v[148:151], v[200:203], v[84:87]
	v_mfma_f32_16x16x32_bf16 v[80:83], v[152:155], v[200:203], v[80:83]
	v_mfma_f32_16x16x32_bf16 v[68:71], v[148:151], v[204:207], v[68:71]
	v_mfma_f32_16x16x32_bf16 v[64:67], v[152:155], v[204:207], v[64:67]
	v_mfma_f32_16x16x32_bf16 v[116:119], v[156:159], v[192:195], v[116:119]
	v_mfma_f32_16x16x32_bf16 v[112:115], v[160:163], v[192:195], v[112:115]
	v_mfma_f32_16x16x32_bf16 v[100:103], v[156:159], v[196:199], v[100:103]
	v_mfma_f32_16x16x32_bf16 v[96:99], v[160:163], v[196:199], v[96:99]
	v_mfma_f32_16x16x32_bf16 v[84:87], v[156:159], v[208:211], v[84:87]
	v_mfma_f32_16x16x32_bf16 v[80:83], v[160:163], v[208:211], v[80:83]
	v_mfma_f32_16x16x32_bf16 v[68:71], v[156:159], v[212:215], v[68:71]
	v_mfma_f32_16x16x32_bf16 v[64:67], v[160:163], v[212:215], v[64:67]
	s_barrier
; #define PG8_STAGE(bufoff, gbase, voff) do { _Pragma("unroll") for (int _i = 0; _i < 2; ++_i) \
;         dma16((const char*)(gbase), (voff)[_i], ldsb + (bufoff) + ldsw + _i * 8192); } while (0)
; #define PG8_LDA(dst, b, h) do { const int a1_ = opqv(aoff0) ^ 64; _Pragma("unroll") for (int m = 0; m < 4; ++m) { dst[m][0] = *(const LAS bf16x8*)(lds + PG8_SA(b, h) + aoff0 + m * 2048); dst[m][1] = *(const LAS bf16x8*)(lds + PG8_SA(b, h) + a1_ + m * 2048); } } while (0)
; #define PG8_LDB(dst, b, h) do { const int b1_ = opqv(boff0) ^ 64; _Pragma("unroll") for (int n = 0; n < 2; ++n) { dst[n][0] = *(const LAS bf16x8*)(lds + PG8_SB(b, h) + boff0 + n * 2048); dst[n][1] = *(const LAS bf16x8*)(lds + PG8_SB(b, h) + b1_ + n * 2048); } } while (0)
; #define PG8_WAIT_V(n) asm volatile("s_waitcnt vmcnt(" #n ")" ::: "memory")
; template <class Epi>
; __device__ __forceinline__ void gemm_phase(LAS unsigned char* lds, const Gemm g, const StaticOrder& S, const Epi& E, int wave_) {
;     ...
;         for (int t = 0; t < nt; t += 2) {
;             const bool last = (t == nt - 2);
;             const char* a1 = cA + (size_t)(t + 1) * kstep;
;             const char* a2 = last ? nA : cA + (size_t)(t + 2) * kstep; const char* b2 = last ? nB : cB + (size_t)(t + 2) * kstep;
;             const char* a3 = a2 + kstep; const char* b3 = b2 + kstep;
;             PG8_STAGE(PG8_SA(1, 1), a1 + hstepA, voffA); PG8_LDB(B0, 0, 0); PG8_LDB(B1, 0, 1); PG8_SCHED; PG8_LDA(At, 0, 0);
;             PG8_WAIT_V(8); PG8_WAIT_L(0); PG8_BAR; PG8_MMA(0, 0, At, B0); PG8_MMA(0, 1, At, B1); PG8_BAR; PG8_SCHED;
;             PG8_STAGE(PG8_SB(0, 0), b2, voffB); PG8_STAGE(PG8_SB(0, 1), b2 + hstepB, voffB); PG8_STAGE(PG8_SA(0, 0), a2, voffA); PG8_LDA(At, 0, 1);
;             PG8_WAIT_V(8); PG8_WAIT_L(0); PG8_BAR; PG8_MMA(1, 0, At, B0); PG8_MMA(1, 1, At, B1); PG8_BAR; PG8_SCHED;
;             PG8_STAGE(PG8_SA(0, 1), a2 + hstepA, voffA); PG8_LDB(B0, 1, 0); PG8_LDB(B1, 1, 1); PG8_SCHED; PG8_LDA(At, 1, 0);
;             PG8_WAIT_V(8); PG8_WAIT_L(0); PG8_BAR; PG8_MMA(0, 0, At, B0); PG8_MMA(0, 1, At, B1); PG8_BAR; PG8_SCHED;
;             PG8_STAGE(PG8_SB(1, 0), b3, voffB); PG8_STAGE(PG8_SB(1, 1), b3 + hstepB, voffB); PG8_STAGE(PG8_SA(1, 0), a3, voffA); PG8_LDA(At, 1, 1);
;             PG8_WAIT_V(8); PG8_WAIT_L(0); PG8_BAR; PG8_MMA(1, 0, At, B0); PG8_MMA(1, 1, At, B1); PG8_BAR; PG8_SCHED;
	s_setprio 0
	s_add_u32 s36, s36, 0x20080
	s_addc_u32 s37, s37, 0
	v_mov_b32_e32 v164, v179
	s_nop 0
	s_nop 0
	v_xad_u32 v172, v164, 64, 0
	ds_read_b128 v[164:167], v182 offset:49152
	ds_read_b128 v[168:171], v182 offset:51200
	ds_read_b128 v[192:195], v172 offset:49152
	ds_read_b128 v[196:199], v172 offset:51200
	ds_read_b128 v[200:203], v182 offset:53248
	ds_read_b128 v[204:207], v182 offset:55296
	ds_read_b128 v[208:211], v172 offset:53248
	ds_read_b128 v[212:215], v172 offset:55296
	s_mov_b32 m0, s35
	s_nop 0
	global_load_lds_dwordx4 v175, s[42:43]
	s_mov_b32 m0, s33
	s_nop 0
	global_load_lds_dwordx4 v177, s[42:43]
	s_mov_b32 m0, s77
	s_nop 0
	global_load_lds_dwordx4 v175, s[36:37]
	s_mov_b32 m0, s3
	s_nop 0
	global_load_lds_dwordx4 v177, s[36:37]
	s_mov_b32 m0, s22
	s_nop 0
	global_load_lds_dwordx4 v137, s[30:31]
	s_mov_b32 m0, s2
	s_nop 0
	global_load_lds_dwordx4 v176, s[30:31]
	s_waitcnt vmcnt(8)
	s_waitcnt lgkmcnt(0)
	s_setprio 1
	s_barrier
	v_mfma_f32_16x16x32_bf16 v[60:63], v[128:131], v[164:167], v[60:63]
	v_mfma_f32_16x16x32_bf16 v[56:59], v[132:135], v[164:167], v[56:59]
	v_mfma_f32_16x16x32_bf16 v[44:47], v[128:131], v[168:171], v[44:47]
	v_mfma_f32_16x16x32_bf16 v[40:43], v[132:135], v[168:171], v[40:43]
	v_mfma_f32_16x16x32_bf16 v[28:31], v[128:131], v[200:203], v[28:31]
	v_mfma_f32_16x16x32_bf16 v[24:27], v[132:135], v[200:203], v[24:27]
	v_mfma_f32_16x16x32_bf16 v[12:15], v[128:131], v[204:207], v[12:15]
	v_mfma_f32_16x16x32_bf16 v[8:11], v[132:135], v[204:207], v[8:11]
	v_mfma_f32_16x16x32_bf16 v[60:63], v[140:143], v[192:195], v[60:63]
	v_mfma_f32_16x16x32_bf16 v[56:59], v[144:147], v[192:195], v[56:59]
	v_mfma_f32_16x16x32_bf16 v[44:47], v[140:143], v[196:199], v[44:47]
	v_mfma_f32_16x16x32_bf16 v[40:43], v[144:147], v[196:199], v[40:43]
	v_mfma_f32_16x16x32_bf16 v[28:31], v[140:143], v[208:211], v[28:31]
	v_mfma_f32_16x16x32_bf16 v[24:27], v[144:147], v[208:211], v[24:27]
	v_mfma_f32_16x16x32_bf16 v[12:15], v[140:143], v[212:215], v[12:15]
	v_mfma_f32_16x16x32_bf16 v[8:11], v[144:147], v[212:215], v[8:11]
	s_setprio 0
	s_setprio 1
	v_mfma_f32_16x16x32_bf16 v[52:55], v[148:151], v[164:167], v[52:55]
	v_mfma_f32_16x16x32_bf16 v[48:51], v[152:155], v[164:167], v[48:51]
	v_mfma_f32_16x16x32_bf16 v[36:39], v[148:151], v[168:171], v[36:39]
	v_mfma_f32_16x16x32_bf16 v[32:35], v[152:155], v[168:171], v[32:35]
	v_mfma_f32_16x16x32_bf16 v[20:23], v[148:151], v[200:203], v[20:23]
	v_mfma_f32_16x16x32_bf16 v[16:19], v[152:155], v[200:203], v[16:19]
	v_mfma_f32_16x16x32_bf16 v[4:7], v[148:151], v[204:207], v[4:7]
	v_mfma_f32_16x16x32_bf16 v[0:3], v[152:155], v[204:207], v[0:3]
	v_mfma_f32_16x16x32_bf16 v[52:55], v[156:159], v[192:195], v[52:55]
	v_mfma_f32_16x16x32_bf16 v[48:51], v[160:163], v[192:195], v[48:51]
	v_mfma_f32_16x16x32_bf16 v[36:39], v[156:159], v[196:199], v[36:39]
	v_mfma_f32_16x16x32_bf16 v[32:35], v[160:163], v[196:199], v[32:35]
	v_mfma_f32_16x16x32_bf16 v[20:23], v[156:159], v[208:211], v[20:23]
	v_mfma_f32_16x16x32_bf16 v[16:19], v[160:163], v[208:211], v[16:19]
	v_mfma_f32_16x16x32_bf16 v[4:7], v[156:159], v[212:215], v[4:7]
	v_mfma_f32_16x16x32_bf16 v[0:3], v[160:163], v[212:215], v[0:3]
	s_barrier
	s_setprio 0
	s_add_i32 s57, s57, 2
	s_add_u32 s52, s52, 0x100
	s_addc_u32 s56, s56, 0
	s_add_u32 s12, s12, 0x100
	s_addc_u32 s13, s13, 0
	s_cmp_gt_u32 s57, 5
	s_cbranch_scc0 .LBB0_744
	s_branch .Lpeel_exit_6
.LBB0_744:
	s_add_u32 s30, s12, 0xfffc0080
	s_addc_u32 s31, s13, -1
	s_cmp_eq_u32 s57, 4
	s_cselect_b32 s42, s17, s30
	s_cselect_b32 s43, s16, s31
	s_cselect_b32 s36, s19, s52
	s_cselect_b32 s37, s11, s56
	s_add_u32 s30, s42, 0x80
	v_mov_b32_e32 v128, v180
	s_addc_u32 s31, s43, 0
	v_add_u32_e32 v132, s23, v180
	v_xad_u32 v144, v128, 64, s23
	v_mov_b32_e32 v148, v180
	s_add_i32 s58, 0, 0x14000
	ds_read_b128 v[128:131], v132
	ds_read_b128 v[132:135], v132 offset:2048
	ds_read_b128 v[140:143], v144
	ds_read_b128 v[144:147], v144 offset:2048
	v_add_u32_e32 v152, s58, v180
	v_xad_u32 v160, v148, 64, s58
	ds_read_b128 v[148:151], v152
	ds_read_b128 v[152:155], v152 offset:2048
	ds_read_b128 v[156:159], v160
	ds_read_b128 v[160:163], v160 offset:2048
	v_mov_b32_e32 v164, v179
	v_add_u32_e32 v182, 0, v179
	v_xad_u32 v172, v164, 64, 0
	ds_read_b128 v[164:167], v182
	ds_read_b128 v[168:171], v182 offset:2048
	ds_read_b128 v[192:195], v172
	ds_read_b128 v[196:199], v172 offset:2048
	ds_read_b128 v[200:203], v182 offset:4096
	ds_read_b128 v[204:207], v182 offset:6144
	ds_read_b128 v[208:211], v172 offset:4096
	ds_read_b128 v[212:215], v172 offset:6144
	s_mov_b32 m0, s14
	s_nop 0
	global_load_lds_dwordx4 v137, s[12:13]
	s_mov_b32 m0, s15
	s_nop 0
	global_load_lds_dwordx4 v176, s[12:13]
	s_waitcnt vmcnt(8)
	s_waitcnt lgkmcnt(0)
	s_setprio 1
	s_barrier
; #define PG8_STAGE(bufoff, gbase, voff) do { _Pragma("unroll") for (int _i = 0; _i < 2; ++_i) \
;         dma16((const char*)(gbase), (voff)[_i], ldsb + (bufoff) + ldsw + _i * 8192); } while (0)
; #define PG8_LDA(dst, b, h) do { const int a1_ = opqv(aoff0) ^ 64; _Pragma("unroll") for (int m = 0; m < 4; ++m) { dst[m][0] = *(const LAS bf16x8*)(lds + PG8_SA(b, h) + aoff0 + m * 2048); dst[m][1] = *(const LAS bf16x8*)(lds + PG8_SA(b, h) + a1_ + m * 2048); } } while (0)
; #define PG8_MMA(ai, bj, At, Bt) do { __builtin_amdgcn_s_setprio(1); _Pragma("unroll") for (int m = 0; m < 4; ++m) _Pragma("unroll") for (int n = 0; n < 2; ++n) _Pragma("unroll") for (int k = 0; k < 2; ++k) \
;         acc[ai][bj][m][n] = __builtin_amdgcn_mfma_f32_16x16x32_bf16(Bt[n][k], At[m][k], acc[ai][bj][m][n], 0, 0, 0); __builtin_amdgcn_s_setprio(0); } while (0)
; #define PG8_WAIT_V(n) asm volatile("s_waitcnt vmcnt(" #n ")" ::: "memory")
; #define PG8_WAIT_L(n) asm volatile("s_waitcnt lgkmcnt(" #n ")" ::: "memory")
; #define PG8_BAR __builtin_amdgcn_s_barrier()
; #define PG8_SCHED __builtin_amdgcn_sched_barrier(0)
; template <class Epi>
; __device__ __forceinline__ void gemm_phase(LAS unsigned char* lds, const Gemm g, const StaticOrder& S, const Epi& E, int wave_) {
;     ...
;             PG8_WAIT_V(8); PG8_WAIT_L(0); PG8_BAR; PG8_MMA(0, 0, At, B0); PG8_MMA(0, 1, At, B1); PG8_BAR; PG8_SCHED;
;             PG8_STAGE(PG8_SB(0, 0), b2, voffB); PG8_STAGE(PG8_SB(0, 1), b2 + hstepB, voffB); PG8_STAGE(PG8_SA(0, 0), a2, voffA); PG8_LDA(At, 0, 1);
;             PG8_WAIT_V(8); PG8_WAIT_L(0); PG8_BAR; PG8_MMA(1, 0, At, B0); PG8_MMA(1, 1, At, B1); PG8_BAR; PG8_SCHED;
	v_mfma_f32_16x16x32_bf16 v[124:127], v[128:131], v[164:167], v[124:127]
	v_mfma_f32_16x16x32_bf16 v[120:123], v[132:135], v[164:167], v[120:123]
	v_mfma_f32_16x16x32_bf16 v[108:111], v[128:131], v[168:171], v[108:111]
	v_mfma_f32_16x16x32_bf16 v[104:107], v[132:135], v[168:171], v[104:107]
	v_mfma_f32_16x16x32_bf16 v[92:95], v[128:131], v[200:203], v[92:95]
	v_mfma_f32_16x16x32_bf16 v[88:91], v[132:135], v[200:203], v[88:91]
	v_mfma_f32_16x16x32_bf16 v[76:79], v[128:131], v[204:207], v[76:79]
	v_mfma_f32_16x16x32_bf16 v[72:75], v[132:135], v[204:207], v[72:75]
	v_mfma_f32_16x16x32_bf16 v[124:127], v[140:143], v[192:195], v[124:127]
	v_mfma_f32_16x16x32_bf16 v[120:123], v[144:147], v[192:195], v[120:123]
	v_mfma_f32_16x16x32_bf16 v[108:111], v[140:143], v[196:199], v[108:111]
	v_mfma_f32_16x16x32_bf16 v[104:107], v[144:147], v[196:199], v[104:107]
	v_mfma_f32_16x16x32_bf16 v[92:95], v[140:143], v[208:211], v[92:95]
	v_mfma_f32_16x16x32_bf16 v[88:91], v[144:147], v[208:211], v[88:91]
	v_mfma_f32_16x16x32_bf16 v[76:79], v[140:143], v[212:215], v[76:79]
	v_mfma_f32_16x16x32_bf16 v[72:75], v[144:147], v[212:215], v[72:75]
	s_setprio 0
	s_setprio 1
	v_mfma_f32_16x16x32_bf16 v[116:119], v[148:151], v[164:167], v[116:119]
	v_mfma_f32_16x16x32_bf16 v[112:115], v[152:155], v[164:167], v[112:115]
	v_mfma_f32_16x16x32_bf16 v[100:103], v[148:151], v[168:171], v[100:103]
	v_mfma_f32_16x16x32_bf16 v[96:99], v[152:155], v[168:171], v[96:99]
	v_mfma_f32_16x16x32_bf16 v[84:87], v[148:151], v[200:203], v[84:87]
	v_mfma_f32_16x16x32_bf16 v[80:83], v[152:155], v[200:203], v[80:83]
	v_mfma_f32_16x16x32_bf16 v[68:71], v[148:151], v[204:207], v[68:71]
	v_mfma_f32_16x16x32_bf16 v[64:67], v[152:155], v[204:207], v[64:67]
	v_mfma_f32_16x16x32_bf16 v[116:119], v[156:159], v[192:195], v[116:119]
	v_mfma_f32_16x16x32_bf16 v[112:115], v[160:163], v[192:195], v[112:115]
	v_mfma_f32_16x16x32_bf16 v[100:103], v[156:159], v[196:199], v[100:103]
	v_mfma_f32_16x16x32_bf16 v[96:99], v[160:163], v[196:199], v[96:99]
	v_mfma_f32_16x16x32_bf16 v[84:87], v[156:159], v[208:211], v[84:87]
	v_mfma_f32_16x16x32_bf16 v[80:83], v[160:163], v[208:211], v[80:83]
	v_mfma_f32_16x16x32_bf16 v[68:71], v[156:159], v[212:215], v[68:71]
	v_mfma_f32_16x16x32_bf16 v[64:67], v[160:163], v[212:215], v[64:67]
	s_barrier
	s_setprio 0
	v_mov_b32_e32 v164, v179
	s_add_u32 s58, s36, 0x20000
	s_addc_u32 s59, s37, 0
	s_nop 0
	s_nop 0
	s_nop 0
	v_xad_u32 v172, v164, 64, 0
	ds_read_b128 v[164:167], v182 offset:16384
	ds_read_b128 v[168:171], v182 offset:18432
	ds_read_b128 v[192:195], v172 offset:16384
	ds_read_b128 v[196:199], v172 offset:18432
	ds_read_b128 v[200:203], v182 offset:20480
	ds_read_b128 v[204:207], v182 offset:22528
	ds_read_b128 v[208:211], v172 offset:20480
	ds_read_b128 v[212:215], v172 offset:22528
	s_mov_b32 m0, s80
	s_nop 0
	global_load_lds_dwordx4 v175, s[36:37]
	s_mov_b32 m0, s81
	s_nop 0
	global_load_lds_dwordx4 v177, s[36:37]
	s_mov_b32 m0, s29
	s_nop 0
	global_load_lds_dwordx4 v175, s[58:59]
	s_mov_b32 m0, s88
	s_nop 0
	global_load_lds_dwordx4 v177, s[58:59]
	s_mov_b32 m0, s76
	s_nop 0
	global_load_lds_dwordx4 v137, s[42:43]
	s_mov_b32 m0, s89
	s_nop 0
	global_load_lds_dwordx4 v176, s[42:43]
	s_waitcnt vmcnt(8)
	s_waitcnt lgkmcnt(0)
	s_setprio 1
	s_barrier
	v_mfma_f32_16x16x32_bf16 v[60:63], v[128:131], v[164:167], v[60:63]
	v_mfma_f32_16x16x32_bf16 v[56:59], v[132:135], v[164:167], v[56:59]
	v_mfma_f32_16x16x32_bf16 v[44:47], v[128:131], v[168:171], v[44:47]
	v_mfma_f32_16x16x32_bf16 v[40:43], v[132:135], v[168:171], v[40:43]
	v_mfma_f32_16x16x32_bf16 v[28:31], v[128:131], v[200:203], v[28:31]
	v_mfma_f32_16x16x32_bf16 v[24:27], v[132:135], v[200:203], v[24:27]
	v_mfma_f32_16x16x32_bf16 v[12:15], v[128:131], v[204:207], v[12:15]
	v_mfma_f32_16x16x32_bf16 v[8:11], v[132:135], v[204:207], v[8:11]
	v_mfma_f32_16x16x32_bf16 v[60:63], v[140:143], v[192:195], v[60:63]
	v_mfma_f32_16x16x32_bf16 v[56:59], v[144:147], v[192:195], v[56:59]
	v_mfma_f32_16x16x32_bf16 v[44:47], v[140:143], v[196:199], v[44:47]
	v_mfma_f32_16x16x32_bf16 v[40:43], v[144:147], v[196:199], v[40:43]
	v_mfma_f32_16x16x32_bf16 v[28:31], v[140:143], v[208:211], v[28:31]
	v_mfma_f32_16x16x32_bf16 v[24:27], v[144:147], v[208:211], v[24:27]
	v_mfma_f32_16x16x32_bf16 v[12:15], v[140:143], v[212:215], v[12:15]
	v_mfma_f32_16x16x32_bf16 v[8:11], v[144:147], v[212:215], v[8:11]
	s_setprio 0
	s_setprio 1
	v_mfma_f32_16x16x32_bf16 v[52:55], v[148:151], v[164:167], v[52:55]
	v_mfma_f32_16x16x32_bf16 v[48:51], v[152:155], v[164:167], v[48:51]
	v_mfma_f32_16x16x32_bf16 v[36:39], v[148:151], v[168:171], v[36:39]
	v_mfma_f32_16x16x32_bf16 v[32:35], v[152:155], v[168:171], v[32:35]
	v_mfma_f32_16x16x32_bf16 v[20:23], v[148:151], v[200:203], v[20:23]
	v_mfma_f32_16x16x32_bf16 v[16:19], v[152:155], v[200:203], v[16:19]
	v_mfma_f32_16x16x32_bf16 v[4:7], v[148:151], v[204:207], v[4:7]
	v_mfma_f32_16x16x32_bf16 v[0:3], v[152:155], v[204:207], v[0:3]
	v_mfma_f32_16x16x32_bf16 v[52:55], v[156:159], v[192:195], v[52:55]
	v_mfma_f32_16x16x32_bf16 v[48:51], v[160:163], v[192:195], v[48:51]
	v_mfma_f32_16x16x32_bf16 v[36:39], v[156:159], v[196:199], v[36:39]
	v_mfma_f32_16x16x32_bf16 v[32:35], v[160:163], v[196:199], v[32:35]
	v_mfma_f32_16x16x32_bf16 v[20:23], v[156:159], v[208:211], v[20:23]
	v_mfma_f32_16x16x32_bf16 v[16:19], v[160:163], v[208:211], v[16:19]
	v_mfma_f32_16x16x32_bf16 v[4:7], v[156:159], v[212:215], v[4:7]
	v_mfma_f32_16x16x32_bf16 v[0:3], v[160:163], v[212:215], v[0:3]
	s_barrier
; #define PG8_STAGE(bufoff, gbase, voff) do { _Pragma("unroll") for (int _i = 0; _i < 2; ++_i) \
;         dma16((const char*)(gbase), (voff)[_i], ldsb + (bufoff) + ldsw + _i * 8192); } while (0)
; #define PG8_LDA(dst, b, h) do { const int a1_ = opqv(aoff0) ^ 64; _Pragma("unroll") for (int m = 0; m < 4; ++m) { dst[m][0] = *(const LAS bf16x8*)(lds + PG8_SA(b, h) + aoff0 + m * 2048); dst[m][1] = *(const LAS bf16x8*)(lds + PG8_SA(b, h) + a1_ + m * 2048); } } while (0)
; #define PG8_LDB(dst, b, h) do { const int b1_ = opqv(boff0) ^ 64; _Pragma("unroll") for (int n = 0; n < 2; ++n) { dst[n][0] = *(const LAS bf16x8*)(lds + PG8_SB(b, h) + boff0 + n * 2048); dst[n][1] = *(const LAS bf16x8*)(lds + PG8_SB(b, h) + b1_ + n * 2048); } } while (0)
; #define PG8_MMA(ai, bj, At, Bt) do { __builtin_amdgcn_s_setprio(1); _Pragma("unroll") for (int m = 0; m < 4; ++m) _Pragma("unroll") for (int n = 0; n < 2; ++n) _Pragma("unroll") for (int k = 0; k < 2; ++k) \
;         acc[ai][bj][m][n] = __builtin_amdgcn_mfma_f32_16x16x32_bf16(Bt[n][k], At[m][k], acc[ai][bj][m][n], 0, 0, 0); __builtin_amdgcn_s_setprio(0); } while (0)
; #define PG8_WAIT_V(n) asm volatile("s_waitcnt vmcnt(" #n ")" ::: "memory")
; #define PG8_WAIT_L(n) asm volatile("s_waitcnt lgkmcnt(" #n ")" ::: "memory")
; #define PG8_BAR __builtin_amdgcn_s_barrier()
; #define PG8_SCHED __builtin_amdgcn_sched_barrier(0)
; template <class Epi>
; __device__ __forceinline__ void gemm_phase(LAS unsigned char* lds, const Gemm g, const StaticOrder& S, const Epi& E, int wave_) {
;     ...
;             PG8_STAGE(PG8_SA(0, 1), a2 + hstepA, voffA); PG8_LDB(B0, 1, 0); PG8_LDB(B1, 1, 1); PG8_SCHED; PG8_LDA(At, 1, 0);
;             PG8_WAIT_V(8); PG8_WAIT_L(0); PG8_BAR; PG8_MMA(0, 0, At, B0); PG8_MMA(0, 1, At, B1); PG8_BAR; PG8_SCHED;
;             PG8_STAGE(PG8_SB(1, 0), b3, voffB); PG8_STAGE(PG8_SB(1, 1), b3 + hstepB, voffB); PG8_STAGE(PG8_SA(1, 0), a3, voffA); PG8_LDA(At, 1, 1);
;             PG8_WAIT_V(8); PG8_WAIT_L(0); PG8_BAR; PG8_MMA(1, 0, At, B0); PG8_MMA(1, 1, At, B1); PG8_BAR; PG8_SCHED;
;         }
	s_setprio 0
	s_add_u32 s42, s42, 0x40000
	s_addc_u32 s43, s43, 0
	s_mov_b32 m0, s1
	s_nop 0
	global_load_lds_dwordx4 v137, s[42:43]
	v_mov_b32_e32 v128, v180
	s_mov_b32 m0, s69
	s_nop 0
	global_load_lds_dwordx4 v176, s[42:43]
	v_add_u32_e32 v132, s34, v180
	v_xad_u32 v144, v128, 64, s34
	v_mov_b32_e32 v148, v180
	s_add_i32 s42, 0, 0x1c000
	ds_read_b128 v[128:131], v132
	ds_read_b128 v[132:135], v132 offset:2048
	ds_read_b128 v[140:143], v144
	ds_read_b128 v[144:147], v144 offset:2048
	v_add_u32_e32 v152, s42, v180
	v_xad_u32 v160, v148, 64, s42
	ds_read_b128 v[148:151], v152
	ds_read_b128 v[152:155], v152 offset:2048
	ds_read_b128 v[156:159], v160
	ds_read_b128 v[160:163], v160 offset:2048
	v_mov_b32_e32 v164, v179
	s_nop 0
	v_xad_u32 v172, v164, 64, 0
	ds_read_b128 v[164:167], v182 offset:32768
	ds_read_b128 v[168:171], v182 offset:34816
	ds_read_b128 v[192:195], v172 offset:32768
	ds_read_b128 v[196:199], v172 offset:34816
	ds_read_b128 v[200:203], v182 offset:36864
	ds_read_b128 v[204:207], v182 offset:38912
	ds_read_b128 v[208:211], v172 offset:36864
	ds_read_b128 v[212:215], v172 offset:38912
	s_waitcnt vmcnt(8)
	s_waitcnt lgkmcnt(0)
	s_setprio 1
	s_barrier
	v_mfma_f32_16x16x32_bf16 v[124:127], v[128:131], v[164:167], v[124:127]
	v_mfma_f32_16x16x32_bf16 v[120:123], v[132:135], v[164:167], v[120:123]
	v_mfma_f32_16x16x32_bf16 v[108:111], v[128:131], v[168:171], v[108:111]
	v_mfma_f32_16x16x32_bf16 v[104:107], v[132:135], v[168:171], v[104:107]
	v_mfma_f32_16x16x32_bf16 v[92:95], v[128:131], v[200:203], v[92:95]
	v_mfma_f32_16x16x32_bf16 v[88:91], v[132:135], v[200:203], v[88:91]
	v_mfma_f32_16x16x32_bf16 v[76:79], v[128:131], v[204:207], v[76:79]
	v_mfma_f32_16x16x32_bf16 v[72:75], v[132:135], v[204:207], v[72:75]
	v_mfma_f32_16x16x32_bf16 v[124:127], v[140:143], v[192:195], v[124:127]
	v_mfma_f32_16x16x32_bf16 v[120:123], v[144:147], v[192:195], v[120:123]
	v_mfma_f32_16x16x32_bf16 v[108:111], v[140:143], v[196:199], v[108:111]
	v_mfma_f32_16x16x32_bf16 v[104:107], v[144:147], v[196:199], v[104:107]
	v_mfma_f32_16x16x32_bf16 v[92:95], v[140:143], v[208:211], v[92:95]
	v_mfma_f32_16x16x32_bf16 v[88:91], v[144:147], v[208:211], v[88:91]
	v_mfma_f32_16x16x32_bf16 v[76:79], v[140:143], v[212:215], v[76:79]
	v_mfma_f32_16x16x32_bf16 v[72:75], v[144:147], v[212:215], v[72:75]
	s_setprio 0
	s_setprio 1
	v_mfma_f32_16x16x32_bf16 v[116:119], v[148:151], v[164:167], v[116:119]
	s_add_u32 s42, s36, 0x80
	s_addc_u32 s43, s37, 0
	v_mfma_f32_16x16x32_bf16 v[112:115], v[152:155], v[164:167], v[112:115]
	v_mfma_f32_16x16x32_bf16 v[100:103], v[148:151], v[168:171], v[100:103]
	v_mfma_f32_16x16x32_bf16 v[96:99], v[152:155], v[168:171], v[96:99]
	v_mfma_f32_16x16x32_bf16 v[84:87], v[148:151], v[200:203], v[84:87]
	v_mfma_f32_16x16x32_bf16 v[80:83], v[152:155], v[200:203], v[80:83]
	v_mfma_f32_16x16x32_bf16 v[68:71], v[148:151], v[204:207], v[68:71]
	v_mfma_f32_16x16x32_bf16 v[64:67], v[152:155], v[204:207], v[64:67]
	v_mfma_f32_16x16x32_bf16 v[116:119], v[156:159], v[192:195], v[116:119]
	v_mfma_f32_16x16x32_bf16 v[112:115], v[160:163], v[192:195], v[112:115]
	v_mfma_f32_16x16x32_bf16 v[100:103], v[156:159], v[196:199], v[100:103]
	v_mfma_f32_16x16x32_bf16 v[96:99], v[160:163], v[196:199], v[96:99]
	v_mfma_f32_16x16x32_bf16 v[84:87], v[156:159], v[208:211], v[84:87]
	v_mfma_f32_16x16x32_bf16 v[80:83], v[160:163], v[208:211], v[80:83]
	v_mfma_f32_16x16x32_bf16 v[68:71], v[156:159], v[212:215], v[68:71]
	v_mfma_f32_16x16x32_bf16 v[64:67], v[160:163], v[212:215], v[64:67]
	s_barrier
	s_setprio 0
	s_add_u32 s36, s36, 0x20080
	s_addc_u32 s37, s37, 0
	v_mov_b32_e32 v164, v179
	s_nop 0
	s_nop 0
	v_xad_u32 v172, v164, 64, 0
	ds_read_b128 v[164:167], v182 offset:49152
	ds_read_b128 v[168:171], v182 offset:51200
	ds_read_b128 v[192:195], v172 offset:49152
	ds_read_b128 v[196:199], v172 offset:51200
	ds_read_b128 v[200:203], v182 offset:53248
	ds_read_b128 v[204:207], v182 offset:55296
	ds_read_b128 v[208:211], v172 offset:53248
	ds_read_b128 v[212:215], v172 offset:55296
	s_mov_b32 m0, s35
	s_nop 0
	global_load_lds_dwordx4 v175, s[42:43]
	s_mov_b32 m0, s33
	s_nop 0
	global_load_lds_dwordx4 v177, s[42:43]
	s_mov_b32 m0, s77
	s_nop 0
	global_load_lds_dwordx4 v175, s[36:37]
	s_mov_b32 m0, s3
	s_nop 0
	global_load_lds_dwordx4 v177, s[36:37]
	s_mov_b32 m0, s22
	s_nop 0
	global_load_lds_dwordx4 v137, s[30:31]
	s_mov_b32 m0, s2
	s_nop 0
	global_load_lds_dwordx4 v176, s[30:31]
	s_waitcnt vmcnt(8)
	s_waitcnt lgkmcnt(0)
	s_setprio 1
	s_barrier
	v_mfma_f32_16x16x32_bf16 v[60:63], v[128:131], v[164:167], v[60:63]
	v_mfma_f32_16x16x32_bf16 v[56:59], v[132:135], v[164:167], v[56:59]
	v_mfma_f32_16x16x32_bf16 v[44:47], v[128:131], v[168:171], v[44:47]
	v_mfma_f32_16x16x32_bf16 v[40:43], v[132:135], v[168:171], v[40:43]
	v_mfma_f32_16x16x32_bf16 v[28:31], v[128:131], v[200:203], v[28:31]
	v_mfma_f32_16x16x32_bf16 v[24:27], v[132:135], v[200:203], v[24:27]
	v_mfma_f32_16x16x32_bf16 v[12:15], v[128:131], v[204:207], v[12:15]
	v_mfma_f32_16x16x32_bf16 v[8:11], v[132:135], v[204:207], v[8:11]
	v_mfma_f32_16x16x32_bf16 v[60:63], v[140:143], v[192:195], v[60:63]
	v_mfma_f32_16x16x32_bf16 v[56:59], v[144:147], v[192:195], v[56:59]
	v_mfma_f32_16x16x32_bf16 v[44:47], v[140:143], v[196:199], v[44:47]
	v_mfma_f32_16x16x32_bf16 v[40:43], v[144:147], v[196:199], v[40:43]
	v_mfma_f32_16x16x32_bf16 v[28:31], v[140:143], v[208:211], v[28:31]
	v_mfma_f32_16x16x32_bf16 v[24:27], v[144:147], v[208:211], v[24:27]
	v_mfma_f32_16x16x32_bf16 v[12:15], v[140:143], v[212:215], v[12:15]
	v_mfma_f32_16x16x32_bf16 v[8:11], v[144:147], v[212:215], v[8:11]
	s_setprio 0
	s_setprio 1
	v_mfma_f32_16x16x32_bf16 v[52:55], v[148:151], v[164:167], v[52:55]
	v_mfma_f32_16x16x32_bf16 v[48:51], v[152:155], v[164:167], v[48:51]
	v_mfma_f32_16x16x32_bf16 v[36:39], v[148:151], v[168:171], v[36:39]
	v_mfma_f32_16x16x32_bf16 v[32:35], v[152:155], v[168:171], v[32:35]
	v_mfma_f32_16x16x32_bf16 v[20:23], v[148:151], v[200:203], v[20:23]
	v_mfma_f32_16x16x32_bf16 v[16:19], v[152:155], v[200:203], v[16:19]
	v_mfma_f32_16x16x32_bf16 v[4:7], v[148:151], v[204:207], v[4:7]
	v_mfma_f32_16x16x32_bf16 v[0:3], v[152:155], v[204:207], v[0:3]
	v_mfma_f32_16x16x32_bf16 v[52:55], v[156:159], v[192:195], v[52:55]
	v_mfma_f32_16x16x32_bf16 v[48:51], v[160:163], v[192:195], v[48:51]
	v_mfma_f32_16x16x32_bf16 v[36:39], v[156:159], v[196:199], v[36:39]
	v_mfma_f32_16x16x32_bf16 v[32:35], v[160:163], v[196:199], v[32:35]
	v_mfma_f32_16x16x32_bf16 v[20:23], v[156:159], v[208:211], v[20:23]
	v_mfma_f32_16x16x32_bf16 v[16:19], v[160:163], v[208:211], v[16:19]
	v_mfma_f32_16x16x32_bf16 v[4:7], v[156:159], v[212:215], v[4:7]
	v_mfma_f32_16x16x32_bf16 v[0:3], v[160:163], v[212:215], v[0:3]
	s_barrier
	s_setprio 0
	s_add_i32 s57, s57, 2
	s_add_u32 s52, s52, 0x100
	s_addc_u32 s56, s56, 0
	s_add_u32 s12, s12, 0x100
	s_addc_u32 s13, s13, 0
	s_cmp_gt_u32 s57, 5
	s_cbranch_scc0 .LBB0_744

; #define PG8_STAGE(bufoff, gbase, voff) do { _Pragma("unroll") for (int _i = 0; _i < 2; ++_i) \
;         dma16((const char*)(gbase), (voff)[_i], ldsb + (bufoff) + ldsw + _i * 8192); } while (0)
; #define PG8_LDA(dst, b, h) do { const int a1_ = opqv(aoff0) ^ 64; _Pragma("unroll") for (int m = 0; m < 4; ++m) { dst[m][0] = *(const LAS bf16x8*)(lds + PG8_SA(b, h) + aoff0 + m * 2048); dst[m][1] = *(const LAS bf16x8*)(lds + PG8_SA(b, h) + a1_ + m * 2048); } } while (0)
; #define PG8_LDB(dst, b, h) do { const int b1_ = opqv(boff0) ^ 64; _Pragma("unroll") for (int n = 0; n < 2; ++n) { dst[n][0] = *(const LAS bf16x8*)(lds + PG8_SB(b, h) + boff0 + n * 2048); dst[n][1] = *(const LAS bf16x8*)(lds + PG8_SB(b, h) + b1_ + n * 2048); } } while (0)
; #define PG8_MMA(ai, bj, At, Bt) do { __builtin_amdgcn_s_setprio(1); _Pragma("unroll") for (int m = 0; m < 4; ++m) _Pragma("unroll") for (int n = 0; n < 2; ++n) _Pragma("unroll") for (int k = 0; k < 2; ++k) \
;         acc[ai][bj][m][n] = __builtin_amdgcn_mfma_f32_16x16x32_bf16(Bt[n][k], At[m][k], acc[ai][bj][m][n], 0, 0, 0); __builtin_amdgcn_s_setprio(0); } while (0)
; template <class Epi>
; __device__ __forceinline__ void gemm_phase(LAS unsigned char* lds, const Gemm g, const StaticOrder& S, const Epi& E, int wave_) {
;     ...
;         const bool has_next = S.next(ui + 1, nxt);
;         const char* nA = has_next ? (const char*)g.A + (size_t)nxt.pm * tstepA : cA; const char* nB = has_next ? (const char*)g.Bt + (size_t)nxt.pn * tstepB : cB;
; #pragma unroll 1
;         for (int t = 0; t < nt; t += 2) {
;             const bool last = (t == nt - 2);
;             const char* a1 = cA + (size_t)(t + 1) * kstep;
;             const char* a2 = last ? nA : cA + (size_t)(t + 2) * kstep; const char* b2 = last ? nB : cB + (size_t)(t + 2) * kstep;
;             const char* a3 = a2 + kstep; const char* b3 = b2 + kstep;
;             PG8_STAGE(PG8_SA(1, 1), a1 + hstepA, voffA); PG8_LDB(B0, 0, 0); PG8_LDB(B1, 0, 1); PG8_SCHED; PG8_LDA(At, 0, 0);
;             PG8_WAIT_V(8); PG8_WAIT_L(0); PG8_BAR; PG8_MMA(0, 0, At, B0); PG8_MMA(0, 1, At, B1); PG8_BAR; PG8_SCHED;
;             PG8_STAGE(PG8_SB(0, 0), b2, voffB); PG8_STAGE(PG8_SB(0, 1), b2 + hstepB, voffB); PG8_STAGE(PG8_SA(0, 0), a2, voffA); PG8_LDA(At, 0, 1);
;             PG8_WAIT_V(8); PG8_WAIT_L(0); PG8_BAR; PG8_MMA(1, 0, At, B0); PG8_MMA(1, 1, At, B1); PG8_BAR; PG8_SCHED;
.LBB0_795:
	s_ashr_i32 s19, s18, 31
	s_lshl_b64 s[16:17], s[18:19], 19
	s_add_u32 s24, s21, s16
	s_addc_u32 s25, s44, s17
	s_and_b64 s[16:17], s[40:41], exec
	s_cselect_b32 s16, s25, s31
	s_cselect_b32 s17, s24, s30
	s_ashr_i32 s11, s10, 31
	s_lshl_b64 s[26:27], s[10:11], 18
	s_add_u32 s26, s45, s26
	s_addc_u32 s27, s46, s27
	s_and_b64 s[36:37], s[40:41], exec
	s_cselect_b32 s11, s27, s13
	s_cselect_b32 s19, s26, s12
	s_add_u32 s52, s12, 0x100
	s_addc_u32 s54, s13, 0
	s_add_u32 s12, s30, 0x40080
	s_addc_u32 s13, s31, 0
	s_mov_b32 s55, -2
	s_add_u32 s30, s12, 0xfffc0080
	s_addc_u32 s31, s13, -1
	s_cmp_eq_u32 s55, 4
	s_cselect_b32 s42, s17, s30
	s_cselect_b32 s43, s16, s31
	s_cselect_b32 s36, s19, s52
	s_cselect_b32 s37, s11, s54
	s_add_u32 s30, s42, 0x80
	v_mov_b32_e32 v130, v161
	s_addc_u32 s31, s43, 0
	v_add_u32_e32 v134, s23, v161
	v_xad_u32 v142, v130, 64, s23
	v_mov_b32_e32 v146, v161
	s_add_i32 s56, 0, 0x14000
	ds_read_b128 v[130:133], v134
	ds_read_b128 v[134:137], v134 offset:2048
	ds_read_b128 v[138:141], v142
	ds_read_b128 v[142:145], v142 offset:2048
	v_add_u32_e32 v150, s56, v161
	v_xad_u32 v154, v146, 64, s56
	ds_read_b128 v[146:149], v150
	ds_read_b128 v[150:153], v150 offset:2048
	ds_read_b128 v[162:165], v154
	ds_read_b128 v[166:169], v154 offset:2048
	v_mov_b32_e32 v154, v160
	v_add_u32_e32 v155, 0, v160
	v_xad_u32 v154, v154, 64, 0
	ds_read_b128 v[176:179], v155
	ds_read_b128 v[180:183], v155 offset:2048
	ds_read_b128 v[192:195], v154
	ds_read_b128 v[196:199], v154 offset:2048
	ds_read_b128 v[200:203], v155 offset:4096
	ds_read_b128 v[204:207], v155 offset:6144
	ds_read_b128 v[208:211], v154 offset:4096
	ds_read_b128 v[212:215], v154 offset:6144
	s_mov_b32 m0, s14
	s_nop 0
	global_load_lds_dwordx4 v129, s[12:13]
	s_mov_b32 m0, s15
	s_nop 0
	global_load_lds_dwordx4 v157, s[12:13]
	s_waitcnt vmcnt(8)
	s_waitcnt lgkmcnt(0)
	s_setprio 1
	s_barrier
	v_mfma_f32_16x16x32_bf16 v[124:127], v[130:133], v[176:179], 0
	v_mfma_f32_16x16x32_bf16 v[120:123], v[134:137], v[176:179], 0
	v_mfma_f32_16x16x32_bf16 v[108:111], v[130:133], v[180:183], 0
	v_mfma_f32_16x16x32_bf16 v[104:107], v[134:137], v[180:183], 0
	v_mfma_f32_16x16x32_bf16 v[92:95], v[130:133], v[200:203], 0
	v_mfma_f32_16x16x32_bf16 v[88:91], v[134:137], v[200:203], 0
	v_mfma_f32_16x16x32_bf16 v[76:79], v[130:133], v[204:207], 0
	v_mfma_f32_16x16x32_bf16 v[72:75], v[134:137], v[204:207], 0
	v_mfma_f32_16x16x32_bf16 v[124:127], v[138:141], v[192:195], v[124:127]
	v_mfma_f32_16x16x32_bf16 v[120:123], v[142:145], v[192:195], v[120:123]
	v_mfma_f32_16x16x32_bf16 v[108:111], v[138:141], v[196:199], v[108:111]
	v_mfma_f32_16x16x32_bf16 v[104:107], v[142:145], v[196:199], v[104:107]
	v_mfma_f32_16x16x32_bf16 v[92:95], v[138:141], v[208:211], v[92:95]
	v_mfma_f32_16x16x32_bf16 v[88:91], v[142:145], v[208:211], v[88:91]
	v_mfma_f32_16x16x32_bf16 v[76:79], v[138:141], v[212:215], v[76:79]
	v_mfma_f32_16x16x32_bf16 v[72:75], v[142:145], v[212:215], v[72:75]
	s_setprio 0
	s_setprio 1
	v_mfma_f32_16x16x32_bf16 v[116:119], v[146:149], v[176:179], 0
	v_mfma_f32_16x16x32_bf16 v[112:115], v[150:153], v[176:179], 0
	v_mfma_f32_16x16x32_bf16 v[100:103], v[146:149], v[180:183], 0
	v_mfma_f32_16x16x32_bf16 v[96:99], v[150:153], v[180:183], 0
	v_mfma_f32_16x16x32_bf16 v[84:87], v[146:149], v[200:203], 0
	v_mfma_f32_16x16x32_bf16 v[80:83], v[150:153], v[200:203], 0
	v_mfma_f32_16x16x32_bf16 v[68:71], v[146:149], v[204:207], 0
	v_mfma_f32_16x16x32_bf16 v[64:67], v[150:153], v[204:207], 0
	v_mfma_f32_16x16x32_bf16 v[116:119], v[162:165], v[192:195], v[116:119]
	v_mfma_f32_16x16x32_bf16 v[112:115], v[166:169], v[192:195], v[112:115]
	v_mfma_f32_16x16x32_bf16 v[100:103], v[162:165], v[196:199], v[100:103]
	v_mfma_f32_16x16x32_bf16 v[96:99], v[166:169], v[196:199], v[96:99]
	v_mfma_f32_16x16x32_bf16 v[84:87], v[162:165], v[208:211], v[84:87]
	v_mfma_f32_16x16x32_bf16 v[80:83], v[166:169], v[208:211], v[80:83]
	v_mfma_f32_16x16x32_bf16 v[68:71], v[162:165], v[212:215], v[68:71]
	v_mfma_f32_16x16x32_bf16 v[64:67], v[166:169], v[212:215], v[64:67]
	s_barrier
	s_setprio 0
	v_mov_b32_e32 v154, v160
	s_add_u32 s56, s36, 0x20000
	s_addc_u32 s57, s37, 0
	s_nop 0
	s_nop 0
	s_nop 0
	v_xad_u32 v154, v154, 64, 0
	ds_read_b128 v[176:179], v155 offset:16384
	ds_read_b128 v[180:183], v155 offset:18432
	ds_read_b128 v[192:195], v154 offset:16384
	ds_read_b128 v[196:199], v154 offset:18432
	ds_read_b128 v[200:203], v155 offset:20480
	ds_read_b128 v[204:207], v155 offset:22528
	ds_read_b128 v[208:211], v154 offset:20480
	ds_read_b128 v[212:215], v154 offset:22528
	s_mov_b32 m0, s80
	s_nop 0
	global_load_lds_dwordx4 v156, s[36:37]
	s_mov_b32 m0, s81
	s_nop 0
	global_load_lds_dwordx4 v158, s[36:37]
	s_mov_b32 m0, s29
	s_nop 0
	global_load_lds_dwordx4 v156, s[56:57]
	s_mov_b32 m0, s88
	s_nop 0
	global_load_lds_dwordx4 v158, s[56:57]
	s_mov_b32 m0, s76
	s_nop 0
	global_load_lds_dwordx4 v129, s[42:43]
	s_mov_b32 m0, s89
	s_nop 0
	global_load_lds_dwordx4 v157, s[42:43]
	s_waitcnt vmcnt(8)
	s_waitcnt lgkmcnt(0)
	s_setprio 1
	s_barrier
; #define PG8_STAGE(bufoff, gbase, voff) do { _Pragma("unroll") for (int _i = 0; _i < 2; ++_i) \
;         dma16((const char*)(gbase), (voff)[_i], ldsb + (bufoff) + ldsw + _i * 8192); } while (0)
; #define PG8_LDA(dst, b, h) do { const int a1_ = opqv(aoff0) ^ 64; _Pragma("unroll") for (int m = 0; m < 4; ++m) { dst[m][0] = *(const LAS bf16x8*)(lds + PG8_SA(b, h) + aoff0 + m * 2048); dst[m][1] = *(const LAS bf16x8*)(lds + PG8_SA(b, h) + a1_ + m * 2048); } } while (0)
; #define PG8_LDB(dst, b, h) do { const int b1_ = opqv(boff0) ^ 64; _Pragma("unroll") for (int n = 0; n < 2; ++n) { dst[n][0] = *(const LAS bf16x8*)(lds + PG8_SB(b, h) + boff0 + n * 2048); dst[n][1] = *(const LAS bf16x8*)(lds + PG8_SB(b, h) + b1_ + n * 2048); } } while (0)
; #define PG8_MMA(ai, bj, At, Bt) do { __builtin_amdgcn_s_setprio(1); _Pragma("unroll") for (int m = 0; m < 4; ++m) _Pragma("unroll") for (int n = 0; n < 2; ++n) _Pragma("unroll") for (int k = 0; k < 2; ++k) \
;         acc[ai][bj][m][n] = __builtin_amdgcn_mfma_f32_16x16x32_bf16(Bt[n][k], At[m][k], acc[ai][bj][m][n], 0, 0, 0); __builtin_amdgcn_s_setprio(0); } while (0)
; #define PG8_WAIT_V(n) asm volatile("s_waitcnt vmcnt(" #n ")" ::: "memory")
; #define PG8_WAIT_L(n) asm volatile("s_waitcnt lgkmcnt(" #n ")" ::: "memory")
; #define PG8_BAR __builtin_amdgcn_s_barrier()
; #define PG8_SCHED __builtin_amdgcn_sched_barrier(0)
; template <class Epi>
; __device__ __forceinline__ void gemm_phase(LAS unsigned char* lds, const Gemm g, const StaticOrder& S, const Epi& E, int wave_) {
;     ...
;             PG8_WAIT_V(8); PG8_WAIT_L(0); PG8_BAR; PG8_MMA(1, 0, At, B0); PG8_MMA(1, 1, At, B1); PG8_BAR; PG8_SCHED;
;             PG8_STAGE(PG8_SA(0, 1), a2 + hstepA, voffA); PG8_LDB(B0, 1, 0); PG8_LDB(B1, 1, 1); PG8_SCHED; PG8_LDA(At, 1, 0);
;             PG8_WAIT_V(8); PG8_WAIT_L(0); PG8_BAR; PG8_MMA(0, 0, At, B0); PG8_MMA(0, 1, At, B1); PG8_BAR; PG8_SCHED;
	v_mfma_f32_16x16x32_bf16 v[60:63], v[130:133], v[176:179], 0
	v_mfma_f32_16x16x32_bf16 v[56:59], v[134:137], v[176:179], 0
	v_mfma_f32_16x16x32_bf16 v[44:47], v[130:133], v[180:183], 0
	v_mfma_f32_16x16x32_bf16 v[40:43], v[134:137], v[180:183], 0
	v_mfma_f32_16x16x32_bf16 v[28:31], v[130:133], v[200:203], 0
	v_mfma_f32_16x16x32_bf16 v[24:27], v[134:137], v[200:203], 0
	v_mfma_f32_16x16x32_bf16 v[12:15], v[130:133], v[204:207], 0
	v_mfma_f32_16x16x32_bf16 v[8:11], v[134:137], v[204:207], 0
	v_mfma_f32_16x16x32_bf16 v[60:63], v[138:141], v[192:195], v[60:63]
	v_mfma_f32_16x16x32_bf16 v[56:59], v[142:145], v[192:195], v[56:59]
	v_mfma_f32_16x16x32_bf16 v[44:47], v[138:141], v[196:199], v[44:47]
	v_mfma_f32_16x16x32_bf16 v[40:43], v[142:145], v[196:199], v[40:43]
	v_mfma_f32_16x16x32_bf16 v[28:31], v[138:141], v[208:211], v[28:31]
	v_mfma_f32_16x16x32_bf16 v[24:27], v[142:145], v[208:211], v[24:27]
	v_mfma_f32_16x16x32_bf16 v[12:15], v[138:141], v[212:215], v[12:15]
	v_mfma_f32_16x16x32_bf16 v[8:11], v[142:145], v[212:215], v[8:11]
	s_setprio 0
	s_setprio 1
	v_mfma_f32_16x16x32_bf16 v[52:55], v[146:149], v[176:179], 0
	v_mfma_f32_16x16x32_bf16 v[48:51], v[150:153], v[176:179], 0
	v_mfma_f32_16x16x32_bf16 v[36:39], v[146:149], v[180:183], 0
	v_mfma_f32_16x16x32_bf16 v[32:35], v[150:153], v[180:183], 0
	v_mfma_f32_16x16x32_bf16 v[20:23], v[146:149], v[200:203], 0
	v_mfma_f32_16x16x32_bf16 v[16:19], v[150:153], v[200:203], 0
	v_mfma_f32_16x16x32_bf16 v[4:7], v[146:149], v[204:207], 0
	v_mfma_f32_16x16x32_bf16 v[0:3], v[150:153], v[204:207], 0
	v_mfma_f32_16x16x32_bf16 v[52:55], v[162:165], v[192:195], v[52:55]
	v_mfma_f32_16x16x32_bf16 v[48:51], v[166:169], v[192:195], v[48:51]
	v_mfma_f32_16x16x32_bf16 v[36:39], v[162:165], v[196:199], v[36:39]
	v_mfma_f32_16x16x32_bf16 v[32:35], v[166:169], v[196:199], v[32:35]
	v_mfma_f32_16x16x32_bf16 v[20:23], v[162:165], v[208:211], v[20:23]
	v_mfma_f32_16x16x32_bf16 v[16:19], v[166:169], v[208:211], v[16:19]
	v_mfma_f32_16x16x32_bf16 v[4:7], v[162:165], v[212:215], v[4:7]
	v_mfma_f32_16x16x32_bf16 v[0:3], v[166:169], v[212:215], v[0:3]
	s_barrier
	s_setprio 0
	s_add_u32 s42, s42, 0x40000
	s_addc_u32 s43, s43, 0
	s_mov_b32 m0, s1
	s_nop 0
	global_load_lds_dwordx4 v129, s[42:43]
	v_mov_b32_e32 v130, v161
	s_mov_b32 m0, s69
	s_nop 0
	global_load_lds_dwordx4 v157, s[42:43]
	v_add_u32_e32 v134, s34, v161
	v_xad_u32 v142, v130, 64, s34
	v_mov_b32_e32 v146, v161
	s_add_i32 s42, 0, 0x1c000
	ds_read_b128 v[130:133], v134
	ds_read_b128 v[134:137], v134 offset:2048
	ds_read_b128 v[138:141], v142
	ds_read_b128 v[142:145], v142 offset:2048
	v_add_u32_e32 v150, s42, v161
	v_xad_u32 v154, v146, 64, s42
	ds_read_b128 v[146:149], v150
	ds_read_b128 v[150:153], v150 offset:2048
	ds_read_b128 v[162:165], v154
	ds_read_b128 v[166:169], v154 offset:2048
	v_mov_b32_e32 v154, v160
	s_nop 0
	v_xad_u32 v154, v154, 64, 0
	ds_read_b128 v[176:179], v155 offset:32768
	ds_read_b128 v[180:183], v155 offset:34816
	ds_read_b128 v[192:195], v154 offset:32768
	ds_read_b128 v[196:199], v154 offset:34816
	ds_read_b128 v[200:203], v155 offset:36864
	ds_read_b128 v[204:207], v155 offset:38912
	ds_read_b128 v[208:211], v154 offset:36864
	ds_read_b128 v[212:215], v154 offset:38912
	s_waitcnt vmcnt(8)
	s_waitcnt lgkmcnt(0)
	s_setprio 1
	s_barrier
	v_mfma_f32_16x16x32_bf16 v[124:127], v[130:133], v[176:179], v[124:127]
	v_mfma_f32_16x16x32_bf16 v[120:123], v[134:137], v[176:179], v[120:123]
	v_mfma_f32_16x16x32_bf16 v[108:111], v[130:133], v[180:183], v[108:111]
	v_mfma_f32_16x16x32_bf16 v[104:107], v[134:137], v[180:183], v[104:107]
	v_mfma_f32_16x16x32_bf16 v[92:95], v[130:133], v[200:203], v[92:95]
	v_mfma_f32_16x16x32_bf16 v[88:91], v[134:137], v[200:203], v[88:91]
	v_mfma_f32_16x16x32_bf16 v[76:79], v[130:133], v[204:207], v[76:79]
	v_mfma_f32_16x16x32_bf16 v[72:75], v[134:137], v[204:207], v[72:75]
	v_mfma_f32_16x16x32_bf16 v[124:127], v[138:141], v[192:195], v[124:127]
	v_mfma_f32_16x16x32_bf16 v[120:123], v[142:145], v[192:195], v[120:123]
	v_mfma_f32_16x16x32_bf16 v[108:111], v[138:141], v[196:199], v[108:111]
	v_mfma_f32_16x16x32_bf16 v[104:107], v[142:145], v[196:199], v[104:107]
	v_mfma_f32_16x16x32_bf16 v[92:95], v[138:141], v[208:211], v[92:95]
	v_mfma_f32_16x16x32_bf16 v[88:91], v[142:145], v[208:211], v[88:91]
	v_mfma_f32_16x16x32_bf16 v[76:79], v[138:141], v[212:215], v[76:79]
	v_mfma_f32_16x16x32_bf16 v[72:75], v[142:145], v[212:215], v[72:75]
	s_setprio 0
	s_setprio 1
	v_mfma_f32_16x16x32_bf16 v[116:119], v[146:149], v[176:179], v[116:119]
	s_add_u32 s42, s36, 0x80
	s_addc_u32 s43, s37, 0
	v_mfma_f32_16x16x32_bf16 v[112:115], v[150:153], v[176:179], v[112:115]
	v_mfma_f32_16x16x32_bf16 v[100:103], v[146:149], v[180:183], v[100:103]
	v_mfma_f32_16x16x32_bf16 v[96:99], v[150:153], v[180:183], v[96:99]
	v_mfma_f32_16x16x32_bf16 v[84:87], v[146:149], v[200:203], v[84:87]
	v_mfma_f32_16x16x32_bf16 v[80:83], v[150:153], v[200:203], v[80:83]
	v_mfma_f32_16x16x32_bf16 v[68:71], v[146:149], v[204:207], v[68:71]
	v_mfma_f32_16x16x32_bf16 v[64:67], v[150:153], v[204:207], v[64:67]
	v_mfma_f32_16x16x32_bf16 v[116:119], v[162:165], v[192:195], v[116:119]
	v_mfma_f32_16x16x32_bf16 v[112:115], v[166:169], v[192:195], v[112:115]
	v_mfma_f32_16x16x32_bf16 v[100:103], v[162:165], v[196:199], v[100:103]
	v_mfma_f32_16x16x32_bf16 v[96:99], v[166:169], v[196:199], v[96:99]
	v_mfma_f32_16x16x32_bf16 v[84:87], v[162:165], v[208:211], v[84:87]
	v_mfma_f32_16x16x32_bf16 v[80:83], v[166:169], v[208:211], v[80:83]
	v_mfma_f32_16x16x32_bf16 v[68:71], v[162:165], v[212:215], v[68:71]
	v_mfma_f32_16x16x32_bf16 v[64:67], v[166:169], v[212:215], v[64:67]
	s_barrier
; #define PG8_STAGE(bufoff, gbase, voff) do { _Pragma("unroll") for (int _i = 0; _i < 2; ++_i) \
;         dma16((const char*)(gbase), (voff)[_i], ldsb + (bufoff) + ldsw + _i * 8192); } while (0)
; #define PG8_LDA(dst, b, h) do { const int a1_ = opqv(aoff0) ^ 64; _Pragma("unroll") for (int m = 0; m < 4; ++m) { dst[m][0] = *(const LAS bf16x8*)(lds + PG8_SA(b, h) + aoff0 + m * 2048); dst[m][1] = *(const LAS bf16x8*)(lds + PG8_SA(b, h) + a1_ + m * 2048); } } while (0)
; #define PG8_LDB(dst, b, h) do { const int b1_ = opqv(boff0) ^ 64; _Pragma("unroll") for (int n = 0; n < 2; ++n) { dst[n][0] = *(const LAS bf16x8*)(lds + PG8_SB(b, h) + boff0 + n * 2048); dst[n][1] = *(const LAS bf16x8*)(lds + PG8_SB(b, h) + b1_ + n * 2048); } } while (0)
; #define PG8_WAIT_V(n) asm volatile("s_waitcnt vmcnt(" #n ")" ::: "memory")
; template <class Epi>
; __device__ __forceinline__ void gemm_phase(LAS unsigned char* lds, const Gemm g, const StaticOrder& S, const Epi& E, int wave_) {
;     ...
;         for (int t = 0; t < nt; t += 2) {
;             const bool last = (t == nt - 2);
;             const char* a1 = cA + (size_t)(t + 1) * kstep;
;             const char* a2 = last ? nA : cA + (size_t)(t + 2) * kstep; const char* b2 = last ? nB : cB + (size_t)(t + 2) * kstep;
;             const char* a3 = a2 + kstep; const char* b3 = b2 + kstep;
;             PG8_STAGE(PG8_SA(1, 1), a1 + hstepA, voffA); PG8_LDB(B0, 0, 0); PG8_LDB(B1, 0, 1); PG8_SCHED; PG8_LDA(At, 0, 0);
;             PG8_WAIT_V(8); PG8_WAIT_L(0); PG8_BAR; PG8_MMA(0, 0, At, B0); PG8_MMA(0, 1, At, B1); PG8_BAR; PG8_SCHED;
;             PG8_STAGE(PG8_SB(0, 0), b2, voffB); PG8_STAGE(PG8_SB(0, 1), b2 + hstepB, voffB); PG8_STAGE(PG8_SA(0, 0), a2, voffA); PG8_LDA(At, 0, 1);
;             PG8_WAIT_V(8); PG8_WAIT_L(0); PG8_BAR; PG8_MMA(1, 0, At, B0); PG8_MMA(1, 1, At, B1); PG8_BAR; PG8_SCHED;
;             PG8_STAGE(PG8_SA(0, 1), a2 + hstepA, voffA); PG8_LDB(B0, 1, 0); PG8_LDB(B1, 1, 1); PG8_SCHED; PG8_LDA(At, 1, 0);
;             PG8_WAIT_V(8); PG8_WAIT_L(0); PG8_BAR; PG8_MMA(0, 0, At, B0); PG8_MMA(0, 1, At, B1); PG8_BAR; PG8_SCHED;
;             PG8_STAGE(PG8_SB(1, 0), b3, voffB); PG8_STAGE(PG8_SB(1, 1), b3 + hstepB, voffB); PG8_STAGE(PG8_SA(1, 0), a3, voffA); PG8_LDA(At, 1, 1);
;             PG8_WAIT_V(8); PG8_WAIT_L(0); PG8_BAR; PG8_MMA(1, 0, At, B0); PG8_MMA(1, 1, At, B1); PG8_BAR; PG8_SCHED;
	s_setprio 0
	s_add_u32 s36, s36, 0x20080
	s_addc_u32 s37, s37, 0
	v_mov_b32_e32 v154, v160
	s_nop 0
	s_nop 0
	v_xad_u32 v154, v154, 64, 0
	ds_read_b128 v[176:179], v155 offset:49152
	ds_read_b128 v[180:183], v155 offset:51200
	ds_read_b128 v[192:195], v154 offset:49152
	ds_read_b128 v[196:199], v154 offset:51200
	ds_read_b128 v[200:203], v155 offset:53248
	ds_read_b128 v[204:207], v155 offset:55296
	ds_read_b128 v[208:211], v154 offset:53248
	ds_read_b128 v[212:215], v154 offset:55296
	s_mov_b32 m0, s35
	s_nop 0
	global_load_lds_dwordx4 v156, s[42:43]
	s_mov_b32 m0, s33
	s_nop 0
	global_load_lds_dwordx4 v158, s[42:43]
	s_mov_b32 m0, s77
	s_nop 0
	global_load_lds_dwordx4 v156, s[36:37]
	s_mov_b32 m0, s3
	s_nop 0
	global_load_lds_dwordx4 v158, s[36:37]
	s_mov_b32 m0, s22
	s_nop 0
	global_load_lds_dwordx4 v129, s[30:31]
	s_mov_b32 m0, s2
	s_nop 0
	global_load_lds_dwordx4 v157, s[30:31]
	s_waitcnt vmcnt(8)
	s_waitcnt lgkmcnt(0)
	s_setprio 1
	s_barrier
	v_mfma_f32_16x16x32_bf16 v[60:63], v[130:133], v[176:179], v[60:63]
	v_mfma_f32_16x16x32_bf16 v[56:59], v[134:137], v[176:179], v[56:59]
	v_mfma_f32_16x16x32_bf16 v[44:47], v[130:133], v[180:183], v[44:47]
	v_mfma_f32_16x16x32_bf16 v[40:43], v[134:137], v[180:183], v[40:43]
	v_mfma_f32_16x16x32_bf16 v[28:31], v[130:133], v[200:203], v[28:31]
	v_mfma_f32_16x16x32_bf16 v[24:27], v[134:137], v[200:203], v[24:27]
	v_mfma_f32_16x16x32_bf16 v[12:15], v[130:133], v[204:207], v[12:15]
	v_mfma_f32_16x16x32_bf16 v[8:11], v[134:137], v[204:207], v[8:11]
	v_mfma_f32_16x16x32_bf16 v[60:63], v[138:141], v[192:195], v[60:63]
	v_mfma_f32_16x16x32_bf16 v[56:59], v[142:145], v[192:195], v[56:59]
	v_mfma_f32_16x16x32_bf16 v[44:47], v[138:141], v[196:199], v[44:47]
	v_mfma_f32_16x16x32_bf16 v[40:43], v[142:145], v[196:199], v[40:43]
	v_mfma_f32_16x16x32_bf16 v[28:31], v[138:141], v[208:211], v[28:31]
	v_mfma_f32_16x16x32_bf16 v[24:27], v[142:145], v[208:211], v[24:27]
	v_mfma_f32_16x16x32_bf16 v[12:15], v[138:141], v[212:215], v[12:15]
	v_mfma_f32_16x16x32_bf16 v[8:11], v[142:145], v[212:215], v[8:11]
	s_setprio 0
	s_setprio 1
	v_mfma_f32_16x16x32_bf16 v[52:55], v[146:149], v[176:179], v[52:55]
	v_mfma_f32_16x16x32_bf16 v[48:51], v[150:153], v[176:179], v[48:51]
	v_mfma_f32_16x16x32_bf16 v[36:39], v[146:149], v[180:183], v[36:39]
	v_mfma_f32_16x16x32_bf16 v[32:35], v[150:153], v[180:183], v[32:35]
	v_mfma_f32_16x16x32_bf16 v[20:23], v[146:149], v[200:203], v[20:23]
	v_mfma_f32_16x16x32_bf16 v[16:19], v[150:153], v[200:203], v[16:19]
	v_mfma_f32_16x16x32_bf16 v[4:7], v[146:149], v[204:207], v[4:7]
	v_mfma_f32_16x16x32_bf16 v[0:3], v[150:153], v[204:207], v[0:3]
	v_mfma_f32_16x16x32_bf16 v[52:55], v[162:165], v[192:195], v[52:55]
	v_mfma_f32_16x16x32_bf16 v[48:51], v[166:169], v[192:195], v[48:51]
	v_mfma_f32_16x16x32_bf16 v[36:39], v[162:165], v[196:199], v[36:39]
	v_mfma_f32_16x16x32_bf16 v[32:35], v[166:169], v[196:199], v[32:35]
	v_mfma_f32_16x16x32_bf16 v[20:23], v[162:165], v[208:211], v[20:23]
	v_mfma_f32_16x16x32_bf16 v[16:19], v[166:169], v[208:211], v[16:19]
	v_mfma_f32_16x16x32_bf16 v[4:7], v[162:165], v[212:215], v[4:7]
	v_mfma_f32_16x16x32_bf16 v[0:3], v[166:169], v[212:215], v[0:3]
	s_barrier
	s_setprio 0
	s_add_i32 s55, s55, 2
	s_add_u32 s52, s52, 0x100
	s_addc_u32 s54, s54, 0
	s_add_u32 s12, s12, 0x100
	s_addc_u32 s13, s13, 0
	s_cmp_gt_u32 s55, 5
	s_cbranch_scc0 .LBB0_796
	s_branch .Lpeel_exit_5
.LBB0_796:
	s_add_u32 s30, s12, 0xfffc0080
	s_addc_u32 s31, s13, -1
	s_cmp_eq_u32 s55, 4
	s_cselect_b32 s42, s17, s30
	s_cselect_b32 s43, s16, s31
	s_cselect_b32 s36, s19, s52
	s_cselect_b32 s37, s11, s54
	s_add_u32 s30, s42, 0x80
	v_mov_b32_e32 v130, v161
	s_addc_u32 s31, s43, 0
	v_add_u32_e32 v134, s23, v161
	v_xad_u32 v142, v130, 64, s23
	v_mov_b32_e32 v146, v161
	s_add_i32 s56, 0, 0x14000
	ds_read_b128 v[130:133], v134
	ds_read_b128 v[134:137], v134 offset:2048
	ds_read_b128 v[138:141], v142
	ds_read_b128 v[142:145], v142 offset:2048
	v_add_u32_e32 v150, s56, v161
	v_xad_u32 v154, v146, 64, s56
	ds_read_b128 v[146:149], v150
	ds_read_b128 v[150:153], v150 offset:2048
	ds_read_b128 v[162:165], v154
	ds_read_b128 v[166:169], v154 offset:2048
	v_mov_b32_e32 v154, v160
	v_add_u32_e32 v155, 0, v160
	v_xad_u32 v154, v154, 64, 0
	ds_read_b128 v[176:179], v155
	ds_read_b128 v[180:183], v155 offset:2048
	ds_read_b128 v[192:195], v154
	ds_read_b128 v[196:199], v154 offset:2048
	ds_read_b128 v[200:203], v155 offset:4096
	ds_read_b128 v[204:207], v155 offset:6144
	ds_read_b128 v[208:211], v154 offset:4096
	ds_read_b128 v[212:215], v154 offset:6144
	s_mov_b32 m0, s14
	s_nop 0
	global_load_lds_dwordx4 v129, s[12:13]
	s_mov_b32 m0, s15
	s_nop 0
	global_load_lds_dwordx4 v157, s[12:13]
	s_waitcnt vmcnt(8)
	s_waitcnt lgkmcnt(0)
	s_setprio 1
	s_barrier
; #define PG8_STAGE(bufoff, gbase, voff) do { _Pragma("unroll") for (int _i = 0; _i < 2; ++_i) \
;         dma16((const char*)(gbase), (voff)[_i], ldsb + (bufoff) + ldsw + _i * 8192); } while (0)
; #define PG8_LDA(dst, b, h) do { const int a1_ = opqv(aoff0) ^ 64; _Pragma("unroll") for (int m = 0; m < 4; ++m) { dst[m][0] = *(const LAS bf16x8*)(lds + PG8_SA(b, h) + aoff0 + m * 2048); dst[m][1] = *(const LAS bf16x8*)(lds + PG8_SA(b, h) + a1_ + m * 2048); } } while (0)
; #define PG8_MMA(ai, bj, At, Bt) do { __builtin_amdgcn_s_setprio(1); _Pragma("unroll") for (int m = 0; m < 4; ++m) _Pragma("unroll") for (int n = 0; n < 2; ++n) _Pragma("unroll") for (int k = 0; k < 2; ++k) \
;         acc[ai][bj][m][n] = __builtin_amdgcn_mfma_f32_16x16x32_bf16(Bt[n][k], At[m][k], acc[ai][bj][m][n], 0, 0, 0); __builtin_amdgcn_s_setprio(0); } while (0)
; #define PG8_WAIT_V(n) asm volatile("s_waitcnt vmcnt(" #n ")" ::: "memory")
; #define PG8_WAIT_L(n) asm volatile("s_waitcnt lgkmcnt(" #n ")" ::: "memory")
; #define PG8_BAR __builtin_amdgcn_s_barrier()
; #define PG8_SCHED __builtin_amdgcn_sched_barrier(0)
; template <class Epi>
; __device__ __forceinline__ void gemm_phase(LAS unsigned char* lds, const Gemm g, const StaticOrder& S, const Epi& E, int wave_) {
;     ...
;             PG8_WAIT_V(8); PG8_WAIT_L(0); PG8_BAR; PG8_MMA(0, 0, At, B0); PG8_MMA(0, 1, At, B1); PG8_BAR; PG8_SCHED;
;             PG8_STAGE(PG8_SB(0, 0), b2, voffB); PG8_STAGE(PG8_SB(0, 1), b2 + hstepB, voffB); PG8_STAGE(PG8_SA(0, 0), a2, voffA); PG8_LDA(At, 0, 1);
;             PG8_WAIT_V(8); PG8_WAIT_L(0); PG8_BAR; PG8_MMA(1, 0, At, B0); PG8_MMA(1, 1, At, B1); PG8_BAR; PG8_SCHED;
	v_mfma_f32_16x16x32_bf16 v[124:127], v[130:133], v[176:179], v[124:127]
	v_mfma_f32_16x16x32_bf16 v[120:123], v[134:137], v[176:179], v[120:123]
	v_mfma_f32_16x16x32_bf16 v[108:111], v[130:133], v[180:183], v[108:111]
	v_mfma_f32_16x16x32_bf16 v[104:107], v[134:137], v[180:183], v[104:107]
	v_mfma_f32_16x16x32_bf16 v[92:95], v[130:133], v[200:203], v[92:95]
	v_mfma_f32_16x16x32_bf16 v[88:91], v[134:137], v[200:203], v[88:91]
	v_mfma_f32_16x16x32_bf16 v[76:79], v[130:133], v[204:207], v[76:79]
	v_mfma_f32_16x16x32_bf16 v[72:75], v[134:137], v[204:207], v[72:75]
	v_mfma_f32_16x16x32_bf16 v[124:127], v[138:141], v[192:195], v[124:127]
	v_mfma_f32_16x16x32_bf16 v[120:123], v[142:145], v[192:195], v[120:123]
	v_mfma_f32_16x16x32_bf16 v[108:111], v[138:141], v[196:199], v[108:111]
	v_mfma_f32_16x16x32_bf16 v[104:107], v[142:145], v[196:199], v[104:107]
	v_mfma_f32_16x16x32_bf16 v[92:95], v[138:141], v[208:211], v[92:95]
	v_mfma_f32_16x16x32_bf16 v[88:91], v[142:145], v[208:211], v[88:91]
	v_mfma_f32_16x16x32_bf16 v[76:79], v[138:141], v[212:215], v[76:79]
	v_mfma_f32_16x16x32_bf16 v[72:75], v[142:145], v[212:215], v[72:75]
	s_setprio 0
	s_setprio 1
	v_mfma_f32_16x16x32_bf16 v[116:119], v[146:149], v[176:179], v[116:119]
	v_mfma_f32_16x16x32_bf16 v[112:115], v[150:153], v[176:179], v[112:115]
	v_mfma_f32_16x16x32_bf16 v[100:103], v[146:149], v[180:183], v[100:103]
	v_mfma_f32_16x16x32_bf16 v[96:99], v[150:153], v[180:183], v[96:99]
	v_mfma_f32_16x16x32_bf16 v[84:87], v[146:149], v[200:203], v[84:87]
	v_mfma_f32_16x16x32_bf16 v[80:83], v[150:153], v[200:203], v[80:83]
	v_mfma_f32_16x16x32_bf16 v[68:71], v[146:149], v[204:207], v[68:71]
	v_mfma_f32_16x16x32_bf16 v[64:67], v[150:153], v[204:207], v[64:67]
	v_mfma_f32_16x16x32_bf16 v[116:119], v[162:165], v[192:195], v[116:119]
	v_mfma_f32_16x16x32_bf16 v[112:115], v[166:169], v[192:195], v[112:115]
	v_mfma_f32_16x16x32_bf16 v[100:103], v[162:165], v[196:199], v[100:103]
	v_mfma_f32_16x16x32_bf16 v[96:99], v[166:169], v[196:199], v[96:99]
	v_mfma_f32_16x16x32_bf16 v[84:87], v[162:165], v[208:211], v[84:87]
	v_mfma_f32_16x16x32_bf16 v[80:83], v[166:169], v[208:211], v[80:83]
	v_mfma_f32_16x16x32_bf16 v[68:71], v[162:165], v[212:215], v[68:71]
	v_mfma_f32_16x16x32_bf16 v[64:67], v[166:169], v[212:215], v[64:67]
	s_barrier
	s_setprio 0
	v_mov_b32_e32 v154, v160
	s_add_u32 s56, s36, 0x20000
	s_addc_u32 s57, s37, 0
	s_nop 0
	s_nop 0
	s_nop 0
	v_xad_u32 v154, v154, 64, 0
	ds_read_b128 v[176:179], v155 offset:16384
	ds_read_b128 v[180:183], v155 offset:18432
	ds_read_b128 v[192:195], v154 offset:16384
	ds_read_b128 v[196:199], v154 offset:18432
	ds_read_b128 v[200:203], v155 offset:20480
	ds_read_b128 v[204:207], v155 offset:22528
	ds_read_b128 v[208:211], v154 offset:20480
	ds_read_b128 v[212:215], v154 offset:22528
	s_mov_b32 m0, s80
	s_nop 0
	global_load_lds_dwordx4 v156, s[36:37]
	s_mov_b32 m0, s81
	s_nop 0
	global_load_lds_dwordx4 v158, s[36:37]
	s_mov_b32 m0, s29
	s_nop 0
	global_load_lds_dwordx4 v156, s[56:57]
	s_mov_b32 m0, s88
	s_nop 0
	global_load_lds_dwordx4 v158, s[56:57]
	s_mov_b32 m0, s76
	s_nop 0
	global_load_lds_dwordx4 v129, s[42:43]
	s_mov_b32 m0, s89
	s_nop 0
	global_load_lds_dwordx4 v157, s[42:43]
	s_waitcnt vmcnt(8)
	s_waitcnt lgkmcnt(0)
	s_setprio 1
	s_barrier
	v_mfma_f32_16x16x32_bf16 v[60:63], v[130:133], v[176:179], v[60:63]
	v_mfma_f32_16x16x32_bf16 v[56:59], v[134:137], v[176:179], v[56:59]
	v_mfma_f32_16x16x32_bf16 v[44:47], v[130:133], v[180:183], v[44:47]
	v_mfma_f32_16x16x32_bf16 v[40:43], v[134:137], v[180:183], v[40:43]
	v_mfma_f32_16x16x32_bf16 v[28:31], v[130:133], v[200:203], v[28:31]
	v_mfma_f32_16x16x32_bf16 v[24:27], v[134:137], v[200:203], v[24:27]
	v_mfma_f32_16x16x32_bf16 v[12:15], v[130:133], v[204:207], v[12:15]
	v_mfma_f32_16x16x32_bf16 v[8:11], v[134:137], v[204:207], v[8:11]
	v_mfma_f32_16x16x32_bf16 v[60:63], v[138:141], v[192:195], v[60:63]
	v_mfma_f32_16x16x32_bf16 v[56:59], v[142:145], v[192:195], v[56:59]
	v_mfma_f32_16x16x32_bf16 v[44:47], v[138:141], v[196:199], v[44:47]
	v_mfma_f32_16x16x32_bf16 v[40:43], v[142:145], v[196:199], v[40:43]
	v_mfma_f32_16x16x32_bf16 v[28:31], v[138:141], v[208:211], v[28:31]
	v_mfma_f32_16x16x32_bf16 v[24:27], v[142:145], v[208:211], v[24:27]
	v_mfma_f32_16x16x32_bf16 v[12:15], v[138:141], v[212:215], v[12:15]
	v_mfma_f32_16x16x32_bf16 v[8:11], v[142:145], v[212:215], v[8:11]
	s_setprio 0
	s_setprio 1
	v_mfma_f32_16x16x32_bf16 v[52:55], v[146:149], v[176:179], v[52:55]
	v_mfma_f32_16x16x32_bf16 v[48:51], v[150:153], v[176:179], v[48:51]
	v_mfma_f32_16x16x32_bf16 v[36:39], v[146:149], v[180:183], v[36:39]
	v_mfma_f32_16x16x32_bf16 v[32:35], v[150:153], v[180:183], v[32:35]
	v_mfma_f32_16x16x32_bf16 v[20:23], v[146:149], v[200:203], v[20:23]
	v_mfma_f32_16x16x32_bf16 v[16:19], v[150:153], v[200:203], v[16:19]
	v_mfma_f32_16x16x32_bf16 v[4:7], v[146:149], v[204:207], v[4:7]
	v_mfma_f32_16x16x32_bf16 v[0:3], v[150:153], v[204:207], v[0:3]
	v_mfma_f32_16x16x32_bf16 v[52:55], v[162:165], v[192:195], v[52:55]
	v_mfma_f32_16x16x32_bf16 v[48:51], v[166:169], v[192:195], v[48:51]
	v_mfma_f32_16x16x32_bf16 v[36:39], v[162:165], v[196:199], v[36:39]
	v_mfma_f32_16x16x32_bf16 v[32:35], v[166:169], v[196:199], v[32:35]
	v_mfma_f32_16x16x32_bf16 v[20:23], v[162:165], v[208:211], v[20:23]
	v_mfma_f32_16x16x32_bf16 v[16:19], v[166:169], v[208:211], v[16:19]
	v_mfma_f32_16x16x32_bf16 v[4:7], v[162:165], v[212:215], v[4:7]
	v_mfma_f32_16x16x32_bf16 v[0:3], v[166:169], v[212:215], v[0:3]
	s_barrier
; #define PG8_STAGE(bufoff, gbase, voff) do { _Pragma("unroll") for (int _i = 0; _i < 2; ++_i) \
;         dma16((const char*)(gbase), (voff)[_i], ldsb + (bufoff) + ldsw + _i * 8192); } while (0)
; #define PG8_LDA(dst, b, h) do { const int a1_ = opqv(aoff0) ^ 64; _Pragma("unroll") for (int m = 0; m < 4; ++m) { dst[m][0] = *(const LAS bf16x8*)(lds + PG8_SA(b, h) + aoff0 + m * 2048); dst[m][1] = *(const LAS bf16x8*)(lds + PG8_SA(b, h) + a1_ + m * 2048); } } while (0)
; #define PG8_LDB(dst, b, h) do { const int b1_ = opqv(boff0) ^ 64; _Pragma("unroll") for (int n = 0; n < 2; ++n) { dst[n][0] = *(const LAS bf16x8*)(lds + PG8_SB(b, h) + boff0 + n * 2048); dst[n][1] = *(const LAS bf16x8*)(lds + PG8_SB(b, h) + b1_ + n * 2048); } } while (0)
; #define PG8_MMA(ai, bj, At, Bt) do { __builtin_amdgcn_s_setprio(1); _Pragma("unroll") for (int m = 0; m < 4; ++m) _Pragma("unroll") for (int n = 0; n < 2; ++n) _Pragma("unroll") for (int k = 0; k < 2; ++k) \
;         acc[ai][bj][m][n] = __builtin_amdgcn_mfma_f32_16x16x32_bf16(Bt[n][k], At[m][k], acc[ai][bj][m][n], 0, 0, 0); __builtin_amdgcn_s_setprio(0); } while (0)
; #define PG8_WAIT_V(n) asm volatile("s_waitcnt vmcnt(" #n ")" ::: "memory")
; #define PG8_WAIT_L(n) asm volatile("s_waitcnt lgkmcnt(" #n ")" ::: "memory")
; #define PG8_BAR __builtin_amdgcn_s_barrier()
; #define PG8_SCHED __builtin_amdgcn_sched_barrier(0)
; template <class Epi>
; __device__ __forceinline__ void gemm_phase(LAS unsigned char* lds, const Gemm g, const StaticOrder& S, const Epi& E, int wave_) {
;     ...
;             PG8_STAGE(PG8_SA(0, 1), a2 + hstepA, voffA); PG8_LDB(B0, 1, 0); PG8_LDB(B1, 1, 1); PG8_SCHED; PG8_LDA(At, 1, 0);
;             PG8_WAIT_V(8); PG8_WAIT_L(0); PG8_BAR; PG8_MMA(0, 0, At, B0); PG8_MMA(0, 1, At, B1); PG8_BAR; PG8_SCHED;
;             PG8_STAGE(PG8_SB(1, 0), b3, voffB); PG8_STAGE(PG8_SB(1, 1), b3 + hstepB, voffB); PG8_STAGE(PG8_SA(1, 0), a3, voffA); PG8_LDA(At, 1, 1);
;             PG8_WAIT_V(8); PG8_WAIT_L(0); PG8_BAR; PG8_MMA(1, 0, At, B0); PG8_MMA(1, 1, At, B1); PG8_BAR; PG8_SCHED;
;         }
	s_setprio 0
	s_add_u32 s42, s42, 0x40000
	s_addc_u32 s43, s43, 0
	s_mov_b32 m0, s1
	s_nop 0
	global_load_lds_dwordx4 v129, s[42:43]
	v_mov_b32_e32 v130, v161
	s_mov_b32 m0, s69
	s_nop 0
	global_load_lds_dwordx4 v157, s[42:43]
	v_add_u32_e32 v134, s34, v161
	v_xad_u32 v142, v130, 64, s34
	v_mov_b32_e32 v146, v161
	s_add_i32 s42, 0, 0x1c000
	ds_read_b128 v[130:133], v134
	ds_read_b128 v[134:137], v134 offset:2048
	ds_read_b128 v[138:141], v142
	ds_read_b128 v[142:145], v142 offset:2048
	v_add_u32_e32 v150, s42, v161
	v_xad_u32 v154, v146, 64, s42
	ds_read_b128 v[146:149], v150
	ds_read_b128 v[150:153], v150 offset:2048
	ds_read_b128 v[162:165], v154
	ds_read_b128 v[166:169], v154 offset:2048
	v_mov_b32_e32 v154, v160
	s_nop 0
	v_xad_u32 v154, v154, 64, 0
	ds_read_b128 v[176:179], v155 offset:32768
	ds_read_b128 v[180:183], v155 offset:34816
	ds_read_b128 v[192:195], v154 offset:32768
	ds_read_b128 v[196:199], v154 offset:34816
	ds_read_b128 v[200:203], v155 offset:36864
	ds_read_b128 v[204:207], v155 offset:38912
	ds_read_b128 v[208:211], v154 offset:36864
	ds_read_b128 v[212:215], v154 offset:38912
	s_waitcnt vmcnt(8)
	s_waitcnt lgkmcnt(0)
	s_setprio 1
	s_barrier
	v_mfma_f32_16x16x32_bf16 v[124:127], v[130:133], v[176:179], v[124:127]
	v_mfma_f32_16x16x32_bf16 v[120:123], v[134:137], v[176:179], v[120:123]
	v_mfma_f32_16x16x32_bf16 v[108:111], v[130:133], v[180:183], v[108:111]
	v_mfma_f32_16x16x32_bf16 v[104:107], v[134:137], v[180:183], v[104:107]
	v_mfma_f32_16x16x32_bf16 v[92:95], v[130:133], v[200:203], v[92:95]
	v_mfma_f32_16x16x32_bf16 v[88:91], v[134:137], v[200:203], v[88:91]
	v_mfma_f32_16x16x32_bf16 v[76:79], v[130:133], v[204:207], v[76:79]
	v_mfma_f32_16x16x32_bf16 v[72:75], v[134:137], v[204:207], v[72:75]
	v_mfma_f32_16x16x32_bf16 v[124:127], v[138:141], v[192:195], v[124:127]
	v_mfma_f32_16x16x32_bf16 v[120:123], v[142:145], v[192:195], v[120:123]
	v_mfma_f32_16x16x32_bf16 v[108:111], v[138:141], v[196:199], v[108:111]
	v_mfma_f32_16x16x32_bf16 v[104:107], v[142:145], v[196:199], v[104:107]
	v_mfma_f32_16x16x32_bf16 v[92:95], v[138:141], v[208:211], v[92:95]
	v_mfma_f32_16x16x32_bf16 v[88:91], v[142:145], v[208:211], v[88:91]
	v_mfma_f32_16x16x32_bf16 v[76:79], v[138:141], v[212:215], v[76:79]
	v_mfma_f32_16x16x32_bf16 v[72:75], v[142:145], v[212:215], v[72:75]
	s_setprio 0
	s_setprio 1
	v_mfma_f32_16x16x32_bf16 v[116:119], v[146:149], v[176:179], v[116:119]
	s_add_u32 s42, s36, 0x80
	s_addc_u32 s43, s37, 0
	v_mfma_f32_16x16x32_bf16 v[112:115], v[150:153], v[176:179], v[112:115]
	v_mfma_f32_16x16x32_bf16 v[100:103], v[146:149], v[180:183], v[100:103]
	v_mfma_f32_16x16x32_bf16 v[96:99], v[150:153], v[180:183], v[96:99]
	v_mfma_f32_16x16x32_bf16 v[84:87], v[146:149], v[200:203], v[84:87]
	v_mfma_f32_16x16x32_bf16 v[80:83], v[150:153], v[200:203], v[80:83]
	v_mfma_f32_16x16x32_bf16 v[68:71], v[146:149], v[204:207], v[68:71]
	v_mfma_f32_16x16x32_bf16 v[64:67], v[150:153], v[204:207], v[64:67]
	v_mfma_f32_16x16x32_bf16 v[116:119], v[162:165], v[192:195], v[116:119]
	v_mfma_f32_16x16x32_bf16 v[112:115], v[166:169], v[192:195], v[112:115]
	v_mfma_f32_16x16x32_bf16 v[100:103], v[162:165], v[196:199], v[100:103]
	v_mfma_f32_16x16x32_bf16 v[96:99], v[166:169], v[196:199], v[96:99]
	v_mfma_f32_16x16x32_bf16 v[84:87], v[162:165], v[208:211], v[84:87]
	v_mfma_f32_16x16x32_bf16 v[80:83], v[166:169], v[208:211], v[80:83]
	v_mfma_f32_16x16x32_bf16 v[68:71], v[162:165], v[212:215], v[68:71]
	v_mfma_f32_16x16x32_bf16 v[64:67], v[166:169], v[212:215], v[64:67]
	s_barrier
	s_setprio 0
	s_add_u32 s36, s36, 0x20080
	s_addc_u32 s37, s37, 0
	v_mov_b32_e32 v154, v160
	s_nop 0
	s_nop 0
	v_xad_u32 v154, v154, 64, 0
	ds_read_b128 v[176:179], v155 offset:49152
	ds_read_b128 v[180:183], v155 offset:51200
	ds_read_b128 v[192:195], v154 offset:49152
	ds_read_b128 v[196:199], v154 offset:51200
	ds_read_b128 v[200:203], v155 offset:53248
	ds_read_b128 v[204:207], v155 offset:55296
	ds_read_b128 v[208:211], v154 offset:53248
	ds_read_b128 v[212:215], v154 offset:55296
	s_mov_b32 m0, s35
	s_nop 0
	global_load_lds_dwordx4 v156, s[42:43]
	s_mov_b32 m0, s33
	s_nop 0
	global_load_lds_dwordx4 v158, s[42:43]
	s_mov_b32 m0, s77
	s_nop 0
	global_load_lds_dwordx4 v156, s[36:37]
	s_mov_b32 m0, s3
	s_nop 0
	global_load_lds_dwordx4 v158, s[36:37]
	s_mov_b32 m0, s22
	s_nop 0
	global_load_lds_dwordx4 v129, s[30:31]
	s_mov_b32 m0, s2
	s_nop 0
	global_load_lds_dwordx4 v157, s[30:31]
	s_waitcnt vmcnt(8)
	s_waitcnt lgkmcnt(0)
	s_setprio 1
	s_barrier
	v_mfma_f32_16x16x32_bf16 v[60:63], v[130:133], v[176:179], v[60:63]
	v_mfma_f32_16x16x32_bf16 v[56:59], v[134:137], v[176:179], v[56:59]
	v_mfma_f32_16x16x32_bf16 v[44:47], v[130:133], v[180:183], v[44:47]
	v_mfma_f32_16x16x32_bf16 v[40:43], v[134:137], v[180:183], v[40:43]
	v_mfma_f32_16x16x32_bf16 v[28:31], v[130:133], v[200:203], v[28:31]
	v_mfma_f32_16x16x32_bf16 v[24:27], v[134:137], v[200:203], v[24:27]
	v_mfma_f32_16x16x32_bf16 v[12:15], v[130:133], v[204:207], v[12:15]
	v_mfma_f32_16x16x32_bf16 v[8:11], v[134:137], v[204:207], v[8:11]
	v_mfma_f32_16x16x32_bf16 v[60:63], v[138:141], v[192:195], v[60:63]
	v_mfma_f32_16x16x32_bf16 v[56:59], v[142:145], v[192:195], v[56:59]
	v_mfma_f32_16x16x32_bf16 v[44:47], v[138:141], v[196:199], v[44:47]
	v_mfma_f32_16x16x32_bf16 v[40:43], v[142:145], v[196:199], v[40:43]
	v_mfma_f32_16x16x32_bf16 v[28:31], v[138:141], v[208:211], v[28:31]
	v_mfma_f32_16x16x32_bf16 v[24:27], v[142:145], v[208:211], v[24:27]
	v_mfma_f32_16x16x32_bf16 v[12:15], v[138:141], v[212:215], v[12:15]
	v_mfma_f32_16x16x32_bf16 v[8:11], v[142:145], v[212:215], v[8:11]
	s_setprio 0
	s_setprio 1
	v_mfma_f32_16x16x32_bf16 v[52:55], v[146:149], v[176:179], v[52:55]
	v_mfma_f32_16x16x32_bf16 v[48:51], v[150:153], v[176:179], v[48:51]
	v_mfma_f32_16x16x32_bf16 v[36:39], v[146:149], v[180:183], v[36:39]
	v_mfma_f32_16x16x32_bf16 v[32:35], v[150:153], v[180:183], v[32:35]
	v_mfma_f32_16x16x32_bf16 v[20:23], v[146:149], v[200:203], v[20:23]
	v_mfma_f32_16x16x32_bf16 v[16:19], v[150:153], v[200:203], v[16:19]
	v_mfma_f32_16x16x32_bf16 v[4:7], v[146:149], v[204:207], v[4:7]
	v_mfma_f32_16x16x32_bf16 v[0:3], v[150:153], v[204:207], v[0:3]
	v_mfma_f32_16x16x32_bf16 v[52:55], v[162:165], v[192:195], v[52:55]
	v_mfma_f32_16x16x32_bf16 v[48:51], v[166:169], v[192:195], v[48:51]
	v_mfma_f32_16x16x32_bf16 v[36:39], v[162:165], v[196:199], v[36:39]
	v_mfma_f32_16x16x32_bf16 v[32:35], v[166:169], v[196:199], v[32:35]
	v_mfma_f32_16x16x32_bf16 v[20:23], v[162:165], v[208:211], v[20:23]
	v_mfma_f32_16x16x32_bf16 v[16:19], v[166:169], v[208:211], v[16:19]
	v_mfma_f32_16x16x32_bf16 v[4:7], v[162:165], v[212:215], v[4:7]
	v_mfma_f32_16x16x32_bf16 v[0:3], v[166:169], v[212:215], v[0:3]
	s_barrier
	s_setprio 0
	s_add_i32 s55, s55, 2
	s_add_u32 s52, s52, 0x100
	s_addc_u32 s54, s54, 0
	s_add_u32 s12, s12, 0x100
	s_addc_u32 s13, s13, 0
	s_cmp_gt_u32 s55, 5
	s_cbranch_scc0 .LBB0_796

; #define PG8_STAGE(bufoff, gbase, voff) do { _Pragma("unroll") for (int _i = 0; _i < 2; ++_i) \
;         dma16((const char*)(gbase), (voff)[_i], ldsb + (bufoff) + ldsw + _i * 8192); } while (0)
; #define PG8_LDA(dst, b, h) do { const int a1_ = opqv(aoff0) ^ 64; _Pragma("unroll") for (int m = 0; m < 4; ++m) { dst[m][0] = *(const LAS bf16x8*)(lds + PG8_SA(b, h) + aoff0 + m * 2048); dst[m][1] = *(const LAS bf16x8*)(lds + PG8_SA(b, h) + a1_ + m * 2048); } } while (0)
; #define PG8_LDB(dst, b, h) do { const int b1_ = opqv(boff0) ^ 64; _Pragma("unroll") for (int n = 0; n < 2; ++n) { dst[n][0] = *(const LAS bf16x8*)(lds + PG8_SB(b, h) + boff0 + n * 2048); dst[n][1] = *(const LAS bf16x8*)(lds + PG8_SB(b, h) + b1_ + n * 2048); } } while (0)
; #define PG8_MMA(ai, bj, At, Bt) do { __builtin_amdgcn_s_setprio(1); _Pragma("unroll") for (int m = 0; m < 4; ++m) _Pragma("unroll") for (int n = 0; n < 2; ++n) _Pragma("unroll") for (int k = 0; k < 2; ++k) \
;         acc[ai][bj][m][n] = __builtin_amdgcn_mfma_f32_16x16x32_bf16(Bt[n][k], At[m][k], acc[ai][bj][m][n], 0, 0, 0); __builtin_amdgcn_s_setprio(0); } while (0)
; template <class Epi>
; __device__ __forceinline__ void gemm_phase(LAS unsigned char* lds, const Gemm g, const StaticOrder& S, const Epi& E, int wave_) {
;     ...
;         const bool has_next = S.next(ui + 1, nxt);
;         const char* nA = has_next ? (const char*)g.A + (size_t)nxt.pm * tstepA : cA; const char* nB = has_next ? (const char*)g.Bt + (size_t)nxt.pn * tstepB : cB;
; #pragma unroll 1
;         for (int t = 0; t < nt; t += 2) {
;             const bool last = (t == nt - 2);
;             const char* a1 = cA + (size_t)(t + 1) * kstep;
;             const char* a2 = last ? nA : cA + (size_t)(t + 2) * kstep; const char* b2 = last ? nB : cB + (size_t)(t + 2) * kstep;
;             const char* a3 = a2 + kstep; const char* b3 = b2 + kstep;
;             PG8_STAGE(PG8_SA(1, 1), a1 + hstepA, voffA); PG8_LDB(B0, 0, 0); PG8_LDB(B1, 0, 1); PG8_SCHED; PG8_LDA(At, 0, 0);
;             PG8_WAIT_V(8); PG8_WAIT_L(0); PG8_BAR; PG8_MMA(0, 0, At, B0); PG8_MMA(0, 1, At, B1); PG8_BAR; PG8_SCHED;
;             PG8_STAGE(PG8_SB(0, 0), b2, voffB); PG8_STAGE(PG8_SB(0, 1), b2 + hstepB, voffB); PG8_STAGE(PG8_SA(0, 0), a2, voffA); PG8_LDA(At, 0, 1);
;             PG8_WAIT_V(8); PG8_WAIT_L(0); PG8_BAR; PG8_MMA(1, 0, At, B0); PG8_MMA(1, 1, At, B1); PG8_BAR; PG8_SCHED;
.LBB0_1103:
	s_ashr_i32 s19, s18, 31
	s_lshl_b64 s[16:17], s[18:19], 20
	s_add_u32 s24, s21, s16
	s_addc_u32 s25, s46, s17
	s_and_b64 s[16:17], s[44:45], exec
	s_cselect_b32 s16, s25, s31
	s_cselect_b32 s17, s24, s30
	s_ashr_i32 s11, s10, 31
	s_lshl_b64 s[26:27], s[10:11], 20
	s_add_u32 s26, s47, s26
	s_addc_u32 s27, s48, s27
	s_and_b64 s[36:37], s[44:45], exec
	s_cselect_b32 s11, s27, s13
	s_cselect_b32 s19, s26, s12
	s_add_u32 s55, s12, 0x100
	s_addc_u32 s56, s13, 0
	s_add_u32 s12, s30, 0x80080
	s_addc_u32 s13, s31, 0
	s_mov_b32 s57, -2
	s_add_u32 s30, s12, 0xfff80080
	s_addc_u32 s31, s13, -1
	s_cmp_eq_u32 s57, 28
	s_cselect_b32 s40, s17, s30
	s_cselect_b32 s41, s16, s31
	s_cselect_b32 s36, s19, s55
	s_cselect_b32 s37, s11, s56
	s_add_u32 s30, s40, 0x80
	v_mov_b32_e32 v128, v172
	s_addc_u32 s31, s41, 0
	v_add_u32_e32 v132, s23, v172
	v_xad_u32 v140, v128, 64, s23
	v_mov_b32_e32 v144, v172
	s_add_i32 s60, 0, 0x14000
	ds_read_b128 v[128:131], v132
	ds_read_b128 v[132:135], v132 offset:2048
	ds_read_b128 v[136:139], v140
	ds_read_b128 v[140:143], v140 offset:2048
	v_add_u32_e32 v148, s60, v172
	v_xad_u32 v156, v144, 64, s60
	ds_read_b128 v[144:147], v148
	ds_read_b128 v[148:151], v148 offset:2048
	ds_read_b128 v[152:155], v156
	ds_read_b128 v[156:159], v156 offset:2048
	v_mov_b32_e32 v160, v171
	v_add_u32_e32 v183, 0, v171
	v_xad_u32 v182, v160, 64, 0
	ds_read_b128 v[160:163], v183
	ds_read_b128 v[174:177], v183 offset:2048
	ds_read_b128 v[178:181], v182
	ds_read_b128 v[192:195], v182 offset:2048
	ds_read_b128 v[196:199], v183 offset:4096
	ds_read_b128 v[200:203], v183 offset:6144
	ds_read_b128 v[204:207], v182 offset:4096
	ds_read_b128 v[208:211], v182 offset:6144
	s_mov_b32 m0, s14
	s_nop 0
	global_load_lds_dwordx4 v166, s[12:13]
	s_mov_b32 m0, s15
	s_nop 0
	global_load_lds_dwordx4 v168, s[12:13]
	s_waitcnt vmcnt(8)
	s_waitcnt lgkmcnt(0)
	s_setprio 1
	s_barrier
	v_mfma_f32_16x16x32_bf16 v[124:127], v[128:131], v[160:163], 0
	v_mfma_f32_16x16x32_bf16 v[120:123], v[132:135], v[160:163], 0
	v_mfma_f32_16x16x32_bf16 v[108:111], v[128:131], v[174:177], 0
	v_mfma_f32_16x16x32_bf16 v[104:107], v[132:135], v[174:177], 0
	v_mfma_f32_16x16x32_bf16 v[92:95], v[128:131], v[196:199], 0
	v_mfma_f32_16x16x32_bf16 v[88:91], v[132:135], v[196:199], 0
	v_mfma_f32_16x16x32_bf16 v[76:79], v[128:131], v[200:203], 0
	v_mfma_f32_16x16x32_bf16 v[72:75], v[132:135], v[200:203], 0
	v_mfma_f32_16x16x32_bf16 v[124:127], v[136:139], v[178:181], v[124:127]
	v_mfma_f32_16x16x32_bf16 v[120:123], v[140:143], v[178:181], v[120:123]
	v_mfma_f32_16x16x32_bf16 v[108:111], v[136:139], v[192:195], v[108:111]
	v_mfma_f32_16x16x32_bf16 v[104:107], v[140:143], v[192:195], v[104:107]
	v_mfma_f32_16x16x32_bf16 v[92:95], v[136:139], v[204:207], v[92:95]
	v_mfma_f32_16x16x32_bf16 v[88:91], v[140:143], v[204:207], v[88:91]
	v_mfma_f32_16x16x32_bf16 v[76:79], v[136:139], v[208:211], v[76:79]
	v_mfma_f32_16x16x32_bf16 v[72:75], v[140:143], v[208:211], v[72:75]
	s_setprio 0
	s_setprio 1
	v_mfma_f32_16x16x32_bf16 v[116:119], v[144:147], v[160:163], 0
	v_mfma_f32_16x16x32_bf16 v[112:115], v[148:151], v[160:163], 0
	v_mfma_f32_16x16x32_bf16 v[100:103], v[144:147], v[174:177], 0
	v_mfma_f32_16x16x32_bf16 v[96:99], v[148:151], v[174:177], 0
	v_mfma_f32_16x16x32_bf16 v[84:87], v[144:147], v[196:199], 0
	v_mfma_f32_16x16x32_bf16 v[80:83], v[148:151], v[196:199], 0
	v_mfma_f32_16x16x32_bf16 v[68:71], v[144:147], v[200:203], 0
	v_mfma_f32_16x16x32_bf16 v[64:67], v[148:151], v[200:203], 0
	v_mfma_f32_16x16x32_bf16 v[116:119], v[152:155], v[178:181], v[116:119]
	v_mfma_f32_16x16x32_bf16 v[112:115], v[156:159], v[178:181], v[112:115]
	v_mfma_f32_16x16x32_bf16 v[100:103], v[152:155], v[192:195], v[100:103]
	v_mfma_f32_16x16x32_bf16 v[96:99], v[156:159], v[192:195], v[96:99]
	v_mfma_f32_16x16x32_bf16 v[84:87], v[152:155], v[204:207], v[84:87]
	v_mfma_f32_16x16x32_bf16 v[80:83], v[156:159], v[204:207], v[80:83]
	v_mfma_f32_16x16x32_bf16 v[68:71], v[152:155], v[208:211], v[68:71]
	v_mfma_f32_16x16x32_bf16 v[64:67], v[156:159], v[208:211], v[64:67]
	s_barrier
	s_setprio 0
	v_mov_b32_e32 v160, v171
	s_add_u32 s60, s36, 0x80000
	s_addc_u32 s61, s37, 0
	s_nop 0
	s_nop 0
	s_nop 0
	v_xad_u32 v182, v160, 64, 0
	ds_read_b128 v[160:163], v183 offset:16384
	ds_read_b128 v[174:177], v183 offset:18432
	ds_read_b128 v[178:181], v182 offset:16384
	ds_read_b128 v[192:195], v182 offset:18432
	ds_read_b128 v[196:199], v183 offset:20480
	ds_read_b128 v[200:203], v183 offset:22528
	ds_read_b128 v[204:207], v182 offset:20480
	ds_read_b128 v[208:211], v182 offset:22528
	s_mov_b32 m0, s80
	s_nop 0
	global_load_lds_dwordx4 v167, s[36:37]
	s_mov_b32 m0, s81
	s_nop 0
	global_load_lds_dwordx4 v169, s[36:37]
	s_mov_b32 m0, s29
	s_nop 0
	global_load_lds_dwordx4 v167, s[60:61]
	s_mov_b32 m0, s88
	s_nop 0
	global_load_lds_dwordx4 v169, s[60:61]
	s_mov_b32 m0, s76
	s_nop 0
	global_load_lds_dwordx4 v166, s[40:41]
	s_mov_b32 m0, s89
	s_nop 0
	global_load_lds_dwordx4 v168, s[40:41]
	s_waitcnt vmcnt(8)
	s_waitcnt lgkmcnt(0)
	s_setprio 1
	s_barrier
; #define PG8_STAGE(bufoff, gbase, voff) do { _Pragma("unroll") for (int _i = 0; _i < 2; ++_i) \
;         dma16((const char*)(gbase), (voff)[_i], ldsb + (bufoff) + ldsw + _i * 8192); } while (0)
; #define PG8_LDA(dst, b, h) do { const int a1_ = opqv(aoff0) ^ 64; _Pragma("unroll") for (int m = 0; m < 4; ++m) { dst[m][0] = *(const LAS bf16x8*)(lds + PG8_SA(b, h) + aoff0 + m * 2048); dst[m][1] = *(const LAS bf16x8*)(lds + PG8_SA(b, h) + a1_ + m * 2048); } } while (0)
; #define PG8_LDB(dst, b, h) do { const int b1_ = opqv(boff0) ^ 64; _Pragma("unroll") for (int n = 0; n < 2; ++n) { dst[n][0] = *(const LAS bf16x8*)(lds + PG8_SB(b, h) + boff0 + n * 2048); dst[n][1] = *(const LAS bf16x8*)(lds + PG8_SB(b, h) + b1_ + n * 2048); } } while (0)
; #define PG8_MMA(ai, bj, At, Bt) do { __builtin_amdgcn_s_setprio(1); _Pragma("unroll") for (int m = 0; m < 4; ++m) _Pragma("unroll") for (int n = 0; n < 2; ++n) _Pragma("unroll") for (int k = 0; k < 2; ++k) \
;         acc[ai][bj][m][n] = __builtin_amdgcn_mfma_f32_16x16x32_bf16(Bt[n][k], At[m][k], acc[ai][bj][m][n], 0, 0, 0); __builtin_amdgcn_s_setprio(0); } while (0)
; #define PG8_WAIT_V(n) asm volatile("s_waitcnt vmcnt(" #n ")" ::: "memory")
; #define PG8_WAIT_L(n) asm volatile("s_waitcnt lgkmcnt(" #n ")" ::: "memory")
; #define PG8_BAR __builtin_amdgcn_s_barrier()
; #define PG8_SCHED __builtin_amdgcn_sched_barrier(0)
; template <class Epi>
; __device__ __forceinline__ void gemm_phase(LAS unsigned char* lds, const Gemm g, const StaticOrder& S, const Epi& E, int wave_) {
;     ...
;             PG8_WAIT_V(8); PG8_WAIT_L(0); PG8_BAR; PG8_MMA(1, 0, At, B0); PG8_MMA(1, 1, At, B1); PG8_BAR; PG8_SCHED;
;             PG8_STAGE(PG8_SA(0, 1), a2 + hstepA, voffA); PG8_LDB(B0, 1, 0); PG8_LDB(B1, 1, 1); PG8_SCHED; PG8_LDA(At, 1, 0);
;             PG8_WAIT_V(8); PG8_WAIT_L(0); PG8_BAR; PG8_MMA(0, 0, At, B0); PG8_MMA(0, 1, At, B1); PG8_BAR; PG8_SCHED;
	v_mfma_f32_16x16x32_bf16 v[60:63], v[128:131], v[160:163], 0
	v_mfma_f32_16x16x32_bf16 v[56:59], v[132:135], v[160:163], 0
	v_mfma_f32_16x16x32_bf16 v[44:47], v[128:131], v[174:177], 0
	v_mfma_f32_16x16x32_bf16 v[40:43], v[132:135], v[174:177], 0
	v_mfma_f32_16x16x32_bf16 v[28:31], v[128:131], v[196:199], 0
	v_mfma_f32_16x16x32_bf16 v[24:27], v[132:135], v[196:199], 0
	v_mfma_f32_16x16x32_bf16 v[12:15], v[128:131], v[200:203], 0
	v_mfma_f32_16x16x32_bf16 v[8:11], v[132:135], v[200:203], 0
	v_mfma_f32_16x16x32_bf16 v[60:63], v[136:139], v[178:181], v[60:63]
	v_mfma_f32_16x16x32_bf16 v[56:59], v[140:143], v[178:181], v[56:59]
	v_mfma_f32_16x16x32_bf16 v[44:47], v[136:139], v[192:195], v[44:47]
	v_mfma_f32_16x16x32_bf16 v[40:43], v[140:143], v[192:195], v[40:43]
	v_mfma_f32_16x16x32_bf16 v[28:31], v[136:139], v[204:207], v[28:31]
	v_mfma_f32_16x16x32_bf16 v[24:27], v[140:143], v[204:207], v[24:27]
	v_mfma_f32_16x16x32_bf16 v[12:15], v[136:139], v[208:211], v[12:15]
	v_mfma_f32_16x16x32_bf16 v[8:11], v[140:143], v[208:211], v[8:11]
	s_setprio 0
	s_setprio 1
	v_mfma_f32_16x16x32_bf16 v[52:55], v[144:147], v[160:163], 0
	v_mfma_f32_16x16x32_bf16 v[48:51], v[148:151], v[160:163], 0
	v_mfma_f32_16x16x32_bf16 v[36:39], v[144:147], v[174:177], 0
	v_mfma_f32_16x16x32_bf16 v[32:35], v[148:151], v[174:177], 0
	v_mfma_f32_16x16x32_bf16 v[20:23], v[144:147], v[196:199], 0
	v_mfma_f32_16x16x32_bf16 v[16:19], v[148:151], v[196:199], 0
	v_mfma_f32_16x16x32_bf16 v[4:7], v[144:147], v[200:203], 0
	v_mfma_f32_16x16x32_bf16 v[0:3], v[148:151], v[200:203], 0
	v_mfma_f32_16x16x32_bf16 v[52:55], v[152:155], v[178:181], v[52:55]
	v_mfma_f32_16x16x32_bf16 v[48:51], v[156:159], v[178:181], v[48:51]
	v_mfma_f32_16x16x32_bf16 v[36:39], v[152:155], v[192:195], v[36:39]
	v_mfma_f32_16x16x32_bf16 v[32:35], v[156:159], v[192:195], v[32:35]
	v_mfma_f32_16x16x32_bf16 v[20:23], v[152:155], v[204:207], v[20:23]
	v_mfma_f32_16x16x32_bf16 v[16:19], v[156:159], v[204:207], v[16:19]
	v_mfma_f32_16x16x32_bf16 v[4:7], v[152:155], v[208:211], v[4:7]
	v_mfma_f32_16x16x32_bf16 v[0:3], v[156:159], v[208:211], v[0:3]
	s_barrier
	s_setprio 0
	s_add_u32 s40, s40, 0x80000
	s_addc_u32 s41, s41, 0
	s_mov_b32 m0, s1
	s_nop 0
	global_load_lds_dwordx4 v166, s[40:41]
	v_mov_b32_e32 v128, v172
	s_mov_b32 m0, s69
	s_nop 0
	global_load_lds_dwordx4 v168, s[40:41]
	v_add_u32_e32 v132, s34, v172
	v_xad_u32 v140, v128, 64, s34
	v_mov_b32_e32 v144, v172
	s_add_i32 s40, 0, 0x1c000
	ds_read_b128 v[128:131], v132
	ds_read_b128 v[132:135], v132 offset:2048
	ds_read_b128 v[136:139], v140
	ds_read_b128 v[140:143], v140 offset:2048
	v_add_u32_e32 v148, s40, v172
	v_xad_u32 v156, v144, 64, s40
	ds_read_b128 v[144:147], v148
	ds_read_b128 v[148:151], v148 offset:2048
	ds_read_b128 v[152:155], v156
	ds_read_b128 v[156:159], v156 offset:2048
	v_mov_b32_e32 v160, v171
	s_nop 0
	v_xad_u32 v182, v160, 64, 0
	ds_read_b128 v[160:163], v183 offset:32768
	ds_read_b128 v[174:177], v183 offset:34816
	ds_read_b128 v[178:181], v182 offset:32768
	ds_read_b128 v[192:195], v182 offset:34816
	ds_read_b128 v[196:199], v183 offset:36864
	ds_read_b128 v[200:203], v183 offset:38912
	ds_read_b128 v[204:207], v182 offset:36864
	ds_read_b128 v[208:211], v182 offset:38912
	s_waitcnt vmcnt(8)
	s_waitcnt lgkmcnt(0)
	s_setprio 1
	s_barrier
	v_mfma_f32_16x16x32_bf16 v[124:127], v[128:131], v[160:163], v[124:127]
	v_mfma_f32_16x16x32_bf16 v[120:123], v[132:135], v[160:163], v[120:123]
	v_mfma_f32_16x16x32_bf16 v[108:111], v[128:131], v[174:177], v[108:111]
	v_mfma_f32_16x16x32_bf16 v[104:107], v[132:135], v[174:177], v[104:107]
	v_mfma_f32_16x16x32_bf16 v[92:95], v[128:131], v[196:199], v[92:95]
	v_mfma_f32_16x16x32_bf16 v[88:91], v[132:135], v[196:199], v[88:91]
	v_mfma_f32_16x16x32_bf16 v[76:79], v[128:131], v[200:203], v[76:79]
	v_mfma_f32_16x16x32_bf16 v[72:75], v[132:135], v[200:203], v[72:75]
	v_mfma_f32_16x16x32_bf16 v[124:127], v[136:139], v[178:181], v[124:127]
	v_mfma_f32_16x16x32_bf16 v[120:123], v[140:143], v[178:181], v[120:123]
	v_mfma_f32_16x16x32_bf16 v[108:111], v[136:139], v[192:195], v[108:111]
	v_mfma_f32_16x16x32_bf16 v[104:107], v[140:143], v[192:195], v[104:107]
	v_mfma_f32_16x16x32_bf16 v[92:95], v[136:139], v[204:207], v[92:95]
	v_mfma_f32_16x16x32_bf16 v[88:91], v[140:143], v[204:207], v[88:91]
	v_mfma_f32_16x16x32_bf16 v[76:79], v[136:139], v[208:211], v[76:79]
	v_mfma_f32_16x16x32_bf16 v[72:75], v[140:143], v[208:211], v[72:75]
	s_setprio 0
	s_setprio 1
	v_mfma_f32_16x16x32_bf16 v[116:119], v[144:147], v[160:163], v[116:119]
	s_add_u32 s40, s36, 0x80
	s_addc_u32 s41, s37, 0
	v_mfma_f32_16x16x32_bf16 v[112:115], v[148:151], v[160:163], v[112:115]
	v_mfma_f32_16x16x32_bf16 v[100:103], v[144:147], v[174:177], v[100:103]
	v_mfma_f32_16x16x32_bf16 v[96:99], v[148:151], v[174:177], v[96:99]
	v_mfma_f32_16x16x32_bf16 v[84:87], v[144:147], v[196:199], v[84:87]
	v_mfma_f32_16x16x32_bf16 v[80:83], v[148:151], v[196:199], v[80:83]
	v_mfma_f32_16x16x32_bf16 v[68:71], v[144:147], v[200:203], v[68:71]
	v_mfma_f32_16x16x32_bf16 v[64:67], v[148:151], v[200:203], v[64:67]
	v_mfma_f32_16x16x32_bf16 v[116:119], v[152:155], v[178:181], v[116:119]
	v_mfma_f32_16x16x32_bf16 v[112:115], v[156:159], v[178:181], v[112:115]
	v_mfma_f32_16x16x32_bf16 v[100:103], v[152:155], v[192:195], v[100:103]
	v_mfma_f32_16x16x32_bf16 v[96:99], v[156:159], v[192:195], v[96:99]
	v_mfma_f32_16x16x32_bf16 v[84:87], v[152:155], v[204:207], v[84:87]
	v_mfma_f32_16x16x32_bf16 v[80:83], v[156:159], v[204:207], v[80:83]
	v_mfma_f32_16x16x32_bf16 v[68:71], v[152:155], v[208:211], v[68:71]
	v_mfma_f32_16x16x32_bf16 v[64:67], v[156:159], v[208:211], v[64:67]
	s_barrier
; #define PG8_STAGE(bufoff, gbase, voff) do { _Pragma("unroll") for (int _i = 0; _i < 2; ++_i) \
;         dma16((const char*)(gbase), (voff)[_i], ldsb + (bufoff) + ldsw + _i * 8192); } while (0)
; #define PG8_LDA(dst, b, h) do { const int a1_ = opqv(aoff0) ^ 64; _Pragma("unroll") for (int m = 0; m < 4; ++m) { dst[m][0] = *(const LAS bf16x8*)(lds + PG8_SA(b, h) + aoff0 + m * 2048); dst[m][1] = *(const LAS bf16x8*)(lds + PG8_SA(b, h) + a1_ + m * 2048); } } while (0)
; #define PG8_LDB(dst, b, h) do { const int b1_ = opqv(boff0) ^ 64; _Pragma("unroll") for (int n = 0; n < 2; ++n) { dst[n][0] = *(const LAS bf16x8*)(lds + PG8_SB(b, h) + boff0 + n * 2048); dst[n][1] = *(const LAS bf16x8*)(lds + PG8_SB(b, h) + b1_ + n * 2048); } } while (0)
; #define PG8_WAIT_V(n) asm volatile("s_waitcnt vmcnt(" #n ")" ::: "memory")
; template <class Epi>
; __device__ __forceinline__ void gemm_phase(LAS unsigned char* lds, const Gemm g, const StaticOrder& S, const Epi& E, int wave_) {
;     ...
;         for (int t = 0; t < nt; t += 2) {
;             const bool last = (t == nt - 2);
;             const char* a1 = cA + (size_t)(t + 1) * kstep;
;             const char* a2 = last ? nA : cA + (size_t)(t + 2) * kstep; const char* b2 = last ? nB : cB + (size_t)(t + 2) * kstep;
;             const char* a3 = a2 + kstep; const char* b3 = b2 + kstep;
;             PG8_STAGE(PG8_SA(1, 1), a1 + hstepA, voffA); PG8_LDB(B0, 0, 0); PG8_LDB(B1, 0, 1); PG8_SCHED; PG8_LDA(At, 0, 0);
;             PG8_WAIT_V(8); PG8_WAIT_L(0); PG8_BAR; PG8_MMA(0, 0, At, B0); PG8_MMA(0, 1, At, B1); PG8_BAR; PG8_SCHED;
;             PG8_STAGE(PG8_SB(0, 0), b2, voffB); PG8_STAGE(PG8_SB(0, 1), b2 + hstepB, voffB); PG8_STAGE(PG8_SA(0, 0), a2, voffA); PG8_LDA(At, 0, 1);
;             PG8_WAIT_V(8); PG8_WAIT_L(0); PG8_BAR; PG8_MMA(1, 0, At, B0); PG8_MMA(1, 1, At, B1); PG8_BAR; PG8_SCHED;
;             PG8_STAGE(PG8_SA(0, 1), a2 + hstepA, voffA); PG8_LDB(B0, 1, 0); PG8_LDB(B1, 1, 1); PG8_SCHED; PG8_LDA(At, 1, 0);
;             PG8_WAIT_V(8); PG8_WAIT_L(0); PG8_BAR; PG8_MMA(0, 0, At, B0); PG8_MMA(0, 1, At, B1); PG8_BAR; PG8_SCHED;
;             PG8_STAGE(PG8_SB(1, 0), b3, voffB); PG8_STAGE(PG8_SB(1, 1), b3 + hstepB, voffB); PG8_STAGE(PG8_SA(1, 0), a3, voffA); PG8_LDA(At, 1, 1);
;             PG8_WAIT_V(8); PG8_WAIT_L(0); PG8_BAR; PG8_MMA(1, 0, At, B0); PG8_MMA(1, 1, At, B1); PG8_BAR; PG8_SCHED;
	s_setprio 0
	s_add_u32 s36, s36, 0x80080
	s_addc_u32 s37, s37, 0
	v_mov_b32_e32 v160, v171
	s_nop 0
	s_nop 0
	v_xad_u32 v182, v160, 64, 0
	ds_read_b128 v[160:163], v183 offset:49152
	ds_read_b128 v[174:177], v183 offset:51200
	ds_read_b128 v[178:181], v182 offset:49152
	ds_read_b128 v[192:195], v182 offset:51200
	ds_read_b128 v[196:199], v183 offset:53248
	ds_read_b128 v[200:203], v183 offset:55296
	ds_read_b128 v[204:207], v182 offset:53248
	ds_read_b128 v[208:211], v182 offset:55296
	s_mov_b32 m0, s35
	s_nop 0
	global_load_lds_dwordx4 v167, s[40:41]
	s_mov_b32 m0, s33
	s_nop 0
	global_load_lds_dwordx4 v169, s[40:41]
	s_mov_b32 m0, s77
	s_nop 0
	global_load_lds_dwordx4 v167, s[36:37]
	s_mov_b32 m0, s3
	s_nop 0
	global_load_lds_dwordx4 v169, s[36:37]
	s_mov_b32 m0, s22
	s_nop 0
	global_load_lds_dwordx4 v166, s[30:31]
	s_mov_b32 m0, s2
	s_nop 0
	global_load_lds_dwordx4 v168, s[30:31]
	s_waitcnt vmcnt(8)
	s_waitcnt lgkmcnt(0)
	s_setprio 1
	s_barrier
	v_mfma_f32_16x16x32_bf16 v[60:63], v[128:131], v[160:163], v[60:63]
	v_mfma_f32_16x16x32_bf16 v[56:59], v[132:135], v[160:163], v[56:59]
	v_mfma_f32_16x16x32_bf16 v[44:47], v[128:131], v[174:177], v[44:47]
	v_mfma_f32_16x16x32_bf16 v[40:43], v[132:135], v[174:177], v[40:43]
	v_mfma_f32_16x16x32_bf16 v[28:31], v[128:131], v[196:199], v[28:31]
	v_mfma_f32_16x16x32_bf16 v[24:27], v[132:135], v[196:199], v[24:27]
	v_mfma_f32_16x16x32_bf16 v[12:15], v[128:131], v[200:203], v[12:15]
	v_mfma_f32_16x16x32_bf16 v[8:11], v[132:135], v[200:203], v[8:11]
	v_mfma_f32_16x16x32_bf16 v[60:63], v[136:139], v[178:181], v[60:63]
	v_mfma_f32_16x16x32_bf16 v[56:59], v[140:143], v[178:181], v[56:59]
	v_mfma_f32_16x16x32_bf16 v[44:47], v[136:139], v[192:195], v[44:47]
	v_mfma_f32_16x16x32_bf16 v[40:43], v[140:143], v[192:195], v[40:43]
	v_mfma_f32_16x16x32_bf16 v[28:31], v[136:139], v[204:207], v[28:31]
	v_mfma_f32_16x16x32_bf16 v[24:27], v[140:143], v[204:207], v[24:27]
	v_mfma_f32_16x16x32_bf16 v[12:15], v[136:139], v[208:211], v[12:15]
	v_mfma_f32_16x16x32_bf16 v[8:11], v[140:143], v[208:211], v[8:11]
	s_setprio 0
	s_setprio 1
	v_mfma_f32_16x16x32_bf16 v[52:55], v[144:147], v[160:163], v[52:55]
	v_mfma_f32_16x16x32_bf16 v[48:51], v[148:151], v[160:163], v[48:51]
	v_mfma_f32_16x16x32_bf16 v[36:39], v[144:147], v[174:177], v[36:39]
	v_mfma_f32_16x16x32_bf16 v[32:35], v[148:151], v[174:177], v[32:35]
	v_mfma_f32_16x16x32_bf16 v[20:23], v[144:147], v[196:199], v[20:23]
	v_mfma_f32_16x16x32_bf16 v[16:19], v[148:151], v[196:199], v[16:19]
	v_mfma_f32_16x16x32_bf16 v[4:7], v[144:147], v[200:203], v[4:7]
	v_mfma_f32_16x16x32_bf16 v[0:3], v[148:151], v[200:203], v[0:3]
	v_mfma_f32_16x16x32_bf16 v[52:55], v[152:155], v[178:181], v[52:55]
	v_mfma_f32_16x16x32_bf16 v[48:51], v[156:159], v[178:181], v[48:51]
	v_mfma_f32_16x16x32_bf16 v[36:39], v[152:155], v[192:195], v[36:39]
	v_mfma_f32_16x16x32_bf16 v[32:35], v[156:159], v[192:195], v[32:35]
	v_mfma_f32_16x16x32_bf16 v[20:23], v[152:155], v[204:207], v[20:23]
	v_mfma_f32_16x16x32_bf16 v[16:19], v[156:159], v[204:207], v[16:19]
	v_mfma_f32_16x16x32_bf16 v[4:7], v[152:155], v[208:211], v[4:7]
	v_mfma_f32_16x16x32_bf16 v[0:3], v[156:159], v[208:211], v[0:3]
	s_barrier
	s_setprio 0
	s_add_i32 s57, s57, 2
	s_add_u32 s55, s55, 0x100
	s_addc_u32 s56, s56, 0
	s_add_u32 s12, s12, 0x100
	s_addc_u32 s13, s13, 0
	s_cmp_gt_u32 s57, 29
	s_cbranch_scc0 .LBB0_1104
	s_branch .Lpeel_exit_4
.LBB0_1104:
	s_add_u32 s30, s12, 0xfff80080
	s_addc_u32 s31, s13, -1
	s_cmp_eq_u32 s57, 28
	s_cselect_b32 s40, s17, s30
	s_cselect_b32 s41, s16, s31
	s_cselect_b32 s36, s19, s55
	s_cselect_b32 s37, s11, s56
	s_add_u32 s30, s40, 0x80
	v_mov_b32_e32 v128, v172
	s_addc_u32 s31, s41, 0
	v_add_u32_e32 v132, s23, v172
	v_xad_u32 v140, v128, 64, s23
	v_mov_b32_e32 v144, v172
	s_add_i32 s60, 0, 0x14000
	ds_read_b128 v[128:131], v132
	ds_read_b128 v[132:135], v132 offset:2048
	ds_read_b128 v[136:139], v140
	ds_read_b128 v[140:143], v140 offset:2048
	v_add_u32_e32 v148, s60, v172
	v_xad_u32 v156, v144, 64, s60
	ds_read_b128 v[144:147], v148
	ds_read_b128 v[148:151], v148 offset:2048
	ds_read_b128 v[152:155], v156
	ds_read_b128 v[156:159], v156 offset:2048
	v_mov_b32_e32 v160, v171
	v_add_u32_e32 v183, 0, v171
	v_xad_u32 v182, v160, 64, 0
	ds_read_b128 v[160:163], v183
	ds_read_b128 v[174:177], v183 offset:2048
	ds_read_b128 v[178:181], v182
	ds_read_b128 v[192:195], v182 offset:2048
	ds_read_b128 v[196:199], v183 offset:4096
	ds_read_b128 v[200:203], v183 offset:6144
	ds_read_b128 v[204:207], v182 offset:4096
	ds_read_b128 v[208:211], v182 offset:6144
	s_mov_b32 m0, s14
	s_nop 0
	global_load_lds_dwordx4 v166, s[12:13]
	s_mov_b32 m0, s15
	s_nop 0
	global_load_lds_dwordx4 v168, s[12:13]
	s_waitcnt vmcnt(8)
	s_waitcnt lgkmcnt(0)
	s_setprio 1
	s_barrier
; #define PG8_STAGE(bufoff, gbase, voff) do { _Pragma("unroll") for (int _i = 0; _i < 2; ++_i) \
;         dma16((const char*)(gbase), (voff)[_i], ldsb + (bufoff) + ldsw + _i * 8192); } while (0)
; #define PG8_LDA(dst, b, h) do { const int a1_ = opqv(aoff0) ^ 64; _Pragma("unroll") for (int m = 0; m < 4; ++m) { dst[m][0] = *(const LAS bf16x8*)(lds + PG8_SA(b, h) + aoff0 + m * 2048); dst[m][1] = *(const LAS bf16x8*)(lds + PG8_SA(b, h) + a1_ + m * 2048); } } while (0)
; #define PG8_MMA(ai, bj, At, Bt) do { __builtin_amdgcn_s_setprio(1); _Pragma("unroll") for (int m = 0; m < 4; ++m) _Pragma("unroll") for (int n = 0; n < 2; ++n) _Pragma("unroll") for (int k = 0; k < 2; ++k) \
;         acc[ai][bj][m][n] = __builtin_amdgcn_mfma_f32_16x16x32_bf16(Bt[n][k], At[m][k], acc[ai][bj][m][n], 0, 0, 0); __builtin_amdgcn_s_setprio(0); } while (0)
; #define PG8_WAIT_V(n) asm volatile("s_waitcnt vmcnt(" #n ")" ::: "memory")
; #define PG8_WAIT_L(n) asm volatile("s_waitcnt lgkmcnt(" #n ")" ::: "memory")
; #define PG8_BAR __builtin_amdgcn_s_barrier()
; #define PG8_SCHED __builtin_amdgcn_sched_barrier(0)
; template <class Epi>
; __device__ __forceinline__ void gemm_phase(LAS unsigned char* lds, const Gemm g, const StaticOrder& S, const Epi& E, int wave_) {
;     ...
;             PG8_WAIT_V(8); PG8_WAIT_L(0); PG8_BAR; PG8_MMA(0, 0, At, B0); PG8_MMA(0, 1, At, B1); PG8_BAR; PG8_SCHED;
;             PG8_STAGE(PG8_SB(0, 0), b2, voffB); PG8_STAGE(PG8_SB(0, 1), b2 + hstepB, voffB); PG8_STAGE(PG8_SA(0, 0), a2, voffA); PG8_LDA(At, 0, 1);
;             PG8_WAIT_V(8); PG8_WAIT_L(0); PG8_BAR; PG8_MMA(1, 0, At, B0); PG8_MMA(1, 1, At, B1); PG8_BAR; PG8_SCHED;
	v_mfma_f32_16x16x32_bf16 v[124:127], v[128:131], v[160:163], v[124:127]
	v_mfma_f32_16x16x32_bf16 v[120:123], v[132:135], v[160:163], v[120:123]
	v_mfma_f32_16x16x32_bf16 v[108:111], v[128:131], v[174:177], v[108:111]
	v_mfma_f32_16x16x32_bf16 v[104:107], v[132:135], v[174:177], v[104:107]
	v_mfma_f32_16x16x32_bf16 v[92:95], v[128:131], v[196:199], v[92:95]
	v_mfma_f32_16x16x32_bf16 v[88:91], v[132:135], v[196:199], v[88:91]
	v_mfma_f32_16x16x32_bf16 v[76:79], v[128:131], v[200:203], v[76:79]
	v_mfma_f32_16x16x32_bf16 v[72:75], v[132:135], v[200:203], v[72:75]
	v_mfma_f32_16x16x32_bf16 v[124:127], v[136:139], v[178:181], v[124:127]
	v_mfma_f32_16x16x32_bf16 v[120:123], v[140:143], v[178:181], v[120:123]
	v_mfma_f32_16x16x32_bf16 v[108:111], v[136:139], v[192:195], v[108:111]
	v_mfma_f32_16x16x32_bf16 v[104:107], v[140:143], v[192:195], v[104:107]
	v_mfma_f32_16x16x32_bf16 v[92:95], v[136:139], v[204:207], v[92:95]
	v_mfma_f32_16x16x32_bf16 v[88:91], v[140:143], v[204:207], v[88:91]
	v_mfma_f32_16x16x32_bf16 v[76:79], v[136:139], v[208:211], v[76:79]
	v_mfma_f32_16x16x32_bf16 v[72:75], v[140:143], v[208:211], v[72:75]
	s_setprio 0
	s_setprio 1
	v_mfma_f32_16x16x32_bf16 v[116:119], v[144:147], v[160:163], v[116:119]
	v_mfma_f32_16x16x32_bf16 v[112:115], v[148:151], v[160:163], v[112:115]
	v_mfma_f32_16x16x32_bf16 v[100:103], v[144:147], v[174:177], v[100:103]
	v_mfma_f32_16x16x32_bf16 v[96:99], v[148:151], v[174:177], v[96:99]
	v_mfma_f32_16x16x32_bf16 v[84:87], v[144:147], v[196:199], v[84:87]
	v_mfma_f32_16x16x32_bf16 v[80:83], v[148:151], v[196:199], v[80:83]
	v_mfma_f32_16x16x32_bf16 v[68:71], v[144:147], v[200:203], v[68:71]
	v_mfma_f32_16x16x32_bf16 v[64:67], v[148:151], v[200:203], v[64:67]
	v_mfma_f32_16x16x32_bf16 v[116:119], v[152:155], v[178:181], v[116:119]
	v_mfma_f32_16x16x32_bf16 v[112:115], v[156:159], v[178:181], v[112:115]
	v_mfma_f32_16x16x32_bf16 v[100:103], v[152:155], v[192:195], v[100:103]
	v_mfma_f32_16x16x32_bf16 v[96:99], v[156:159], v[192:195], v[96:99]
	v_mfma_f32_16x16x32_bf16 v[84:87], v[152:155], v[204:207], v[84:87]
	v_mfma_f32_16x16x32_bf16 v[80:83], v[156:159], v[204:207], v[80:83]
	v_mfma_f32_16x16x32_bf16 v[68:71], v[152:155], v[208:211], v[68:71]
	v_mfma_f32_16x16x32_bf16 v[64:67], v[156:159], v[208:211], v[64:67]
	s_barrier
	s_setprio 0
	v_mov_b32_e32 v160, v171
	s_add_u32 s60, s36, 0x80000
	s_addc_u32 s61, s37, 0
	s_nop 0
	s_nop 0
	s_nop 0
	v_xad_u32 v182, v160, 64, 0
	ds_read_b128 v[160:163], v183 offset:16384
	ds_read_b128 v[174:177], v183 offset:18432
	ds_read_b128 v[178:181], v182 offset:16384
	ds_read_b128 v[192:195], v182 offset:18432
	ds_read_b128 v[196:199], v183 offset:20480
	ds_read_b128 v[200:203], v183 offset:22528
	ds_read_b128 v[204:207], v182 offset:20480
	ds_read_b128 v[208:211], v182 offset:22528
	s_mov_b32 m0, s80
	s_nop 0
	global_load_lds_dwordx4 v167, s[36:37]
	s_mov_b32 m0, s81
	s_nop 0
	global_load_lds_dwordx4 v169, s[36:37]
	s_mov_b32 m0, s29
	s_nop 0
	global_load_lds_dwordx4 v167, s[60:61]
	s_mov_b32 m0, s88
	s_nop 0
	global_load_lds_dwordx4 v169, s[60:61]
	s_mov_b32 m0, s76
	s_nop 0
	global_load_lds_dwordx4 v166, s[40:41]
	s_mov_b32 m0, s89
	s_nop 0
	global_load_lds_dwordx4 v168, s[40:41]
	s_waitcnt vmcnt(8)
	s_waitcnt lgkmcnt(0)
	s_setprio 1
	s_barrier
	v_mfma_f32_16x16x32_bf16 v[60:63], v[128:131], v[160:163], v[60:63]
	v_mfma_f32_16x16x32_bf16 v[56:59], v[132:135], v[160:163], v[56:59]
	v_mfma_f32_16x16x32_bf16 v[44:47], v[128:131], v[174:177], v[44:47]
	v_mfma_f32_16x16x32_bf16 v[40:43], v[132:135], v[174:177], v[40:43]
	v_mfma_f32_16x16x32_bf16 v[28:31], v[128:131], v[196:199], v[28:31]
	v_mfma_f32_16x16x32_bf16 v[24:27], v[132:135], v[196:199], v[24:27]
	v_mfma_f32_16x16x32_bf16 v[12:15], v[128:131], v[200:203], v[12:15]
	v_mfma_f32_16x16x32_bf16 v[8:11], v[132:135], v[200:203], v[8:11]
	v_mfma_f32_16x16x32_bf16 v[60:63], v[136:139], v[178:181], v[60:63]
	v_mfma_f32_16x16x32_bf16 v[56:59], v[140:143], v[178:181], v[56:59]
	v_mfma_f32_16x16x32_bf16 v[44:47], v[136:139], v[192:195], v[44:47]
	v_mfma_f32_16x16x32_bf16 v[40:43], v[140:143], v[192:195], v[40:43]
	v_mfma_f32_16x16x32_bf16 v[28:31], v[136:139], v[204:207], v[28:31]
	v_mfma_f32_16x16x32_bf16 v[24:27], v[140:143], v[204:207], v[24:27]
	v_mfma_f32_16x16x32_bf16 v[12:15], v[136:139], v[208:211], v[12:15]
	v_mfma_f32_16x16x32_bf16 v[8:11], v[140:143], v[208:211], v[8:11]
	s_setprio 0
	s_setprio 1
	v_mfma_f32_16x16x32_bf16 v[52:55], v[144:147], v[160:163], v[52:55]
	v_mfma_f32_16x16x32_bf16 v[48:51], v[148:151], v[160:163], v[48:51]
	v_mfma_f32_16x16x32_bf16 v[36:39], v[144:147], v[174:177], v[36:39]
	v_mfma_f32_16x16x32_bf16 v[32:35], v[148:151], v[174:177], v[32:35]
	v_mfma_f32_16x16x32_bf16 v[20:23], v[144:147], v[196:199], v[20:23]
	v_mfma_f32_16x16x32_bf16 v[16:19], v[148:151], v[196:199], v[16:19]
	v_mfma_f32_16x16x32_bf16 v[4:7], v[144:147], v[200:203], v[4:7]
	v_mfma_f32_16x16x32_bf16 v[0:3], v[148:151], v[200:203], v[0:3]
	v_mfma_f32_16x16x32_bf16 v[52:55], v[152:155], v[178:181], v[52:55]
	v_mfma_f32_16x16x32_bf16 v[48:51], v[156:159], v[178:181], v[48:51]
	v_mfma_f32_16x16x32_bf16 v[36:39], v[152:155], v[192:195], v[36:39]
	v_mfma_f32_16x16x32_bf16 v[32:35], v[156:159], v[192:195], v[32:35]
	v_mfma_f32_16x16x32_bf16 v[20:23], v[152:155], v[204:207], v[20:23]
	v_mfma_f32_16x16x32_bf16 v[16:19], v[156:159], v[204:207], v[16:19]
	v_mfma_f32_16x16x32_bf16 v[4:7], v[152:155], v[208:211], v[4:7]
	v_mfma_f32_16x16x32_bf16 v[0:3], v[156:159], v[208:211], v[0:3]
	s_barrier
; #define PG8_STAGE(bufoff, gbase, voff) do { _Pragma("unroll") for (int _i = 0; _i < 2; ++_i) \
;         dma16((const char*)(gbase), (voff)[_i], ldsb + (bufoff) + ldsw + _i * 8192); } while (0)
; #define PG8_LDA(dst, b, h) do { const int a1_ = opqv(aoff0) ^ 64; _Pragma("unroll") for (int m = 0; m < 4; ++m) { dst[m][0] = *(const LAS bf16x8*)(lds + PG8_SA(b, h) + aoff0 + m * 2048); dst[m][1] = *(const LAS bf16x8*)(lds + PG8_SA(b, h) + a1_ + m * 2048); } } while (0)
; #define PG8_LDB(dst, b, h) do { const int b1_ = opqv(boff0) ^ 64; _Pragma("unroll") for (int n = 0; n < 2; ++n) { dst[n][0] = *(const LAS bf16x8*)(lds + PG8_SB(b, h) + boff0 + n * 2048); dst[n][1] = *(const LAS bf16x8*)(lds + PG8_SB(b, h) + b1_ + n * 2048); } } while (0)
; #define PG8_MMA(ai, bj, At, Bt) do { __builtin_amdgcn_s_setprio(1); _Pragma("unroll") for (int m = 0; m < 4; ++m) _Pragma("unroll") for (int n = 0; n < 2; ++n) _Pragma("unroll") for (int k = 0; k < 2; ++k) \
;         acc[ai][bj][m][n] = __builtin_amdgcn_mfma_f32_16x16x32_bf16(Bt[n][k], At[m][k], acc[ai][bj][m][n], 0, 0, 0); __builtin_amdgcn_s_setprio(0); } while (0)
; #define PG8_WAIT_V(n) asm volatile("s_waitcnt vmcnt(" #n ")" ::: "memory")
; #define PG8_WAIT_L(n) asm volatile("s_waitcnt lgkmcnt(" #n ")" ::: "memory")
; #define PG8_BAR __builtin_amdgcn_s_barrier()
; #define PG8_SCHED __builtin_amdgcn_sched_barrier(0)
; template <class Epi>
; __device__ __forceinline__ void gemm_phase(LAS unsigned char* lds, const Gemm g, const StaticOrder& S, const Epi& E, int wave_) {
;     ...
;             PG8_STAGE(PG8_SA(0, 1), a2 + hstepA, voffA); PG8_LDB(B0, 1, 0); PG8_LDB(B1, 1, 1); PG8_SCHED; PG8_LDA(At, 1, 0);
;             PG8_WAIT_V(8); PG8_WAIT_L(0); PG8_BAR; PG8_MMA(0, 0, At, B0); PG8_MMA(0, 1, At, B1); PG8_BAR; PG8_SCHED;
;             PG8_STAGE(PG8_SB(1, 0), b3, voffB); PG8_STAGE(PG8_SB(1, 1), b3 + hstepB, voffB); PG8_STAGE(PG8_SA(1, 0), a3, voffA); PG8_LDA(At, 1, 1);
;             PG8_WAIT_V(8); PG8_WAIT_L(0); PG8_BAR; PG8_MMA(1, 0, At, B0); PG8_MMA(1, 1, At, B1); PG8_BAR; PG8_SCHED;
;         }
	s_setprio 0
	s_add_u32 s40, s40, 0x80000
	s_addc_u32 s41, s41, 0
	s_mov_b32 m0, s1
	s_nop 0
	global_load_lds_dwordx4 v166, s[40:41]
	v_mov_b32_e32 v128, v172
	s_mov_b32 m0, s69
	s_nop 0
	global_load_lds_dwordx4 v168, s[40:41]
	v_add_u32_e32 v132, s34, v172
	v_xad_u32 v140, v128, 64, s34
	v_mov_b32_e32 v144, v172
	s_add_i32 s40, 0, 0x1c000
	ds_read_b128 v[128:131], v132
	ds_read_b128 v[132:135], v132 offset:2048
	ds_read_b128 v[136:139], v140
	ds_read_b128 v[140:143], v140 offset:2048
	v_add_u32_e32 v148, s40, v172
	v_xad_u32 v156, v144, 64, s40
	ds_read_b128 v[144:147], v148
	ds_read_b128 v[148:151], v148 offset:2048
	ds_read_b128 v[152:155], v156
	ds_read_b128 v[156:159], v156 offset:2048
	v_mov_b32_e32 v160, v171
	s_nop 0
	v_xad_u32 v182, v160, 64, 0
	ds_read_b128 v[160:163], v183 offset:32768
	ds_read_b128 v[174:177], v183 offset:34816
	ds_read_b128 v[178:181], v182 offset:32768
	ds_read_b128 v[192:195], v182 offset:34816
	ds_read_b128 v[196:199], v183 offset:36864
	ds_read_b128 v[200:203], v183 offset:38912
	ds_read_b128 v[204:207], v182 offset:36864
	ds_read_b128 v[208:211], v182 offset:38912
	s_waitcnt vmcnt(8)
	s_waitcnt lgkmcnt(0)
	s_setprio 1
	s_barrier
	v_mfma_f32_16x16x32_bf16 v[124:127], v[128:131], v[160:163], v[124:127]
	v_mfma_f32_16x16x32_bf16 v[120:123], v[132:135], v[160:163], v[120:123]
	v_mfma_f32_16x16x32_bf16 v[108:111], v[128:131], v[174:177], v[108:111]
	v_mfma_f32_16x16x32_bf16 v[104:107], v[132:135], v[174:177], v[104:107]
	v_mfma_f32_16x16x32_bf16 v[92:95], v[128:131], v[196:199], v[92:95]
	v_mfma_f32_16x16x32_bf16 v[88:91], v[132:135], v[196:199], v[88:91]
	v_mfma_f32_16x16x32_bf16 v[76:79], v[128:131], v[200:203], v[76:79]
	v_mfma_f32_16x16x32_bf16 v[72:75], v[132:135], v[200:203], v[72:75]
	v_mfma_f32_16x16x32_bf16 v[124:127], v[136:139], v[178:181], v[124:127]
	v_mfma_f32_16x16x32_bf16 v[120:123], v[140:143], v[178:181], v[120:123]
	v_mfma_f32_16x16x32_bf16 v[108:111], v[136:139], v[192:195], v[108:111]
	v_mfma_f32_16x16x32_bf16 v[104:107], v[140:143], v[192:195], v[104:107]
	v_mfma_f32_16x16x32_bf16 v[92:95], v[136:139], v[204:207], v[92:95]
	v_mfma_f32_16x16x32_bf16 v[88:91], v[140:143], v[204:207], v[88:91]
	v_mfma_f32_16x16x32_bf16 v[76:79], v[136:139], v[208:211], v[76:79]
	v_mfma_f32_16x16x32_bf16 v[72:75], v[140:143], v[208:211], v[72:75]
	s_setprio 0
	s_setprio 1
	v_mfma_f32_16x16x32_bf16 v[116:119], v[144:147], v[160:163], v[116:119]
	s_add_u32 s40, s36, 0x80
	s_addc_u32 s41, s37, 0
	v_mfma_f32_16x16x32_bf16 v[112:115], v[148:151], v[160:163], v[112:115]
	v_mfma_f32_16x16x32_bf16 v[100:103], v[144:147], v[174:177], v[100:103]
	v_mfma_f32_16x16x32_bf16 v[96:99], v[148:151], v[174:177], v[96:99]
	v_mfma_f32_16x16x32_bf16 v[84:87], v[144:147], v[196:199], v[84:87]
	v_mfma_f32_16x16x32_bf16 v[80:83], v[148:151], v[196:199], v[80:83]
	v_mfma_f32_16x16x32_bf16 v[68:71], v[144:147], v[200:203], v[68:71]
	v_mfma_f32_16x16x32_bf16 v[64:67], v[148:151], v[200:203], v[64:67]
	v_mfma_f32_16x16x32_bf16 v[116:119], v[152:155], v[178:181], v[116:119]
	v_mfma_f32_16x16x32_bf16 v[112:115], v[156:159], v[178:181], v[112:115]
	v_mfma_f32_16x16x32_bf16 v[100:103], v[152:155], v[192:195], v[100:103]
	v_mfma_f32_16x16x32_bf16 v[96:99], v[156:159], v[192:195], v[96:99]
	v_mfma_f32_16x16x32_bf16 v[84:87], v[152:155], v[204:207], v[84:87]
	v_mfma_f32_16x16x32_bf16 v[80:83], v[156:159], v[204:207], v[80:83]
	v_mfma_f32_16x16x32_bf16 v[68:71], v[152:155], v[208:211], v[68:71]
	v_mfma_f32_16x16x32_bf16 v[64:67], v[156:159], v[208:211], v[64:67]
	s_barrier
	s_setprio 0
	s_add_u32 s36, s36, 0x80080
	s_addc_u32 s37, s37, 0
	v_mov_b32_e32 v160, v171
	s_nop 0
	s_nop 0
	v_xad_u32 v182, v160, 64, 0
	ds_read_b128 v[160:163], v183 offset:49152
	ds_read_b128 v[174:177], v183 offset:51200
	ds_read_b128 v[178:181], v182 offset:49152
	ds_read_b128 v[192:195], v182 offset:51200
	ds_read_b128 v[196:199], v183 offset:53248
	ds_read_b128 v[200:203], v183 offset:55296
	ds_read_b128 v[204:207], v182 offset:53248
	ds_read_b128 v[208:211], v182 offset:55296
	s_mov_b32 m0, s35
	s_nop 0
	global_load_lds_dwordx4 v167, s[40:41]
	s_mov_b32 m0, s33
	s_nop 0
	global_load_lds_dwordx4 v169, s[40:41]
	s_mov_b32 m0, s77
	s_nop 0
	global_load_lds_dwordx4 v167, s[36:37]
	s_mov_b32 m0, s3
	s_nop 0
	global_load_lds_dwordx4 v169, s[36:37]
	s_mov_b32 m0, s22
	s_nop 0
	global_load_lds_dwordx4 v166, s[30:31]
	s_mov_b32 m0, s2
	s_nop 0
	global_load_lds_dwordx4 v168, s[30:31]
	s_waitcnt vmcnt(8)
	s_waitcnt lgkmcnt(0)
	s_setprio 1
	s_barrier
	v_mfma_f32_16x16x32_bf16 v[60:63], v[128:131], v[160:163], v[60:63]
	v_mfma_f32_16x16x32_bf16 v[56:59], v[132:135], v[160:163], v[56:59]
	v_mfma_f32_16x16x32_bf16 v[44:47], v[128:131], v[174:177], v[44:47]
	v_mfma_f32_16x16x32_bf16 v[40:43], v[132:135], v[174:177], v[40:43]
	v_mfma_f32_16x16x32_bf16 v[28:31], v[128:131], v[196:199], v[28:31]
	v_mfma_f32_16x16x32_bf16 v[24:27], v[132:135], v[196:199], v[24:27]
	v_mfma_f32_16x16x32_bf16 v[12:15], v[128:131], v[200:203], v[12:15]
	v_mfma_f32_16x16x32_bf16 v[8:11], v[132:135], v[200:203], v[8:11]
	v_mfma_f32_16x16x32_bf16 v[60:63], v[136:139], v[178:181], v[60:63]
	v_mfma_f32_16x16x32_bf16 v[56:59], v[140:143], v[178:181], v[56:59]
	v_mfma_f32_16x16x32_bf16 v[44:47], v[136:139], v[192:195], v[44:47]
	v_mfma_f32_16x16x32_bf16 v[40:43], v[140:143], v[192:195], v[40:43]
	v_mfma_f32_16x16x32_bf16 v[28:31], v[136:139], v[204:207], v[28:31]
	v_mfma_f32_16x16x32_bf16 v[24:27], v[140:143], v[204:207], v[24:27]
	v_mfma_f32_16x16x32_bf16 v[12:15], v[136:139], v[208:211], v[12:15]
	v_mfma_f32_16x16x32_bf16 v[8:11], v[140:143], v[208:211], v[8:11]
	s_setprio 0
	s_setprio 1
	v_mfma_f32_16x16x32_bf16 v[52:55], v[144:147], v[160:163], v[52:55]
	v_mfma_f32_16x16x32_bf16 v[48:51], v[148:151], v[160:163], v[48:51]
	v_mfma_f32_16x16x32_bf16 v[36:39], v[144:147], v[174:177], v[36:39]
	v_mfma_f32_16x16x32_bf16 v[32:35], v[148:151], v[174:177], v[32:35]
	v_mfma_f32_16x16x32_bf16 v[20:23], v[144:147], v[196:199], v[20:23]
	v_mfma_f32_16x16x32_bf16 v[16:19], v[148:151], v[196:199], v[16:19]
	v_mfma_f32_16x16x32_bf16 v[4:7], v[144:147], v[200:203], v[4:7]
	v_mfma_f32_16x16x32_bf16 v[0:3], v[148:151], v[200:203], v[0:3]
	v_mfma_f32_16x16x32_bf16 v[52:55], v[152:155], v[178:181], v[52:55]
	v_mfma_f32_16x16x32_bf16 v[48:51], v[156:159], v[178:181], v[48:51]
	v_mfma_f32_16x16x32_bf16 v[36:39], v[152:155], v[192:195], v[36:39]
	v_mfma_f32_16x16x32_bf16 v[32:35], v[156:159], v[192:195], v[32:35]
	v_mfma_f32_16x16x32_bf16 v[20:23], v[152:155], v[204:207], v[20:23]
	v_mfma_f32_16x16x32_bf16 v[16:19], v[156:159], v[204:207], v[16:19]
	v_mfma_f32_16x16x32_bf16 v[4:7], v[152:155], v[208:211], v[4:7]
	v_mfma_f32_16x16x32_bf16 v[0:3], v[156:159], v[208:211], v[0:3]
	s_barrier
	s_setprio 0
	s_add_i32 s57, s57, 2
	s_add_u32 s55, s55, 0x100
	s_addc_u32 s56, s56, 0
	s_add_u32 s12, s12, 0x100
	s_addc_u32 s13, s13, 0
	s_cmp_gt_u32 s57, 29
	s_cbranch_scc0 .LBB0_1104

; #define PG8_STAGE(bufoff, gbase, voff) do { _Pragma("unroll") for (int _i = 0; _i < 2; ++_i) \
;         dma16((const char*)(gbase), (voff)[_i], ldsb + (bufoff) + ldsw + _i * 8192); } while (0)
; #define PG8_LDA(dst, b, h) do { const int a1_ = opqv(aoff0) ^ 64; _Pragma("unroll") for (int m = 0; m < 4; ++m) { dst[m][0] = *(const LAS bf16x8*)(lds + PG8_SA(b, h) + aoff0 + m * 2048); dst[m][1] = *(const LAS bf16x8*)(lds + PG8_SA(b, h) + a1_ + m * 2048); } } while (0)
; #define PG8_LDB(dst, b, h) do { const int b1_ = opqv(boff0) ^ 64; _Pragma("unroll") for (int n = 0; n < 2; ++n) { dst[n][0] = *(const LAS bf16x8*)(lds + PG8_SB(b, h) + boff0 + n * 2048); dst[n][1] = *(const LAS bf16x8*)(lds + PG8_SB(b, h) + b1_ + n * 2048); } } while (0)
; #define PG8_MMA(ai, bj, At, Bt) do { __builtin_amdgcn_s_setprio(1); _Pragma("unroll") for (int m = 0; m < 4; ++m) _Pragma("unroll") for (int n = 0; n < 2; ++n) _Pragma("unroll") for (int k = 0; k < 2; ++k) \
;         acc[ai][bj][m][n] = __builtin_amdgcn_mfma_f32_16x16x32_bf16(Bt[n][k], At[m][k], acc[ai][bj][m][n], 0, 0, 0); __builtin_amdgcn_s_setprio(0); } while (0)
; template <class Epi>
; __device__ __forceinline__ void gemm_phase(LAS unsigned char* lds, const Gemm g, const StaticOrder& S, const Epi& E, int wave_) {
;     ...
;         const bool has_next = S.next(ui + 1, nxt);
;         const char* nA = has_next ? (const char*)g.A + (size_t)nxt.pm * tstepA : cA; const char* nB = has_next ? (const char*)g.Bt + (size_t)nxt.pn * tstepB : cB;
; #pragma unroll 1
;         for (int t = 0; t < nt; t += 2) {
;             const bool last = (t == nt - 2);
;             const char* a1 = cA + (size_t)(t + 1) * kstep;
;             const char* a2 = last ? nA : cA + (size_t)(t + 2) * kstep; const char* b2 = last ? nB : cB + (size_t)(t + 2) * kstep;
;             const char* a3 = a2 + kstep; const char* b3 = b2 + kstep;
;             PG8_STAGE(PG8_SA(1, 1), a1 + hstepA, voffA); PG8_LDB(B0, 0, 0); PG8_LDB(B1, 0, 1); PG8_SCHED; PG8_LDA(At, 0, 0);
;             PG8_WAIT_V(8); PG8_WAIT_L(0); PG8_BAR; PG8_MMA(0, 0, At, B0); PG8_MMA(0, 1, At, B1); PG8_BAR; PG8_SCHED;
;             PG8_STAGE(PG8_SB(0, 0), b2, voffB); PG8_STAGE(PG8_SB(0, 1), b2 + hstepB, voffB); PG8_STAGE(PG8_SA(0, 0), a2, voffA); PG8_LDA(At, 0, 1);
;             PG8_WAIT_V(8); PG8_WAIT_L(0); PG8_BAR; PG8_MMA(1, 0, At, B0); PG8_MMA(1, 1, At, B1); PG8_BAR; PG8_SCHED;
.LBB0_1321:
	s_ashr_i32 s25, s24, 31
	s_lshl_b64 s[16:17], s[24:25], 20
	s_add_u32 s26, s21, s16
	s_addc_u32 s27, s46, s17
	s_and_b64 s[16:17], s[42:43], exec
	s_cselect_b32 s16, s27, s37
	s_cselect_b32 s17, s26, s36
	s_ashr_i32 s19, s18, 31
	s_lshl_b64 s[30:31], s[18:19], 20
	s_add_u32 s30, s47, s30
	s_addc_u32 s31, s48, s31
	s_and_b64 s[40:41], s[42:43], exec
	s_cselect_b32 s19, s31, s13
	s_cselect_b32 s25, s30, s12
	s_add_u32 s55, s12, 0x100
	s_addc_u32 s56, s13, 0
	s_add_u32 s12, s36, 0x80080
	s_addc_u32 s13, s37, 0
	s_mov_b32 s57, -2
	s_add_u32 s36, s12, 0xfff80080
	s_addc_u32 s37, s13, -1
	s_cmp_eq_u32 s57, 28
	s_cselect_b32 s44, s17, s36
	s_cselect_b32 s45, s16, s37
	s_cselect_b32 s40, s25, s55
	s_cselect_b32 s41, s19, s56
	s_add_u32 s36, s44, 0x80
	v_mov_b32_e32 v128, v178
	s_addc_u32 s37, s45, 0
	v_add_u32_e32 v132, s23, v178
	v_xad_u32 v140, v128, 64, s23
	v_mov_b32_e32 v144, v178
	s_add_i32 s60, 0, 0x14000
	ds_read_b128 v[128:131], v132
	ds_read_b128 v[132:135], v132 offset:2048
	ds_read_b128 v[136:139], v140
	ds_read_b128 v[140:143], v140 offset:2048
	v_add_u32_e32 v148, s60, v178
	v_xad_u32 v156, v144, 64, s60
	ds_read_b128 v[144:147], v148
	ds_read_b128 v[148:151], v148 offset:2048
	ds_read_b128 v[152:155], v156
	ds_read_b128 v[156:159], v156 offset:2048
	v_mov_b32_e32 v160, v177
	v_add_u32_e32 v169, 0, v177
	v_xad_u32 v168, v160, 64, 0
	ds_read_b128 v[160:163], v169
	ds_read_b128 v[164:167], v169 offset:2048
	ds_read_b128 v[180:183], v168
	ds_read_b128 v[192:195], v168 offset:2048
	ds_read_b128 v[196:199], v169 offset:4096
	ds_read_b128 v[200:203], v169 offset:6144
	ds_read_b128 v[204:207], v168 offset:4096
	ds_read_b128 v[208:211], v168 offset:6144
	s_mov_b32 m0, s14
	s_nop 0
	global_load_lds_dwordx4 v172, s[12:13]
	s_mov_b32 m0, s15
	s_nop 0
	global_load_lds_dwordx4 v174, s[12:13]
	s_waitcnt vmcnt(8)
	s_waitcnt lgkmcnt(0)
	s_setprio 1
	s_barrier
	v_mfma_f32_16x16x32_bf16 v[124:127], v[128:131], v[160:163], 0
	v_mfma_f32_16x16x32_bf16 v[120:123], v[132:135], v[160:163], 0
	v_mfma_f32_16x16x32_bf16 v[108:111], v[128:131], v[164:167], 0
	v_mfma_f32_16x16x32_bf16 v[104:107], v[132:135], v[164:167], 0
	v_mfma_f32_16x16x32_bf16 v[92:95], v[128:131], v[196:199], 0
	v_mfma_f32_16x16x32_bf16 v[88:91], v[132:135], v[196:199], 0
	v_mfma_f32_16x16x32_bf16 v[76:79], v[128:131], v[200:203], 0
	v_mfma_f32_16x16x32_bf16 v[72:75], v[132:135], v[200:203], 0
	v_mfma_f32_16x16x32_bf16 v[124:127], v[136:139], v[180:183], v[124:127]
	v_mfma_f32_16x16x32_bf16 v[120:123], v[140:143], v[180:183], v[120:123]
	v_mfma_f32_16x16x32_bf16 v[108:111], v[136:139], v[192:195], v[108:111]
	v_mfma_f32_16x16x32_bf16 v[104:107], v[140:143], v[192:195], v[104:107]
	v_mfma_f32_16x16x32_bf16 v[92:95], v[136:139], v[204:207], v[92:95]
	v_mfma_f32_16x16x32_bf16 v[88:91], v[140:143], v[204:207], v[88:91]
	v_mfma_f32_16x16x32_bf16 v[76:79], v[136:139], v[208:211], v[76:79]
	v_mfma_f32_16x16x32_bf16 v[72:75], v[140:143], v[208:211], v[72:75]
	s_setprio 0
	s_setprio 1
	v_mfma_f32_16x16x32_bf16 v[116:119], v[144:147], v[160:163], 0
	v_mfma_f32_16x16x32_bf16 v[112:115], v[148:151], v[160:163], 0
	v_mfma_f32_16x16x32_bf16 v[100:103], v[144:147], v[164:167], 0
	v_mfma_f32_16x16x32_bf16 v[96:99], v[148:151], v[164:167], 0
	v_mfma_f32_16x16x32_bf16 v[84:87], v[144:147], v[196:199], 0
	v_mfma_f32_16x16x32_bf16 v[80:83], v[148:151], v[196:199], 0
	v_mfma_f32_16x16x32_bf16 v[68:71], v[144:147], v[200:203], 0
	v_mfma_f32_16x16x32_bf16 v[64:67], v[148:151], v[200:203], 0
	v_mfma_f32_16x16x32_bf16 v[116:119], v[152:155], v[180:183], v[116:119]
	v_mfma_f32_16x16x32_bf16 v[112:115], v[156:159], v[180:183], v[112:115]
	v_mfma_f32_16x16x32_bf16 v[100:103], v[152:155], v[192:195], v[100:103]
	v_mfma_f32_16x16x32_bf16 v[96:99], v[156:159], v[192:195], v[96:99]
	v_mfma_f32_16x16x32_bf16 v[84:87], v[152:155], v[204:207], v[84:87]
	v_mfma_f32_16x16x32_bf16 v[80:83], v[156:159], v[204:207], v[80:83]
	v_mfma_f32_16x16x32_bf16 v[68:71], v[152:155], v[208:211], v[68:71]
	v_mfma_f32_16x16x32_bf16 v[64:67], v[156:159], v[208:211], v[64:67]
	s_barrier
	s_setprio 0
	v_mov_b32_e32 v160, v177
	s_add_u32 s60, s40, 0x80000
	s_addc_u32 s61, s41, 0
	s_nop 0
	s_nop 0
	s_nop 0
	v_xad_u32 v168, v160, 64, 0
	ds_read_b128 v[160:163], v169 offset:16384
	ds_read_b128 v[164:167], v169 offset:18432
	ds_read_b128 v[180:183], v168 offset:16384
	ds_read_b128 v[192:195], v168 offset:18432
	ds_read_b128 v[196:199], v169 offset:20480
	ds_read_b128 v[200:203], v169 offset:22528
	ds_read_b128 v[204:207], v168 offset:20480
	ds_read_b128 v[208:211], v168 offset:22528
	s_mov_b32 m0, s80
	s_nop 0
	global_load_lds_dwordx4 v173, s[40:41]
	s_mov_b32 m0, s81
	s_nop 0
	global_load_lds_dwordx4 v175, s[40:41]
	s_mov_b32 m0, s29
	s_nop 0
	global_load_lds_dwordx4 v173, s[60:61]
	s_mov_b32 m0, s88
	s_nop 0
	global_load_lds_dwordx4 v175, s[60:61]
	s_mov_b32 m0, s76
	s_nop 0
	global_load_lds_dwordx4 v172, s[44:45]
	s_mov_b32 m0, s89
	s_nop 0
	global_load_lds_dwordx4 v174, s[44:45]
	s_waitcnt vmcnt(8)
	s_waitcnt lgkmcnt(0)
	s_setprio 1
	s_barrier
; #define PG8_STAGE(bufoff, gbase, voff) do { _Pragma("unroll") for (int _i = 0; _i < 2; ++_i) \
;         dma16((const char*)(gbase), (voff)[_i], ldsb + (bufoff) + ldsw + _i * 8192); } while (0)
; #define PG8_LDA(dst, b, h) do { const int a1_ = opqv(aoff0) ^ 64; _Pragma("unroll") for (int m = 0; m < 4; ++m) { dst[m][0] = *(const LAS bf16x8*)(lds + PG8_SA(b, h) + aoff0 + m * 2048); dst[m][1] = *(const LAS bf16x8*)(lds + PG8_SA(b, h) + a1_ + m * 2048); } } while (0)
; #define PG8_LDB(dst, b, h) do { const int b1_ = opqv(boff0) ^ 64; _Pragma("unroll") for (int n = 0; n < 2; ++n) { dst[n][0] = *(const LAS bf16x8*)(lds + PG8_SB(b, h) + boff0 + n * 2048); dst[n][1] = *(const LAS bf16x8*)(lds + PG8_SB(b, h) + b1_ + n * 2048); } } while (0)
; #define PG8_MMA(ai, bj, At, Bt) do { __builtin_amdgcn_s_setprio(1); _Pragma("unroll") for (int m = 0; m < 4; ++m) _Pragma("unroll") for (int n = 0; n < 2; ++n) _Pragma("unroll") for (int k = 0; k < 2; ++k) \
;         acc[ai][bj][m][n] = __builtin_amdgcn_mfma_f32_16x16x32_bf16(Bt[n][k], At[m][k], acc[ai][bj][m][n], 0, 0, 0); __builtin_amdgcn_s_setprio(0); } while (0)
; #define PG8_WAIT_V(n) asm volatile("s_waitcnt vmcnt(" #n ")" ::: "memory")
; #define PG8_WAIT_L(n) asm volatile("s_waitcnt lgkmcnt(" #n ")" ::: "memory")
; #define PG8_BAR __builtin_amdgcn_s_barrier()
; #define PG8_SCHED __builtin_amdgcn_sched_barrier(0)
; template <class Epi>
; __device__ __forceinline__ void gemm_phase(LAS unsigned char* lds, const Gemm g, const StaticOrder& S, const Epi& E, int wave_) {
;     ...
;             PG8_WAIT_V(8); PG8_WAIT_L(0); PG8_BAR; PG8_MMA(1, 0, At, B0); PG8_MMA(1, 1, At, B1); PG8_BAR; PG8_SCHED;
;             PG8_STAGE(PG8_SA(0, 1), a2 + hstepA, voffA); PG8_LDB(B0, 1, 0); PG8_LDB(B1, 1, 1); PG8_SCHED; PG8_LDA(At, 1, 0);
;             PG8_WAIT_V(8); PG8_WAIT_L(0); PG8_BAR; PG8_MMA(0, 0, At, B0); PG8_MMA(0, 1, At, B1); PG8_BAR; PG8_SCHED;
	v_mfma_f32_16x16x32_bf16 v[60:63], v[128:131], v[160:163], 0
	v_mfma_f32_16x16x32_bf16 v[56:59], v[132:135], v[160:163], 0
	v_mfma_f32_16x16x32_bf16 v[44:47], v[128:131], v[164:167], 0
	v_mfma_f32_16x16x32_bf16 v[40:43], v[132:135], v[164:167], 0
	v_mfma_f32_16x16x32_bf16 v[28:31], v[128:131], v[196:199], 0
	v_mfma_f32_16x16x32_bf16 v[24:27], v[132:135], v[196:199], 0
	v_mfma_f32_16x16x32_bf16 v[12:15], v[128:131], v[200:203], 0
	v_mfma_f32_16x16x32_bf16 v[8:11], v[132:135], v[200:203], 0
	v_mfma_f32_16x16x32_bf16 v[60:63], v[136:139], v[180:183], v[60:63]
	v_mfma_f32_16x16x32_bf16 v[56:59], v[140:143], v[180:183], v[56:59]
	v_mfma_f32_16x16x32_bf16 v[44:47], v[136:139], v[192:195], v[44:47]
	v_mfma_f32_16x16x32_bf16 v[40:43], v[140:143], v[192:195], v[40:43]
	v_mfma_f32_16x16x32_bf16 v[28:31], v[136:139], v[204:207], v[28:31]
	v_mfma_f32_16x16x32_bf16 v[24:27], v[140:143], v[204:207], v[24:27]
	v_mfma_f32_16x16x32_bf16 v[12:15], v[136:139], v[208:211], v[12:15]
	v_mfma_f32_16x16x32_bf16 v[8:11], v[140:143], v[208:211], v[8:11]
	s_setprio 0
	s_setprio 1
	v_mfma_f32_16x16x32_bf16 v[52:55], v[144:147], v[160:163], 0
	v_mfma_f32_16x16x32_bf16 v[48:51], v[148:151], v[160:163], 0
	v_mfma_f32_16x16x32_bf16 v[36:39], v[144:147], v[164:167], 0
	v_mfma_f32_16x16x32_bf16 v[32:35], v[148:151], v[164:167], 0
	v_mfma_f32_16x16x32_bf16 v[20:23], v[144:147], v[196:199], 0
	v_mfma_f32_16x16x32_bf16 v[16:19], v[148:151], v[196:199], 0
	v_mfma_f32_16x16x32_bf16 v[4:7], v[144:147], v[200:203], 0
	v_mfma_f32_16x16x32_bf16 v[0:3], v[148:151], v[200:203], 0
	v_mfma_f32_16x16x32_bf16 v[52:55], v[152:155], v[180:183], v[52:55]
	v_mfma_f32_16x16x32_bf16 v[48:51], v[156:159], v[180:183], v[48:51]
	v_mfma_f32_16x16x32_bf16 v[36:39], v[152:155], v[192:195], v[36:39]
	v_mfma_f32_16x16x32_bf16 v[32:35], v[156:159], v[192:195], v[32:35]
	v_mfma_f32_16x16x32_bf16 v[20:23], v[152:155], v[204:207], v[20:23]
	v_mfma_f32_16x16x32_bf16 v[16:19], v[156:159], v[204:207], v[16:19]
	v_mfma_f32_16x16x32_bf16 v[4:7], v[152:155], v[208:211], v[4:7]
	v_mfma_f32_16x16x32_bf16 v[0:3], v[156:159], v[208:211], v[0:3]
	s_barrier
	s_setprio 0
	s_add_u32 s44, s44, 0x80000
	s_addc_u32 s45, s45, 0
	s_mov_b32 m0, s1
	s_nop 0
	global_load_lds_dwordx4 v172, s[44:45]
	v_mov_b32_e32 v128, v178
	s_mov_b32 m0, s69
	s_nop 0
	global_load_lds_dwordx4 v174, s[44:45]
	v_add_u32_e32 v132, s34, v178
	v_xad_u32 v140, v128, 64, s34
	v_mov_b32_e32 v144, v178
	s_add_i32 s44, 0, 0x1c000
	ds_read_b128 v[128:131], v132
	ds_read_b128 v[132:135], v132 offset:2048
	ds_read_b128 v[136:139], v140
	ds_read_b128 v[140:143], v140 offset:2048
	v_add_u32_e32 v148, s44, v178
	v_xad_u32 v156, v144, 64, s44
	ds_read_b128 v[144:147], v148
	ds_read_b128 v[148:151], v148 offset:2048
	ds_read_b128 v[152:155], v156
	ds_read_b128 v[156:159], v156 offset:2048
	v_mov_b32_e32 v160, v177
	s_nop 0
	v_xad_u32 v168, v160, 64, 0
	ds_read_b128 v[160:163], v169 offset:32768
	ds_read_b128 v[164:167], v169 offset:34816
	ds_read_b128 v[180:183], v168 offset:32768
	ds_read_b128 v[192:195], v168 offset:34816
	ds_read_b128 v[196:199], v169 offset:36864
	ds_read_b128 v[200:203], v169 offset:38912
	ds_read_b128 v[204:207], v168 offset:36864
	ds_read_b128 v[208:211], v168 offset:38912
	s_waitcnt vmcnt(8)
	s_waitcnt lgkmcnt(0)
	s_setprio 1
	s_barrier
	v_mfma_f32_16x16x32_bf16 v[124:127], v[128:131], v[160:163], v[124:127]
	v_mfma_f32_16x16x32_bf16 v[120:123], v[132:135], v[160:163], v[120:123]
	v_mfma_f32_16x16x32_bf16 v[108:111], v[128:131], v[164:167], v[108:111]
	v_mfma_f32_16x16x32_bf16 v[104:107], v[132:135], v[164:167], v[104:107]
	v_mfma_f32_16x16x32_bf16 v[92:95], v[128:131], v[196:199], v[92:95]
	v_mfma_f32_16x16x32_bf16 v[88:91], v[132:135], v[196:199], v[88:91]
	v_mfma_f32_16x16x32_bf16 v[76:79], v[128:131], v[200:203], v[76:79]
	v_mfma_f32_16x16x32_bf16 v[72:75], v[132:135], v[200:203], v[72:75]
	v_mfma_f32_16x16x32_bf16 v[124:127], v[136:139], v[180:183], v[124:127]
	v_mfma_f32_16x16x32_bf16 v[120:123], v[140:143], v[180:183], v[120:123]
	v_mfma_f32_16x16x32_bf16 v[108:111], v[136:139], v[192:195], v[108:111]
	v_mfma_f32_16x16x32_bf16 v[104:107], v[140:143], v[192:195], v[104:107]
	v_mfma_f32_16x16x32_bf16 v[92:95], v[136:139], v[204:207], v[92:95]
	v_mfma_f32_16x16x32_bf16 v[88:91], v[140:143], v[204:207], v[88:91]
	v_mfma_f32_16x16x32_bf16 v[76:79], v[136:139], v[208:211], v[76:79]
	v_mfma_f32_16x16x32_bf16 v[72:75], v[140:143], v[208:211], v[72:75]
	s_setprio 0
	s_setprio 1
	v_mfma_f32_16x16x32_bf16 v[116:119], v[144:147], v[160:163], v[116:119]
	s_add_u32 s44, s40, 0x80
	s_addc_u32 s45, s41, 0
	v_mfma_f32_16x16x32_bf16 v[112:115], v[148:151], v[160:163], v[112:115]
	v_mfma_f32_16x16x32_bf16 v[100:103], v[144:147], v[164:167], v[100:103]
	v_mfma_f32_16x16x32_bf16 v[96:99], v[148:151], v[164:167], v[96:99]
	v_mfma_f32_16x16x32_bf16 v[84:87], v[144:147], v[196:199], v[84:87]
	v_mfma_f32_16x16x32_bf16 v[80:83], v[148:151], v[196:199], v[80:83]
	v_mfma_f32_16x16x32_bf16 v[68:71], v[144:147], v[200:203], v[68:71]
	v_mfma_f32_16x16x32_bf16 v[64:67], v[148:151], v[200:203], v[64:67]
	v_mfma_f32_16x16x32_bf16 v[116:119], v[152:155], v[180:183], v[116:119]
	v_mfma_f32_16x16x32_bf16 v[112:115], v[156:159], v[180:183], v[112:115]
	v_mfma_f32_16x16x32_bf16 v[100:103], v[152:155], v[192:195], v[100:103]
	v_mfma_f32_16x16x32_bf16 v[96:99], v[156:159], v[192:195], v[96:99]
	v_mfma_f32_16x16x32_bf16 v[84:87], v[152:155], v[204:207], v[84:87]
	v_mfma_f32_16x16x32_bf16 v[80:83], v[156:159], v[204:207], v[80:83]
	v_mfma_f32_16x16x32_bf16 v[68:71], v[152:155], v[208:211], v[68:71]
	v_mfma_f32_16x16x32_bf16 v[64:67], v[156:159], v[208:211], v[64:67]
	s_barrier
; #define PG8_STAGE(bufoff, gbase, voff) do { _Pragma("unroll") for (int _i = 0; _i < 2; ++_i) \
;         dma16((const char*)(gbase), (voff)[_i], ldsb + (bufoff) + ldsw + _i * 8192); } while (0)
; #define PG8_LDA(dst, b, h) do { const int a1_ = opqv(aoff0) ^ 64; _Pragma("unroll") for (int m = 0; m < 4; ++m) { dst[m][0] = *(const LAS bf16x8*)(lds + PG8_SA(b, h) + aoff0 + m * 2048); dst[m][1] = *(const LAS bf16x8*)(lds + PG8_SA(b, h) + a1_ + m * 2048); } } while (0)
; #define PG8_LDB(dst, b, h) do { const int b1_ = opqv(boff0) ^ 64; _Pragma("unroll") for (int n = 0; n < 2; ++n) { dst[n][0] = *(const LAS bf16x8*)(lds + PG8_SB(b, h) + boff0 + n * 2048); dst[n][1] = *(const LAS bf16x8*)(lds + PG8_SB(b, h) + b1_ + n * 2048); } } while (0)
; #define PG8_WAIT_V(n) asm volatile("s_waitcnt vmcnt(" #n ")" ::: "memory")
; template <class Epi>
; __device__ __forceinline__ void gemm_phase(LAS unsigned char* lds, const Gemm g, const StaticOrder& S, const Epi& E, int wave_) {
;     ...
;         for (int t = 0; t < nt; t += 2) {
;             const bool last = (t == nt - 2);
;             const char* a1 = cA + (size_t)(t + 1) * kstep;
;             const char* a2 = last ? nA : cA + (size_t)(t + 2) * kstep; const char* b2 = last ? nB : cB + (size_t)(t + 2) * kstep;
;             const char* a3 = a2 + kstep; const char* b3 = b2 + kstep;
;             PG8_STAGE(PG8_SA(1, 1), a1 + hstepA, voffA); PG8_LDB(B0, 0, 0); PG8_LDB(B1, 0, 1); PG8_SCHED; PG8_LDA(At, 0, 0);
;             PG8_WAIT_V(8); PG8_WAIT_L(0); PG8_BAR; PG8_MMA(0, 0, At, B0); PG8_MMA(0, 1, At, B1); PG8_BAR; PG8_SCHED;
;             PG8_STAGE(PG8_SB(0, 0), b2, voffB); PG8_STAGE(PG8_SB(0, 1), b2 + hstepB, voffB); PG8_STAGE(PG8_SA(0, 0), a2, voffA); PG8_LDA(At, 0, 1);
;             PG8_WAIT_V(8); PG8_WAIT_L(0); PG8_BAR; PG8_MMA(1, 0, At, B0); PG8_MMA(1, 1, At, B1); PG8_BAR; PG8_SCHED;
;             PG8_STAGE(PG8_SA(0, 1), a2 + hstepA, voffA); PG8_LDB(B0, 1, 0); PG8_LDB(B1, 1, 1); PG8_SCHED; PG8_LDA(At, 1, 0);
;             PG8_WAIT_V(8); PG8_WAIT_L(0); PG8_BAR; PG8_MMA(0, 0, At, B0); PG8_MMA(0, 1, At, B1); PG8_BAR; PG8_SCHED;
;             PG8_STAGE(PG8_SB(1, 0), b3, voffB); PG8_STAGE(PG8_SB(1, 1), b3 + hstepB, voffB); PG8_STAGE(PG8_SA(1, 0), a3, voffA); PG8_LDA(At, 1, 1);
;             PG8_WAIT_V(8); PG8_WAIT_L(0); PG8_BAR; PG8_MMA(1, 0, At, B0); PG8_MMA(1, 1, At, B1); PG8_BAR; PG8_SCHED;
	s_setprio 0
	s_add_u32 s40, s40, 0x80080
	s_addc_u32 s41, s41, 0
	v_mov_b32_e32 v160, v177
	s_nop 0
	s_nop 0
	v_xad_u32 v168, v160, 64, 0
	ds_read_b128 v[160:163], v169 offset:49152
	ds_read_b128 v[164:167], v169 offset:51200
	ds_read_b128 v[180:183], v168 offset:49152
	ds_read_b128 v[192:195], v168 offset:51200
	ds_read_b128 v[196:199], v169 offset:53248
	ds_read_b128 v[200:203], v169 offset:55296
	ds_read_b128 v[204:207], v168 offset:53248
	ds_read_b128 v[208:211], v168 offset:55296
	s_mov_b32 m0, s35
	s_nop 0
	global_load_lds_dwordx4 v173, s[44:45]
	s_mov_b32 m0, s33
	s_nop 0
	global_load_lds_dwordx4 v175, s[44:45]
	s_mov_b32 m0, s77
	s_nop 0
	global_load_lds_dwordx4 v173, s[40:41]
	s_mov_b32 m0, s3
	s_nop 0
	global_load_lds_dwordx4 v175, s[40:41]
	s_mov_b32 m0, s22
	s_nop 0
	global_load_lds_dwordx4 v172, s[36:37]
	s_mov_b32 m0, s2
	s_nop 0
	global_load_lds_dwordx4 v174, s[36:37]
	s_waitcnt vmcnt(8)
	s_waitcnt lgkmcnt(0)
	s_setprio 1
	s_barrier
	v_mfma_f32_16x16x32_bf16 v[60:63], v[128:131], v[160:163], v[60:63]
	v_mfma_f32_16x16x32_bf16 v[56:59], v[132:135], v[160:163], v[56:59]
	v_mfma_f32_16x16x32_bf16 v[44:47], v[128:131], v[164:167], v[44:47]
	v_mfma_f32_16x16x32_bf16 v[40:43], v[132:135], v[164:167], v[40:43]
	v_mfma_f32_16x16x32_bf16 v[28:31], v[128:131], v[196:199], v[28:31]
	v_mfma_f32_16x16x32_bf16 v[24:27], v[132:135], v[196:199], v[24:27]
	v_mfma_f32_16x16x32_bf16 v[12:15], v[128:131], v[200:203], v[12:15]
	v_mfma_f32_16x16x32_bf16 v[8:11], v[132:135], v[200:203], v[8:11]
	v_mfma_f32_16x16x32_bf16 v[60:63], v[136:139], v[180:183], v[60:63]
	v_mfma_f32_16x16x32_bf16 v[56:59], v[140:143], v[180:183], v[56:59]
	v_mfma_f32_16x16x32_bf16 v[44:47], v[136:139], v[192:195], v[44:47]
	v_mfma_f32_16x16x32_bf16 v[40:43], v[140:143], v[192:195], v[40:43]
	v_mfma_f32_16x16x32_bf16 v[28:31], v[136:139], v[204:207], v[28:31]
	v_mfma_f32_16x16x32_bf16 v[24:27], v[140:143], v[204:207], v[24:27]
	v_mfma_f32_16x16x32_bf16 v[12:15], v[136:139], v[208:211], v[12:15]
	v_mfma_f32_16x16x32_bf16 v[8:11], v[140:143], v[208:211], v[8:11]
	s_setprio 0
	s_setprio 1
	v_mfma_f32_16x16x32_bf16 v[52:55], v[144:147], v[160:163], v[52:55]
	v_mfma_f32_16x16x32_bf16 v[48:51], v[148:151], v[160:163], v[48:51]
	v_mfma_f32_16x16x32_bf16 v[36:39], v[144:147], v[164:167], v[36:39]
	v_mfma_f32_16x16x32_bf16 v[32:35], v[148:151], v[164:167], v[32:35]
	v_mfma_f32_16x16x32_bf16 v[20:23], v[144:147], v[196:199], v[20:23]
	v_mfma_f32_16x16x32_bf16 v[16:19], v[148:151], v[196:199], v[16:19]
	v_mfma_f32_16x16x32_bf16 v[4:7], v[144:147], v[200:203], v[4:7]
	v_mfma_f32_16x16x32_bf16 v[0:3], v[148:151], v[200:203], v[0:3]
	v_mfma_f32_16x16x32_bf16 v[52:55], v[152:155], v[180:183], v[52:55]
	v_mfma_f32_16x16x32_bf16 v[48:51], v[156:159], v[180:183], v[48:51]
	v_mfma_f32_16x16x32_bf16 v[36:39], v[152:155], v[192:195], v[36:39]
	v_mfma_f32_16x16x32_bf16 v[32:35], v[156:159], v[192:195], v[32:35]
	v_mfma_f32_16x16x32_bf16 v[20:23], v[152:155], v[204:207], v[20:23]
	v_mfma_f32_16x16x32_bf16 v[16:19], v[156:159], v[204:207], v[16:19]
	v_mfma_f32_16x16x32_bf16 v[4:7], v[152:155], v[208:211], v[4:7]
	v_mfma_f32_16x16x32_bf16 v[0:3], v[156:159], v[208:211], v[0:3]
	s_barrier
	s_setprio 0
	s_add_i32 s57, s57, 2
	s_add_u32 s55, s55, 0x100
	s_addc_u32 s56, s56, 0
	s_add_u32 s12, s12, 0x100
	s_addc_u32 s13, s13, 0
	s_cmp_gt_u32 s57, 29
	s_cbranch_scc0 .LBB0_1322
	s_branch .Lpeel_exit_3
.LBB0_1322:
	s_add_u32 s36, s12, 0xfff80080
	s_addc_u32 s37, s13, -1
	s_cmp_eq_u32 s57, 28
	s_cselect_b32 s44, s17, s36
	s_cselect_b32 s45, s16, s37
	s_cselect_b32 s40, s25, s55
	s_cselect_b32 s41, s19, s56
	s_add_u32 s36, s44, 0x80
	v_mov_b32_e32 v128, v178
	s_addc_u32 s37, s45, 0
	v_add_u32_e32 v132, s23, v178
	v_xad_u32 v140, v128, 64, s23
	v_mov_b32_e32 v144, v178
	s_add_i32 s60, 0, 0x14000
	ds_read_b128 v[128:131], v132
	ds_read_b128 v[132:135], v132 offset:2048
	ds_read_b128 v[136:139], v140
	ds_read_b128 v[140:143], v140 offset:2048
	v_add_u32_e32 v148, s60, v178
	v_xad_u32 v156, v144, 64, s60
	ds_read_b128 v[144:147], v148
	ds_read_b128 v[148:151], v148 offset:2048
	ds_read_b128 v[152:155], v156
	ds_read_b128 v[156:159], v156 offset:2048
	v_mov_b32_e32 v160, v177
	v_add_u32_e32 v169, 0, v177
	v_xad_u32 v168, v160, 64, 0
	ds_read_b128 v[160:163], v169
	ds_read_b128 v[164:167], v169 offset:2048
	ds_read_b128 v[180:183], v168
	ds_read_b128 v[192:195], v168 offset:2048
	ds_read_b128 v[196:199], v169 offset:4096
	ds_read_b128 v[200:203], v169 offset:6144
	ds_read_b128 v[204:207], v168 offset:4096
	ds_read_b128 v[208:211], v168 offset:6144
	s_mov_b32 m0, s14
	s_nop 0
	global_load_lds_dwordx4 v172, s[12:13]
	s_mov_b32 m0, s15
	s_nop 0
	global_load_lds_dwordx4 v174, s[12:13]
	s_waitcnt vmcnt(8)
	s_waitcnt lgkmcnt(0)
	s_setprio 1
	s_barrier
; #define PG8_STAGE(bufoff, gbase, voff) do { _Pragma("unroll") for (int _i = 0; _i < 2; ++_i) \
;         dma16((const char*)(gbase), (voff)[_i], ldsb + (bufoff) + ldsw + _i * 8192); } while (0)
; #define PG8_LDA(dst, b, h) do { const int a1_ = opqv(aoff0) ^ 64; _Pragma("unroll") for (int m = 0; m < 4; ++m) { dst[m][0] = *(const LAS bf16x8*)(lds + PG8_SA(b, h) + aoff0 + m * 2048); dst[m][1] = *(const LAS bf16x8*)(lds + PG8_SA(b, h) + a1_ + m * 2048); } } while (0)
; #define PG8_LDB(dst, b, h) do { const int b1_ = opqv(boff0) ^ 64; _Pragma("unroll") for (int n = 0; n < 2; ++n) { dst[n][0] = *(const LAS bf16x8*)(lds + PG8_SB(b, h) + boff0 + n * 2048); dst[n][1] = *(const LAS bf16x8*)(lds + PG8_SB(b, h) + b1_ + n * 2048); } } while (0)
; #define PG8_MMA(ai, bj, At, Bt) do { __builtin_amdgcn_s_setprio(1); _Pragma("unroll") for (int m = 0; m < 4; ++m) _Pragma("unroll") for (int n = 0; n < 2; ++n) _Pragma("unroll") for (int k = 0; k < 2; ++k) \
;         acc[ai][bj][m][n] = __builtin_amdgcn_mfma_f32_16x16x32_bf16(Bt[n][k], At[m][k], acc[ai][bj][m][n], 0, 0, 0); __builtin_amdgcn_s_setprio(0); } while (0)
; #define PG8_WAIT_V(n) asm volatile("s_waitcnt vmcnt(" #n ")" ::: "memory")
; #define PG8_WAIT_L(n) asm volatile("s_waitcnt lgkmcnt(" #n ")" ::: "memory")
; #define PG8_BAR __builtin_amdgcn_s_barrier()
; #define PG8_SCHED __builtin_amdgcn_sched_barrier(0)
; template <class Epi>
; __device__ __forceinline__ void gemm_phase(LAS unsigned char* lds, const Gemm g, const StaticOrder& S, const Epi& E, int wave_) {
;     ...
;             PG8_STAGE(PG8_SA(1, 1), a1 + hstepA, voffA); PG8_LDB(B0, 0, 0); PG8_LDB(B1, 0, 1); PG8_SCHED; PG8_LDA(At, 0, 0);
;             PG8_WAIT_V(8); PG8_WAIT_L(0); PG8_BAR; PG8_MMA(0, 0, At, B0); PG8_MMA(0, 1, At, B1); PG8_BAR; PG8_SCHED;
;             PG8_STAGE(PG8_SB(0, 0), b2, voffB); PG8_STAGE(PG8_SB(0, 1), b2 + hstepB, voffB); PG8_STAGE(PG8_SA(0, 0), a2, voffA); PG8_LDA(At, 0, 1);
;             PG8_WAIT_V(8); PG8_WAIT_L(0); PG8_BAR; PG8_MMA(1, 0, At, B0); PG8_MMA(1, 1, At, B1); PG8_BAR; PG8_SCHED;
	v_mfma_f32_16x16x32_bf16 v[124:127], v[128:131], v[160:163], v[124:127]
	v_mfma_f32_16x16x32_bf16 v[120:123], v[132:135], v[160:163], v[120:123]
	v_mfma_f32_16x16x32_bf16 v[108:111], v[128:131], v[164:167], v[108:111]
	v_mfma_f32_16x16x32_bf16 v[104:107], v[132:135], v[164:167], v[104:107]
	v_mfma_f32_16x16x32_bf16 v[92:95], v[128:131], v[196:199], v[92:95]
	v_mfma_f32_16x16x32_bf16 v[88:91], v[132:135], v[196:199], v[88:91]
	v_mfma_f32_16x16x32_bf16 v[76:79], v[128:131], v[200:203], v[76:79]
	v_mfma_f32_16x16x32_bf16 v[72:75], v[132:135], v[200:203], v[72:75]
	v_mfma_f32_16x16x32_bf16 v[124:127], v[136:139], v[180:183], v[124:127]
	v_mfma_f32_16x16x32_bf16 v[120:123], v[140:143], v[180:183], v[120:123]
	v_mfma_f32_16x16x32_bf16 v[108:111], v[136:139], v[192:195], v[108:111]
	v_mfma_f32_16x16x32_bf16 v[104:107], v[140:143], v[192:195], v[104:107]
	v_mfma_f32_16x16x32_bf16 v[92:95], v[136:139], v[204:207], v[92:95]
	v_mfma_f32_16x16x32_bf16 v[88:91], v[140:143], v[204:207], v[88:91]
	v_mfma_f32_16x16x32_bf16 v[76:79], v[136:139], v[208:211], v[76:79]
	v_mfma_f32_16x16x32_bf16 v[72:75], v[140:143], v[208:211], v[72:75]
	s_setprio 0
	s_setprio 1
	v_mfma_f32_16x16x32_bf16 v[116:119], v[144:147], v[160:163], v[116:119]
	v_mfma_f32_16x16x32_bf16 v[112:115], v[148:151], v[160:163], v[112:115]
	v_mfma_f32_16x16x32_bf16 v[100:103], v[144:147], v[164:167], v[100:103]
	v_mfma_f32_16x16x32_bf16 v[96:99], v[148:151], v[164:167], v[96:99]
	v_mfma_f32_16x16x32_bf16 v[84:87], v[144:147], v[196:199], v[84:87]
	v_mfma_f32_16x16x32_bf16 v[80:83], v[148:151], v[196:199], v[80:83]
	v_mfma_f32_16x16x32_bf16 v[68:71], v[144:147], v[200:203], v[68:71]
	v_mfma_f32_16x16x32_bf16 v[64:67], v[148:151], v[200:203], v[64:67]
	v_mfma_f32_16x16x32_bf16 v[116:119], v[152:155], v[180:183], v[116:119]
	v_mfma_f32_16x16x32_bf16 v[112:115], v[156:159], v[180:183], v[112:115]
	v_mfma_f32_16x16x32_bf16 v[100:103], v[152:155], v[192:195], v[100:103]
	v_mfma_f32_16x16x32_bf16 v[96:99], v[156:159], v[192:195], v[96:99]
	v_mfma_f32_16x16x32_bf16 v[84:87], v[152:155], v[204:207], v[84:87]
	v_mfma_f32_16x16x32_bf16 v[80:83], v[156:159], v[204:207], v[80:83]
	v_mfma_f32_16x16x32_bf16 v[68:71], v[152:155], v[208:211], v[68:71]
	v_mfma_f32_16x16x32_bf16 v[64:67], v[156:159], v[208:211], v[64:67]
	s_barrier
	s_setprio 0
	v_mov_b32_e32 v160, v177
	s_add_u32 s60, s40, 0x80000
	s_addc_u32 s61, s41, 0
	s_nop 0
	s_nop 0
	s_nop 0
	v_xad_u32 v168, v160, 64, 0
	ds_read_b128 v[160:163], v169 offset:16384
	ds_read_b128 v[164:167], v169 offset:18432
	ds_read_b128 v[180:183], v168 offset:16384
	ds_read_b128 v[192:195], v168 offset:18432
	ds_read_b128 v[196:199], v169 offset:20480
	ds_read_b128 v[200:203], v169 offset:22528
	ds_read_b128 v[204:207], v168 offset:20480
	ds_read_b128 v[208:211], v168 offset:22528
	s_mov_b32 m0, s80
	s_nop 0
	global_load_lds_dwordx4 v173, s[40:41]
	s_mov_b32 m0, s81
	s_nop 0
	global_load_lds_dwordx4 v175, s[40:41]
	s_mov_b32 m0, s29
	s_nop 0
	global_load_lds_dwordx4 v173, s[60:61]
	s_mov_b32 m0, s88
	s_nop 0
	global_load_lds_dwordx4 v175, s[60:61]
	s_mov_b32 m0, s76
	s_nop 0
	global_load_lds_dwordx4 v172, s[44:45]
	s_mov_b32 m0, s89
	s_nop 0
	global_load_lds_dwordx4 v174, s[44:45]
	s_waitcnt vmcnt(8)
	s_waitcnt lgkmcnt(0)
	s_setprio 1
	s_barrier
	v_mfma_f32_16x16x32_bf16 v[60:63], v[128:131], v[160:163], v[60:63]
	v_mfma_f32_16x16x32_bf16 v[56:59], v[132:135], v[160:163], v[56:59]
	v_mfma_f32_16x16x32_bf16 v[44:47], v[128:131], v[164:167], v[44:47]
	v_mfma_f32_16x16x32_bf16 v[40:43], v[132:135], v[164:167], v[40:43]
	v_mfma_f32_16x16x32_bf16 v[28:31], v[128:131], v[196:199], v[28:31]
	v_mfma_f32_16x16x32_bf16 v[24:27], v[132:135], v[196:199], v[24:27]
	v_mfma_f32_16x16x32_bf16 v[12:15], v[128:131], v[200:203], v[12:15]
	v_mfma_f32_16x16x32_bf16 v[8:11], v[132:135], v[200:203], v[8:11]
	v_mfma_f32_16x16x32_bf16 v[60:63], v[136:139], v[180:183], v[60:63]
	v_mfma_f32_16x16x32_bf16 v[56:59], v[140:143], v[180:183], v[56:59]
	v_mfma_f32_16x16x32_bf16 v[44:47], v[136:139], v[192:195], v[44:47]
	v_mfma_f32_16x16x32_bf16 v[40:43], v[140:143], v[192:195], v[40:43]
	v_mfma_f32_16x16x32_bf16 v[28:31], v[136:139], v[204:207], v[28:31]
	v_mfma_f32_16x16x32_bf16 v[24:27], v[140:143], v[204:207], v[24:27]
	v_mfma_f32_16x16x32_bf16 v[12:15], v[136:139], v[208:211], v[12:15]
	v_mfma_f32_16x16x32_bf16 v[8:11], v[140:143], v[208:211], v[8:11]
	s_setprio 0
	s_setprio 1
	v_mfma_f32_16x16x32_bf16 v[52:55], v[144:147], v[160:163], v[52:55]
	v_mfma_f32_16x16x32_bf16 v[48:51], v[148:151], v[160:163], v[48:51]
	v_mfma_f32_16x16x32_bf16 v[36:39], v[144:147], v[164:167], v[36:39]
	v_mfma_f32_16x16x32_bf16 v[32:35], v[148:151], v[164:167], v[32:35]
	v_mfma_f32_16x16x32_bf16 v[20:23], v[144:147], v[196:199], v[20:23]
	v_mfma_f32_16x16x32_bf16 v[16:19], v[148:151], v[196:199], v[16:19]
	v_mfma_f32_16x16x32_bf16 v[4:7], v[144:147], v[200:203], v[4:7]
	v_mfma_f32_16x16x32_bf16 v[0:3], v[148:151], v[200:203], v[0:3]
	v_mfma_f32_16x16x32_bf16 v[52:55], v[152:155], v[180:183], v[52:55]
	v_mfma_f32_16x16x32_bf16 v[48:51], v[156:159], v[180:183], v[48:51]
	v_mfma_f32_16x16x32_bf16 v[36:39], v[152:155], v[192:195], v[36:39]
	v_mfma_f32_16x16x32_bf16 v[32:35], v[156:159], v[192:195], v[32:35]
	v_mfma_f32_16x16x32_bf16 v[20:23], v[152:155], v[204:207], v[20:23]
	v_mfma_f32_16x16x32_bf16 v[16:19], v[156:159], v[204:207], v[16:19]
	v_mfma_f32_16x16x32_bf16 v[4:7], v[152:155], v[208:211], v[4:7]
	v_mfma_f32_16x16x32_bf16 v[0:3], v[156:159], v[208:211], v[0:3]
	s_barrier
; #define PG8_STAGE(bufoff, gbase, voff) do { _Pragma("unroll") for (int _i = 0; _i < 2; ++_i) \
;         dma16((const char*)(gbase), (voff)[_i], ldsb + (bufoff) + ldsw + _i * 8192); } while (0)
; #define PG8_LDA(dst, b, h) do { const int a1_ = opqv(aoff0) ^ 64; _Pragma("unroll") for (int m = 0; m < 4; ++m) { dst[m][0] = *(const LAS bf16x8*)(lds + PG8_SA(b, h) + aoff0 + m * 2048); dst[m][1] = *(const LAS bf16x8*)(lds + PG8_SA(b, h) + a1_ + m * 2048); } } while (0)
; #define PG8_LDB(dst, b, h) do { const int b1_ = opqv(boff0) ^ 64; _Pragma("unroll") for (int n = 0; n < 2; ++n) { dst[n][0] = *(const LAS bf16x8*)(lds + PG8_SB(b, h) + boff0 + n * 2048); dst[n][1] = *(const LAS bf16x8*)(lds + PG8_SB(b, h) + b1_ + n * 2048); } } while (0)
; #define PG8_MMA(ai, bj, At, Bt) do { __builtin_amdgcn_s_setprio(1); _Pragma("unroll") for (int m = 0; m < 4; ++m) _Pragma("unroll") for (int n = 0; n < 2; ++n) _Pragma("unroll") for (int k = 0; k < 2; ++k) \
;         acc[ai][bj][m][n] = __builtin_amdgcn_mfma_f32_16x16x32_bf16(Bt[n][k], At[m][k], acc[ai][bj][m][n], 0, 0, 0); __builtin_amdgcn_s_setprio(0); } while (0)
; #define PG8_WAIT_V(n) asm volatile("s_waitcnt vmcnt(" #n ")" ::: "memory")
; #define PG8_WAIT_L(n) asm volatile("s_waitcnt lgkmcnt(" #n ")" ::: "memory")
; #define PG8_BAR __builtin_amdgcn_s_barrier()
; #define PG8_SCHED __builtin_amdgcn_sched_barrier(0)
; template <class Epi>
; __device__ __forceinline__ void gemm_phase(LAS unsigned char* lds, const Gemm g, const StaticOrder& S, const Epi& E, int wave_) {
;     ...
;             PG8_STAGE(PG8_SA(0, 1), a2 + hstepA, voffA); PG8_LDB(B0, 1, 0); PG8_LDB(B1, 1, 1); PG8_SCHED; PG8_LDA(At, 1, 0);
;             PG8_WAIT_V(8); PG8_WAIT_L(0); PG8_BAR; PG8_MMA(0, 0, At, B0); PG8_MMA(0, 1, At, B1); PG8_BAR; PG8_SCHED;
;             PG8_STAGE(PG8_SB(1, 0), b3, voffB); PG8_STAGE(PG8_SB(1, 1), b3 + hstepB, voffB); PG8_STAGE(PG8_SA(1, 0), a3, voffA); PG8_LDA(At, 1, 1);
;             PG8_WAIT_V(8); PG8_WAIT_L(0); PG8_BAR; PG8_MMA(1, 0, At, B0); PG8_MMA(1, 1, At, B1); PG8_BAR; PG8_SCHED;
;         }
	s_setprio 0
	s_add_u32 s44, s44, 0x80000
	s_addc_u32 s45, s45, 0
	s_mov_b32 m0, s1
	s_nop 0
	global_load_lds_dwordx4 v172, s[44:45]
	v_mov_b32_e32 v128, v178
	s_mov_b32 m0, s69
	s_nop 0
	global_load_lds_dwordx4 v174, s[44:45]
	v_add_u32_e32 v132, s34, v178
	v_xad_u32 v140, v128, 64, s34
	v_mov_b32_e32 v144, v178
	s_add_i32 s44, 0, 0x1c000
	ds_read_b128 v[128:131], v132
	ds_read_b128 v[132:135], v132 offset:2048
	ds_read_b128 v[136:139], v140
	ds_read_b128 v[140:143], v140 offset:2048
	v_add_u32_e32 v148, s44, v178
	v_xad_u32 v156, v144, 64, s44
	ds_read_b128 v[144:147], v148
	ds_read_b128 v[148:151], v148 offset:2048
	ds_read_b128 v[152:155], v156
	ds_read_b128 v[156:159], v156 offset:2048
	v_mov_b32_e32 v160, v177
	s_nop 0
	v_xad_u32 v168, v160, 64, 0
	ds_read_b128 v[160:163], v169 offset:32768
	ds_read_b128 v[164:167], v169 offset:34816
	ds_read_b128 v[180:183], v168 offset:32768
	ds_read_b128 v[192:195], v168 offset:34816
	ds_read_b128 v[196:199], v169 offset:36864
	ds_read_b128 v[200:203], v169 offset:38912
	ds_read_b128 v[204:207], v168 offset:36864
	ds_read_b128 v[208:211], v168 offset:38912
	s_waitcnt vmcnt(8)
	s_waitcnt lgkmcnt(0)
	s_setprio 1
	s_barrier
	v_mfma_f32_16x16x32_bf16 v[124:127], v[128:131], v[160:163], v[124:127]
	v_mfma_f32_16x16x32_bf16 v[120:123], v[132:135], v[160:163], v[120:123]
	v_mfma_f32_16x16x32_bf16 v[108:111], v[128:131], v[164:167], v[108:111]
	v_mfma_f32_16x16x32_bf16 v[104:107], v[132:135], v[164:167], v[104:107]
	v_mfma_f32_16x16x32_bf16 v[92:95], v[128:131], v[196:199], v[92:95]
	v_mfma_f32_16x16x32_bf16 v[88:91], v[132:135], v[196:199], v[88:91]
	v_mfma_f32_16x16x32_bf16 v[76:79], v[128:131], v[200:203], v[76:79]
	v_mfma_f32_16x16x32_bf16 v[72:75], v[132:135], v[200:203], v[72:75]
	v_mfma_f32_16x16x32_bf16 v[124:127], v[136:139], v[180:183], v[124:127]
	v_mfma_f32_16x16x32_bf16 v[120:123], v[140:143], v[180:183], v[120:123]
	v_mfma_f32_16x16x32_bf16 v[108:111], v[136:139], v[192:195], v[108:111]
	v_mfma_f32_16x16x32_bf16 v[104:107], v[140:143], v[192:195], v[104:107]
	v_mfma_f32_16x16x32_bf16 v[92:95], v[136:139], v[204:207], v[92:95]
	v_mfma_f32_16x16x32_bf16 v[88:91], v[140:143], v[204:207], v[88:91]
	v_mfma_f32_16x16x32_bf16 v[76:79], v[136:139], v[208:211], v[76:79]
	v_mfma_f32_16x16x32_bf16 v[72:75], v[140:143], v[208:211], v[72:75]
	s_setprio 0
	s_setprio 1
	v_mfma_f32_16x16x32_bf16 v[116:119], v[144:147], v[160:163], v[116:119]
	s_add_u32 s44, s40, 0x80
	s_addc_u32 s45, s41, 0
	v_mfma_f32_16x16x32_bf16 v[112:115], v[148:151], v[160:163], v[112:115]
	v_mfma_f32_16x16x32_bf16 v[100:103], v[144:147], v[164:167], v[100:103]
	v_mfma_f32_16x16x32_bf16 v[96:99], v[148:151], v[164:167], v[96:99]
	v_mfma_f32_16x16x32_bf16 v[84:87], v[144:147], v[196:199], v[84:87]
	v_mfma_f32_16x16x32_bf16 v[80:83], v[148:151], v[196:199], v[80:83]
	v_mfma_f32_16x16x32_bf16 v[68:71], v[144:147], v[200:203], v[68:71]
	v_mfma_f32_16x16x32_bf16 v[64:67], v[148:151], v[200:203], v[64:67]
	v_mfma_f32_16x16x32_bf16 v[116:119], v[152:155], v[180:183], v[116:119]
	v_mfma_f32_16x16x32_bf16 v[112:115], v[156:159], v[180:183], v[112:115]
	v_mfma_f32_16x16x32_bf16 v[100:103], v[152:155], v[192:195], v[100:103]
	v_mfma_f32_16x16x32_bf16 v[96:99], v[156:159], v[192:195], v[96:99]
	v_mfma_f32_16x16x32_bf16 v[84:87], v[152:155], v[204:207], v[84:87]
	v_mfma_f32_16x16x32_bf16 v[80:83], v[156:159], v[204:207], v[80:83]
	v_mfma_f32_16x16x32_bf16 v[68:71], v[152:155], v[208:211], v[68:71]
	v_mfma_f32_16x16x32_bf16 v[64:67], v[156:159], v[208:211], v[64:67]
	s_barrier
	s_setprio 0
	s_add_u32 s40, s40, 0x80080
	s_addc_u32 s41, s41, 0
	v_mov_b32_e32 v160, v177
	s_nop 0
	s_nop 0
	v_xad_u32 v168, v160, 64, 0
	ds_read_b128 v[160:163], v169 offset:49152
	ds_read_b128 v[164:167], v169 offset:51200
	ds_read_b128 v[180:183], v168 offset:49152
	ds_read_b128 v[192:195], v168 offset:51200
	ds_read_b128 v[196:199], v169 offset:53248
	ds_read_b128 v[200:203], v169 offset:55296
	ds_read_b128 v[204:207], v168 offset:53248
	ds_read_b128 v[208:211], v168 offset:55296
	s_mov_b32 m0, s35
	s_nop 0
	global_load_lds_dwordx4 v173, s[44:45]
	s_mov_b32 m0, s33
	s_nop 0
	global_load_lds_dwordx4 v175, s[44:45]
	s_mov_b32 m0, s77
	s_nop 0
	global_load_lds_dwordx4 v173, s[40:41]
	s_mov_b32 m0, s3
	s_nop 0
	global_load_lds_dwordx4 v175, s[40:41]
	s_mov_b32 m0, s22
	s_nop 0
	global_load_lds_dwordx4 v172, s[36:37]
	s_mov_b32 m0, s2
	s_nop 0
	global_load_lds_dwordx4 v174, s[36:37]
	s_waitcnt vmcnt(8)
	s_waitcnt lgkmcnt(0)
	s_setprio 1
	s_barrier
	v_mfma_f32_16x16x32_bf16 v[60:63], v[128:131], v[160:163], v[60:63]
	v_mfma_f32_16x16x32_bf16 v[56:59], v[132:135], v[160:163], v[56:59]
	v_mfma_f32_16x16x32_bf16 v[44:47], v[128:131], v[164:167], v[44:47]
	v_mfma_f32_16x16x32_bf16 v[40:43], v[132:135], v[164:167], v[40:43]
	v_mfma_f32_16x16x32_bf16 v[28:31], v[128:131], v[196:199], v[28:31]
	v_mfma_f32_16x16x32_bf16 v[24:27], v[132:135], v[196:199], v[24:27]
	v_mfma_f32_16x16x32_bf16 v[12:15], v[128:131], v[200:203], v[12:15]
	v_mfma_f32_16x16x32_bf16 v[8:11], v[132:135], v[200:203], v[8:11]
	v_mfma_f32_16x16x32_bf16 v[60:63], v[136:139], v[180:183], v[60:63]
	v_mfma_f32_16x16x32_bf16 v[56:59], v[140:143], v[180:183], v[56:59]
	v_mfma_f32_16x16x32_bf16 v[44:47], v[136:139], v[192:195], v[44:47]
	v_mfma_f32_16x16x32_bf16 v[40:43], v[140:143], v[192:195], v[40:43]
	v_mfma_f32_16x16x32_bf16 v[28:31], v[136:139], v[204:207], v[28:31]
	v_mfma_f32_16x16x32_bf16 v[24:27], v[140:143], v[204:207], v[24:27]
	v_mfma_f32_16x16x32_bf16 v[12:15], v[136:139], v[208:211], v[12:15]
	v_mfma_f32_16x16x32_bf16 v[8:11], v[140:143], v[208:211], v[8:11]
	s_setprio 0
	s_setprio 1
	v_mfma_f32_16x16x32_bf16 v[52:55], v[144:147], v[160:163], v[52:55]
	v_mfma_f32_16x16x32_bf16 v[48:51], v[148:151], v[160:163], v[48:51]
	v_mfma_f32_16x16x32_bf16 v[36:39], v[144:147], v[164:167], v[36:39]
	v_mfma_f32_16x16x32_bf16 v[32:35], v[148:151], v[164:167], v[32:35]
	v_mfma_f32_16x16x32_bf16 v[20:23], v[144:147], v[196:199], v[20:23]
	v_mfma_f32_16x16x32_bf16 v[16:19], v[148:151], v[196:199], v[16:19]
	v_mfma_f32_16x16x32_bf16 v[4:7], v[144:147], v[200:203], v[4:7]
	v_mfma_f32_16x16x32_bf16 v[0:3], v[148:151], v[200:203], v[0:3]
	v_mfma_f32_16x16x32_bf16 v[52:55], v[152:155], v[180:183], v[52:55]
	v_mfma_f32_16x16x32_bf16 v[48:51], v[156:159], v[180:183], v[48:51]
	v_mfma_f32_16x16x32_bf16 v[36:39], v[152:155], v[192:195], v[36:39]
	v_mfma_f32_16x16x32_bf16 v[32:35], v[156:159], v[192:195], v[32:35]
	v_mfma_f32_16x16x32_bf16 v[20:23], v[152:155], v[204:207], v[20:23]
	v_mfma_f32_16x16x32_bf16 v[16:19], v[156:159], v[204:207], v[16:19]
	v_mfma_f32_16x16x32_bf16 v[4:7], v[152:155], v[208:211], v[4:7]
	v_mfma_f32_16x16x32_bf16 v[0:3], v[156:159], v[208:211], v[0:3]
	s_barrier
	s_setprio 0
	s_add_i32 s57, s57, 2
	s_add_u32 s55, s55, 0x100
	s_addc_u32 s56, s56, 0
	s_add_u32 s12, s12, 0x100
	s_addc_u32 s13, s13, 0
	s_cmp_gt_u32 s57, 29
	s_cbranch_scc0 .LBB0_1322

; #define PG8_STAGE(bufoff, gbase, voff) do { _Pragma("unroll") for (int _i = 0; _i < 2; ++_i) \
;         dma16((const char*)(gbase), (voff)[_i], ldsb + (bufoff) + ldsw + _i * 8192); } while (0)
; #define PG8_LDA(dst, b, h) do { const int a1_ = opqv(aoff0) ^ 64; _Pragma("unroll") for (int m = 0; m < 4; ++m) { dst[m][0] = *(const LAS bf16x8*)(lds + PG8_SA(b, h) + aoff0 + m * 2048); dst[m][1] = *(const LAS bf16x8*)(lds + PG8_SA(b, h) + a1_ + m * 2048); } } while (0)
; #define PG8_WAIT_V(n) asm volatile("s_waitcnt vmcnt(" #n ")" ::: "memory")
; #define PG8_BAR __builtin_amdgcn_s_barrier()
; template <class Epi>
; __device__ __forceinline__ void gemm_phase(LAS unsigned char* lds, const Gemm g, const StaticOrder& S, const Epi& E, int wave_) {
;     ...
;         const bool has_next = S.next(ui + 1, nxt);
;         const char* nA = has_next ? (const char*)g.A + (size_t)nxt.pm * tstepA : cA; const char* nB = has_next ? (const char*)g.Bt + (size_t)nxt.pn * tstepB : cB;
; #pragma unroll 1
;         for (int t = 0; t < nt; t += 2) {
;             const bool last = (t == nt - 2);
;             const char* a1 = cA + (size_t)(t + 1) * kstep;
;             const char* a2 = last ? nA : cA + (size_t)(t + 2) * kstep; const char* b2 = last ? nB : cB + (size_t)(t + 2) * kstep;
;             const char* a3 = a2 + kstep; const char* b3 = b2 + kstep;
;             PG8_STAGE(PG8_SA(1, 1), a1 + hstepA, voffA); PG8_LDB(B0, 0, 0); PG8_LDB(B1, 0, 1); PG8_SCHED; PG8_LDA(At, 0, 0);
;             PG8_WAIT_V(8); PG8_WAIT_L(0); PG8_BAR; PG8_MMA(0, 0, At, B0); PG8_MMA(0, 1, At, B1); PG8_BAR; PG8_SCHED;
;             PG8_STAGE(PG8_SB(0, 0), b2, voffB); PG8_STAGE(PG8_SB(0, 1), b2 + hstepB, voffB); PG8_STAGE(PG8_SA(0, 0), a2, voffA); PG8_LDA(At, 0, 1);
;             PG8_WAIT_V(8); PG8_WAIT_L(0); PG8_BAR; PG8_MMA(1, 0, At, B0); PG8_MMA(1, 1, At, B1); PG8_BAR; PG8_SCHED;
;             PG8_STAGE(PG8_SA(0, 1), a2 + hstepA, voffA); PG8_LDB(B0, 1, 0); PG8_LDB(B1, 1, 1); PG8_SCHED; PG8_LDA(At, 1, 0);
;             PG8_WAIT_V(8); PG8_WAIT_L(0); PG8_BAR; PG8_MMA(0, 0, At, B0); PG8_MMA(0, 1, At, B1); PG8_BAR; PG8_SCHED;
;             PG8_STAGE(PG8_SB(1, 0), b3, voffB); PG8_STAGE(PG8_SB(1, 1), b3 + hstepB, voffB); PG8_STAGE(PG8_SA(1, 0), a3, voffA); PG8_LDA(At, 1, 1);
;             PG8_WAIT_V(8); PG8_WAIT_L(0); PG8_BAR; PG8_MMA(1, 0, At, B0); PG8_MMA(1, 1, At, B1); PG8_BAR; PG8_SCHED;
.LBB0_1341:
	s_ashr_i32 s9, s8, 31
	s_lshl_b64 s[10:11], s[8:9], 17
	s_add_u32 s10, s16, s10
	s_addc_u32 s11, s17, s11
	s_and_b64 s[12:13], s[42:43], exec
	s_cselect_b32 s9, s11, s27
	s_cselect_b32 s61, s10, s26
	s_ashr_i32 s7, s6, 31
	s_lshl_b64 s[12:13], s[6:7], 17
	s_add_u32 s18, s21, s12
	s_addc_u32 s19, s52, s13
	s_and_b64 s[12:13], s[42:43], exec
	s_cselect_b32 s7, s19, s25
	s_cselect_b32 s62, s18, s24
	s_mov_b64 s[30:31], 0
	s_mov_b64 s[12:13], -1
	s_mov_b64 s[36:37], 0
	s_add_u32 s46, s26, s30
	s_addc_u32 s47, s27, s31
	s_add_u32 s44, s46, 0x100
	s_addc_u32 s45, s47, 0
	s_and_b64 s[40:41], s[36:37], exec
	s_cselect_b32 s45, s9, s45
	s_cselect_b32 s44, s61, s44
	s_add_u32 s30, s24, s30
	s_addc_u32 s31, s25, s31
	s_add_u32 s40, s30, 0x100
	s_addc_u32 s41, s31, 0
	s_add_u32 s30, s44, 0x80
	s_addc_u32 s31, s45, 0
	s_add_u32 s56, s46, 0x10080
	s_addc_u32 s57, s47, 0
	s_mov_b32 m0, s14
	s_nop 0
	global_load_lds_dwordx4 v130, s[56:57]
	v_mov_b32_e32 v128, v136
	s_mov_b32 m0, s15
	s_nop 0
	global_load_lds_dwordx4 v132, s[56:57]
	s_and_b64 s[36:37], s[36:37], exec
	v_xad_u32 v128, v128, 64, s23
	v_add_u32_e32 v129, s23, v136
	s_cselect_b32 s49, s7, s41
	s_cselect_b32 s48, s62, s40
	s_add_i32 s37, 0, 0x14000
	ds_read_b128 v[138:141], v129
	ds_read_b128 v[142:145], v129 offset:2048
	ds_read_b128 v[146:149], v128
	ds_read_b128 v[150:153], v128 offset:2048
	v_mov_b32_e32 v128, v136
	v_add_u32_e32 v129, s37, v136
	s_add_u32 s46, s48, 0x10000
	v_xad_u32 v128, v128, 64, s37
	ds_read_b128 v[154:157], v129
	ds_read_b128 v[158:161], v129 offset:2048
	ds_read_b128 v[162:165], v128
	ds_read_b128 v[166:169], v128 offset:2048
	s_addc_u32 s47, s49, 0
	s_add_u32 s40, s44, 0x10000
	s_addc_u32 s41, s45, 0
	s_add_i32 s63, 0, 0x1c000
	s_add_u32 s36, s48, 0x80
	s_addc_u32 s37, s49, 0
	s_add_u32 s56, s48, 0x10080
	s_addc_u32 s57, s49, 0
	v_mov_b32_e32 v128, v135
	v_add_u32_e32 v129, 0, v135
	v_xad_u32 v128, v128, 64, 0
	ds_read_b128 v[172:175], v129
	ds_read_b128 v[176:179], v129 offset:2048
	ds_read_b128 v[180:183], v128
	ds_read_b128 v[192:195], v128 offset:2048
	ds_read_b128 v[196:199], v129 offset:4096
	ds_read_b128 v[200:203], v129 offset:6144
	ds_read_b128 v[204:207], v128 offset:4096
	ds_read_b128 v[208:211], v128 offset:6144
	s_waitcnt vmcnt(8)
	s_waitcnt lgkmcnt(0)
	s_setprio 1
	s_barrier
	v_mfma_f32_16x16x32_bf16 v[124:127], v[138:141], v[172:175], 0
	v_mfma_f32_16x16x32_bf16 v[120:123], v[142:145], v[172:175], 0
	v_mfma_f32_16x16x32_bf16 v[116:119], v[138:141], v[176:179], 0
	v_mfma_f32_16x16x32_bf16 v[108:111], v[142:145], v[176:179], 0
	v_mfma_f32_16x16x32_bf16 v[100:103], v[138:141], v[196:199], 0
	v_mfma_f32_16x16x32_bf16 v[92:95], v[142:145], v[196:199], 0
	v_mfma_f32_16x16x32_bf16 v[84:87], v[138:141], v[200:203], 0
	v_mfma_f32_16x16x32_bf16 v[76:79], v[142:145], v[200:203], 0
	v_mfma_f32_16x16x32_bf16 v[124:127], v[146:149], v[180:183], v[124:127]
	v_mfma_f32_16x16x32_bf16 v[120:123], v[150:153], v[180:183], v[120:123]
	v_mfma_f32_16x16x32_bf16 v[116:119], v[146:149], v[192:195], v[116:119]
	v_mfma_f32_16x16x32_bf16 v[108:111], v[150:153], v[192:195], v[108:111]
	v_mfma_f32_16x16x32_bf16 v[100:103], v[146:149], v[204:207], v[100:103]
	v_mfma_f32_16x16x32_bf16 v[92:95], v[150:153], v[204:207], v[92:95]
	v_mfma_f32_16x16x32_bf16 v[84:87], v[146:149], v[208:211], v[84:87]
	v_mfma_f32_16x16x32_bf16 v[76:79], v[150:153], v[208:211], v[76:79]
	s_setprio 0
	s_setprio 1
	v_mfma_f32_16x16x32_bf16 v[112:115], v[154:157], v[172:175], 0
	v_mfma_f32_16x16x32_bf16 v[104:107], v[158:161], v[172:175], 0
	v_mfma_f32_16x16x32_bf16 v[96:99], v[154:157], v[176:179], 0
	v_mfma_f32_16x16x32_bf16 v[88:91], v[158:161], v[176:179], 0
	v_mfma_f32_16x16x32_bf16 v[80:83], v[154:157], v[196:199], 0
	v_mfma_f32_16x16x32_bf16 v[72:75], v[158:161], v[196:199], 0
	v_mfma_f32_16x16x32_bf16 v[68:71], v[154:157], v[200:203], 0
	v_mfma_f32_16x16x32_bf16 v[64:67], v[158:161], v[200:203], 0
	v_mfma_f32_16x16x32_bf16 v[112:115], v[162:165], v[180:183], v[112:115]
	v_mfma_f32_16x16x32_bf16 v[104:107], v[166:169], v[180:183], v[104:107]
	v_mfma_f32_16x16x32_bf16 v[96:99], v[162:165], v[192:195], v[96:99]
	v_mfma_f32_16x16x32_bf16 v[88:91], v[166:169], v[192:195], v[88:91]
	v_mfma_f32_16x16x32_bf16 v[80:83], v[162:165], v[204:207], v[80:83]
	v_mfma_f32_16x16x32_bf16 v[72:75], v[166:169], v[204:207], v[72:75]
	v_mfma_f32_16x16x32_bf16 v[68:71], v[162:165], v[208:211], v[68:71]
	v_mfma_f32_16x16x32_bf16 v[64:67], v[166:169], v[208:211], v[64:67]
	s_barrier
	s_setprio 0
	v_mov_b32_e32 v128, v135
	s_nop 0
	s_nop 0
	s_nop 0
	v_xad_u32 v128, v128, 64, 0
	ds_read_b128 v[172:175], v129 offset:16384
	ds_read_b128 v[176:179], v129 offset:18432
	ds_read_b128 v[180:183], v128 offset:16384
	ds_read_b128 v[192:195], v128 offset:18432
	ds_read_b128 v[196:199], v129 offset:20480
	ds_read_b128 v[200:203], v129 offset:22528
	ds_read_b128 v[204:207], v128 offset:20480
	ds_read_b128 v[208:211], v128 offset:22528
	s_mov_b32 m0, s80
	s_nop 0
	global_load_lds_dwordx4 v131, s[48:49]
	s_mov_b32 m0, s81
	s_nop 0
	global_load_lds_dwordx4 v133, s[48:49]
	s_mov_b32 m0, s29
	s_nop 0
	global_load_lds_dwordx4 v131, s[46:47]
	s_mov_b32 m0, s88
	s_nop 0
	global_load_lds_dwordx4 v133, s[46:47]
	s_mov_b32 m0, s76
	s_nop 0
	global_load_lds_dwordx4 v130, s[44:45]
	s_mov_b32 m0, s89
	s_nop 0
	global_load_lds_dwordx4 v132, s[44:45]
	s_waitcnt vmcnt(8)
	s_waitcnt lgkmcnt(0)
	s_setprio 1
	s_barrier
; #define PG8_STAGE(bufoff, gbase, voff) do { _Pragma("unroll") for (int _i = 0; _i < 2; ++_i) \
;         dma16((const char*)(gbase), (voff)[_i], ldsb + (bufoff) + ldsw + _i * 8192); } while (0)
; #define PG8_LDA(dst, b, h) do { const int a1_ = opqv(aoff0) ^ 64; _Pragma("unroll") for (int m = 0; m < 4; ++m) { dst[m][0] = *(const LAS bf16x8*)(lds + PG8_SA(b, h) + aoff0 + m * 2048); dst[m][1] = *(const LAS bf16x8*)(lds + PG8_SA(b, h) + a1_ + m * 2048); } } while (0)
; #define PG8_LDB(dst, b, h) do { const int b1_ = opqv(boff0) ^ 64; _Pragma("unroll") for (int n = 0; n < 2; ++n) { dst[n][0] = *(const LAS bf16x8*)(lds + PG8_SB(b, h) + boff0 + n * 2048); dst[n][1] = *(const LAS bf16x8*)(lds + PG8_SB(b, h) + b1_ + n * 2048); } } while (0)
; #define PG8_MMA(ai, bj, At, Bt) do { __builtin_amdgcn_s_setprio(1); _Pragma("unroll") for (int m = 0; m < 4; ++m) _Pragma("unroll") for (int n = 0; n < 2; ++n) _Pragma("unroll") for (int k = 0; k < 2; ++k) \
;         acc[ai][bj][m][n] = __builtin_amdgcn_mfma_f32_16x16x32_bf16(Bt[n][k], At[m][k], acc[ai][bj][m][n], 0, 0, 0); __builtin_amdgcn_s_setprio(0); } while (0)
; #define PG8_WAIT_V(n) asm volatile("s_waitcnt vmcnt(" #n ")" ::: "memory")
; #define PG8_WAIT_L(n) asm volatile("s_waitcnt lgkmcnt(" #n ")" ::: "memory")
; #define PG8_BAR __builtin_amdgcn_s_barrier()
; #define PG8_SCHED __builtin_amdgcn_sched_barrier(0)
; template <class Epi>
; __device__ __forceinline__ void gemm_phase(LAS unsigned char* lds, const Gemm g, const StaticOrder& S, const Epi& E, int wave_) {
;     ...
;             PG8_STAGE(PG8_SB(0, 0), b2, voffB); PG8_STAGE(PG8_SB(0, 1), b2 + hstepB, voffB); PG8_STAGE(PG8_SA(0, 0), a2, voffA); PG8_LDA(At, 0, 1);
;             PG8_WAIT_V(8); PG8_WAIT_L(0); PG8_BAR; PG8_MMA(1, 0, At, B0); PG8_MMA(1, 1, At, B1); PG8_BAR; PG8_SCHED;
;             PG8_STAGE(PG8_SA(0, 1), a2 + hstepA, voffA); PG8_LDB(B0, 1, 0); PG8_LDB(B1, 1, 1); PG8_SCHED; PG8_LDA(At, 1, 0);
;             PG8_WAIT_V(8); PG8_WAIT_L(0); PG8_BAR; PG8_MMA(0, 0, At, B0); PG8_MMA(0, 1, At, B1); PG8_BAR; PG8_SCHED;
;             PG8_STAGE(PG8_SB(1, 0), b3, voffB); PG8_STAGE(PG8_SB(1, 1), b3 + hstepB, voffB); PG8_STAGE(PG8_SA(1, 0), a3, voffA); PG8_LDA(At, 1, 1);
	v_mfma_f32_16x16x32_bf16 v[60:63], v[138:141], v[172:175], 0
	v_mfma_f32_16x16x32_bf16 v[56:59], v[142:145], v[172:175], 0
	v_mfma_f32_16x16x32_bf16 v[52:55], v[138:141], v[176:179], 0
	v_mfma_f32_16x16x32_bf16 v[44:47], v[142:145], v[176:179], 0
	v_mfma_f32_16x16x32_bf16 v[36:39], v[138:141], v[196:199], 0
	v_mfma_f32_16x16x32_bf16 v[28:31], v[142:145], v[196:199], 0
	v_mfma_f32_16x16x32_bf16 v[20:23], v[138:141], v[200:203], 0
	v_mfma_f32_16x16x32_bf16 v[12:15], v[142:145], v[200:203], 0
	v_mfma_f32_16x16x32_bf16 v[60:63], v[146:149], v[180:183], v[60:63]
	v_mfma_f32_16x16x32_bf16 v[56:59], v[150:153], v[180:183], v[56:59]
	v_mfma_f32_16x16x32_bf16 v[52:55], v[146:149], v[192:195], v[52:55]
	v_mfma_f32_16x16x32_bf16 v[44:47], v[150:153], v[192:195], v[44:47]
	v_mfma_f32_16x16x32_bf16 v[36:39], v[146:149], v[204:207], v[36:39]
	v_mfma_f32_16x16x32_bf16 v[28:31], v[150:153], v[204:207], v[28:31]
	v_mfma_f32_16x16x32_bf16 v[20:23], v[146:149], v[208:211], v[20:23]
	v_mfma_f32_16x16x32_bf16 v[12:15], v[150:153], v[208:211], v[12:15]
	s_setprio 0
	s_setprio 1
	v_mfma_f32_16x16x32_bf16 v[48:51], v[154:157], v[172:175], 0
	v_mfma_f32_16x16x32_bf16 v[40:43], v[158:161], v[172:175], 0
	v_mfma_f32_16x16x32_bf16 v[32:35], v[154:157], v[176:179], 0
	v_mfma_f32_16x16x32_bf16 v[24:27], v[158:161], v[176:179], 0
	v_mfma_f32_16x16x32_bf16 v[16:19], v[154:157], v[196:199], 0
	v_mfma_f32_16x16x32_bf16 v[8:11], v[158:161], v[196:199], 0
	v_mfma_f32_16x16x32_bf16 v[4:7], v[154:157], v[200:203], 0
	v_mfma_f32_16x16x32_bf16 v[0:3], v[158:161], v[200:203], 0
	v_mfma_f32_16x16x32_bf16 v[48:51], v[162:165], v[180:183], v[48:51]
	v_mfma_f32_16x16x32_bf16 v[40:43], v[166:169], v[180:183], v[40:43]
	v_mfma_f32_16x16x32_bf16 v[32:35], v[162:165], v[192:195], v[32:35]
	v_mfma_f32_16x16x32_bf16 v[24:27], v[166:169], v[192:195], v[24:27]
	v_mfma_f32_16x16x32_bf16 v[16:19], v[162:165], v[204:207], v[16:19]
	v_mfma_f32_16x16x32_bf16 v[8:11], v[166:169], v[204:207], v[8:11]
	v_mfma_f32_16x16x32_bf16 v[4:7], v[162:165], v[208:211], v[4:7]
	v_mfma_f32_16x16x32_bf16 v[0:3], v[166:169], v[208:211], v[0:3]
	s_barrier
	s_setprio 0
	v_mov_b32_e32 v128, v136
	v_add_u32_e32 v142, s34, v136
	v_xad_u32 v128, v128, 64, s34
	ds_read_b128 v[138:141], v142
	ds_read_b128 v[142:145], v142 offset:2048
	ds_read_b128 v[146:149], v128
	ds_read_b128 v[150:153], v128 offset:2048
	v_mov_b32_e32 v128, v136
	v_add_u32_e32 v158, s63, v136
	v_xad_u32 v128, v128, 64, s63
	ds_read_b128 v[154:157], v158
	ds_read_b128 v[158:161], v158 offset:2048
	ds_read_b128 v[162:165], v128
	ds_read_b128 v[166:169], v128 offset:2048
	v_mov_b32_e32 v128, v135
	s_nop 0
	v_xad_u32 v128, v128, 64, 0
	ds_read_b128 v[172:175], v129 offset:32768
	ds_read_b128 v[176:179], v129 offset:34816
	ds_read_b128 v[180:183], v128 offset:32768
	ds_read_b128 v[192:195], v128 offset:34816
	ds_read_b128 v[196:199], v129 offset:36864
	ds_read_b128 v[200:203], v129 offset:38912
	ds_read_b128 v[204:207], v128 offset:36864
	ds_read_b128 v[208:211], v128 offset:38912
	s_mov_b32 m0, s1
	s_nop 0
	global_load_lds_dwordx4 v130, s[40:41]
	s_mov_b32 m0, s69
	s_nop 0
	global_load_lds_dwordx4 v132, s[40:41]
	s_waitcnt vmcnt(8)
	s_waitcnt lgkmcnt(0)
	s_setprio 1
	s_barrier
	v_mfma_f32_16x16x32_bf16 v[124:127], v[138:141], v[172:175], v[124:127]
	v_mfma_f32_16x16x32_bf16 v[120:123], v[142:145], v[172:175], v[120:123]
	v_mfma_f32_16x16x32_bf16 v[116:119], v[138:141], v[176:179], v[116:119]
	v_mfma_f32_16x16x32_bf16 v[108:111], v[142:145], v[176:179], v[108:111]
	v_mfma_f32_16x16x32_bf16 v[100:103], v[138:141], v[196:199], v[100:103]
	v_mfma_f32_16x16x32_bf16 v[92:95], v[142:145], v[196:199], v[92:95]
	v_mfma_f32_16x16x32_bf16 v[84:87], v[138:141], v[200:203], v[84:87]
	v_mfma_f32_16x16x32_bf16 v[76:79], v[142:145], v[200:203], v[76:79]
	v_mfma_f32_16x16x32_bf16 v[124:127], v[146:149], v[180:183], v[124:127]
	v_mfma_f32_16x16x32_bf16 v[120:123], v[150:153], v[180:183], v[120:123]
	v_mfma_f32_16x16x32_bf16 v[116:119], v[146:149], v[192:195], v[116:119]
	v_mfma_f32_16x16x32_bf16 v[108:111], v[150:153], v[192:195], v[108:111]
	v_mfma_f32_16x16x32_bf16 v[100:103], v[146:149], v[204:207], v[100:103]
	v_mfma_f32_16x16x32_bf16 v[92:95], v[150:153], v[204:207], v[92:95]
	v_mfma_f32_16x16x32_bf16 v[84:87], v[146:149], v[208:211], v[84:87]
	v_mfma_f32_16x16x32_bf16 v[76:79], v[150:153], v[208:211], v[76:79]
	s_setprio 0
	s_setprio 1
	v_mfma_f32_16x16x32_bf16 v[112:115], v[154:157], v[172:175], v[112:115]
	v_mfma_f32_16x16x32_bf16 v[104:107], v[158:161], v[172:175], v[104:107]
	v_mfma_f32_16x16x32_bf16 v[96:99], v[154:157], v[176:179], v[96:99]
	v_mfma_f32_16x16x32_bf16 v[88:91], v[158:161], v[176:179], v[88:91]
	v_mfma_f32_16x16x32_bf16 v[80:83], v[154:157], v[196:199], v[80:83]
	v_mfma_f32_16x16x32_bf16 v[72:75], v[158:161], v[196:199], v[72:75]
	v_mfma_f32_16x16x32_bf16 v[68:71], v[154:157], v[200:203], v[68:71]
	v_mfma_f32_16x16x32_bf16 v[64:67], v[158:161], v[200:203], v[64:67]
	v_mfma_f32_16x16x32_bf16 v[112:115], v[162:165], v[180:183], v[112:115]
	v_mfma_f32_16x16x32_bf16 v[104:107], v[166:169], v[180:183], v[104:107]
	v_mfma_f32_16x16x32_bf16 v[96:99], v[162:165], v[192:195], v[96:99]
	v_mfma_f32_16x16x32_bf16 v[88:91], v[166:169], v[192:195], v[88:91]
	v_mfma_f32_16x16x32_bf16 v[80:83], v[162:165], v[204:207], v[80:83]
	v_mfma_f32_16x16x32_bf16 v[72:75], v[166:169], v[204:207], v[72:75]
	v_mfma_f32_16x16x32_bf16 v[68:71], v[162:165], v[208:211], v[68:71]
	v_mfma_f32_16x16x32_bf16 v[64:67], v[166:169], v[208:211], v[64:67]
	s_barrier
; #define PG8_STAGE(bufoff, gbase, voff) do { _Pragma("unroll") for (int _i = 0; _i < 2; ++_i) \
;         dma16((const char*)(gbase), (voff)[_i], ldsb + (bufoff) + ldsw + _i * 8192); } while (0)
; #define PG8_LDA(dst, b, h) do { const int a1_ = opqv(aoff0) ^ 64; _Pragma("unroll") for (int m = 0; m < 4; ++m) { dst[m][0] = *(const LAS bf16x8*)(lds + PG8_SA(b, h) + aoff0 + m * 2048); dst[m][1] = *(const LAS bf16x8*)(lds + PG8_SA(b, h) + a1_ + m * 2048); } } while (0)
; #define PG8_LDB(dst, b, h) do { const int b1_ = opqv(boff0) ^ 64; _Pragma("unroll") for (int n = 0; n < 2; ++n) { dst[n][0] = *(const LAS bf16x8*)(lds + PG8_SB(b, h) + boff0 + n * 2048); dst[n][1] = *(const LAS bf16x8*)(lds + PG8_SB(b, h) + b1_ + n * 2048); } } while (0)
; #define PG8_MMA(ai, bj, At, Bt) do { __builtin_amdgcn_s_setprio(1); _Pragma("unroll") for (int m = 0; m < 4; ++m) _Pragma("unroll") for (int n = 0; n < 2; ++n) _Pragma("unroll") for (int k = 0; k < 2; ++k) \
;         acc[ai][bj][m][n] = __builtin_amdgcn_mfma_f32_16x16x32_bf16(Bt[n][k], At[m][k], acc[ai][bj][m][n], 0, 0, 0); __builtin_amdgcn_s_setprio(0); } while (0)
; #define PG8_WAIT_V(n) asm volatile("s_waitcnt vmcnt(" #n ")" ::: "memory")
; #define PG8_BAR __builtin_amdgcn_s_barrier()
; template <class Epi>
; __device__ __forceinline__ void gemm_phase(LAS unsigned char* lds, const Gemm g, const StaticOrder& S, const Epi& E, int wave_) {
;     ...
;         const bool has_next = S.next(ui + 1, nxt);
;         const char* nA = has_next ? (const char*)g.A + (size_t)nxt.pm * tstepA : cA; const char* nB = has_next ? (const char*)g.Bt + (size_t)nxt.pn * tstepB : cB;
; #pragma unroll 1
;         for (int t = 0; t < nt; t += 2) {
;             const bool last = (t == nt - 2);
;             const char* a1 = cA + (size_t)(t + 1) * kstep;
;             const char* a2 = last ? nA : cA + (size_t)(t + 2) * kstep; const char* b2 = last ? nB : cB + (size_t)(t + 2) * kstep;
;             const char* a3 = a2 + kstep; const char* b3 = b2 + kstep;
;             PG8_STAGE(PG8_SA(1, 1), a1 + hstepA, voffA); PG8_LDB(B0, 0, 0); PG8_LDB(B1, 0, 1); PG8_SCHED; PG8_LDA(At, 0, 0);
;     ...
;             PG8_STAGE(PG8_SB(1, 0), b3, voffB); PG8_STAGE(PG8_SB(1, 1), b3 + hstepB, voffB); PG8_STAGE(PG8_SA(1, 0), a3, voffA); PG8_LDA(At, 1, 1);
;             PG8_WAIT_V(8); PG8_WAIT_L(0); PG8_BAR; PG8_MMA(1, 0, At, B0); PG8_MMA(1, 1, At, B1); PG8_BAR; PG8_SCHED;
;         }
	s_setprio 0
	v_mov_b32_e32 v128, v135
	s_nop 0
	s_nop 0
	s_nop 0
	s_nop 0
	v_xad_u32 v128, v128, 64, 0
	ds_read_b128 v[172:175], v129 offset:49152
	ds_read_b128 v[176:179], v129 offset:51200
	ds_read_b128 v[180:183], v128 offset:49152
	ds_read_b128 v[192:195], v128 offset:51200
	ds_read_b128 v[196:199], v129 offset:53248
	ds_read_b128 v[200:203], v129 offset:55296
	ds_read_b128 v[204:207], v128 offset:53248
	ds_read_b128 v[208:211], v128 offset:55296
	s_mov_b32 m0, s35
	s_nop 0
	global_load_lds_dwordx4 v131, s[36:37]
	s_mov_b32 m0, s33
	s_nop 0
	global_load_lds_dwordx4 v133, s[36:37]
	s_mov_b32 m0, s77
	s_nop 0
	global_load_lds_dwordx4 v131, s[56:57]
	s_mov_b32 m0, s3
	s_nop 0
	global_load_lds_dwordx4 v133, s[56:57]
	s_mov_b32 m0, s22
	s_nop 0
	global_load_lds_dwordx4 v130, s[30:31]
	s_mov_b32 m0, s2
	s_nop 0
	global_load_lds_dwordx4 v132, s[30:31]
	s_waitcnt vmcnt(8)
	s_waitcnt lgkmcnt(0)
	s_setprio 1
	s_barrier
	v_mfma_f32_16x16x32_bf16 v[60:63], v[138:141], v[172:175], v[60:63]
	v_mfma_f32_16x16x32_bf16 v[56:59], v[142:145], v[172:175], v[56:59]
	v_mfma_f32_16x16x32_bf16 v[52:55], v[138:141], v[176:179], v[52:55]
	v_mfma_f32_16x16x32_bf16 v[44:47], v[142:145], v[176:179], v[44:47]
	v_mfma_f32_16x16x32_bf16 v[36:39], v[138:141], v[196:199], v[36:39]
	v_mfma_f32_16x16x32_bf16 v[28:31], v[142:145], v[196:199], v[28:31]
	v_mfma_f32_16x16x32_bf16 v[20:23], v[138:141], v[200:203], v[20:23]
	v_mfma_f32_16x16x32_bf16 v[12:15], v[142:145], v[200:203], v[12:15]
	v_mfma_f32_16x16x32_bf16 v[60:63], v[146:149], v[180:183], v[60:63]
	v_mfma_f32_16x16x32_bf16 v[56:59], v[150:153], v[180:183], v[56:59]
	v_mfma_f32_16x16x32_bf16 v[52:55], v[146:149], v[192:195], v[52:55]
	v_mfma_f32_16x16x32_bf16 v[44:47], v[150:153], v[192:195], v[44:47]
	v_mfma_f32_16x16x32_bf16 v[36:39], v[146:149], v[204:207], v[36:39]
	v_mfma_f32_16x16x32_bf16 v[28:31], v[150:153], v[204:207], v[28:31]
	v_mfma_f32_16x16x32_bf16 v[20:23], v[146:149], v[208:211], v[20:23]
	v_mfma_f32_16x16x32_bf16 v[12:15], v[150:153], v[208:211], v[12:15]
	s_setprio 0
	s_setprio 1
	v_mfma_f32_16x16x32_bf16 v[48:51], v[154:157], v[172:175], v[48:51]
	v_mfma_f32_16x16x32_bf16 v[40:43], v[158:161], v[172:175], v[40:43]
	v_mfma_f32_16x16x32_bf16 v[32:35], v[154:157], v[176:179], v[32:35]
	v_mfma_f32_16x16x32_bf16 v[24:27], v[158:161], v[176:179], v[24:27]
	v_mfma_f32_16x16x32_bf16 v[16:19], v[154:157], v[196:199], v[16:19]
	v_mfma_f32_16x16x32_bf16 v[8:11], v[158:161], v[196:199], v[8:11]
	v_mfma_f32_16x16x32_bf16 v[4:7], v[154:157], v[200:203], v[4:7]
	v_mfma_f32_16x16x32_bf16 v[0:3], v[158:161], v[200:203], v[0:3]
	v_mfma_f32_16x16x32_bf16 v[48:51], v[162:165], v[180:183], v[48:51]
	v_mfma_f32_16x16x32_bf16 v[40:43], v[166:169], v[180:183], v[40:43]
	v_mfma_f32_16x16x32_bf16 v[32:35], v[162:165], v[192:195], v[32:35]
	v_mfma_f32_16x16x32_bf16 v[24:27], v[166:169], v[192:195], v[24:27]
	v_mfma_f32_16x16x32_bf16 v[16:19], v[162:165], v[204:207], v[16:19]
	v_mfma_f32_16x16x32_bf16 v[8:11], v[166:169], v[204:207], v[8:11]
	v_mfma_f32_16x16x32_bf16 v[4:7], v[162:165], v[208:211], v[4:7]
	v_mfma_f32_16x16x32_bf16 v[0:3], v[166:169], v[208:211], v[0:3]
	s_barrier
	s_setprio 0
	s_andn2_b64 vcc, exec, s[12:13]
	s_mov_b64 s[36:37], -1
	s_mov_b64 s[12:13], 0
	s_mov_b64 s[30:31], 0x100
	s_cbranch_vccz .LBB0_1342
	s_branch .Lpeel_exit_2
.LBB0_1342:
	s_add_u32 s46, s26, s30
	s_addc_u32 s47, s27, s31
	s_add_u32 s44, s46, 0x100
	s_addc_u32 s45, s47, 0
	s_and_b64 s[40:41], s[36:37], exec
	s_cselect_b32 s45, s9, s45
	s_cselect_b32 s44, s61, s44
	s_add_u32 s30, s24, s30
	s_addc_u32 s31, s25, s31
	s_add_u32 s40, s30, 0x100
	s_addc_u32 s41, s31, 0
	s_add_u32 s30, s44, 0x80
	s_addc_u32 s31, s45, 0
	s_add_u32 s56, s46, 0x10080
	s_addc_u32 s57, s47, 0
	s_mov_b32 m0, s14
	s_nop 0
	global_load_lds_dwordx4 v130, s[56:57]
	v_mov_b32_e32 v128, v136
	s_mov_b32 m0, s15
	s_nop 0
	global_load_lds_dwordx4 v132, s[56:57]
	s_and_b64 s[36:37], s[36:37], exec
	v_xad_u32 v128, v128, 64, s23
	v_add_u32_e32 v129, s23, v136
	s_cselect_b32 s49, s7, s41
	s_cselect_b32 s48, s62, s40
	s_add_i32 s37, 0, 0x14000
	ds_read_b128 v[138:141], v129
	ds_read_b128 v[142:145], v129 offset:2048
	ds_read_b128 v[146:149], v128
	ds_read_b128 v[150:153], v128 offset:2048
	v_mov_b32_e32 v128, v136
	v_add_u32_e32 v129, s37, v136
	s_add_u32 s46, s48, 0x10000
	v_xad_u32 v128, v128, 64, s37
	ds_read_b128 v[154:157], v129
	ds_read_b128 v[158:161], v129 offset:2048
	ds_read_b128 v[162:165], v128
	ds_read_b128 v[166:169], v128 offset:2048
	s_addc_u32 s47, s49, 0
	s_add_u32 s40, s44, 0x10000
	s_addc_u32 s41, s45, 0
	s_add_i32 s63, 0, 0x1c000
	s_add_u32 s36, s48, 0x80
	s_addc_u32 s37, s49, 0
	s_add_u32 s56, s48, 0x10080
	s_addc_u32 s57, s49, 0
	v_mov_b32_e32 v128, v135
	v_add_u32_e32 v129, 0, v135
	v_xad_u32 v128, v128, 64, 0
	ds_read_b128 v[172:175], v129
	ds_read_b128 v[176:179], v129 offset:2048
	ds_read_b128 v[180:183], v128
	ds_read_b128 v[192:195], v128 offset:2048
	ds_read_b128 v[196:199], v129 offset:4096
	ds_read_b128 v[200:203], v129 offset:6144
	ds_read_b128 v[204:207], v128 offset:4096
	ds_read_b128 v[208:211], v128 offset:6144
	s_waitcnt vmcnt(8)
	s_waitcnt lgkmcnt(0)
	s_setprio 1
	s_barrier
; #define PG8_STAGE(bufoff, gbase, voff) do { _Pragma("unroll") for (int _i = 0; _i < 2; ++_i) \
;         dma16((const char*)(gbase), (voff)[_i], ldsb + (bufoff) + ldsw + _i * 8192); } while (0)
; #define PG8_LDA(dst, b, h) do { const int a1_ = opqv(aoff0) ^ 64; _Pragma("unroll") for (int m = 0; m < 4; ++m) { dst[m][0] = *(const LAS bf16x8*)(lds + PG8_SA(b, h) + aoff0 + m * 2048); dst[m][1] = *(const LAS bf16x8*)(lds + PG8_SA(b, h) + a1_ + m * 2048); } } while (0)
; #define PG8_LDB(dst, b, h) do { const int b1_ = opqv(boff0) ^ 64; _Pragma("unroll") for (int n = 0; n < 2; ++n) { dst[n][0] = *(const LAS bf16x8*)(lds + PG8_SB(b, h) + boff0 + n * 2048); dst[n][1] = *(const LAS bf16x8*)(lds + PG8_SB(b, h) + b1_ + n * 2048); } } while (0)
; #define PG8_MMA(ai, bj, At, Bt) do { __builtin_amdgcn_s_setprio(1); _Pragma("unroll") for (int m = 0; m < 4; ++m) _Pragma("unroll") for (int n = 0; n < 2; ++n) _Pragma("unroll") for (int k = 0; k < 2; ++k) \
;         acc[ai][bj][m][n] = __builtin_amdgcn_mfma_f32_16x16x32_bf16(Bt[n][k], At[m][k], acc[ai][bj][m][n], 0, 0, 0); __builtin_amdgcn_s_setprio(0); } while (0)
; #define PG8_WAIT_V(n) asm volatile("s_waitcnt vmcnt(" #n ")" ::: "memory")
; #define PG8_WAIT_L(n) asm volatile("s_waitcnt lgkmcnt(" #n ")" ::: "memory")
; #define PG8_BAR __builtin_amdgcn_s_barrier()
; #define PG8_SCHED __builtin_amdgcn_sched_barrier(0)
; template <class Epi>
; __device__ __forceinline__ void gemm_phase(LAS unsigned char* lds, const Gemm g, const StaticOrder& S, const Epi& E, int wave_) {
;     ...
;             PG8_WAIT_V(8); PG8_WAIT_L(0); PG8_BAR; PG8_MMA(0, 0, At, B0); PG8_MMA(0, 1, At, B1); PG8_BAR; PG8_SCHED;
;             PG8_STAGE(PG8_SB(0, 0), b2, voffB); PG8_STAGE(PG8_SB(0, 1), b2 + hstepB, voffB); PG8_STAGE(PG8_SA(0, 0), a2, voffA); PG8_LDA(At, 0, 1);
;             PG8_WAIT_V(8); PG8_WAIT_L(0); PG8_BAR; PG8_MMA(1, 0, At, B0); PG8_MMA(1, 1, At, B1); PG8_BAR; PG8_SCHED;
;             PG8_STAGE(PG8_SA(0, 1), a2 + hstepA, voffA); PG8_LDB(B0, 1, 0); PG8_LDB(B1, 1, 1); PG8_SCHED; PG8_LDA(At, 1, 0);
;             PG8_WAIT_V(8); PG8_WAIT_L(0); PG8_BAR; PG8_MMA(0, 0, At, B0); PG8_MMA(0, 1, At, B1); PG8_BAR; PG8_SCHED;
	v_mfma_f32_16x16x32_bf16 v[124:127], v[138:141], v[172:175], v[124:127]
	v_mfma_f32_16x16x32_bf16 v[120:123], v[142:145], v[172:175], v[120:123]
	v_mfma_f32_16x16x32_bf16 v[116:119], v[138:141], v[176:179], v[116:119]
	v_mfma_f32_16x16x32_bf16 v[108:111], v[142:145], v[176:179], v[108:111]
	v_mfma_f32_16x16x32_bf16 v[100:103], v[138:141], v[196:199], v[100:103]
	v_mfma_f32_16x16x32_bf16 v[92:95], v[142:145], v[196:199], v[92:95]
	v_mfma_f32_16x16x32_bf16 v[84:87], v[138:141], v[200:203], v[84:87]
	v_mfma_f32_16x16x32_bf16 v[76:79], v[142:145], v[200:203], v[76:79]
	v_mfma_f32_16x16x32_bf16 v[124:127], v[146:149], v[180:183], v[124:127]
	v_mfma_f32_16x16x32_bf16 v[120:123], v[150:153], v[180:183], v[120:123]
	v_mfma_f32_16x16x32_bf16 v[116:119], v[146:149], v[192:195], v[116:119]
	v_mfma_f32_16x16x32_bf16 v[108:111], v[150:153], v[192:195], v[108:111]
	v_mfma_f32_16x16x32_bf16 v[100:103], v[146:149], v[204:207], v[100:103]
	v_mfma_f32_16x16x32_bf16 v[92:95], v[150:153], v[204:207], v[92:95]
	v_mfma_f32_16x16x32_bf16 v[84:87], v[146:149], v[208:211], v[84:87]
	v_mfma_f32_16x16x32_bf16 v[76:79], v[150:153], v[208:211], v[76:79]
	s_setprio 0
	s_setprio 1
	v_mfma_f32_16x16x32_bf16 v[112:115], v[154:157], v[172:175], v[112:115]
	v_mfma_f32_16x16x32_bf16 v[104:107], v[158:161], v[172:175], v[104:107]
	v_mfma_f32_16x16x32_bf16 v[96:99], v[154:157], v[176:179], v[96:99]
	v_mfma_f32_16x16x32_bf16 v[88:91], v[158:161], v[176:179], v[88:91]
	v_mfma_f32_16x16x32_bf16 v[80:83], v[154:157], v[196:199], v[80:83]
	v_mfma_f32_16x16x32_bf16 v[72:75], v[158:161], v[196:199], v[72:75]
	v_mfma_f32_16x16x32_bf16 v[68:71], v[154:157], v[200:203], v[68:71]
	v_mfma_f32_16x16x32_bf16 v[64:67], v[158:161], v[200:203], v[64:67]
	v_mfma_f32_16x16x32_bf16 v[112:115], v[162:165], v[180:183], v[112:115]
	v_mfma_f32_16x16x32_bf16 v[104:107], v[166:169], v[180:183], v[104:107]
	v_mfma_f32_16x16x32_bf16 v[96:99], v[162:165], v[192:195], v[96:99]
	v_mfma_f32_16x16x32_bf16 v[88:91], v[166:169], v[192:195], v[88:91]
	v_mfma_f32_16x16x32_bf16 v[80:83], v[162:165], v[204:207], v[80:83]
	v_mfma_f32_16x16x32_bf16 v[72:75], v[166:169], v[204:207], v[72:75]
	v_mfma_f32_16x16x32_bf16 v[68:71], v[162:165], v[208:211], v[68:71]
	v_mfma_f32_16x16x32_bf16 v[64:67], v[166:169], v[208:211], v[64:67]
	s_barrier
	s_setprio 0
	v_mov_b32_e32 v128, v135
	s_nop 0
	s_nop 0
	s_nop 0
	v_xad_u32 v128, v128, 64, 0
	ds_read_b128 v[172:175], v129 offset:16384
	ds_read_b128 v[176:179], v129 offset:18432
	ds_read_b128 v[180:183], v128 offset:16384
	ds_read_b128 v[192:195], v128 offset:18432
	ds_read_b128 v[196:199], v129 offset:20480
	ds_read_b128 v[200:203], v129 offset:22528
	ds_read_b128 v[204:207], v128 offset:20480
	ds_read_b128 v[208:211], v128 offset:22528
	s_mov_b32 m0, s80
	s_nop 0
	global_load_lds_dwordx4 v131, s[48:49]
	s_mov_b32 m0, s81
	s_nop 0
	global_load_lds_dwordx4 v133, s[48:49]
	s_mov_b32 m0, s29
	s_nop 0
	global_load_lds_dwordx4 v131, s[46:47]
	s_mov_b32 m0, s88
	s_nop 0
	global_load_lds_dwordx4 v133, s[46:47]
	s_mov_b32 m0, s76
	s_nop 0
	global_load_lds_dwordx4 v130, s[44:45]
	s_mov_b32 m0, s89
	s_nop 0
	global_load_lds_dwordx4 v132, s[44:45]
	s_waitcnt vmcnt(8)
	s_waitcnt lgkmcnt(0)
	s_setprio 1
	s_barrier
	v_mfma_f32_16x16x32_bf16 v[60:63], v[138:141], v[172:175], v[60:63]
	v_mfma_f32_16x16x32_bf16 v[56:59], v[142:145], v[172:175], v[56:59]
	v_mfma_f32_16x16x32_bf16 v[52:55], v[138:141], v[176:179], v[52:55]
	v_mfma_f32_16x16x32_bf16 v[44:47], v[142:145], v[176:179], v[44:47]
	v_mfma_f32_16x16x32_bf16 v[36:39], v[138:141], v[196:199], v[36:39]
	v_mfma_f32_16x16x32_bf16 v[28:31], v[142:145], v[196:199], v[28:31]
	v_mfma_f32_16x16x32_bf16 v[20:23], v[138:141], v[200:203], v[20:23]
	v_mfma_f32_16x16x32_bf16 v[12:15], v[142:145], v[200:203], v[12:15]
	v_mfma_f32_16x16x32_bf16 v[60:63], v[146:149], v[180:183], v[60:63]
	v_mfma_f32_16x16x32_bf16 v[56:59], v[150:153], v[180:183], v[56:59]
	v_mfma_f32_16x16x32_bf16 v[52:55], v[146:149], v[192:195], v[52:55]
	v_mfma_f32_16x16x32_bf16 v[44:47], v[150:153], v[192:195], v[44:47]
	v_mfma_f32_16x16x32_bf16 v[36:39], v[146:149], v[204:207], v[36:39]
	v_mfma_f32_16x16x32_bf16 v[28:31], v[150:153], v[204:207], v[28:31]
	v_mfma_f32_16x16x32_bf16 v[20:23], v[146:149], v[208:211], v[20:23]
	v_mfma_f32_16x16x32_bf16 v[12:15], v[150:153], v[208:211], v[12:15]
	s_setprio 0
	s_setprio 1
	v_mfma_f32_16x16x32_bf16 v[48:51], v[154:157], v[172:175], v[48:51]
	v_mfma_f32_16x16x32_bf16 v[40:43], v[158:161], v[172:175], v[40:43]
	v_mfma_f32_16x16x32_bf16 v[32:35], v[154:157], v[176:179], v[32:35]
	v_mfma_f32_16x16x32_bf16 v[24:27], v[158:161], v[176:179], v[24:27]
	v_mfma_f32_16x16x32_bf16 v[16:19], v[154:157], v[196:199], v[16:19]
	v_mfma_f32_16x16x32_bf16 v[8:11], v[158:161], v[196:199], v[8:11]
	v_mfma_f32_16x16x32_bf16 v[4:7], v[154:157], v[200:203], v[4:7]
	v_mfma_f32_16x16x32_bf16 v[0:3], v[158:161], v[200:203], v[0:3]
	v_mfma_f32_16x16x32_bf16 v[48:51], v[162:165], v[180:183], v[48:51]
	v_mfma_f32_16x16x32_bf16 v[40:43], v[166:169], v[180:183], v[40:43]
	v_mfma_f32_16x16x32_bf16 v[32:35], v[162:165], v[192:195], v[32:35]
	v_mfma_f32_16x16x32_bf16 v[24:27], v[166:169], v[192:195], v[24:27]
	v_mfma_f32_16x16x32_bf16 v[16:19], v[162:165], v[204:207], v[16:19]
	v_mfma_f32_16x16x32_bf16 v[8:11], v[166:169], v[204:207], v[8:11]
	v_mfma_f32_16x16x32_bf16 v[4:7], v[162:165], v[208:211], v[4:7]
	v_mfma_f32_16x16x32_bf16 v[0:3], v[166:169], v[208:211], v[0:3]
	s_barrier
; #define PG8_STAGE(bufoff, gbase, voff) do { _Pragma("unroll") for (int _i = 0; _i < 2; ++_i) \
;         dma16((const char*)(gbase), (voff)[_i], ldsb + (bufoff) + ldsw + _i * 8192); } while (0)
; #define PG8_LDA(dst, b, h) do { const int a1_ = opqv(aoff0) ^ 64; _Pragma("unroll") for (int m = 0; m < 4; ++m) { dst[m][0] = *(const LAS bf16x8*)(lds + PG8_SA(b, h) + aoff0 + m * 2048); dst[m][1] = *(const LAS bf16x8*)(lds + PG8_SA(b, h) + a1_ + m * 2048); } } while (0)
; #define PG8_LDB(dst, b, h) do { const int b1_ = opqv(boff0) ^ 64; _Pragma("unroll") for (int n = 0; n < 2; ++n) { dst[n][0] = *(const LAS bf16x8*)(lds + PG8_SB(b, h) + boff0 + n * 2048); dst[n][1] = *(const LAS bf16x8*)(lds + PG8_SB(b, h) + b1_ + n * 2048); } } while (0)
; #define PG8_MMA(ai, bj, At, Bt) do { __builtin_amdgcn_s_setprio(1); _Pragma("unroll") for (int m = 0; m < 4; ++m) _Pragma("unroll") for (int n = 0; n < 2; ++n) _Pragma("unroll") for (int k = 0; k < 2; ++k) \
;         acc[ai][bj][m][n] = __builtin_amdgcn_mfma_f32_16x16x32_bf16(Bt[n][k], At[m][k], acc[ai][bj][m][n], 0, 0, 0); __builtin_amdgcn_s_setprio(0); } while (0)
; #define PG8_WAIT_V(n) asm volatile("s_waitcnt vmcnt(" #n ")" ::: "memory")
; #define PG8_WAIT_L(n) asm volatile("s_waitcnt lgkmcnt(" #n ")" ::: "memory")
; #define PG8_BAR __builtin_amdgcn_s_barrier()
; #define PG8_SCHED __builtin_amdgcn_sched_barrier(0)
; template <class Epi>
; __device__ __forceinline__ void gemm_phase(LAS unsigned char* lds, const Gemm g, const StaticOrder& S, const Epi& E, int wave_) {
;     ...
;             PG8_STAGE(PG8_SA(0, 1), a2 + hstepA, voffA); PG8_LDB(B0, 1, 0); PG8_LDB(B1, 1, 1); PG8_SCHED; PG8_LDA(At, 1, 0);
;             PG8_WAIT_V(8); PG8_WAIT_L(0); PG8_BAR; PG8_MMA(0, 0, At, B0); PG8_MMA(0, 1, At, B1); PG8_BAR; PG8_SCHED;
;             PG8_STAGE(PG8_SB(1, 0), b3, voffB); PG8_STAGE(PG8_SB(1, 1), b3 + hstepB, voffB); PG8_STAGE(PG8_SA(1, 0), a3, voffA); PG8_LDA(At, 1, 1);
;             PG8_WAIT_V(8); PG8_WAIT_L(0); PG8_BAR; PG8_MMA(1, 0, At, B0); PG8_MMA(1, 1, At, B1); PG8_BAR; PG8_SCHED;
;         }
	s_setprio 0
	v_mov_b32_e32 v128, v136
	v_add_u32_e32 v142, s34, v136
	v_xad_u32 v128, v128, 64, s34
	ds_read_b128 v[138:141], v142
	ds_read_b128 v[142:145], v142 offset:2048
	ds_read_b128 v[146:149], v128
	ds_read_b128 v[150:153], v128 offset:2048
	v_mov_b32_e32 v128, v136
	v_add_u32_e32 v158, s63, v136
	v_xad_u32 v128, v128, 64, s63
	ds_read_b128 v[154:157], v158
	ds_read_b128 v[158:161], v158 offset:2048
	ds_read_b128 v[162:165], v128
	ds_read_b128 v[166:169], v128 offset:2048
	v_mov_b32_e32 v128, v135
	s_nop 0
	v_xad_u32 v128, v128, 64, 0
	ds_read_b128 v[172:175], v129 offset:32768
	ds_read_b128 v[176:179], v129 offset:34816
	ds_read_b128 v[180:183], v128 offset:32768
	ds_read_b128 v[192:195], v128 offset:34816
	ds_read_b128 v[196:199], v129 offset:36864
	ds_read_b128 v[200:203], v129 offset:38912
	ds_read_b128 v[204:207], v128 offset:36864
	ds_read_b128 v[208:211], v128 offset:38912
	s_mov_b32 m0, s1
	s_nop 0
	global_load_lds_dwordx4 v130, s[40:41]
	s_mov_b32 m0, s69
	s_nop 0
	global_load_lds_dwordx4 v132, s[40:41]
	s_waitcnt vmcnt(8)
	s_waitcnt lgkmcnt(0)
	s_setprio 1
	s_barrier
	v_mfma_f32_16x16x32_bf16 v[124:127], v[138:141], v[172:175], v[124:127]
	v_mfma_f32_16x16x32_bf16 v[120:123], v[142:145], v[172:175], v[120:123]
	v_mfma_f32_16x16x32_bf16 v[116:119], v[138:141], v[176:179], v[116:119]
	v_mfma_f32_16x16x32_bf16 v[108:111], v[142:145], v[176:179], v[108:111]
	v_mfma_f32_16x16x32_bf16 v[100:103], v[138:141], v[196:199], v[100:103]
	v_mfma_f32_16x16x32_bf16 v[92:95], v[142:145], v[196:199], v[92:95]
	v_mfma_f32_16x16x32_bf16 v[84:87], v[138:141], v[200:203], v[84:87]
	v_mfma_f32_16x16x32_bf16 v[76:79], v[142:145], v[200:203], v[76:79]
	v_mfma_f32_16x16x32_bf16 v[124:127], v[146:149], v[180:183], v[124:127]
	v_mfma_f32_16x16x32_bf16 v[120:123], v[150:153], v[180:183], v[120:123]
	v_mfma_f32_16x16x32_bf16 v[116:119], v[146:149], v[192:195], v[116:119]
	v_mfma_f32_16x16x32_bf16 v[108:111], v[150:153], v[192:195], v[108:111]
	v_mfma_f32_16x16x32_bf16 v[100:103], v[146:149], v[204:207], v[100:103]
	v_mfma_f32_16x16x32_bf16 v[92:95], v[150:153], v[204:207], v[92:95]
	v_mfma_f32_16x16x32_bf16 v[84:87], v[146:149], v[208:211], v[84:87]
	v_mfma_f32_16x16x32_bf16 v[76:79], v[150:153], v[208:211], v[76:79]
	s_setprio 0
	s_setprio 1
	v_mfma_f32_16x16x32_bf16 v[112:115], v[154:157], v[172:175], v[112:115]
	v_mfma_f32_16x16x32_bf16 v[104:107], v[158:161], v[172:175], v[104:107]
	v_mfma_f32_16x16x32_bf16 v[96:99], v[154:157], v[176:179], v[96:99]
	v_mfma_f32_16x16x32_bf16 v[88:91], v[158:161], v[176:179], v[88:91]
	v_mfma_f32_16x16x32_bf16 v[80:83], v[154:157], v[196:199], v[80:83]
	v_mfma_f32_16x16x32_bf16 v[72:75], v[158:161], v[196:199], v[72:75]
	v_mfma_f32_16x16x32_bf16 v[68:71], v[154:157], v[200:203], v[68:71]
	v_mfma_f32_16x16x32_bf16 v[64:67], v[158:161], v[200:203], v[64:67]
	v_mfma_f32_16x16x32_bf16 v[112:115], v[162:165], v[180:183], v[112:115]
	v_mfma_f32_16x16x32_bf16 v[104:107], v[166:169], v[180:183], v[104:107]
	v_mfma_f32_16x16x32_bf16 v[96:99], v[162:165], v[192:195], v[96:99]
	v_mfma_f32_16x16x32_bf16 v[88:91], v[166:169], v[192:195], v[88:91]
	v_mfma_f32_16x16x32_bf16 v[80:83], v[162:165], v[204:207], v[80:83]
	v_mfma_f32_16x16x32_bf16 v[72:75], v[166:169], v[204:207], v[72:75]
	v_mfma_f32_16x16x32_bf16 v[68:71], v[162:165], v[208:211], v[68:71]
	v_mfma_f32_16x16x32_bf16 v[64:67], v[166:169], v[208:211], v[64:67]
	s_barrier
	s_setprio 0
	v_mov_b32_e32 v128, v135
	s_nop 0
	s_nop 0
	s_nop 0
	s_nop 0
	v_xad_u32 v128, v128, 64, 0
	ds_read_b128 v[172:175], v129 offset:49152
	ds_read_b128 v[176:179], v129 offset:51200
	ds_read_b128 v[180:183], v128 offset:49152
	ds_read_b128 v[192:195], v128 offset:51200
	ds_read_b128 v[196:199], v129 offset:53248
	ds_read_b128 v[200:203], v129 offset:55296
	ds_read_b128 v[204:207], v128 offset:53248
	ds_read_b128 v[208:211], v128 offset:55296
	s_mov_b32 m0, s35
	s_nop 0
	global_load_lds_dwordx4 v131, s[36:37]
	s_mov_b32 m0, s33
	s_nop 0
	global_load_lds_dwordx4 v133, s[36:37]
	s_mov_b32 m0, s77
	s_nop 0
	global_load_lds_dwordx4 v131, s[56:57]
	s_mov_b32 m0, s3
	s_nop 0
	global_load_lds_dwordx4 v133, s[56:57]
	s_mov_b32 m0, s22
	s_nop 0
	global_load_lds_dwordx4 v130, s[30:31]
	s_mov_b32 m0, s2
	s_nop 0
	global_load_lds_dwordx4 v132, s[30:31]
	s_waitcnt vmcnt(8)
	s_waitcnt lgkmcnt(0)
	s_setprio 1
	s_barrier
	v_mfma_f32_16x16x32_bf16 v[60:63], v[138:141], v[172:175], v[60:63]
	v_mfma_f32_16x16x32_bf16 v[56:59], v[142:145], v[172:175], v[56:59]
	v_mfma_f32_16x16x32_bf16 v[52:55], v[138:141], v[176:179], v[52:55]
	v_mfma_f32_16x16x32_bf16 v[44:47], v[142:145], v[176:179], v[44:47]
	v_mfma_f32_16x16x32_bf16 v[36:39], v[138:141], v[196:199], v[36:39]
	v_mfma_f32_16x16x32_bf16 v[28:31], v[142:145], v[196:199], v[28:31]
	v_mfma_f32_16x16x32_bf16 v[20:23], v[138:141], v[200:203], v[20:23]
	v_mfma_f32_16x16x32_bf16 v[12:15], v[142:145], v[200:203], v[12:15]
	v_mfma_f32_16x16x32_bf16 v[60:63], v[146:149], v[180:183], v[60:63]
	v_mfma_f32_16x16x32_bf16 v[56:59], v[150:153], v[180:183], v[56:59]
	v_mfma_f32_16x16x32_bf16 v[52:55], v[146:149], v[192:195], v[52:55]
	v_mfma_f32_16x16x32_bf16 v[44:47], v[150:153], v[192:195], v[44:47]
	v_mfma_f32_16x16x32_bf16 v[36:39], v[146:149], v[204:207], v[36:39]
	v_mfma_f32_16x16x32_bf16 v[28:31], v[150:153], v[204:207], v[28:31]
	v_mfma_f32_16x16x32_bf16 v[20:23], v[146:149], v[208:211], v[20:23]
	v_mfma_f32_16x16x32_bf16 v[12:15], v[150:153], v[208:211], v[12:15]
	s_setprio 0
	s_setprio 1
	v_mfma_f32_16x16x32_bf16 v[48:51], v[154:157], v[172:175], v[48:51]
	v_mfma_f32_16x16x32_bf16 v[40:43], v[158:161], v[172:175], v[40:43]
	v_mfma_f32_16x16x32_bf16 v[32:35], v[154:157], v[176:179], v[32:35]
	v_mfma_f32_16x16x32_bf16 v[24:27], v[158:161], v[176:179], v[24:27]
	v_mfma_f32_16x16x32_bf16 v[16:19], v[154:157], v[196:199], v[16:19]
	v_mfma_f32_16x16x32_bf16 v[8:11], v[158:161], v[196:199], v[8:11]
	v_mfma_f32_16x16x32_bf16 v[4:7], v[154:157], v[200:203], v[4:7]
	v_mfma_f32_16x16x32_bf16 v[0:3], v[158:161], v[200:203], v[0:3]
	v_mfma_f32_16x16x32_bf16 v[48:51], v[162:165], v[180:183], v[48:51]
	v_mfma_f32_16x16x32_bf16 v[40:43], v[166:169], v[180:183], v[40:43]
	v_mfma_f32_16x16x32_bf16 v[32:35], v[162:165], v[192:195], v[32:35]
	v_mfma_f32_16x16x32_bf16 v[24:27], v[166:169], v[192:195], v[24:27]
	v_mfma_f32_16x16x32_bf16 v[16:19], v[162:165], v[204:207], v[16:19]
	v_mfma_f32_16x16x32_bf16 v[8:11], v[166:169], v[204:207], v[8:11]
	v_mfma_f32_16x16x32_bf16 v[4:7], v[162:165], v[208:211], v[4:7]
	v_mfma_f32_16x16x32_bf16 v[0:3], v[166:169], v[208:211], v[0:3]
	s_barrier
	s_setprio 0
	s_andn2_b64 vcc, exec, s[12:13]
	s_mov_b64 s[36:37], -1
	s_mov_b64 s[12:13], 0
	s_mov_b64 s[30:31], 0x100
	s_cbranch_vccz .LBB0_1342

; #define PG8_STAGE(bufoff, gbase, voff) do { _Pragma("unroll") for (int _i = 0; _i < 2; ++_i) \
;         dma16((const char*)(gbase), (voff)[_i], ldsb + (bufoff) + ldsw + _i * 8192); } while (0)
; #define PG8_LDA(dst, b, h) do { const int a1_ = opqv(aoff0) ^ 64; _Pragma("unroll") for (int m = 0; m < 4; ++m) { dst[m][0] = *(const LAS bf16x8*)(lds + PG8_SA(b, h) + aoff0 + m * 2048); dst[m][1] = *(const LAS bf16x8*)(lds + PG8_SA(b, h) + a1_ + m * 2048); } } while (0)
; #define PG8_WAIT_V(n) asm volatile("s_waitcnt vmcnt(" #n ")" ::: "memory")
; #define PG8_BAR __builtin_amdgcn_s_barrier()
; template <class Epi>
; __device__ __forceinline__ void gemm_phase(LAS unsigned char* lds, const Gemm g, const StaticOrder& S, const Epi& E, int wave_) {
;     ...
;         const bool has_next = S.next(ui + 1, nxt);
;         const char* nA = has_next ? (const char*)g.A + (size_t)nxt.pm * tstepA : cA; const char* nB = has_next ? (const char*)g.Bt + (size_t)nxt.pn * tstepB : cB;
; #pragma unroll 1
;         for (int t = 0; t < nt; t += 2) {
;             const bool last = (t == nt - 2);
;             const char* a1 = cA + (size_t)(t + 1) * kstep;
;             const char* a2 = last ? nA : cA + (size_t)(t + 2) * kstep; const char* b2 = last ? nB : cB + (size_t)(t + 2) * kstep;
;             const char* a3 = a2 + kstep; const char* b3 = b2 + kstep;
;             PG8_STAGE(PG8_SA(1, 1), a1 + hstepA, voffA); PG8_LDB(B0, 0, 0); PG8_LDB(B1, 0, 1); PG8_SCHED; PG8_LDA(At, 0, 0);
;             PG8_WAIT_V(8); PG8_WAIT_L(0); PG8_BAR; PG8_MMA(0, 0, At, B0); PG8_MMA(0, 1, At, B1); PG8_BAR; PG8_SCHED;
;             PG8_STAGE(PG8_SB(0, 0), b2, voffB); PG8_STAGE(PG8_SB(0, 1), b2 + hstepB, voffB); PG8_STAGE(PG8_SA(0, 0), a2, voffA); PG8_LDA(At, 0, 1);
;             PG8_WAIT_V(8); PG8_WAIT_L(0); PG8_BAR; PG8_MMA(1, 0, At, B0); PG8_MMA(1, 1, At, B1); PG8_BAR; PG8_SCHED;
;             PG8_STAGE(PG8_SA(0, 1), a2 + hstepA, voffA); PG8_LDB(B0, 1, 0); PG8_LDB(B1, 1, 1); PG8_SCHED; PG8_LDA(At, 1, 0);
;             PG8_WAIT_V(8); PG8_WAIT_L(0); PG8_BAR; PG8_MMA(0, 0, At, B0); PG8_MMA(0, 1, At, B1); PG8_BAR; PG8_SCHED;
;             PG8_STAGE(PG8_SB(1, 0), b3, voffB); PG8_STAGE(PG8_SB(1, 1), b3 + hstepB, voffB); PG8_STAGE(PG8_SA(1, 0), a3, voffA); PG8_LDA(At, 1, 1);
;             PG8_WAIT_V(8); PG8_WAIT_L(0); PG8_BAR; PG8_MMA(1, 0, At, B0); PG8_MMA(1, 1, At, B1); PG8_BAR; PG8_SCHED;
.LBB0_1551:
	s_add_u32 s16, s12, 0x100
	s_addc_u32 s17, s13, 0
	s_add_u32 s12, s36, 0x160080
	s_addc_u32 s13, s37, 0
	s_mov_b32 s59, -2
	s_add_u32 s36, s12, 0xffea0080
	s_addc_u32 s37, s13, -1
	s_cmpk_eq_i32 s59, 0x54
	s_cselect_b32 s46, s26, s36
	s_cselect_b32 s47, s27, s37
	s_cselect_b32 s40, s30, s16
	s_cselect_b32 s41, s31, s17
	s_add_u32 s36, s46, 0x80
	v_mov_b32_e32 v64, v219
	s_addc_u32 s37, s47, 0
	v_add_u32_e32 v68, s23, v219
	v_xad_u32 v76, v64, 64, s23
	v_mov_b32_e32 v80, v219
	s_add_i32 s60, 0, 0x14000
	ds_read_b128 v[64:67], v68
	ds_read_b128 v[68:71], v68 offset:2048
	ds_read_b128 v[72:75], v76
	ds_read_b128 v[76:79], v76 offset:2048
	v_add_u32_e32 v84, s60, v219
	v_xad_u32 v92, v80, 64, s60
	ds_read_b128 v[80:83], v84
	ds_read_b128 v[84:87], v84 offset:2048
	ds_read_b128 v[88:91], v92
	ds_read_b128 v[92:95], v92 offset:2048
	v_mov_b32_e32 v160, v218
	v_add_u32_e32 v191, 0, v218
	v_xad_u32 v190, v160, 64, 0
	ds_read_b128 v[160:163], v191
	ds_read_b128 v[164:167], v191 offset:2048
	ds_read_b128 v[168:171], v190
	ds_read_b128 v[172:175], v190 offset:2048
	ds_read_b128 v[176:179], v191 offset:4096
	ds_read_b128 v[180:183], v191 offset:6144
	ds_read_b128 v[192:195], v190 offset:4096
	ds_read_b128 v[196:199], v190 offset:6144
	s_mov_b32 m0, s14
	s_nop 0
	global_load_lds_dwordx4 v184, s[12:13]
	s_mov_b32 m0, s15
	s_nop 0
	global_load_lds_dwordx4 v215, s[12:13]
	s_waitcnt vmcnt(8)
	s_waitcnt lgkmcnt(0)
	s_setprio 1
	s_barrier
	v_mfma_f32_16x16x32_bf16 v[156:159], v[64:67], v[160:163], 0
	v_mfma_f32_16x16x32_bf16 v[152:155], v[68:71], v[160:163], 0
	v_mfma_f32_16x16x32_bf16 v[140:143], v[64:67], v[164:167], 0
	v_mfma_f32_16x16x32_bf16 v[136:139], v[68:71], v[164:167], 0
	v_mfma_f32_16x16x32_bf16 v[124:127], v[64:67], v[176:179], 0
	v_mfma_f32_16x16x32_bf16 v[120:123], v[68:71], v[176:179], 0
	v_mfma_f32_16x16x32_bf16 v[108:111], v[64:67], v[180:183], 0
	v_mfma_f32_16x16x32_bf16 v[104:107], v[68:71], v[180:183], 0
	v_mfma_f32_16x16x32_bf16 v[156:159], v[72:75], v[168:171], v[156:159]
	v_mfma_f32_16x16x32_bf16 v[152:155], v[76:79], v[168:171], v[152:155]
	v_mfma_f32_16x16x32_bf16 v[140:143], v[72:75], v[172:175], v[140:143]
	v_mfma_f32_16x16x32_bf16 v[136:139], v[76:79], v[172:175], v[136:139]
	v_mfma_f32_16x16x32_bf16 v[124:127], v[72:75], v[192:195], v[124:127]
	v_mfma_f32_16x16x32_bf16 v[120:123], v[76:79], v[192:195], v[120:123]
	v_mfma_f32_16x16x32_bf16 v[108:111], v[72:75], v[196:199], v[108:111]
	v_mfma_f32_16x16x32_bf16 v[104:107], v[76:79], v[196:199], v[104:107]
	s_setprio 0
	s_setprio 1
	v_mfma_f32_16x16x32_bf16 v[148:151], v[80:83], v[160:163], 0
	v_mfma_f32_16x16x32_bf16 v[144:147], v[84:87], v[160:163], 0
	v_mfma_f32_16x16x32_bf16 v[132:135], v[80:83], v[164:167], 0
	v_mfma_f32_16x16x32_bf16 v[128:131], v[84:87], v[164:167], 0
	v_mfma_f32_16x16x32_bf16 v[116:119], v[80:83], v[176:179], 0
	v_mfma_f32_16x16x32_bf16 v[112:115], v[84:87], v[176:179], 0
	v_mfma_f32_16x16x32_bf16 v[100:103], v[80:83], v[180:183], 0
	v_mfma_f32_16x16x32_bf16 v[96:99], v[84:87], v[180:183], 0
	v_mfma_f32_16x16x32_bf16 v[148:151], v[88:91], v[168:171], v[148:151]
	v_mfma_f32_16x16x32_bf16 v[144:147], v[92:95], v[168:171], v[144:147]
	v_mfma_f32_16x16x32_bf16 v[132:135], v[88:91], v[172:175], v[132:135]
	v_mfma_f32_16x16x32_bf16 v[128:131], v[92:95], v[172:175], v[128:131]
	v_mfma_f32_16x16x32_bf16 v[116:119], v[88:91], v[192:195], v[116:119]
	v_mfma_f32_16x16x32_bf16 v[112:115], v[92:95], v[192:195], v[112:115]
	v_mfma_f32_16x16x32_bf16 v[100:103], v[88:91], v[196:199], v[100:103]
	v_mfma_f32_16x16x32_bf16 v[96:99], v[92:95], v[196:199], v[96:99]
	s_barrier
	s_setprio 0
	v_mov_b32_e32 v160, v218
	s_add_u32 s60, s40, 0x160000
	s_addc_u32 s61, s41, 0
	s_nop 0
	s_nop 0
	s_nop 0
	v_xad_u32 v190, v160, 64, 0
	ds_read_b128 v[160:163], v191 offset:16384
	ds_read_b128 v[164:167], v191 offset:18432
	ds_read_b128 v[168:171], v190 offset:16384
	ds_read_b128 v[172:175], v190 offset:18432
	ds_read_b128 v[176:179], v191 offset:20480
	ds_read_b128 v[180:183], v191 offset:22528
	ds_read_b128 v[192:195], v190 offset:20480
	ds_read_b128 v[196:199], v190 offset:22528
	s_mov_b32 m0, s80
	s_nop 0
	global_load_lds_dwordx4 v214, s[40:41]
	s_mov_b32 m0, s81
	s_nop 0
	global_load_lds_dwordx4 v216, s[40:41]
	s_mov_b32 m0, s29
	s_nop 0
	global_load_lds_dwordx4 v214, s[60:61]
	s_mov_b32 m0, s88
	s_nop 0
	global_load_lds_dwordx4 v216, s[60:61]
	s_mov_b32 m0, s76
	s_nop 0
	global_load_lds_dwordx4 v184, s[46:47]
	s_mov_b32 m0, s89
	s_nop 0
	global_load_lds_dwordx4 v215, s[46:47]
	s_waitcnt vmcnt(8)
	s_waitcnt lgkmcnt(0)
	s_setprio 1
	s_barrier
	v_mfma_f32_16x16x32_bf16 v[60:63], v[64:67], v[160:163], 0
	v_mfma_f32_16x16x32_bf16 v[56:59], v[68:71], v[160:163], 0
	v_mfma_f32_16x16x32_bf16 v[44:47], v[64:67], v[164:167], 0
	v_mfma_f32_16x16x32_bf16 v[40:43], v[68:71], v[164:167], 0
	v_mfma_f32_16x16x32_bf16 v[28:31], v[64:67], v[176:179], 0
	v_mfma_f32_16x16x32_bf16 v[24:27], v[68:71], v[176:179], 0
	v_mfma_f32_16x16x32_bf16 v[12:15], v[64:67], v[180:183], 0
	v_mfma_f32_16x16x32_bf16 v[8:11], v[68:71], v[180:183], 0
	v_mfma_f32_16x16x32_bf16 v[60:63], v[72:75], v[168:171], v[60:63]
	v_mfma_f32_16x16x32_bf16 v[56:59], v[76:79], v[168:171], v[56:59]
	v_mfma_f32_16x16x32_bf16 v[44:47], v[72:75], v[172:175], v[44:47]
	v_mfma_f32_16x16x32_bf16 v[40:43], v[76:79], v[172:175], v[40:43]
	v_mfma_f32_16x16x32_bf16 v[28:31], v[72:75], v[192:195], v[28:31]
	v_mfma_f32_16x16x32_bf16 v[24:27], v[76:79], v[192:195], v[24:27]
	v_mfma_f32_16x16x32_bf16 v[12:15], v[72:75], v[196:199], v[12:15]
	v_mfma_f32_16x16x32_bf16 v[8:11], v[76:79], v[196:199], v[8:11]
	s_setprio 0
	s_setprio 1
	v_mfma_f32_16x16x32_bf16 v[52:55], v[80:83], v[160:163], 0
	v_mfma_f32_16x16x32_bf16 v[48:51], v[84:87], v[160:163], 0
	v_mfma_f32_16x16x32_bf16 v[36:39], v[80:83], v[164:167], 0
	v_mfma_f32_16x16x32_bf16 v[32:35], v[84:87], v[164:167], 0
	v_mfma_f32_16x16x32_bf16 v[20:23], v[80:83], v[176:179], 0
	v_mfma_f32_16x16x32_bf16 v[16:19], v[84:87], v[176:179], 0
	v_mfma_f32_16x16x32_bf16 v[4:7], v[80:83], v[180:183], 0
	v_mfma_f32_16x16x32_bf16 v[0:3], v[84:87], v[180:183], 0
	v_mfma_f32_16x16x32_bf16 v[52:55], v[88:91], v[168:171], v[52:55]
	v_mfma_f32_16x16x32_bf16 v[48:51], v[92:95], v[168:171], v[48:51]
	v_mfma_f32_16x16x32_bf16 v[36:39], v[88:91], v[172:175], v[36:39]
	v_mfma_f32_16x16x32_bf16 v[32:35], v[92:95], v[172:175], v[32:35]
	v_mfma_f32_16x16x32_bf16 v[20:23], v[88:91], v[192:195], v[20:23]
	v_mfma_f32_16x16x32_bf16 v[16:19], v[92:95], v[192:195], v[16:19]
	v_mfma_f32_16x16x32_bf16 v[4:7], v[88:91], v[196:199], v[4:7]
	v_mfma_f32_16x16x32_bf16 v[0:3], v[92:95], v[196:199], v[0:3]
	s_barrier
; #define PG8_STAGE(bufoff, gbase, voff) do { _Pragma("unroll") for (int _i = 0; _i < 2; ++_i) \
;         dma16((const char*)(gbase), (voff)[_i], ldsb + (bufoff) + ldsw + _i * 8192); } while (0)
; #define PG8_LDA(dst, b, h) do { const int a1_ = opqv(aoff0) ^ 64; _Pragma("unroll") for (int m = 0; m < 4; ++m) { dst[m][0] = *(const LAS bf16x8*)(lds + PG8_SA(b, h) + aoff0 + m * 2048); dst[m][1] = *(const LAS bf16x8*)(lds + PG8_SA(b, h) + a1_ + m * 2048); } } while (0)
; #define PG8_LDB(dst, b, h) do { const int b1_ = opqv(boff0) ^ 64; _Pragma("unroll") for (int n = 0; n < 2; ++n) { dst[n][0] = *(const LAS bf16x8*)(lds + PG8_SB(b, h) + boff0 + n * 2048); dst[n][1] = *(const LAS bf16x8*)(lds + PG8_SB(b, h) + b1_ + n * 2048); } } while (0)
; #define PG8_MMA(ai, bj, At, Bt) do { __builtin_amdgcn_s_setprio(1); _Pragma("unroll") for (int m = 0; m < 4; ++m) _Pragma("unroll") for (int n = 0; n < 2; ++n) _Pragma("unroll") for (int k = 0; k < 2; ++k) \
;         acc[ai][bj][m][n] = __builtin_amdgcn_mfma_f32_16x16x32_bf16(Bt[n][k], At[m][k], acc[ai][bj][m][n], 0, 0, 0); __builtin_amdgcn_s_setprio(0); } while (0)
; #define PG8_WAIT_V(n) asm volatile("s_waitcnt vmcnt(" #n ")" ::: "memory")
; #define PG8_WAIT_L(n) asm volatile("s_waitcnt lgkmcnt(" #n ")" ::: "memory")
; #define PG8_BAR __builtin_amdgcn_s_barrier()
; #define PG8_SCHED __builtin_amdgcn_sched_barrier(0)
; template <class Epi>
; __device__ __forceinline__ void gemm_phase(LAS unsigned char* lds, const Gemm g, const StaticOrder& S, const Epi& E, int wave_) {
;     ...
;             PG8_STAGE(PG8_SA(0, 1), a2 + hstepA, voffA); PG8_LDB(B0, 1, 0); PG8_LDB(B1, 1, 1); PG8_SCHED; PG8_LDA(At, 1, 0);
;             PG8_WAIT_V(8); PG8_WAIT_L(0); PG8_BAR; PG8_MMA(0, 0, At, B0); PG8_MMA(0, 1, At, B1); PG8_BAR; PG8_SCHED;
;             PG8_STAGE(PG8_SB(1, 0), b3, voffB); PG8_STAGE(PG8_SB(1, 1), b3 + hstepB, voffB); PG8_STAGE(PG8_SA(1, 0), a3, voffA); PG8_LDA(At, 1, 1);
;             PG8_WAIT_V(8); PG8_WAIT_L(0); PG8_BAR; PG8_MMA(1, 0, At, B0); PG8_MMA(1, 1, At, B1); PG8_BAR; PG8_SCHED;
;         }
	s_setprio 0
	s_add_u32 s46, s46, 0x160000
	s_addc_u32 s47, s47, 0
	s_mov_b32 m0, s1
	s_nop 0
	global_load_lds_dwordx4 v184, s[46:47]
	v_mov_b32_e32 v64, v219
	s_mov_b32 m0, s69
	s_nop 0
	global_load_lds_dwordx4 v215, s[46:47]
	v_add_u32_e32 v68, s34, v219
	v_xad_u32 v76, v64, 64, s34
	v_mov_b32_e32 v80, v219
	s_add_i32 s46, 0, 0x1c000
	ds_read_b128 v[64:67], v68
	ds_read_b128 v[68:71], v68 offset:2048
	ds_read_b128 v[72:75], v76
	ds_read_b128 v[76:79], v76 offset:2048
	v_add_u32_e32 v84, s46, v219
	v_xad_u32 v92, v80, 64, s46
	ds_read_b128 v[80:83], v84
	ds_read_b128 v[84:87], v84 offset:2048
	ds_read_b128 v[88:91], v92
	ds_read_b128 v[92:95], v92 offset:2048
	v_mov_b32_e32 v160, v218
	s_nop 0
	v_xad_u32 v190, v160, 64, 0
	ds_read_b128 v[160:163], v191 offset:32768
	ds_read_b128 v[164:167], v191 offset:34816
	ds_read_b128 v[168:171], v190 offset:32768
	ds_read_b128 v[172:175], v190 offset:34816
	ds_read_b128 v[176:179], v191 offset:36864
	ds_read_b128 v[180:183], v191 offset:38912
	ds_read_b128 v[192:195], v190 offset:36864
	ds_read_b128 v[196:199], v190 offset:38912
	s_waitcnt vmcnt(8)
	s_waitcnt lgkmcnt(0)
	s_setprio 1
	s_barrier
	v_mfma_f32_16x16x32_bf16 v[156:159], v[64:67], v[160:163], v[156:159]
	v_mfma_f32_16x16x32_bf16 v[152:155], v[68:71], v[160:163], v[152:155]
	v_mfma_f32_16x16x32_bf16 v[140:143], v[64:67], v[164:167], v[140:143]
	v_mfma_f32_16x16x32_bf16 v[136:139], v[68:71], v[164:167], v[136:139]
	v_mfma_f32_16x16x32_bf16 v[124:127], v[64:67], v[176:179], v[124:127]
	v_mfma_f32_16x16x32_bf16 v[120:123], v[68:71], v[176:179], v[120:123]
	v_mfma_f32_16x16x32_bf16 v[108:111], v[64:67], v[180:183], v[108:111]
	v_mfma_f32_16x16x32_bf16 v[104:107], v[68:71], v[180:183], v[104:107]
	v_mfma_f32_16x16x32_bf16 v[156:159], v[72:75], v[168:171], v[156:159]
	v_mfma_f32_16x16x32_bf16 v[152:155], v[76:79], v[168:171], v[152:155]
	v_mfma_f32_16x16x32_bf16 v[140:143], v[72:75], v[172:175], v[140:143]
	v_mfma_f32_16x16x32_bf16 v[136:139], v[76:79], v[172:175], v[136:139]
	v_mfma_f32_16x16x32_bf16 v[124:127], v[72:75], v[192:195], v[124:127]
	v_mfma_f32_16x16x32_bf16 v[120:123], v[76:79], v[192:195], v[120:123]
	v_mfma_f32_16x16x32_bf16 v[108:111], v[72:75], v[196:199], v[108:111]
	v_mfma_f32_16x16x32_bf16 v[104:107], v[76:79], v[196:199], v[104:107]
	s_setprio 0
	s_setprio 1
	v_mfma_f32_16x16x32_bf16 v[148:151], v[80:83], v[160:163], v[148:151]
	s_add_u32 s46, s40, 0x80
	s_addc_u32 s47, s41, 0
	v_mfma_f32_16x16x32_bf16 v[144:147], v[84:87], v[160:163], v[144:147]
	v_mfma_f32_16x16x32_bf16 v[132:135], v[80:83], v[164:167], v[132:135]
	v_mfma_f32_16x16x32_bf16 v[128:131], v[84:87], v[164:167], v[128:131]
	v_mfma_f32_16x16x32_bf16 v[116:119], v[80:83], v[176:179], v[116:119]
	v_mfma_f32_16x16x32_bf16 v[112:115], v[84:87], v[176:179], v[112:115]
	v_mfma_f32_16x16x32_bf16 v[100:103], v[80:83], v[180:183], v[100:103]
	v_mfma_f32_16x16x32_bf16 v[96:99], v[84:87], v[180:183], v[96:99]
	v_mfma_f32_16x16x32_bf16 v[148:151], v[88:91], v[168:171], v[148:151]
	v_mfma_f32_16x16x32_bf16 v[144:147], v[92:95], v[168:171], v[144:147]
	v_mfma_f32_16x16x32_bf16 v[132:135], v[88:91], v[172:175], v[132:135]
	v_mfma_f32_16x16x32_bf16 v[128:131], v[92:95], v[172:175], v[128:131]
	v_mfma_f32_16x16x32_bf16 v[116:119], v[88:91], v[192:195], v[116:119]
	v_mfma_f32_16x16x32_bf16 v[112:115], v[92:95], v[192:195], v[112:115]
	v_mfma_f32_16x16x32_bf16 v[100:103], v[88:91], v[196:199], v[100:103]
	v_mfma_f32_16x16x32_bf16 v[96:99], v[92:95], v[196:199], v[96:99]
	s_barrier
	s_setprio 0
	s_add_u32 s40, s40, 0x160080
	s_addc_u32 s41, s41, 0
	v_mov_b32_e32 v160, v218
	s_nop 0
	s_nop 0
	v_xad_u32 v190, v160, 64, 0
	ds_read_b128 v[160:163], v191 offset:49152
	ds_read_b128 v[164:167], v191 offset:51200
	ds_read_b128 v[168:171], v190 offset:49152
	ds_read_b128 v[172:175], v190 offset:51200
	ds_read_b128 v[176:179], v191 offset:53248
	ds_read_b128 v[180:183], v191 offset:55296
	ds_read_b128 v[192:195], v190 offset:53248
	ds_read_b128 v[196:199], v190 offset:55296
	s_mov_b32 m0, s35
	s_nop 0
	global_load_lds_dwordx4 v214, s[46:47]
	s_mov_b32 m0, s33
	s_nop 0
	global_load_lds_dwordx4 v216, s[46:47]
	s_mov_b32 m0, s77
	s_nop 0
	global_load_lds_dwordx4 v214, s[40:41]
	s_mov_b32 m0, s3
	s_nop 0
	global_load_lds_dwordx4 v216, s[40:41]
	s_mov_b32 m0, s22
	s_nop 0
	global_load_lds_dwordx4 v184, s[36:37]
	s_mov_b32 m0, s2
	s_nop 0
	global_load_lds_dwordx4 v215, s[36:37]
	s_waitcnt vmcnt(8)
	s_waitcnt lgkmcnt(0)
	s_setprio 1
	s_barrier
	v_mfma_f32_16x16x32_bf16 v[60:63], v[64:67], v[160:163], v[60:63]
	v_mfma_f32_16x16x32_bf16 v[56:59], v[68:71], v[160:163], v[56:59]
	v_mfma_f32_16x16x32_bf16 v[44:47], v[64:67], v[164:167], v[44:47]
	v_mfma_f32_16x16x32_bf16 v[40:43], v[68:71], v[164:167], v[40:43]
	v_mfma_f32_16x16x32_bf16 v[28:31], v[64:67], v[176:179], v[28:31]
	v_mfma_f32_16x16x32_bf16 v[24:27], v[68:71], v[176:179], v[24:27]
	v_mfma_f32_16x16x32_bf16 v[12:15], v[64:67], v[180:183], v[12:15]
	v_mfma_f32_16x16x32_bf16 v[8:11], v[68:71], v[180:183], v[8:11]
	v_mfma_f32_16x16x32_bf16 v[60:63], v[72:75], v[168:171], v[60:63]
	v_mfma_f32_16x16x32_bf16 v[56:59], v[76:79], v[168:171], v[56:59]
	v_mfma_f32_16x16x32_bf16 v[44:47], v[72:75], v[172:175], v[44:47]
	v_mfma_f32_16x16x32_bf16 v[40:43], v[76:79], v[172:175], v[40:43]
	v_mfma_f32_16x16x32_bf16 v[28:31], v[72:75], v[192:195], v[28:31]
	v_mfma_f32_16x16x32_bf16 v[24:27], v[76:79], v[192:195], v[24:27]
	v_mfma_f32_16x16x32_bf16 v[12:15], v[72:75], v[196:199], v[12:15]
	v_mfma_f32_16x16x32_bf16 v[8:11], v[76:79], v[196:199], v[8:11]
	s_setprio 0
	s_setprio 1
	v_mfma_f32_16x16x32_bf16 v[52:55], v[80:83], v[160:163], v[52:55]
	v_mfma_f32_16x16x32_bf16 v[48:51], v[84:87], v[160:163], v[48:51]
	v_mfma_f32_16x16x32_bf16 v[36:39], v[80:83], v[164:167], v[36:39]
	v_mfma_f32_16x16x32_bf16 v[32:35], v[84:87], v[164:167], v[32:35]
	v_mfma_f32_16x16x32_bf16 v[20:23], v[80:83], v[176:179], v[20:23]
	v_mfma_f32_16x16x32_bf16 v[16:19], v[84:87], v[176:179], v[16:19]
	v_mfma_f32_16x16x32_bf16 v[4:7], v[80:83], v[180:183], v[4:7]
	v_mfma_f32_16x16x32_bf16 v[0:3], v[84:87], v[180:183], v[0:3]
	v_mfma_f32_16x16x32_bf16 v[52:55], v[88:91], v[168:171], v[52:55]
	v_mfma_f32_16x16x32_bf16 v[48:51], v[92:95], v[168:171], v[48:51]
	v_mfma_f32_16x16x32_bf16 v[36:39], v[88:91], v[172:175], v[36:39]
	v_mfma_f32_16x16x32_bf16 v[32:35], v[92:95], v[172:175], v[32:35]
	v_mfma_f32_16x16x32_bf16 v[20:23], v[88:91], v[192:195], v[20:23]
	v_mfma_f32_16x16x32_bf16 v[16:19], v[92:95], v[192:195], v[16:19]
	v_mfma_f32_16x16x32_bf16 v[4:7], v[88:91], v[196:199], v[4:7]
	v_mfma_f32_16x16x32_bf16 v[0:3], v[92:95], v[196:199], v[0:3]
	s_barrier
	s_setprio 0
	s_add_i32 s59, s59, 2
	s_add_u32 s16, s16, 0x100
	s_addc_u32 s17, s17, 0
	s_add_u32 s12, s12, 0x100
	s_addc_u32 s13, s13, 0
	s_cmpk_gt_u32 s59, 0x55
	s_cbranch_scc0 .LBB0_1552
	s_branch .Lpeel_exit_1
; #define PG8_STAGE(bufoff, gbase, voff) do { _Pragma("unroll") for (int _i = 0; _i < 2; ++_i) \
;         dma16((const char*)(gbase), (voff)[_i], ldsb + (bufoff) + ldsw + _i * 8192); } while (0)
; #define PG8_LDA(dst, b, h) do { const int a1_ = opqv(aoff0) ^ 64; _Pragma("unroll") for (int m = 0; m < 4; ++m) { dst[m][0] = *(const LAS bf16x8*)(lds + PG8_SA(b, h) + aoff0 + m * 2048); dst[m][1] = *(const LAS bf16x8*)(lds + PG8_SA(b, h) + a1_ + m * 2048); } } while (0)
; #define PG8_LDB(dst, b, h) do { const int b1_ = opqv(boff0) ^ 64; _Pragma("unroll") for (int n = 0; n < 2; ++n) { dst[n][0] = *(const LAS bf16x8*)(lds + PG8_SB(b, h) + boff0 + n * 2048); dst[n][1] = *(const LAS bf16x8*)(lds + PG8_SB(b, h) + b1_ + n * 2048); } } while (0)
; #define PG8_MMA(ai, bj, At, Bt) do { __builtin_amdgcn_s_setprio(1); _Pragma("unroll") for (int m = 0; m < 4; ++m) _Pragma("unroll") for (int n = 0; n < 2; ++n) _Pragma("unroll") for (int k = 0; k < 2; ++k) \
;         acc[ai][bj][m][n] = __builtin_amdgcn_mfma_f32_16x16x32_bf16(Bt[n][k], At[m][k], acc[ai][bj][m][n], 0, 0, 0); __builtin_amdgcn_s_setprio(0); } while (0)
; #define PG8_WAIT_V(n) asm volatile("s_waitcnt vmcnt(" #n ")" ::: "memory")
; #define PG8_WAIT_L(n) asm volatile("s_waitcnt lgkmcnt(" #n ")" ::: "memory")
; #define PG8_BAR __builtin_amdgcn_s_barrier()
; #define PG8_SCHED __builtin_amdgcn_sched_barrier(0)
; template <class Epi>
; __device__ __forceinline__ void gemm_phase(LAS unsigned char* lds, const Gemm g, const StaticOrder& S, const Epi& E, int wave_) {
;     ...
;             const char* a2 = last ? nA : cA + (size_t)(t + 2) * kstep; const char* b2 = last ? nB : cB + (size_t)(t + 2) * kstep;
;             const char* a3 = a2 + kstep; const char* b3 = b2 + kstep;
;             PG8_STAGE(PG8_SA(1, 1), a1 + hstepA, voffA); PG8_LDB(B0, 0, 0); PG8_LDB(B1, 0, 1); PG8_SCHED; PG8_LDA(At, 0, 0);
;             PG8_WAIT_V(8); PG8_WAIT_L(0); PG8_BAR; PG8_MMA(0, 0, At, B0); PG8_MMA(0, 1, At, B1); PG8_BAR; PG8_SCHED;
;             PG8_STAGE(PG8_SB(0, 0), b2, voffB); PG8_STAGE(PG8_SB(0, 1), b2 + hstepB, voffB); PG8_STAGE(PG8_SA(0, 0), a2, voffA); PG8_LDA(At, 0, 1);
;             PG8_WAIT_V(8); PG8_WAIT_L(0); PG8_BAR; PG8_MMA(1, 0, At, B0); PG8_MMA(1, 1, At, B1); PG8_BAR; PG8_SCHED;
;             PG8_STAGE(PG8_SA(0, 1), a2 + hstepA, voffA); PG8_LDB(B0, 1, 0); PG8_LDB(B1, 1, 1); PG8_SCHED; PG8_LDA(At, 1, 0);
.LBB0_1552:
	s_add_u32 s36, s12, 0xffea0080
	s_addc_u32 s37, s13, -1
	s_cmpk_eq_i32 s59, 0x54
	s_cselect_b32 s46, s26, s36
	s_cselect_b32 s47, s27, s37
	s_cselect_b32 s40, s30, s16
	s_cselect_b32 s41, s31, s17
	s_add_u32 s36, s46, 0x80
	v_mov_b32_e32 v64, v219
	s_addc_u32 s37, s47, 0
	v_add_u32_e32 v68, s23, v219
	v_xad_u32 v76, v64, 64, s23
	v_mov_b32_e32 v80, v219
	s_add_i32 s60, 0, 0x14000
	ds_read_b128 v[64:67], v68
	ds_read_b128 v[68:71], v68 offset:2048
	ds_read_b128 v[72:75], v76
	ds_read_b128 v[76:79], v76 offset:2048
	v_add_u32_e32 v84, s60, v219
	v_xad_u32 v92, v80, 64, s60
	ds_read_b128 v[80:83], v84
	ds_read_b128 v[84:87], v84 offset:2048
	ds_read_b128 v[88:91], v92
	ds_read_b128 v[92:95], v92 offset:2048
	v_mov_b32_e32 v160, v218
	v_add_u32_e32 v191, 0, v218
	v_xad_u32 v190, v160, 64, 0
	ds_read_b128 v[160:163], v191
	ds_read_b128 v[164:167], v191 offset:2048
	ds_read_b128 v[168:171], v190
	ds_read_b128 v[172:175], v190 offset:2048
	ds_read_b128 v[176:179], v191 offset:4096
	ds_read_b128 v[180:183], v191 offset:6144
	ds_read_b128 v[192:195], v190 offset:4096
	ds_read_b128 v[196:199], v190 offset:6144
	s_mov_b32 m0, s14
	s_nop 0
	global_load_lds_dwordx4 v184, s[12:13]
	s_mov_b32 m0, s15
	s_nop 0
	global_load_lds_dwordx4 v215, s[12:13]
	s_waitcnt vmcnt(8)
	s_waitcnt lgkmcnt(0)
	s_setprio 1
	s_barrier
	v_mfma_f32_16x16x32_bf16 v[156:159], v[64:67], v[160:163], v[156:159]
	v_mfma_f32_16x16x32_bf16 v[152:155], v[68:71], v[160:163], v[152:155]
	v_mfma_f32_16x16x32_bf16 v[140:143], v[64:67], v[164:167], v[140:143]
	v_mfma_f32_16x16x32_bf16 v[136:139], v[68:71], v[164:167], v[136:139]
	v_mfma_f32_16x16x32_bf16 v[124:127], v[64:67], v[176:179], v[124:127]
	v_mfma_f32_16x16x32_bf16 v[120:123], v[68:71], v[176:179], v[120:123]
	v_mfma_f32_16x16x32_bf16 v[108:111], v[64:67], v[180:183], v[108:111]
	v_mfma_f32_16x16x32_bf16 v[104:107], v[68:71], v[180:183], v[104:107]
	v_mfma_f32_16x16x32_bf16 v[156:159], v[72:75], v[168:171], v[156:159]
	v_mfma_f32_16x16x32_bf16 v[152:155], v[76:79], v[168:171], v[152:155]
	v_mfma_f32_16x16x32_bf16 v[140:143], v[72:75], v[172:175], v[140:143]
	v_mfma_f32_16x16x32_bf16 v[136:139], v[76:79], v[172:175], v[136:139]
	v_mfma_f32_16x16x32_bf16 v[124:127], v[72:75], v[192:195], v[124:127]
	v_mfma_f32_16x16x32_bf16 v[120:123], v[76:79], v[192:195], v[120:123]
	v_mfma_f32_16x16x32_bf16 v[108:111], v[72:75], v[196:199], v[108:111]
	v_mfma_f32_16x16x32_bf16 v[104:107], v[76:79], v[196:199], v[104:107]
	s_setprio 0
	s_setprio 1
	v_mfma_f32_16x16x32_bf16 v[148:151], v[80:83], v[160:163], v[148:151]
	v_mfma_f32_16x16x32_bf16 v[144:147], v[84:87], v[160:163], v[144:147]
	v_mfma_f32_16x16x32_bf16 v[132:135], v[80:83], v[164:167], v[132:135]
	v_mfma_f32_16x16x32_bf16 v[128:131], v[84:87], v[164:167], v[128:131]
	v_mfma_f32_16x16x32_bf16 v[116:119], v[80:83], v[176:179], v[116:119]
	v_mfma_f32_16x16x32_bf16 v[112:115], v[84:87], v[176:179], v[112:115]
	v_mfma_f32_16x16x32_bf16 v[100:103], v[80:83], v[180:183], v[100:103]
	v_mfma_f32_16x16x32_bf16 v[96:99], v[84:87], v[180:183], v[96:99]
	v_mfma_f32_16x16x32_bf16 v[148:151], v[88:91], v[168:171], v[148:151]
	v_mfma_f32_16x16x32_bf16 v[144:147], v[92:95], v[168:171], v[144:147]
	v_mfma_f32_16x16x32_bf16 v[132:135], v[88:91], v[172:175], v[132:135]
	v_mfma_f32_16x16x32_bf16 v[128:131], v[92:95], v[172:175], v[128:131]
	v_mfma_f32_16x16x32_bf16 v[116:119], v[88:91], v[192:195], v[116:119]
	v_mfma_f32_16x16x32_bf16 v[112:115], v[92:95], v[192:195], v[112:115]
	v_mfma_f32_16x16x32_bf16 v[100:103], v[88:91], v[196:199], v[100:103]
	v_mfma_f32_16x16x32_bf16 v[96:99], v[92:95], v[196:199], v[96:99]
	s_barrier
	s_setprio 0
	v_mov_b32_e32 v160, v218
	s_add_u32 s60, s40, 0x160000
	s_addc_u32 s61, s41, 0
	s_nop 0
	s_nop 0
	s_nop 0
	v_xad_u32 v190, v160, 64, 0
	ds_read_b128 v[160:163], v191 offset:16384
	ds_read_b128 v[164:167], v191 offset:18432
	ds_read_b128 v[168:171], v190 offset:16384
	ds_read_b128 v[172:175], v190 offset:18432
	ds_read_b128 v[176:179], v191 offset:20480
	ds_read_b128 v[180:183], v191 offset:22528
	ds_read_b128 v[192:195], v190 offset:20480
	ds_read_b128 v[196:199], v190 offset:22528
	s_mov_b32 m0, s80
	s_nop 0
	global_load_lds_dwordx4 v214, s[40:41]
	s_mov_b32 m0, s81
	s_nop 0
	global_load_lds_dwordx4 v216, s[40:41]
	s_mov_b32 m0, s29
	s_nop 0
	global_load_lds_dwordx4 v214, s[60:61]
	s_mov_b32 m0, s88
	s_nop 0
	global_load_lds_dwordx4 v216, s[60:61]
	s_mov_b32 m0, s76
	s_nop 0
	global_load_lds_dwordx4 v184, s[46:47]
	s_mov_b32 m0, s89
	s_nop 0
	global_load_lds_dwordx4 v215, s[46:47]
	s_waitcnt vmcnt(8)
	s_waitcnt lgkmcnt(0)
	s_setprio 1
	s_barrier
; #define PG8_STAGE(bufoff, gbase, voff) do { _Pragma("unroll") for (int _i = 0; _i < 2; ++_i) \
;         dma16((const char*)(gbase), (voff)[_i], ldsb + (bufoff) + ldsw + _i * 8192); } while (0)
; #define PG8_LDA(dst, b, h) do { const int a1_ = opqv(aoff0) ^ 64; _Pragma("unroll") for (int m = 0; m < 4; ++m) { dst[m][0] = *(const LAS bf16x8*)(lds + PG8_SA(b, h) + aoff0 + m * 2048); dst[m][1] = *(const LAS bf16x8*)(lds + PG8_SA(b, h) + a1_ + m * 2048); } } while (0)
; #define PG8_LDB(dst, b, h) do { const int b1_ = opqv(boff0) ^ 64; _Pragma("unroll") for (int n = 0; n < 2; ++n) { dst[n][0] = *(const LAS bf16x8*)(lds + PG8_SB(b, h) + boff0 + n * 2048); dst[n][1] = *(const LAS bf16x8*)(lds + PG8_SB(b, h) + b1_ + n * 2048); } } while (0)
; #define PG8_MMA(ai, bj, At, Bt) do { __builtin_amdgcn_s_setprio(1); _Pragma("unroll") for (int m = 0; m < 4; ++m) _Pragma("unroll") for (int n = 0; n < 2; ++n) _Pragma("unroll") for (int k = 0; k < 2; ++k) \
;         acc[ai][bj][m][n] = __builtin_amdgcn_mfma_f32_16x16x32_bf16(Bt[n][k], At[m][k], acc[ai][bj][m][n], 0, 0, 0); __builtin_amdgcn_s_setprio(0); } while (0)
; #define PG8_WAIT_V(n) asm volatile("s_waitcnt vmcnt(" #n ")" ::: "memory")
; #define PG8_WAIT_L(n) asm volatile("s_waitcnt lgkmcnt(" #n ")" ::: "memory")
; #define PG8_BAR __builtin_amdgcn_s_barrier()
; #define PG8_SCHED __builtin_amdgcn_sched_barrier(0)
; template <class Epi>
; __device__ __forceinline__ void gemm_phase(LAS unsigned char* lds, const Gemm g, const StaticOrder& S, const Epi& E, int wave_) {
;     ...
;             PG8_WAIT_V(8); PG8_WAIT_L(0); PG8_BAR; PG8_MMA(1, 0, At, B0); PG8_MMA(1, 1, At, B1); PG8_BAR; PG8_SCHED;
;             PG8_STAGE(PG8_SA(0, 1), a2 + hstepA, voffA); PG8_LDB(B0, 1, 0); PG8_LDB(B1, 1, 1); PG8_SCHED; PG8_LDA(At, 1, 0);
;             PG8_WAIT_V(8); PG8_WAIT_L(0); PG8_BAR; PG8_MMA(0, 0, At, B0); PG8_MMA(0, 1, At, B1); PG8_BAR; PG8_SCHED;
	v_mfma_f32_16x16x32_bf16 v[60:63], v[64:67], v[160:163], v[60:63]
	v_mfma_f32_16x16x32_bf16 v[56:59], v[68:71], v[160:163], v[56:59]
	v_mfma_f32_16x16x32_bf16 v[44:47], v[64:67], v[164:167], v[44:47]
	v_mfma_f32_16x16x32_bf16 v[40:43], v[68:71], v[164:167], v[40:43]
	v_mfma_f32_16x16x32_bf16 v[28:31], v[64:67], v[176:179], v[28:31]
	v_mfma_f32_16x16x32_bf16 v[24:27], v[68:71], v[176:179], v[24:27]
	v_mfma_f32_16x16x32_bf16 v[12:15], v[64:67], v[180:183], v[12:15]
	v_mfma_f32_16x16x32_bf16 v[8:11], v[68:71], v[180:183], v[8:11]
	v_mfma_f32_16x16x32_bf16 v[60:63], v[72:75], v[168:171], v[60:63]
	v_mfma_f32_16x16x32_bf16 v[56:59], v[76:79], v[168:171], v[56:59]
	v_mfma_f32_16x16x32_bf16 v[44:47], v[72:75], v[172:175], v[44:47]
	v_mfma_f32_16x16x32_bf16 v[40:43], v[76:79], v[172:175], v[40:43]
	v_mfma_f32_16x16x32_bf16 v[28:31], v[72:75], v[192:195], v[28:31]
	v_mfma_f32_16x16x32_bf16 v[24:27], v[76:79], v[192:195], v[24:27]
	v_mfma_f32_16x16x32_bf16 v[12:15], v[72:75], v[196:199], v[12:15]
	v_mfma_f32_16x16x32_bf16 v[8:11], v[76:79], v[196:199], v[8:11]
	s_setprio 0
	s_setprio 1
	v_mfma_f32_16x16x32_bf16 v[52:55], v[80:83], v[160:163], v[52:55]
	v_mfma_f32_16x16x32_bf16 v[48:51], v[84:87], v[160:163], v[48:51]
	v_mfma_f32_16x16x32_bf16 v[36:39], v[80:83], v[164:167], v[36:39]
	v_mfma_f32_16x16x32_bf16 v[32:35], v[84:87], v[164:167], v[32:35]
	v_mfma_f32_16x16x32_bf16 v[20:23], v[80:83], v[176:179], v[20:23]
	v_mfma_f32_16x16x32_bf16 v[16:19], v[84:87], v[176:179], v[16:19]
	v_mfma_f32_16x16x32_bf16 v[4:7], v[80:83], v[180:183], v[4:7]
	v_mfma_f32_16x16x32_bf16 v[0:3], v[84:87], v[180:183], v[0:3]
	v_mfma_f32_16x16x32_bf16 v[52:55], v[88:91], v[168:171], v[52:55]
	v_mfma_f32_16x16x32_bf16 v[48:51], v[92:95], v[168:171], v[48:51]
	v_mfma_f32_16x16x32_bf16 v[36:39], v[88:91], v[172:175], v[36:39]
	v_mfma_f32_16x16x32_bf16 v[32:35], v[92:95], v[172:175], v[32:35]
	v_mfma_f32_16x16x32_bf16 v[20:23], v[88:91], v[192:195], v[20:23]
	v_mfma_f32_16x16x32_bf16 v[16:19], v[92:95], v[192:195], v[16:19]
	v_mfma_f32_16x16x32_bf16 v[4:7], v[88:91], v[196:199], v[4:7]
	v_mfma_f32_16x16x32_bf16 v[0:3], v[92:95], v[196:199], v[0:3]
	s_barrier
	s_setprio 0
	s_add_u32 s46, s46, 0x160000
	s_addc_u32 s47, s47, 0
	s_mov_b32 m0, s1
	s_nop 0
	global_load_lds_dwordx4 v184, s[46:47]
	v_mov_b32_e32 v64, v219
	s_mov_b32 m0, s69
	s_nop 0
	global_load_lds_dwordx4 v215, s[46:47]
	v_add_u32_e32 v68, s34, v219
	v_xad_u32 v76, v64, 64, s34
	v_mov_b32_e32 v80, v219
	s_add_i32 s46, 0, 0x1c000
	ds_read_b128 v[64:67], v68
	ds_read_b128 v[68:71], v68 offset:2048
	ds_read_b128 v[72:75], v76
	ds_read_b128 v[76:79], v76 offset:2048
	v_add_u32_e32 v84, s46, v219
	v_xad_u32 v92, v80, 64, s46
	ds_read_b128 v[80:83], v84
	ds_read_b128 v[84:87], v84 offset:2048
	ds_read_b128 v[88:91], v92
	ds_read_b128 v[92:95], v92 offset:2048
	v_mov_b32_e32 v160, v218
	s_nop 0
	v_xad_u32 v190, v160, 64, 0
	ds_read_b128 v[160:163], v191 offset:32768
	ds_read_b128 v[164:167], v191 offset:34816
	ds_read_b128 v[168:171], v190 offset:32768
	ds_read_b128 v[172:175], v190 offset:34816
	ds_read_b128 v[176:179], v191 offset:36864
	ds_read_b128 v[180:183], v191 offset:38912
	ds_read_b128 v[192:195], v190 offset:36864
	ds_read_b128 v[196:199], v190 offset:38912
	s_waitcnt vmcnt(8)
	s_waitcnt lgkmcnt(0)
	s_setprio 1
	s_barrier
	v_mfma_f32_16x16x32_bf16 v[156:159], v[64:67], v[160:163], v[156:159]
	v_mfma_f32_16x16x32_bf16 v[152:155], v[68:71], v[160:163], v[152:155]
	v_mfma_f32_16x16x32_bf16 v[140:143], v[64:67], v[164:167], v[140:143]
	v_mfma_f32_16x16x32_bf16 v[136:139], v[68:71], v[164:167], v[136:139]
	v_mfma_f32_16x16x32_bf16 v[124:127], v[64:67], v[176:179], v[124:127]
	v_mfma_f32_16x16x32_bf16 v[120:123], v[68:71], v[176:179], v[120:123]
	v_mfma_f32_16x16x32_bf16 v[108:111], v[64:67], v[180:183], v[108:111]
	v_mfma_f32_16x16x32_bf16 v[104:107], v[68:71], v[180:183], v[104:107]
	v_mfma_f32_16x16x32_bf16 v[156:159], v[72:75], v[168:171], v[156:159]
	v_mfma_f32_16x16x32_bf16 v[152:155], v[76:79], v[168:171], v[152:155]
	v_mfma_f32_16x16x32_bf16 v[140:143], v[72:75], v[172:175], v[140:143]
	v_mfma_f32_16x16x32_bf16 v[136:139], v[76:79], v[172:175], v[136:139]
	v_mfma_f32_16x16x32_bf16 v[124:127], v[72:75], v[192:195], v[124:127]
	v_mfma_f32_16x16x32_bf16 v[120:123], v[76:79], v[192:195], v[120:123]
	v_mfma_f32_16x16x32_bf16 v[108:111], v[72:75], v[196:199], v[108:111]
	v_mfma_f32_16x16x32_bf16 v[104:107], v[76:79], v[196:199], v[104:107]
	s_setprio 0
	s_setprio 1
	v_mfma_f32_16x16x32_bf16 v[148:151], v[80:83], v[160:163], v[148:151]
	s_add_u32 s46, s40, 0x80
	s_addc_u32 s47, s41, 0
	v_mfma_f32_16x16x32_bf16 v[144:147], v[84:87], v[160:163], v[144:147]
	v_mfma_f32_16x16x32_bf16 v[132:135], v[80:83], v[164:167], v[132:135]
	v_mfma_f32_16x16x32_bf16 v[128:131], v[84:87], v[164:167], v[128:131]
	v_mfma_f32_16x16x32_bf16 v[116:119], v[80:83], v[176:179], v[116:119]
	v_mfma_f32_16x16x32_bf16 v[112:115], v[84:87], v[176:179], v[112:115]
	v_mfma_f32_16x16x32_bf16 v[100:103], v[80:83], v[180:183], v[100:103]
	v_mfma_f32_16x16x32_bf16 v[96:99], v[84:87], v[180:183], v[96:99]
	v_mfma_f32_16x16x32_bf16 v[148:151], v[88:91], v[168:171], v[148:151]
	v_mfma_f32_16x16x32_bf16 v[144:147], v[92:95], v[168:171], v[144:147]
	v_mfma_f32_16x16x32_bf16 v[132:135], v[88:91], v[172:175], v[132:135]
	v_mfma_f32_16x16x32_bf16 v[128:131], v[92:95], v[172:175], v[128:131]
	v_mfma_f32_16x16x32_bf16 v[116:119], v[88:91], v[192:195], v[116:119]
	v_mfma_f32_16x16x32_bf16 v[112:115], v[92:95], v[192:195], v[112:115]
	v_mfma_f32_16x16x32_bf16 v[100:103], v[88:91], v[196:199], v[100:103]
	v_mfma_f32_16x16x32_bf16 v[96:99], v[92:95], v[196:199], v[96:99]
	s_barrier
; #define PG8_STAGE(bufoff, gbase, voff) do { _Pragma("unroll") for (int _i = 0; _i < 2; ++_i) \
;         dma16((const char*)(gbase), (voff)[_i], ldsb + (bufoff) + ldsw + _i * 8192); } while (0)
; #define PG8_LDA(dst, b, h) do { const int a1_ = opqv(aoff0) ^ 64; _Pragma("unroll") for (int m = 0; m < 4; ++m) { dst[m][0] = *(const LAS bf16x8*)(lds + PG8_SA(b, h) + aoff0 + m * 2048); dst[m][1] = *(const LAS bf16x8*)(lds + PG8_SA(b, h) + a1_ + m * 2048); } } while (0)
; #define PG8_MMA(ai, bj, At, Bt) do { __builtin_amdgcn_s_setprio(1); _Pragma("unroll") for (int m = 0; m < 4; ++m) _Pragma("unroll") for (int n = 0; n < 2; ++n) _Pragma("unroll") for (int k = 0; k < 2; ++k) \
;         acc[ai][bj][m][n] = __builtin_amdgcn_mfma_f32_16x16x32_bf16(Bt[n][k], At[m][k], acc[ai][bj][m][n], 0, 0, 0); __builtin_amdgcn_s_setprio(0); } while (0)
; #define PG8_WAIT_V(n) asm volatile("s_waitcnt vmcnt(" #n ")" ::: "memory")
; #define PG8_WAIT_L(n) asm volatile("s_waitcnt lgkmcnt(" #n ")" ::: "memory")
; #define PG8_BAR __builtin_amdgcn_s_barrier()
; #define PG8_SCHED __builtin_amdgcn_sched_barrier(0)
; template <class Epi>
; __device__ __forceinline__ void gemm_phase(LAS unsigned char* lds, const Gemm g, const StaticOrder& S, const Epi& E, int wave_) {
;     ...
;             PG8_STAGE(PG8_SB(1, 0), b3, voffB); PG8_STAGE(PG8_SB(1, 1), b3 + hstepB, voffB); PG8_STAGE(PG8_SA(1, 0), a3, voffA); PG8_LDA(At, 1, 1);
;             PG8_WAIT_V(8); PG8_WAIT_L(0); PG8_BAR; PG8_MMA(1, 0, At, B0); PG8_MMA(1, 1, At, B1); PG8_BAR; PG8_SCHED;
;         }
	s_setprio 0
	s_add_u32 s40, s40, 0x160080
	s_addc_u32 s41, s41, 0
	v_mov_b32_e32 v160, v218
	s_nop 0
	s_nop 0
	v_xad_u32 v190, v160, 64, 0
	ds_read_b128 v[160:163], v191 offset:49152
	ds_read_b128 v[164:167], v191 offset:51200
	ds_read_b128 v[168:171], v190 offset:49152
	ds_read_b128 v[172:175], v190 offset:51200
	ds_read_b128 v[176:179], v191 offset:53248
	ds_read_b128 v[180:183], v191 offset:55296
	ds_read_b128 v[192:195], v190 offset:53248
	ds_read_b128 v[196:199], v190 offset:55296
	s_mov_b32 m0, s35
	s_nop 0
	global_load_lds_dwordx4 v214, s[46:47]
	s_mov_b32 m0, s33
	s_nop 0
	global_load_lds_dwordx4 v216, s[46:47]
	s_mov_b32 m0, s77
	s_nop 0
	global_load_lds_dwordx4 v214, s[40:41]
	s_mov_b32 m0, s3
	s_nop 0
	global_load_lds_dwordx4 v216, s[40:41]
	s_mov_b32 m0, s22
	s_nop 0
	global_load_lds_dwordx4 v184, s[36:37]
	s_mov_b32 m0, s2
	s_nop 0
	global_load_lds_dwordx4 v215, s[36:37]
	s_waitcnt vmcnt(8)
	s_waitcnt lgkmcnt(0)
	s_setprio 1
	s_barrier
	v_mfma_f32_16x16x32_bf16 v[60:63], v[64:67], v[160:163], v[60:63]
	v_mfma_f32_16x16x32_bf16 v[56:59], v[68:71], v[160:163], v[56:59]
	v_mfma_f32_16x16x32_bf16 v[44:47], v[64:67], v[164:167], v[44:47]
	v_mfma_f32_16x16x32_bf16 v[40:43], v[68:71], v[164:167], v[40:43]
	v_mfma_f32_16x16x32_bf16 v[28:31], v[64:67], v[176:179], v[28:31]
	v_mfma_f32_16x16x32_bf16 v[24:27], v[68:71], v[176:179], v[24:27]
	v_mfma_f32_16x16x32_bf16 v[12:15], v[64:67], v[180:183], v[12:15]
	v_mfma_f32_16x16x32_bf16 v[8:11], v[68:71], v[180:183], v[8:11]
	v_mfma_f32_16x16x32_bf16 v[60:63], v[72:75], v[168:171], v[60:63]
	v_mfma_f32_16x16x32_bf16 v[56:59], v[76:79], v[168:171], v[56:59]
	v_mfma_f32_16x16x32_bf16 v[44:47], v[72:75], v[172:175], v[44:47]
	v_mfma_f32_16x16x32_bf16 v[40:43], v[76:79], v[172:175], v[40:43]
	v_mfma_f32_16x16x32_bf16 v[28:31], v[72:75], v[192:195], v[28:31]
	v_mfma_f32_16x16x32_bf16 v[24:27], v[76:79], v[192:195], v[24:27]
	v_mfma_f32_16x16x32_bf16 v[12:15], v[72:75], v[196:199], v[12:15]
	v_mfma_f32_16x16x32_bf16 v[8:11], v[76:79], v[196:199], v[8:11]
	s_setprio 0
	s_setprio 1
	v_mfma_f32_16x16x32_bf16 v[52:55], v[80:83], v[160:163], v[52:55]
	v_mfma_f32_16x16x32_bf16 v[48:51], v[84:87], v[160:163], v[48:51]
	v_mfma_f32_16x16x32_bf16 v[36:39], v[80:83], v[164:167], v[36:39]
	v_mfma_f32_16x16x32_bf16 v[32:35], v[84:87], v[164:167], v[32:35]
	v_mfma_f32_16x16x32_bf16 v[20:23], v[80:83], v[176:179], v[20:23]
	v_mfma_f32_16x16x32_bf16 v[16:19], v[84:87], v[176:179], v[16:19]
	v_mfma_f32_16x16x32_bf16 v[4:7], v[80:83], v[180:183], v[4:7]
	v_mfma_f32_16x16x32_bf16 v[0:3], v[84:87], v[180:183], v[0:3]
	v_mfma_f32_16x16x32_bf16 v[52:55], v[88:91], v[168:171], v[52:55]
	v_mfma_f32_16x16x32_bf16 v[48:51], v[92:95], v[168:171], v[48:51]
	v_mfma_f32_16x16x32_bf16 v[36:39], v[88:91], v[172:175], v[36:39]
	v_mfma_f32_16x16x32_bf16 v[32:35], v[92:95], v[172:175], v[32:35]
	v_mfma_f32_16x16x32_bf16 v[20:23], v[88:91], v[192:195], v[20:23]
	v_mfma_f32_16x16x32_bf16 v[16:19], v[92:95], v[192:195], v[16:19]
	v_mfma_f32_16x16x32_bf16 v[4:7], v[88:91], v[196:199], v[4:7]
	v_mfma_f32_16x16x32_bf16 v[0:3], v[92:95], v[196:199], v[0:3]
	s_barrier
	s_setprio 0
	s_add_i32 s59, s59, 2
	s_add_u32 s16, s16, 0x100
	s_addc_u32 s17, s17, 0
	s_add_u32 s12, s12, 0x100
	s_addc_u32 s13, s13, 0
	s_cmpk_gt_u32 s59, 0x55
	s_cbranch_scc0 .LBB0_1552

; #define PG8_STAGE(bufoff, gbase, voff) do { _Pragma("unroll") for (int _i = 0; _i < 2; ++_i) \
;         dma16((const char*)(gbase), (voff)[_i], ldsb + (bufoff) + ldsw + _i * 8192); } while (0)
; #define PG8_LDA(dst, b, h) do { const int a1_ = opqv(aoff0) ^ 64; _Pragma("unroll") for (int m = 0; m < 4; ++m) { dst[m][0] = *(const LAS bf16x8*)(lds + PG8_SA(b, h) + aoff0 + m * 2048); dst[m][1] = *(const LAS bf16x8*)(lds + PG8_SA(b, h) + a1_ + m * 2048); } } while (0)
; #define PG8_WAIT_V(n) asm volatile("s_waitcnt vmcnt(" #n ")" ::: "memory")
; #define PG8_BAR __builtin_amdgcn_s_barrier()
; template <class Epi>
; __device__ __forceinline__ void gemm_phase(LAS unsigned char* lds, const Gemm g, const StaticOrder& S, const Epi& E, int wave_) {
;     ...
;         const bool has_next = S.next(ui + 1, nxt);
;         const char* nA = has_next ? (const char*)g.A + (size_t)nxt.pm * tstepA : cA; const char* nB = has_next ? (const char*)g.Bt + (size_t)nxt.pn * tstepB : cB;
; #pragma unroll 1
;         for (int t = 0; t < nt; t += 2) {
;             const bool last = (t == nt - 2);
;             const char* a1 = cA + (size_t)(t + 1) * kstep;
;             const char* a2 = last ? nA : cA + (size_t)(t + 2) * kstep; const char* b2 = last ? nB : cB + (size_t)(t + 2) * kstep;
;             const char* a3 = a2 + kstep; const char* b3 = b2 + kstep;
;             PG8_STAGE(PG8_SA(1, 1), a1 + hstepA, voffA); PG8_LDB(B0, 0, 0); PG8_LDB(B1, 0, 1); PG8_SCHED; PG8_LDA(At, 0, 0);
;             PG8_WAIT_V(8); PG8_WAIT_L(0); PG8_BAR; PG8_MMA(0, 0, At, B0); PG8_MMA(0, 1, At, B1); PG8_BAR; PG8_SCHED;
;             PG8_STAGE(PG8_SB(0, 0), b2, voffB); PG8_STAGE(PG8_SB(0, 1), b2 + hstepB, voffB); PG8_STAGE(PG8_SA(0, 0), a2, voffA); PG8_LDA(At, 0, 1);
;             PG8_WAIT_V(8); PG8_WAIT_L(0); PG8_BAR; PG8_MMA(1, 0, At, B0); PG8_MMA(1, 1, At, B1); PG8_BAR; PG8_SCHED;
;             PG8_STAGE(PG8_SA(0, 1), a2 + hstepA, voffA); PG8_LDB(B0, 1, 0); PG8_LDB(B1, 1, 1); PG8_SCHED; PG8_LDA(At, 1, 0);
;             PG8_WAIT_V(8); PG8_WAIT_L(0); PG8_BAR; PG8_MMA(0, 0, At, B0); PG8_MMA(0, 1, At, B1); PG8_BAR; PG8_SCHED;
;             PG8_STAGE(PG8_SB(1, 0), b3, voffB); PG8_STAGE(PG8_SB(1, 1), b3 + hstepB, voffB); PG8_STAGE(PG8_SA(1, 0), a3, voffA); PG8_LDA(At, 1, 1);
;             PG8_WAIT_V(8); PG8_WAIT_L(0); PG8_BAR; PG8_MMA(1, 0, At, B0); PG8_MMA(1, 1, At, B1); PG8_BAR; PG8_SCHED;
.LBB0_1775:
	s_ashr_i32 s59, s58, 31
	s_lshl_b64 s[16:17], s[58:59], 20
	s_add_u32 s60, s21, s16
	s_addc_u32 s61, s52, s17
	s_and_b64 s[16:17], s[44:45], exec
	s_cselect_b32 s16, s61, s47
	s_cselect_b32 s17, s60, s46
	s_ashr_i32 s57, s56, 31
	s_lshl_b64 s[48:49], s[56:57], 20
	s_add_u32 s62, s66, s48
	s_addc_u32 s63, s67, s49
	s_and_b64 s[48:49], s[44:45], exec
	s_cselect_b32 s57, s63, s13
	s_cselect_b32 s59, s62, s12
	s_add_u32 s75, s12, 0x100
	s_addc_u32 s78, s13, 0
	s_add_u32 s12, s46, 0x80080
	s_addc_u32 s13, s47, 0
	s_mov_b32 s79, -2
	s_add_u32 s46, s12, 0xfff80080
	s_addc_u32 s47, s13, -1
	s_cmp_eq_u32 s79, 28
	s_cselect_b32 s64, s17, s46
	s_cselect_b32 s65, s16, s47
	s_cselect_b32 s48, s59, s75
	s_cselect_b32 s49, s57, s78
	s_add_u32 s46, s64, 0x80
	v_mov_b32_e32 v88, v238
	s_addc_u32 s47, s65, 0
	v_add_u32_e32 v92, s23, v238
	v_xad_u32 v100, v88, 64, s23
	v_mov_b32_e32 v108, v238
	s_add_i32 s82, 0, 0x14000
	ds_read_b128 v[88:91], v92
	ds_read_b128 v[92:95], v92 offset:2048
	ds_read_b128 v[96:99], v100
	ds_read_b128 v[100:103], v100 offset:2048
	v_add_u32_e32 v112, s82, v238
	v_xad_u32 v124, v108, 64, s82
	ds_read_b128 v[108:111], v112
	ds_read_b128 v[112:115], v112 offset:2048
	ds_read_b128 v[120:123], v124
	ds_read_b128 v[124:127], v124 offset:2048
	v_mov_b32_e32 v160, v237
	v_add_u32_e32 v191, 0, v237
	v_xad_u32 v190, v160, 64, 0
	ds_read_b128 v[160:163], v191
	ds_read_b128 v[164:167], v191 offset:2048
	ds_read_b128 v[168:171], v190
	ds_read_b128 v[172:175], v190 offset:2048
	ds_read_b128 v[176:179], v191 offset:4096
	ds_read_b128 v[180:183], v191 offset:6144
	ds_read_b128 v[192:195], v190 offset:4096
	ds_read_b128 v[196:199], v190 offset:6144
	s_mov_b32 m0, s14
	s_nop 0
	global_load_lds_dwordx4 v184, s[12:13]
	s_mov_b32 m0, s15
	s_nop 0
	global_load_lds_dwordx4 v234, s[12:13]
	s_waitcnt vmcnt(8)
	s_waitcnt lgkmcnt(0)
	s_setprio 1
	s_barrier
	v_mfma_f32_16x16x32_bf16 v[156:159], v[88:91], v[160:163], 0
	v_mfma_f32_16x16x32_bf16 v[152:155], v[92:95], v[160:163], 0
	v_mfma_f32_16x16x32_bf16 v[148:151], v[88:91], v[164:167], 0
	v_mfma_f32_16x16x32_bf16 v[144:147], v[92:95], v[164:167], 0
	v_mfma_f32_16x16x32_bf16 v[140:143], v[88:91], v[176:179], 0
	v_mfma_f32_16x16x32_bf16 v[136:139], v[92:95], v[176:179], 0
	v_mfma_f32_16x16x32_bf16 v[132:135], v[88:91], v[180:183], 0
	v_mfma_f32_16x16x32_bf16 v[128:131], v[92:95], v[180:183], 0
	v_mfma_f32_16x16x32_bf16 v[156:159], v[96:99], v[168:171], v[156:159]
	v_mfma_f32_16x16x32_bf16 v[152:155], v[100:103], v[168:171], v[152:155]
	v_mfma_f32_16x16x32_bf16 v[148:151], v[96:99], v[172:175], v[148:151]
	v_mfma_f32_16x16x32_bf16 v[144:147], v[100:103], v[172:175], v[144:147]
	v_mfma_f32_16x16x32_bf16 v[140:143], v[96:99], v[192:195], v[140:143]
	v_mfma_f32_16x16x32_bf16 v[136:139], v[100:103], v[192:195], v[136:139]
	v_mfma_f32_16x16x32_bf16 v[132:135], v[96:99], v[196:199], v[132:135]
	v_mfma_f32_16x16x32_bf16 v[128:131], v[100:103], v[196:199], v[128:131]
	s_setprio 0
	s_setprio 1
	v_mfma_f32_16x16x32_bf16 v[60:63], v[108:111], v[160:163], 0
	v_mfma_f32_16x16x32_bf16 v[56:59], v[112:115], v[160:163], 0
	v_mfma_f32_16x16x32_bf16 v[52:55], v[108:111], v[164:167], 0
	v_mfma_f32_16x16x32_bf16 v[48:51], v[112:115], v[164:167], 0
	v_mfma_f32_16x16x32_bf16 v[44:47], v[108:111], v[176:179], 0
	v_mfma_f32_16x16x32_bf16 v[40:43], v[112:115], v[176:179], 0
	v_mfma_f32_16x16x32_bf16 v[36:39], v[108:111], v[180:183], 0
	v_mfma_f32_16x16x32_bf16 v[32:35], v[112:115], v[180:183], 0
	v_mfma_f32_16x16x32_bf16 v[60:63], v[120:123], v[168:171], v[60:63]
	v_mfma_f32_16x16x32_bf16 v[56:59], v[124:127], v[168:171], v[56:59]
	v_mfma_f32_16x16x32_bf16 v[52:55], v[120:123], v[172:175], v[52:55]
	v_mfma_f32_16x16x32_bf16 v[48:51], v[124:127], v[172:175], v[48:51]
	v_mfma_f32_16x16x32_bf16 v[44:47], v[120:123], v[192:195], v[44:47]
	v_mfma_f32_16x16x32_bf16 v[40:43], v[124:127], v[192:195], v[40:43]
	v_mfma_f32_16x16x32_bf16 v[36:39], v[120:123], v[196:199], v[36:39]
	v_mfma_f32_16x16x32_bf16 v[32:35], v[124:127], v[196:199], v[32:35]
	s_barrier
	s_setprio 0
	v_mov_b32_e32 v160, v237
	s_add_u32 s82, s48, 0x80000
	s_addc_u32 s83, s49, 0
	s_nop 0
	s_nop 0
	s_nop 0
	v_xad_u32 v190, v160, 64, 0
	ds_read_b128 v[160:163], v191 offset:16384
	ds_read_b128 v[164:167], v191 offset:18432
	ds_read_b128 v[168:171], v190 offset:16384
	ds_read_b128 v[172:175], v190 offset:18432
	ds_read_b128 v[176:179], v191 offset:20480
	ds_read_b128 v[180:183], v191 offset:22528
	ds_read_b128 v[192:195], v190 offset:20480
	ds_read_b128 v[196:199], v190 offset:22528
	s_mov_b32 m0, s80
	s_nop 0
	global_load_lds_dwordx4 v233, s[48:49]
	s_mov_b32 m0, s81
	s_nop 0
	global_load_lds_dwordx4 v235, s[48:49]
	s_mov_b32 m0, s29
	s_nop 0
	global_load_lds_dwordx4 v233, s[82:83]
	s_mov_b32 m0, s88
	s_nop 0
	global_load_lds_dwordx4 v235, s[82:83]
	s_mov_b32 m0, s76
	s_nop 0
	global_load_lds_dwordx4 v184, s[64:65]
	s_mov_b32 m0, s89
	s_nop 0
	global_load_lds_dwordx4 v234, s[64:65]
	s_waitcnt vmcnt(8)
	s_waitcnt lgkmcnt(0)
	s_setprio 1
	s_barrier
; #define PG8_STAGE(bufoff, gbase, voff) do { _Pragma("unroll") for (int _i = 0; _i < 2; ++_i) \
;         dma16((const char*)(gbase), (voff)[_i], ldsb + (bufoff) + ldsw + _i * 8192); } while (0)
; #define PG8_LDA(dst, b, h) do { const int a1_ = opqv(aoff0) ^ 64; _Pragma("unroll") for (int m = 0; m < 4; ++m) { dst[m][0] = *(const LAS bf16x8*)(lds + PG8_SA(b, h) + aoff0 + m * 2048); dst[m][1] = *(const LAS bf16x8*)(lds + PG8_SA(b, h) + a1_ + m * 2048); } } while (0)
; #define PG8_LDB(dst, b, h) do { const int b1_ = opqv(boff0) ^ 64; _Pragma("unroll") for (int n = 0; n < 2; ++n) { dst[n][0] = *(const LAS bf16x8*)(lds + PG8_SB(b, h) + boff0 + n * 2048); dst[n][1] = *(const LAS bf16x8*)(lds + PG8_SB(b, h) + b1_ + n * 2048); } } while (0)
; #define PG8_MMA(ai, bj, At, Bt) do { __builtin_amdgcn_s_setprio(1); _Pragma("unroll") for (int m = 0; m < 4; ++m) _Pragma("unroll") for (int n = 0; n < 2; ++n) _Pragma("unroll") for (int k = 0; k < 2; ++k) \
;         acc[ai][bj][m][n] = __builtin_amdgcn_mfma_f32_16x16x32_bf16(Bt[n][k], At[m][k], acc[ai][bj][m][n], 0, 0, 0); __builtin_amdgcn_s_setprio(0); } while (0)
; #define PG8_WAIT_V(n) asm volatile("s_waitcnt vmcnt(" #n ")" ::: "memory")
; #define PG8_WAIT_L(n) asm volatile("s_waitcnt lgkmcnt(" #n ")" ::: "memory")
; #define PG8_BAR __builtin_amdgcn_s_barrier()
; #define PG8_SCHED __builtin_amdgcn_sched_barrier(0)
; template <class Epi>
; __device__ __forceinline__ void gemm_phase(LAS unsigned char* lds, const Gemm g, const StaticOrder& S, const Epi& E, int wave_) {
;     ...
;             PG8_WAIT_V(8); PG8_WAIT_L(0); PG8_BAR; PG8_MMA(1, 0, At, B0); PG8_MMA(1, 1, At, B1); PG8_BAR; PG8_SCHED;
;             PG8_STAGE(PG8_SA(0, 1), a2 + hstepA, voffA); PG8_LDB(B0, 1, 0); PG8_LDB(B1, 1, 1); PG8_SCHED; PG8_LDA(At, 1, 0);
;             PG8_WAIT_V(8); PG8_WAIT_L(0); PG8_BAR; PG8_MMA(0, 0, At, B0); PG8_MMA(0, 1, At, B1); PG8_BAR; PG8_SCHED;
	v_mfma_f32_16x16x32_bf16 v[116:119], v[88:91], v[160:163], 0
	v_mfma_f32_16x16x32_bf16 v[104:107], v[92:95], v[160:163], 0
	v_mfma_f32_16x16x32_bf16 v[84:87], v[88:91], v[164:167], 0
	v_mfma_f32_16x16x32_bf16 v[80:83], v[92:95], v[164:167], 0
	v_mfma_f32_16x16x32_bf16 v[76:79], v[88:91], v[176:179], 0
	v_mfma_f32_16x16x32_bf16 v[72:75], v[92:95], v[176:179], 0
	v_mfma_f32_16x16x32_bf16 v[68:71], v[88:91], v[180:183], 0
	v_mfma_f32_16x16x32_bf16 v[64:67], v[92:95], v[180:183], 0
	v_mfma_f32_16x16x32_bf16 v[116:119], v[96:99], v[168:171], v[116:119]
	v_mfma_f32_16x16x32_bf16 v[104:107], v[100:103], v[168:171], v[104:107]
	v_mfma_f32_16x16x32_bf16 v[84:87], v[96:99], v[172:175], v[84:87]
	v_mfma_f32_16x16x32_bf16 v[80:83], v[100:103], v[172:175], v[80:83]
	v_mfma_f32_16x16x32_bf16 v[76:79], v[96:99], v[192:195], v[76:79]
	v_mfma_f32_16x16x32_bf16 v[72:75], v[100:103], v[192:195], v[72:75]
	v_mfma_f32_16x16x32_bf16 v[68:71], v[96:99], v[196:199], v[68:71]
	v_mfma_f32_16x16x32_bf16 v[64:67], v[100:103], v[196:199], v[64:67]
	s_setprio 0
	s_setprio 1
	v_mfma_f32_16x16x32_bf16 v[28:31], v[108:111], v[160:163], 0
	v_mfma_f32_16x16x32_bf16 v[24:27], v[112:115], v[160:163], 0
	v_mfma_f32_16x16x32_bf16 v[20:23], v[108:111], v[164:167], 0
	v_mfma_f32_16x16x32_bf16 v[16:19], v[112:115], v[164:167], 0
	v_mfma_f32_16x16x32_bf16 v[12:15], v[108:111], v[176:179], 0
	v_mfma_f32_16x16x32_bf16 v[8:11], v[112:115], v[176:179], 0
	v_mfma_f32_16x16x32_bf16 v[4:7], v[108:111], v[180:183], 0
	v_mfma_f32_16x16x32_bf16 v[0:3], v[112:115], v[180:183], 0
	v_mfma_f32_16x16x32_bf16 v[28:31], v[120:123], v[168:171], v[28:31]
	v_mfma_f32_16x16x32_bf16 v[24:27], v[124:127], v[168:171], v[24:27]
	v_mfma_f32_16x16x32_bf16 v[20:23], v[120:123], v[172:175], v[20:23]
	v_mfma_f32_16x16x32_bf16 v[16:19], v[124:127], v[172:175], v[16:19]
	v_mfma_f32_16x16x32_bf16 v[12:15], v[120:123], v[192:195], v[12:15]
	v_mfma_f32_16x16x32_bf16 v[8:11], v[124:127], v[192:195], v[8:11]
	v_mfma_f32_16x16x32_bf16 v[4:7], v[120:123], v[196:199], v[4:7]
	v_mfma_f32_16x16x32_bf16 v[0:3], v[124:127], v[196:199], v[0:3]
	s_barrier
	s_setprio 0
	s_add_u32 s64, s64, 0x80000
	s_addc_u32 s65, s65, 0
	s_mov_b32 m0, s1
	s_nop 0
	global_load_lds_dwordx4 v184, s[64:65]
	v_mov_b32_e32 v88, v238
	s_mov_b32 m0, s69
	s_nop 0
	global_load_lds_dwordx4 v234, s[64:65]
	v_add_u32_e32 v92, s34, v238
	v_xad_u32 v100, v88, 64, s34
	v_mov_b32_e32 v108, v238
	s_add_i32 s64, 0, 0x1c000
	ds_read_b128 v[88:91], v92
	ds_read_b128 v[92:95], v92 offset:2048
	ds_read_b128 v[96:99], v100
	ds_read_b128 v[100:103], v100 offset:2048
	v_add_u32_e32 v112, s64, v238
	v_xad_u32 v124, v108, 64, s64
	ds_read_b128 v[108:111], v112
	ds_read_b128 v[112:115], v112 offset:2048
	ds_read_b128 v[120:123], v124
	ds_read_b128 v[124:127], v124 offset:2048
	v_mov_b32_e32 v160, v237
	s_nop 0
	v_xad_u32 v190, v160, 64, 0
	ds_read_b128 v[160:163], v191 offset:32768
	ds_read_b128 v[164:167], v191 offset:34816
	ds_read_b128 v[168:171], v190 offset:32768
	ds_read_b128 v[172:175], v190 offset:34816
	ds_read_b128 v[176:179], v191 offset:36864
	ds_read_b128 v[180:183], v191 offset:38912
	ds_read_b128 v[192:195], v190 offset:36864
	ds_read_b128 v[196:199], v190 offset:38912
	s_waitcnt vmcnt(8)
	s_waitcnt lgkmcnt(0)
	s_setprio 1
	s_barrier
	v_mfma_f32_16x16x32_bf16 v[156:159], v[88:91], v[160:163], v[156:159]
	v_mfma_f32_16x16x32_bf16 v[152:155], v[92:95], v[160:163], v[152:155]
	v_mfma_f32_16x16x32_bf16 v[148:151], v[88:91], v[164:167], v[148:151]
	v_mfma_f32_16x16x32_bf16 v[144:147], v[92:95], v[164:167], v[144:147]
	v_mfma_f32_16x16x32_bf16 v[140:143], v[88:91], v[176:179], v[140:143]
	v_mfma_f32_16x16x32_bf16 v[136:139], v[92:95], v[176:179], v[136:139]
	v_mfma_f32_16x16x32_bf16 v[132:135], v[88:91], v[180:183], v[132:135]
	v_mfma_f32_16x16x32_bf16 v[128:131], v[92:95], v[180:183], v[128:131]
	v_mfma_f32_16x16x32_bf16 v[156:159], v[96:99], v[168:171], v[156:159]
	v_mfma_f32_16x16x32_bf16 v[152:155], v[100:103], v[168:171], v[152:155]
	v_mfma_f32_16x16x32_bf16 v[148:151], v[96:99], v[172:175], v[148:151]
	v_mfma_f32_16x16x32_bf16 v[144:147], v[100:103], v[172:175], v[144:147]
	v_mfma_f32_16x16x32_bf16 v[140:143], v[96:99], v[192:195], v[140:143]
	v_mfma_f32_16x16x32_bf16 v[136:139], v[100:103], v[192:195], v[136:139]
	v_mfma_f32_16x16x32_bf16 v[132:135], v[96:99], v[196:199], v[132:135]
	v_mfma_f32_16x16x32_bf16 v[128:131], v[100:103], v[196:199], v[128:131]
	s_setprio 0
	s_setprio 1
	v_mfma_f32_16x16x32_bf16 v[60:63], v[108:111], v[160:163], v[60:63]
	s_add_u32 s64, s48, 0x80
	s_addc_u32 s65, s49, 0
	v_mfma_f32_16x16x32_bf16 v[56:59], v[112:115], v[160:163], v[56:59]
	v_mfma_f32_16x16x32_bf16 v[52:55], v[108:111], v[164:167], v[52:55]
	v_mfma_f32_16x16x32_bf16 v[48:51], v[112:115], v[164:167], v[48:51]
	v_mfma_f32_16x16x32_bf16 v[44:47], v[108:111], v[176:179], v[44:47]
	v_mfma_f32_16x16x32_bf16 v[40:43], v[112:115], v[176:179], v[40:43]
	v_mfma_f32_16x16x32_bf16 v[36:39], v[108:111], v[180:183], v[36:39]
	v_mfma_f32_16x16x32_bf16 v[32:35], v[112:115], v[180:183], v[32:35]
	v_mfma_f32_16x16x32_bf16 v[60:63], v[120:123], v[168:171], v[60:63]
	v_mfma_f32_16x16x32_bf16 v[56:59], v[124:127], v[168:171], v[56:59]
	v_mfma_f32_16x16x32_bf16 v[52:55], v[120:123], v[172:175], v[52:55]
	v_mfma_f32_16x16x32_bf16 v[48:51], v[124:127], v[172:175], v[48:51]
	v_mfma_f32_16x16x32_bf16 v[44:47], v[120:123], v[192:195], v[44:47]
	v_mfma_f32_16x16x32_bf16 v[40:43], v[124:127], v[192:195], v[40:43]
	v_mfma_f32_16x16x32_bf16 v[36:39], v[120:123], v[196:199], v[36:39]
	v_mfma_f32_16x16x32_bf16 v[32:35], v[124:127], v[196:199], v[32:35]
	s_barrier
; #define PG8_STAGE(bufoff, gbase, voff) do { _Pragma("unroll") for (int _i = 0; _i < 2; ++_i) \
;         dma16((const char*)(gbase), (voff)[_i], ldsb + (bufoff) + ldsw + _i * 8192); } while (0)
; #define PG8_LDA(dst, b, h) do { const int a1_ = opqv(aoff0) ^ 64; _Pragma("unroll") for (int m = 0; m < 4; ++m) { dst[m][0] = *(const LAS bf16x8*)(lds + PG8_SA(b, h) + aoff0 + m * 2048); dst[m][1] = *(const LAS bf16x8*)(lds + PG8_SA(b, h) + a1_ + m * 2048); } } while (0)
; #define PG8_LDB(dst, b, h) do { const int b1_ = opqv(boff0) ^ 64; _Pragma("unroll") for (int n = 0; n < 2; ++n) { dst[n][0] = *(const LAS bf16x8*)(lds + PG8_SB(b, h) + boff0 + n * 2048); dst[n][1] = *(const LAS bf16x8*)(lds + PG8_SB(b, h) + b1_ + n * 2048); } } while (0)
; #define PG8_MMA(ai, bj, At, Bt) do { __builtin_amdgcn_s_setprio(1); _Pragma("unroll") for (int m = 0; m < 4; ++m) _Pragma("unroll") for (int n = 0; n < 2; ++n) _Pragma("unroll") for (int k = 0; k < 2; ++k) \
;         acc[ai][bj][m][n] = __builtin_amdgcn_mfma_f32_16x16x32_bf16(Bt[n][k], At[m][k], acc[ai][bj][m][n], 0, 0, 0); __builtin_amdgcn_s_setprio(0); } while (0)
; #define PG8_WAIT_V(n) asm volatile("s_waitcnt vmcnt(" #n ")" ::: "memory")
; #define PG8_WAIT_L(n) asm volatile("s_waitcnt lgkmcnt(" #n ")" ::: "memory")
; #define PG8_BAR __builtin_amdgcn_s_barrier()
; template <class Epi>
; __device__ __forceinline__ void gemm_phase(LAS unsigned char* lds, const Gemm g, const StaticOrder& S, const Epi& E, int wave_) {
;     ...
;             const char* a2 = last ? nA : cA + (size_t)(t + 2) * kstep; const char* b2 = last ? nB : cB + (size_t)(t + 2) * kstep;
;             const char* a3 = a2 + kstep; const char* b3 = b2 + kstep;
;             PG8_STAGE(PG8_SA(1, 1), a1 + hstepA, voffA); PG8_LDB(B0, 0, 0); PG8_LDB(B1, 0, 1); PG8_SCHED; PG8_LDA(At, 0, 0);
;             PG8_WAIT_V(8); PG8_WAIT_L(0); PG8_BAR; PG8_MMA(0, 0, At, B0); PG8_MMA(0, 1, At, B1); PG8_BAR; PG8_SCHED;
;             PG8_STAGE(PG8_SB(0, 0), b2, voffB); PG8_STAGE(PG8_SB(0, 1), b2 + hstepB, voffB); PG8_STAGE(PG8_SA(0, 0), a2, voffA); PG8_LDA(At, 0, 1);
;     ...
;             PG8_STAGE(PG8_SB(1, 0), b3, voffB); PG8_STAGE(PG8_SB(1, 1), b3 + hstepB, voffB); PG8_STAGE(PG8_SA(1, 0), a3, voffA); PG8_LDA(At, 1, 1);
;             PG8_WAIT_V(8); PG8_WAIT_L(0); PG8_BAR; PG8_MMA(1, 0, At, B0); PG8_MMA(1, 1, At, B1); PG8_BAR; PG8_SCHED;
;         }
	s_setprio 0
	s_add_u32 s48, s48, 0x80080
	s_addc_u32 s49, s49, 0
	v_mov_b32_e32 v160, v237
	s_nop 0
	s_nop 0
	v_xad_u32 v190, v160, 64, 0
	ds_read_b128 v[160:163], v191 offset:49152
	ds_read_b128 v[164:167], v191 offset:51200
	ds_read_b128 v[168:171], v190 offset:49152
	ds_read_b128 v[172:175], v190 offset:51200
	ds_read_b128 v[176:179], v191 offset:53248
	ds_read_b128 v[180:183], v191 offset:55296
	ds_read_b128 v[192:195], v190 offset:53248
	ds_read_b128 v[196:199], v190 offset:55296
	s_mov_b32 m0, s35
	s_nop 0
	global_load_lds_dwordx4 v233, s[64:65]
	s_mov_b32 m0, s33
	s_nop 0
	global_load_lds_dwordx4 v235, s[64:65]
	s_mov_b32 m0, s77
	s_nop 0
	global_load_lds_dwordx4 v233, s[48:49]
	s_mov_b32 m0, s3
	s_nop 0
	global_load_lds_dwordx4 v235, s[48:49]
	s_mov_b32 m0, s22
	s_nop 0
	global_load_lds_dwordx4 v184, s[46:47]
	s_mov_b32 m0, s2
	s_nop 0
	global_load_lds_dwordx4 v234, s[46:47]
	s_waitcnt vmcnt(8)
	s_waitcnt lgkmcnt(0)
	s_setprio 1
	s_barrier
	v_mfma_f32_16x16x32_bf16 v[116:119], v[88:91], v[160:163], v[116:119]
	v_mfma_f32_16x16x32_bf16 v[104:107], v[92:95], v[160:163], v[104:107]
	v_mfma_f32_16x16x32_bf16 v[84:87], v[88:91], v[164:167], v[84:87]
	v_mfma_f32_16x16x32_bf16 v[80:83], v[92:95], v[164:167], v[80:83]
	v_mfma_f32_16x16x32_bf16 v[76:79], v[88:91], v[176:179], v[76:79]
	v_mfma_f32_16x16x32_bf16 v[72:75], v[92:95], v[176:179], v[72:75]
	v_mfma_f32_16x16x32_bf16 v[68:71], v[88:91], v[180:183], v[68:71]
	v_mfma_f32_16x16x32_bf16 v[64:67], v[92:95], v[180:183], v[64:67]
	v_mfma_f32_16x16x32_bf16 v[116:119], v[96:99], v[168:171], v[116:119]
	v_mfma_f32_16x16x32_bf16 v[104:107], v[100:103], v[168:171], v[104:107]
	v_mfma_f32_16x16x32_bf16 v[84:87], v[96:99], v[172:175], v[84:87]
	v_mfma_f32_16x16x32_bf16 v[80:83], v[100:103], v[172:175], v[80:83]
	v_mfma_f32_16x16x32_bf16 v[76:79], v[96:99], v[192:195], v[76:79]
	v_mfma_f32_16x16x32_bf16 v[72:75], v[100:103], v[192:195], v[72:75]
	v_mfma_f32_16x16x32_bf16 v[68:71], v[96:99], v[196:199], v[68:71]
	v_mfma_f32_16x16x32_bf16 v[64:67], v[100:103], v[196:199], v[64:67]
	s_setprio 0
	s_setprio 1
	v_mfma_f32_16x16x32_bf16 v[28:31], v[108:111], v[160:163], v[28:31]
	v_mfma_f32_16x16x32_bf16 v[24:27], v[112:115], v[160:163], v[24:27]
	v_mfma_f32_16x16x32_bf16 v[20:23], v[108:111], v[164:167], v[20:23]
	v_mfma_f32_16x16x32_bf16 v[16:19], v[112:115], v[164:167], v[16:19]
	v_mfma_f32_16x16x32_bf16 v[12:15], v[108:111], v[176:179], v[12:15]
	v_mfma_f32_16x16x32_bf16 v[8:11], v[112:115], v[176:179], v[8:11]
	v_mfma_f32_16x16x32_bf16 v[4:7], v[108:111], v[180:183], v[4:7]
	v_mfma_f32_16x16x32_bf16 v[0:3], v[112:115], v[180:183], v[0:3]
	v_mfma_f32_16x16x32_bf16 v[28:31], v[120:123], v[168:171], v[28:31]
	v_mfma_f32_16x16x32_bf16 v[24:27], v[124:127], v[168:171], v[24:27]
	v_mfma_f32_16x16x32_bf16 v[20:23], v[120:123], v[172:175], v[20:23]
	v_mfma_f32_16x16x32_bf16 v[16:19], v[124:127], v[172:175], v[16:19]
	v_mfma_f32_16x16x32_bf16 v[12:15], v[120:123], v[192:195], v[12:15]
	v_mfma_f32_16x16x32_bf16 v[8:11], v[124:127], v[192:195], v[8:11]
	v_mfma_f32_16x16x32_bf16 v[4:7], v[120:123], v[196:199], v[4:7]
	v_mfma_f32_16x16x32_bf16 v[0:3], v[124:127], v[196:199], v[0:3]
	s_barrier
	s_setprio 0
	s_add_i32 s79, s79, 2
	s_add_u32 s75, s75, 0x100
	s_addc_u32 s78, s78, 0
	s_add_u32 s12, s12, 0x100
	s_addc_u32 s13, s13, 0
	s_cmp_gt_u32 s79, 29
	s_cbranch_scc0 .LBB0_1776
	s_branch .Lpeel_exit_0
.LBB0_1776:
	s_add_u32 s46, s12, 0xfff80080
	s_addc_u32 s47, s13, -1
	s_cmp_eq_u32 s79, 28
	s_cselect_b32 s64, s17, s46
	s_cselect_b32 s65, s16, s47
	s_cselect_b32 s48, s59, s75
	s_cselect_b32 s49, s57, s78
	s_add_u32 s46, s64, 0x80
	v_mov_b32_e32 v88, v238
	s_addc_u32 s47, s65, 0
	v_add_u32_e32 v92, s23, v238
	v_xad_u32 v100, v88, 64, s23
	v_mov_b32_e32 v108, v238
	s_add_i32 s82, 0, 0x14000
	ds_read_b128 v[88:91], v92
	ds_read_b128 v[92:95], v92 offset:2048
	ds_read_b128 v[96:99], v100
	ds_read_b128 v[100:103], v100 offset:2048
	v_add_u32_e32 v112, s82, v238
	v_xad_u32 v124, v108, 64, s82
	ds_read_b128 v[108:111], v112
	ds_read_b128 v[112:115], v112 offset:2048
	ds_read_b128 v[120:123], v124
	ds_read_b128 v[124:127], v124 offset:2048
	v_mov_b32_e32 v160, v237
	v_add_u32_e32 v191, 0, v237
	v_xad_u32 v190, v160, 64, 0
	ds_read_b128 v[160:163], v191
	ds_read_b128 v[164:167], v191 offset:2048
	ds_read_b128 v[168:171], v190
	ds_read_b128 v[172:175], v190 offset:2048
	ds_read_b128 v[176:179], v191 offset:4096
	ds_read_b128 v[180:183], v191 offset:6144
	ds_read_b128 v[192:195], v190 offset:4096
	ds_read_b128 v[196:199], v190 offset:6144
	s_mov_b32 m0, s14
	s_nop 0
	global_load_lds_dwordx4 v184, s[12:13]
	s_mov_b32 m0, s15
	s_nop 0
	global_load_lds_dwordx4 v234, s[12:13]
	s_waitcnt vmcnt(8)
	s_waitcnt lgkmcnt(0)
	s_setprio 1
	s_barrier
; #define PG8_STAGE(bufoff, gbase, voff) do { _Pragma("unroll") for (int _i = 0; _i < 2; ++_i) \
;         dma16((const char*)(gbase), (voff)[_i], ldsb + (bufoff) + ldsw + _i * 8192); } while (0)
; #define PG8_LDA(dst, b, h) do { const int a1_ = opqv(aoff0) ^ 64; _Pragma("unroll") for (int m = 0; m < 4; ++m) { dst[m][0] = *(const LAS bf16x8*)(lds + PG8_SA(b, h) + aoff0 + m * 2048); dst[m][1] = *(const LAS bf16x8*)(lds + PG8_SA(b, h) + a1_ + m * 2048); } } while (0)
; #define PG8_MMA(ai, bj, At, Bt) do { __builtin_amdgcn_s_setprio(1); _Pragma("unroll") for (int m = 0; m < 4; ++m) _Pragma("unroll") for (int n = 0; n < 2; ++n) _Pragma("unroll") for (int k = 0; k < 2; ++k) \
;         acc[ai][bj][m][n] = __builtin_amdgcn_mfma_f32_16x16x32_bf16(Bt[n][k], At[m][k], acc[ai][bj][m][n], 0, 0, 0); __builtin_amdgcn_s_setprio(0); } while (0)
; #define PG8_WAIT_V(n) asm volatile("s_waitcnt vmcnt(" #n ")" ::: "memory")
; #define PG8_WAIT_L(n) asm volatile("s_waitcnt lgkmcnt(" #n ")" ::: "memory")
; #define PG8_BAR __builtin_amdgcn_s_barrier()
; #define PG8_SCHED __builtin_amdgcn_sched_barrier(0)
; template <class Epi>
; __device__ __forceinline__ void gemm_phase(LAS unsigned char* lds, const Gemm g, const StaticOrder& S, const Epi& E, int wave_) {
;     ...
;             PG8_WAIT_V(8); PG8_WAIT_L(0); PG8_BAR; PG8_MMA(0, 0, At, B0); PG8_MMA(0, 1, At, B1); PG8_BAR; PG8_SCHED;
;             PG8_STAGE(PG8_SB(0, 0), b2, voffB); PG8_STAGE(PG8_SB(0, 1), b2 + hstepB, voffB); PG8_STAGE(PG8_SA(0, 0), a2, voffA); PG8_LDA(At, 0, 1);
;             PG8_WAIT_V(8); PG8_WAIT_L(0); PG8_BAR; PG8_MMA(1, 0, At, B0); PG8_MMA(1, 1, At, B1); PG8_BAR; PG8_SCHED;
	v_mfma_f32_16x16x32_bf16 v[156:159], v[88:91], v[160:163], v[156:159]
	v_mfma_f32_16x16x32_bf16 v[152:155], v[92:95], v[160:163], v[152:155]
	v_mfma_f32_16x16x32_bf16 v[148:151], v[88:91], v[164:167], v[148:151]
	v_mfma_f32_16x16x32_bf16 v[144:147], v[92:95], v[164:167], v[144:147]
	v_mfma_f32_16x16x32_bf16 v[140:143], v[88:91], v[176:179], v[140:143]
	v_mfma_f32_16x16x32_bf16 v[136:139], v[92:95], v[176:179], v[136:139]
	v_mfma_f32_16x16x32_bf16 v[132:135], v[88:91], v[180:183], v[132:135]
	v_mfma_f32_16x16x32_bf16 v[128:131], v[92:95], v[180:183], v[128:131]
	v_mfma_f32_16x16x32_bf16 v[156:159], v[96:99], v[168:171], v[156:159]
	v_mfma_f32_16x16x32_bf16 v[152:155], v[100:103], v[168:171], v[152:155]
	v_mfma_f32_16x16x32_bf16 v[148:151], v[96:99], v[172:175], v[148:151]
	v_mfma_f32_16x16x32_bf16 v[144:147], v[100:103], v[172:175], v[144:147]
	v_mfma_f32_16x16x32_bf16 v[140:143], v[96:99], v[192:195], v[140:143]
	v_mfma_f32_16x16x32_bf16 v[136:139], v[100:103], v[192:195], v[136:139]
	v_mfma_f32_16x16x32_bf16 v[132:135], v[96:99], v[196:199], v[132:135]
	v_mfma_f32_16x16x32_bf16 v[128:131], v[100:103], v[196:199], v[128:131]
	s_setprio 0
	s_setprio 1
	v_mfma_f32_16x16x32_bf16 v[60:63], v[108:111], v[160:163], v[60:63]
	v_mfma_f32_16x16x32_bf16 v[56:59], v[112:115], v[160:163], v[56:59]
	v_mfma_f32_16x16x32_bf16 v[52:55], v[108:111], v[164:167], v[52:55]
	v_mfma_f32_16x16x32_bf16 v[48:51], v[112:115], v[164:167], v[48:51]
	v_mfma_f32_16x16x32_bf16 v[44:47], v[108:111], v[176:179], v[44:47]
	v_mfma_f32_16x16x32_bf16 v[40:43], v[112:115], v[176:179], v[40:43]
	v_mfma_f32_16x16x32_bf16 v[36:39], v[108:111], v[180:183], v[36:39]
	v_mfma_f32_16x16x32_bf16 v[32:35], v[112:115], v[180:183], v[32:35]
	v_mfma_f32_16x16x32_bf16 v[60:63], v[120:123], v[168:171], v[60:63]
	v_mfma_f32_16x16x32_bf16 v[56:59], v[124:127], v[168:171], v[56:59]
	v_mfma_f32_16x16x32_bf16 v[52:55], v[120:123], v[172:175], v[52:55]
	v_mfma_f32_16x16x32_bf16 v[48:51], v[124:127], v[172:175], v[48:51]
	v_mfma_f32_16x16x32_bf16 v[44:47], v[120:123], v[192:195], v[44:47]
	v_mfma_f32_16x16x32_bf16 v[40:43], v[124:127], v[192:195], v[40:43]
	v_mfma_f32_16x16x32_bf16 v[36:39], v[120:123], v[196:199], v[36:39]
	v_mfma_f32_16x16x32_bf16 v[32:35], v[124:127], v[196:199], v[32:35]
	s_barrier
	s_setprio 0
	v_mov_b32_e32 v160, v237
	s_add_u32 s82, s48, 0x80000
	s_addc_u32 s83, s49, 0
	s_nop 0
	s_nop 0
	s_nop 0
	v_xad_u32 v190, v160, 64, 0
	ds_read_b128 v[160:163], v191 offset:16384
	ds_read_b128 v[164:167], v191 offset:18432
	ds_read_b128 v[168:171], v190 offset:16384
	ds_read_b128 v[172:175], v190 offset:18432
	ds_read_b128 v[176:179], v191 offset:20480
	ds_read_b128 v[180:183], v191 offset:22528
	ds_read_b128 v[192:195], v190 offset:20480
	ds_read_b128 v[196:199], v190 offset:22528
	s_mov_b32 m0, s80
	s_nop 0
	global_load_lds_dwordx4 v233, s[48:49]
	s_mov_b32 m0, s81
	s_nop 0
	global_load_lds_dwordx4 v235, s[48:49]
	s_mov_b32 m0, s29
	s_nop 0
	global_load_lds_dwordx4 v233, s[82:83]
	s_mov_b32 m0, s88
	s_nop 0
	global_load_lds_dwordx4 v235, s[82:83]
	s_mov_b32 m0, s76
	s_nop 0
	global_load_lds_dwordx4 v184, s[64:65]
	s_mov_b32 m0, s89
	s_nop 0
	global_load_lds_dwordx4 v234, s[64:65]
	s_waitcnt vmcnt(8)
	s_waitcnt lgkmcnt(0)
	s_setprio 1
	s_barrier
	v_mfma_f32_16x16x32_bf16 v[116:119], v[88:91], v[160:163], v[116:119]
	v_mfma_f32_16x16x32_bf16 v[104:107], v[92:95], v[160:163], v[104:107]
	v_mfma_f32_16x16x32_bf16 v[84:87], v[88:91], v[164:167], v[84:87]
	v_mfma_f32_16x16x32_bf16 v[80:83], v[92:95], v[164:167], v[80:83]
	v_mfma_f32_16x16x32_bf16 v[76:79], v[88:91], v[176:179], v[76:79]
	v_mfma_f32_16x16x32_bf16 v[72:75], v[92:95], v[176:179], v[72:75]
	v_mfma_f32_16x16x32_bf16 v[68:71], v[88:91], v[180:183], v[68:71]
	v_mfma_f32_16x16x32_bf16 v[64:67], v[92:95], v[180:183], v[64:67]
	v_mfma_f32_16x16x32_bf16 v[116:119], v[96:99], v[168:171], v[116:119]
	v_mfma_f32_16x16x32_bf16 v[104:107], v[100:103], v[168:171], v[104:107]
	v_mfma_f32_16x16x32_bf16 v[84:87], v[96:99], v[172:175], v[84:87]
	v_mfma_f32_16x16x32_bf16 v[80:83], v[100:103], v[172:175], v[80:83]
	v_mfma_f32_16x16x32_bf16 v[76:79], v[96:99], v[192:195], v[76:79]
	v_mfma_f32_16x16x32_bf16 v[72:75], v[100:103], v[192:195], v[72:75]
	v_mfma_f32_16x16x32_bf16 v[68:71], v[96:99], v[196:199], v[68:71]
	v_mfma_f32_16x16x32_bf16 v[64:67], v[100:103], v[196:199], v[64:67]
	s_setprio 0
	s_setprio 1
	v_mfma_f32_16x16x32_bf16 v[28:31], v[108:111], v[160:163], v[28:31]
	v_mfma_f32_16x16x32_bf16 v[24:27], v[112:115], v[160:163], v[24:27]
	v_mfma_f32_16x16x32_bf16 v[20:23], v[108:111], v[164:167], v[20:23]
	v_mfma_f32_16x16x32_bf16 v[16:19], v[112:115], v[164:167], v[16:19]
	v_mfma_f32_16x16x32_bf16 v[12:15], v[108:111], v[176:179], v[12:15]
	v_mfma_f32_16x16x32_bf16 v[8:11], v[112:115], v[176:179], v[8:11]
	v_mfma_f32_16x16x32_bf16 v[4:7], v[108:111], v[180:183], v[4:7]
	v_mfma_f32_16x16x32_bf16 v[0:3], v[112:115], v[180:183], v[0:3]
	v_mfma_f32_16x16x32_bf16 v[28:31], v[120:123], v[168:171], v[28:31]
	v_mfma_f32_16x16x32_bf16 v[24:27], v[124:127], v[168:171], v[24:27]
	v_mfma_f32_16x16x32_bf16 v[20:23], v[120:123], v[172:175], v[20:23]
	v_mfma_f32_16x16x32_bf16 v[16:19], v[124:127], v[172:175], v[16:19]
	v_mfma_f32_16x16x32_bf16 v[12:15], v[120:123], v[192:195], v[12:15]
	v_mfma_f32_16x16x32_bf16 v[8:11], v[124:127], v[192:195], v[8:11]
	v_mfma_f32_16x16x32_bf16 v[4:7], v[120:123], v[196:199], v[4:7]
	v_mfma_f32_16x16x32_bf16 v[0:3], v[124:127], v[196:199], v[0:3]
	s_barrier
; #define PG8_STAGE(bufoff, gbase, voff) do { _Pragma("unroll") for (int _i = 0; _i < 2; ++_i) \
;         dma16((const char*)(gbase), (voff)[_i], ldsb + (bufoff) + ldsw + _i * 8192); } while (0)
; #define PG8_LDA(dst, b, h) do { const int a1_ = opqv(aoff0) ^ 64; _Pragma("unroll") for (int m = 0; m < 4; ++m) { dst[m][0] = *(const LAS bf16x8*)(lds + PG8_SA(b, h) + aoff0 + m * 2048); dst[m][1] = *(const LAS bf16x8*)(lds + PG8_SA(b, h) + a1_ + m * 2048); } } while (0)
; #define PG8_LDB(dst, b, h) do { const int b1_ = opqv(boff0) ^ 64; _Pragma("unroll") for (int n = 0; n < 2; ++n) { dst[n][0] = *(const LAS bf16x8*)(lds + PG8_SB(b, h) + boff0 + n * 2048); dst[n][1] = *(const LAS bf16x8*)(lds + PG8_SB(b, h) + b1_ + n * 2048); } } while (0)
; #define PG8_MMA(ai, bj, At, Bt) do { __builtin_amdgcn_s_setprio(1); _Pragma("unroll") for (int m = 0; m < 4; ++m) _Pragma("unroll") for (int n = 0; n < 2; ++n) _Pragma("unroll") for (int k = 0; k < 2; ++k) \
;         acc[ai][bj][m][n] = __builtin_amdgcn_mfma_f32_16x16x32_bf16(Bt[n][k], At[m][k], acc[ai][bj][m][n], 0, 0, 0); __builtin_amdgcn_s_setprio(0); } while (0)
; #define PG8_WAIT_V(n) asm volatile("s_waitcnt vmcnt(" #n ")" ::: "memory")
; #define PG8_WAIT_L(n) asm volatile("s_waitcnt lgkmcnt(" #n ")" ::: "memory")
; #define PG8_BAR __builtin_amdgcn_s_barrier()
; #define PG8_SCHED __builtin_amdgcn_sched_barrier(0)
; template <class Epi>
; __device__ __forceinline__ void gemm_phase(LAS unsigned char* lds, const Gemm g, const StaticOrder& S, const Epi& E, int wave_) {
;     ...
;             PG8_STAGE(PG8_SA(0, 1), a2 + hstepA, voffA); PG8_LDB(B0, 1, 0); PG8_LDB(B1, 1, 1); PG8_SCHED; PG8_LDA(At, 1, 0);
;             PG8_WAIT_V(8); PG8_WAIT_L(0); PG8_BAR; PG8_MMA(0, 0, At, B0); PG8_MMA(0, 1, At, B1); PG8_BAR; PG8_SCHED;
;             PG8_STAGE(PG8_SB(1, 0), b3, voffB); PG8_STAGE(PG8_SB(1, 1), b3 + hstepB, voffB); PG8_STAGE(PG8_SA(1, 0), a3, voffA); PG8_LDA(At, 1, 1);
;             PG8_WAIT_V(8); PG8_WAIT_L(0); PG8_BAR; PG8_MMA(1, 0, At, B0); PG8_MMA(1, 1, At, B1); PG8_BAR; PG8_SCHED;
;         }
	s_setprio 0
	s_add_u32 s64, s64, 0x80000
	s_addc_u32 s65, s65, 0
	s_mov_b32 m0, s1
	s_nop 0
	global_load_lds_dwordx4 v184, s[64:65]
	v_mov_b32_e32 v88, v238
	s_mov_b32 m0, s69
	s_nop 0
	global_load_lds_dwordx4 v234, s[64:65]
	v_add_u32_e32 v92, s34, v238
	v_xad_u32 v100, v88, 64, s34
	v_mov_b32_e32 v108, v238
	s_add_i32 s64, 0, 0x1c000
	ds_read_b128 v[88:91], v92
	ds_read_b128 v[92:95], v92 offset:2048
	ds_read_b128 v[96:99], v100
	ds_read_b128 v[100:103], v100 offset:2048
	v_add_u32_e32 v112, s64, v238
	v_xad_u32 v124, v108, 64, s64
	ds_read_b128 v[108:111], v112
	ds_read_b128 v[112:115], v112 offset:2048
	ds_read_b128 v[120:123], v124
	ds_read_b128 v[124:127], v124 offset:2048
	v_mov_b32_e32 v160, v237
	s_nop 0
	v_xad_u32 v190, v160, 64, 0
	ds_read_b128 v[160:163], v191 offset:32768
	ds_read_b128 v[164:167], v191 offset:34816
	ds_read_b128 v[168:171], v190 offset:32768
	ds_read_b128 v[172:175], v190 offset:34816
	ds_read_b128 v[176:179], v191 offset:36864
	ds_read_b128 v[180:183], v191 offset:38912
	ds_read_b128 v[192:195], v190 offset:36864
	ds_read_b128 v[196:199], v190 offset:38912
	s_waitcnt vmcnt(8)
	s_waitcnt lgkmcnt(0)
	s_setprio 1
	s_barrier
	v_mfma_f32_16x16x32_bf16 v[156:159], v[88:91], v[160:163], v[156:159]
	v_mfma_f32_16x16x32_bf16 v[152:155], v[92:95], v[160:163], v[152:155]
	v_mfma_f32_16x16x32_bf16 v[148:151], v[88:91], v[164:167], v[148:151]
	v_mfma_f32_16x16x32_bf16 v[144:147], v[92:95], v[164:167], v[144:147]
	v_mfma_f32_16x16x32_bf16 v[140:143], v[88:91], v[176:179], v[140:143]
	v_mfma_f32_16x16x32_bf16 v[136:139], v[92:95], v[176:179], v[136:139]
	v_mfma_f32_16x16x32_bf16 v[132:135], v[88:91], v[180:183], v[132:135]
	v_mfma_f32_16x16x32_bf16 v[128:131], v[92:95], v[180:183], v[128:131]
	v_mfma_f32_16x16x32_bf16 v[156:159], v[96:99], v[168:171], v[156:159]
	v_mfma_f32_16x16x32_bf16 v[152:155], v[100:103], v[168:171], v[152:155]
	v_mfma_f32_16x16x32_bf16 v[148:151], v[96:99], v[172:175], v[148:151]
	v_mfma_f32_16x16x32_bf16 v[144:147], v[100:103], v[172:175], v[144:147]
	v_mfma_f32_16x16x32_bf16 v[140:143], v[96:99], v[192:195], v[140:143]
	v_mfma_f32_16x16x32_bf16 v[136:139], v[100:103], v[192:195], v[136:139]
	v_mfma_f32_16x16x32_bf16 v[132:135], v[96:99], v[196:199], v[132:135]
	v_mfma_f32_16x16x32_bf16 v[128:131], v[100:103], v[196:199], v[128:131]
	s_setprio 0
	s_setprio 1
	v_mfma_f32_16x16x32_bf16 v[60:63], v[108:111], v[160:163], v[60:63]
	s_add_u32 s64, s48, 0x80
	s_addc_u32 s65, s49, 0
	v_mfma_f32_16x16x32_bf16 v[56:59], v[112:115], v[160:163], v[56:59]
	v_mfma_f32_16x16x32_bf16 v[52:55], v[108:111], v[164:167], v[52:55]
	v_mfma_f32_16x16x32_bf16 v[48:51], v[112:115], v[164:167], v[48:51]
	v_mfma_f32_16x16x32_bf16 v[44:47], v[108:111], v[176:179], v[44:47]
	v_mfma_f32_16x16x32_bf16 v[40:43], v[112:115], v[176:179], v[40:43]
	v_mfma_f32_16x16x32_bf16 v[36:39], v[108:111], v[180:183], v[36:39]
	v_mfma_f32_16x16x32_bf16 v[32:35], v[112:115], v[180:183], v[32:35]
	v_mfma_f32_16x16x32_bf16 v[60:63], v[120:123], v[168:171], v[60:63]
	v_mfma_f32_16x16x32_bf16 v[56:59], v[124:127], v[168:171], v[56:59]
	v_mfma_f32_16x16x32_bf16 v[52:55], v[120:123], v[172:175], v[52:55]
	v_mfma_f32_16x16x32_bf16 v[48:51], v[124:127], v[172:175], v[48:51]
	v_mfma_f32_16x16x32_bf16 v[44:47], v[120:123], v[192:195], v[44:47]
	v_mfma_f32_16x16x32_bf16 v[40:43], v[124:127], v[192:195], v[40:43]
	v_mfma_f32_16x16x32_bf16 v[36:39], v[120:123], v[196:199], v[36:39]
	v_mfma_f32_16x16x32_bf16 v[32:35], v[124:127], v[196:199], v[32:35]
	s_barrier
	s_setprio 0
	s_add_u32 s48, s48, 0x80080
	s_addc_u32 s49, s49, 0
	v_mov_b32_e32 v160, v237
	s_nop 0
	s_nop 0
	v_xad_u32 v190, v160, 64, 0
	ds_read_b128 v[160:163], v191 offset:49152
	ds_read_b128 v[164:167], v191 offset:51200
	ds_read_b128 v[168:171], v190 offset:49152
	ds_read_b128 v[172:175], v190 offset:51200
	ds_read_b128 v[176:179], v191 offset:53248
	ds_read_b128 v[180:183], v191 offset:55296
	ds_read_b128 v[192:195], v190 offset:53248
	ds_read_b128 v[196:199], v190 offset:55296
	s_mov_b32 m0, s35
	s_nop 0
	global_load_lds_dwordx4 v233, s[64:65]
	s_mov_b32 m0, s33
	s_nop 0
	global_load_lds_dwordx4 v235, s[64:65]
	s_mov_b32 m0, s77
	s_nop 0
	global_load_lds_dwordx4 v233, s[48:49]
	s_mov_b32 m0, s3
	s_nop 0
	global_load_lds_dwordx4 v235, s[48:49]
	s_mov_b32 m0, s22
	s_nop 0
	global_load_lds_dwordx4 v184, s[46:47]
	s_mov_b32 m0, s2
	s_nop 0
	global_load_lds_dwordx4 v234, s[46:47]
	s_waitcnt vmcnt(8)
	s_waitcnt lgkmcnt(0)
	s_setprio 1
	s_barrier
	v_mfma_f32_16x16x32_bf16 v[116:119], v[88:91], v[160:163], v[116:119]
	v_mfma_f32_16x16x32_bf16 v[104:107], v[92:95], v[160:163], v[104:107]
	v_mfma_f32_16x16x32_bf16 v[84:87], v[88:91], v[164:167], v[84:87]
	v_mfma_f32_16x16x32_bf16 v[80:83], v[92:95], v[164:167], v[80:83]
	v_mfma_f32_16x16x32_bf16 v[76:79], v[88:91], v[176:179], v[76:79]
	v_mfma_f32_16x16x32_bf16 v[72:75], v[92:95], v[176:179], v[72:75]
	v_mfma_f32_16x16x32_bf16 v[68:71], v[88:91], v[180:183], v[68:71]
	v_mfma_f32_16x16x32_bf16 v[64:67], v[92:95], v[180:183], v[64:67]
	v_mfma_f32_16x16x32_bf16 v[116:119], v[96:99], v[168:171], v[116:119]
	v_mfma_f32_16x16x32_bf16 v[104:107], v[100:103], v[168:171], v[104:107]
	v_mfma_f32_16x16x32_bf16 v[84:87], v[96:99], v[172:175], v[84:87]
	v_mfma_f32_16x16x32_bf16 v[80:83], v[100:103], v[172:175], v[80:83]
	v_mfma_f32_16x16x32_bf16 v[76:79], v[96:99], v[192:195], v[76:79]
	v_mfma_f32_16x16x32_bf16 v[72:75], v[100:103], v[192:195], v[72:75]
	v_mfma_f32_16x16x32_bf16 v[68:71], v[96:99], v[196:199], v[68:71]
	v_mfma_f32_16x16x32_bf16 v[64:67], v[100:103], v[196:199], v[64:67]
	s_setprio 0
	s_setprio 1
	v_mfma_f32_16x16x32_bf16 v[28:31], v[108:111], v[160:163], v[28:31]
	v_mfma_f32_16x16x32_bf16 v[24:27], v[112:115], v[160:163], v[24:27]
	v_mfma_f32_16x16x32_bf16 v[20:23], v[108:111], v[164:167], v[20:23]
	v_mfma_f32_16x16x32_bf16 v[16:19], v[112:115], v[164:167], v[16:19]
	v_mfma_f32_16x16x32_bf16 v[12:15], v[108:111], v[176:179], v[12:15]
	v_mfma_f32_16x16x32_bf16 v[8:11], v[112:115], v[176:179], v[8:11]
	v_mfma_f32_16x16x32_bf16 v[4:7], v[108:111], v[180:183], v[4:7]
	v_mfma_f32_16x16x32_bf16 v[0:3], v[112:115], v[180:183], v[0:3]
	v_mfma_f32_16x16x32_bf16 v[28:31], v[120:123], v[168:171], v[28:31]
	v_mfma_f32_16x16x32_bf16 v[24:27], v[124:127], v[168:171], v[24:27]
	v_mfma_f32_16x16x32_bf16 v[20:23], v[120:123], v[172:175], v[20:23]
	v_mfma_f32_16x16x32_bf16 v[16:19], v[124:127], v[172:175], v[16:19]
	v_mfma_f32_16x16x32_bf16 v[12:15], v[120:123], v[192:195], v[12:15]
	v_mfma_f32_16x16x32_bf16 v[8:11], v[124:127], v[192:195], v[8:11]
	v_mfma_f32_16x16x32_bf16 v[4:7], v[120:123], v[196:199], v[4:7]
	v_mfma_f32_16x16x32_bf16 v[0:3], v[124:127], v[196:199], v[0:3]
	s_barrier
	s_setprio 0
	s_add_i32 s79, s79, 2
	s_add_u32 s75, s75, 0x100
	s_addc_u32 s78, s78, 0
	s_add_u32 s12, s12, 0x100
	s_addc_u32 s13, s13, 0
	s_cmp_gt_u32 s79, 29
	s_cbranch_scc0 .LBB0_1776
